# merged GEMM phases + all 16 LDS reads issued first in X load part (DMA temp renamed)
# speedup vs baseline: 1.0085x; 1.0085x over previous
; #define PG8_STAGE(bufoff, gbase, voff) do { _Pragma("unroll") for (int _i = 0; _i < 2; ++_i) \
;         __builtin_amdgcn_global_load_lds((const unsigned*)((const char*)(gbase) + (voff)[_i]), (PG8_LAS unsigned*)(lds + (bufoff) + ldsw + _i * 8192), 16, 0, 0); } while (0)
; #define PG8_LDA(dst, b, h) do { _Pragma("unroll") for (int m = 0; m < 4; ++m) _Pragma("unroll") for (int k = 0; k < 2; ++k) dst[m][k] = *(const PG8_LAS bf16x8*)(lds + PG8_SA(b, h) + aoff + m * 2048 + k * 1024); } while (0)
; #define PG8_LDB(dst, b, h) do { _Pragma("unroll") for (int n = 0; n < 2; ++n) _Pragma("unroll") for (int k = 0; k < 2; ++k) dst[n][k] = *(const PG8_LAS bf16x8*)(lds + PG8_SB(b, h) + boff + n * 2048 + k * 1024); } while (0)
; #define PG8_WAIT_V(n) asm volatile("s_waitcnt vmcnt(" #n ")" ::: "memory")
; #define PG8_WAIT_L(n) asm volatile("s_waitcnt lgkmcnt(" #n ")" ::: "memory")
; #define PG8_BAR __builtin_amdgcn_s_barrier()
; #define PG8_SCHED __builtin_amdgcn_sched_barrier(0)
; template <class Epi>
; __device__ __forceinline__ void gemm_phase(PG8_LAS unsigned char* lds, const Gemm g, const StaticOrder& S, const Epi& E) {
;     ...
;     for (;;) {
;         const bool has_next = S.next(ui + 1, nxt);
;         const char* nA = has_next ? (const char*)g.A + (size_t)nxt.pm * tstepA : cA; const char* nB = has_next ? (const char*)g.Bt + (size_t)nxt.pn * tstepB : cB;
;         for (int t = 0; t < nt; t += 2) {
;             const bool last = (t == nt - 2);
;             const char* a1 = cA + (size_t)(t + 1) * kstep;
;             const char* a2 = last ? nA : cA + (size_t)(t + 2) * kstep; const char* b2 = last ? nB : cB + (size_t)(t + 2) * kstep;
;             const char* a3 = a2 + kstep; const char* b3 = b2 + kstep;
;             PG8_LDB(B0, 0, 0); PG8_SCHED; PG8_LDA(At, 0, 0); PG8_STAGE(PG8_SA(1, 1), a1 + hstepA, voffA);
;             PG8_WAIT_L(8); PG8_BAR; PG8_WAIT_L(0); PG8_MMA(0, 0, At, B0); PG8_BAR; PG8_SCHED;
;             PG8_LDB(B1, 0, 1); PG8_STAGE(PG8_SB(0, 0), b2, voffB);
;             PG8_BAR; PG8_WAIT_L(0); PG8_MMA(0, 1, At, B1); PG8_BAR;
;             PG8_LDA(At, 0, 1); PG8_STAGE(PG8_SA(0, 0), a2, voffA);
;             PG8_BAR; PG8_WAIT_L(0); PG8_MMA(1, 0, At, B0); PG8_BAR; PG8_SCHED;
;             PG8_STAGE(PG8_SB(0, 1), b2 + hstepB, voffB);
;             PG8_WAIT_V(6); PG8_BAR; PG8_MMA(1, 1, At, B1); PG8_BAR;
.LBB0_226:
	ds_read_b128 v[0:3], v174
	ds_read_b128 v[4:7], v174 offset:1024
	ds_read_b128 v[156:159], v174 offset:2048
	ds_read_b128 v[160:163], v174 offset:3072
	ds_read_b128 v[164:167], v175
	ds_read_b128 v[178:181], v175 offset:1024
	ds_read_b128 v[182:185], v175 offset:2048
	ds_read_b128 v[186:189], v175 offset:3072
	ds_read_b128 v[190:193], v175 offset:4096
	ds_read_b128 v[194:197], v175 offset:5120
	ds_read_b128 v[198:201], v175 offset:6144
	ds_read_b128 v[202:205], v175 offset:7168
	ds_read_b128 v[206:209], v176
	ds_read_b128 v[210:213], v176 offset:1024
	ds_read_b128 v[214:217], v176 offset:2048
	ds_read_b128 v[218:221], v176 offset:3072
	s_add_u32 s4, s0, 0xfff80080
	s_addc_u32 s5, s1, -1
	s_cmp_eq_u32 s62, 28
	s_cselect_b32 s7, s47, s5
	s_cselect_b32 s6, s49, s4
	s_cselect_b32 s5, s51, s61
	s_cselect_b32 s4, s53, s60
	v_lshl_add_u64 v[170:171], s[0:1], 0, v[148:149]
	s_add_i32 m0, s14, 0xc000
	s_nop 0
	global_load_lds_dwordx4 v[170:171], off
	v_lshl_add_u64 v[170:171], s[0:1], 0, v[150:151]
	s_add_i32 m0, s14, 0xe000
	s_nop 0
	global_load_lds_dwordx4 v[170:171], off
	s_waitcnt lgkmcnt(0)
	s_waitcnt vmcnt(8)
	s_barrier
	s_setprio 1
	v_mfma_f32_16x16x32_bf16 v[132:135], v[0:3], v[164:167], v[132:135]
	v_mfma_f32_16x16x32_bf16 v[124:127], v[156:159], v[164:167], v[124:127]
	v_mfma_f32_16x16x32_bf16 v[116:119], v[0:3], v[182:185], v[116:119]
	v_mfma_f32_16x16x32_bf16 v[108:111], v[156:159], v[182:185], v[108:111]
	v_mfma_f32_16x16x32_bf16 v[100:103], v[0:3], v[190:193], v[100:103]
	v_mfma_f32_16x16x32_bf16 v[92:95], v[156:159], v[190:193], v[92:95]
	v_mfma_f32_16x16x32_bf16 v[84:87], v[0:3], v[198:201], v[84:87]
	v_mfma_f32_16x16x32_bf16 v[76:79], v[156:159], v[198:201], v[76:79]
	v_mfma_f32_16x16x32_bf16 v[132:135], v[4:7], v[178:181], v[132:135]
	v_mfma_f32_16x16x32_bf16 v[124:127], v[160:163], v[178:181], v[124:127]
	v_mfma_f32_16x16x32_bf16 v[116:119], v[4:7], v[186:189], v[116:119]
	v_mfma_f32_16x16x32_bf16 v[108:111], v[160:163], v[186:189], v[108:111]
	v_mfma_f32_16x16x32_bf16 v[100:103], v[4:7], v[194:197], v[100:103]
	v_mfma_f32_16x16x32_bf16 v[92:95], v[160:163], v[194:197], v[92:95]
	v_mfma_f32_16x16x32_bf16 v[84:87], v[4:7], v[202:205], v[84:87]
	v_mfma_f32_16x16x32_bf16 v[76:79], v[160:163], v[202:205], v[76:79]
	v_mfma_f32_16x16x32_bf16 v[128:131], v[206:209], v[164:167], v[128:131]
	v_mfma_f32_16x16x32_bf16 v[120:123], v[214:217], v[164:167], v[120:123]
	v_mfma_f32_16x16x32_bf16 v[112:115], v[206:209], v[182:185], v[112:115]
	v_mfma_f32_16x16x32_bf16 v[104:107], v[214:217], v[182:185], v[104:107]
	v_mfma_f32_16x16x32_bf16 v[96:99], v[206:209], v[190:193], v[96:99]
	v_mfma_f32_16x16x32_bf16 v[88:91], v[214:217], v[190:193], v[88:91]
	v_mfma_f32_16x16x32_bf16 v[80:83], v[206:209], v[198:201], v[80:83]
	v_mfma_f32_16x16x32_bf16 v[72:75], v[214:217], v[198:201], v[72:75]
	v_mfma_f32_16x16x32_bf16 v[128:131], v[210:213], v[178:181], v[128:131]
	v_mfma_f32_16x16x32_bf16 v[120:123], v[218:221], v[178:181], v[120:123]
	v_mfma_f32_16x16x32_bf16 v[112:115], v[210:213], v[186:189], v[112:115]
	v_mfma_f32_16x16x32_bf16 v[104:107], v[218:221], v[186:189], v[104:107]
	v_mfma_f32_16x16x32_bf16 v[96:99], v[210:213], v[194:197], v[96:99]
	v_mfma_f32_16x16x32_bf16 v[88:91], v[218:221], v[194:197], v[88:91]
	v_mfma_f32_16x16x32_bf16 v[80:83], v[210:213], v[202:205], v[80:83]
	v_mfma_f32_16x16x32_bf16 v[72:75], v[218:221], v[202:205], v[72:75]
	s_setprio 0
	s_barrier
	ds_read_b128 v[164:167], v175 offset:16384
	ds_read_b128 v[178:181], v175 offset:17408
	ds_read_b128 v[182:185], v175 offset:18432
	ds_read_b128 v[186:189], v175 offset:19456
	ds_read_b128 v[190:193], v175 offset:20480
	ds_read_b128 v[194:197], v175 offset:21504
	ds_read_b128 v[198:201], v175 offset:22528
	ds_read_b128 v[202:205], v175 offset:23552
	s_add_i32 s63, s37, s11
	v_lshl_add_u64 v[170:171], s[4:5], 0, v[142:143]
	s_mov_b32 m0, s63
	s_nop 0
	global_load_lds_dwordx4 v[170:171], off
	v_lshl_add_u64 v[222:223], s[4:5], 0, v[138:139]
	s_add_i32 m0, s63, 0x2000
	s_nop 0
	global_load_lds_dwordx4 v[222:223], off
	s_mov_b32 m0, s14
	v_lshl_add_u64 v[224:225], s[6:7], 0, v[144:145]
	global_load_lds_dwordx4 v[224:225], off
	v_lshl_add_u64 v[226:227], s[6:7], 0, v[140:141]
	s_mov_b32 m0, s15
	s_nop 0
	global_load_lds_dwordx4 v[226:227], off
	s_add_u32 s64, s4, 0x80000
	s_addc_u32 s65, s5, 0
	s_add_i32 s63, s38, s11
	v_lshl_add_u64 v[228:229], s[64:65], 0, v[142:143]
	s_mov_b32 m0, s63
	s_nop 0
	global_load_lds_dwordx4 v[228:229], off
	v_lshl_add_u64 v[228:229], s[64:65], 0, v[138:139]
	s_add_i32 m0, s63, 0x2000
	s_nop 0
	global_load_lds_dwordx4 v[228:229], off
	s_waitcnt lgkmcnt(0)
	s_waitcnt vmcnt(8)
	s_barrier
; #define PG8_STAGE(bufoff, gbase, voff) do { _Pragma("unroll") for (int _i = 0; _i < 2; ++_i) \
;         __builtin_amdgcn_global_load_lds((const unsigned*)((const char*)(gbase) + (voff)[_i]), (PG8_LAS unsigned*)(lds + (bufoff) + ldsw + _i * 8192), 16, 0, 0); } while (0)
; #define PG8_LDA(dst, b, h) do { _Pragma("unroll") for (int m = 0; m < 4; ++m) _Pragma("unroll") for (int k = 0; k < 2; ++k) dst[m][k] = *(const PG8_LAS bf16x8*)(lds + PG8_SA(b, h) + aoff + m * 2048 + k * 1024); } while (0)
; #define PG8_LDB(dst, b, h) do { _Pragma("unroll") for (int n = 0; n < 2; ++n) _Pragma("unroll") for (int k = 0; k < 2; ++k) dst[n][k] = *(const PG8_LAS bf16x8*)(lds + PG8_SB(b, h) + boff + n * 2048 + k * 1024); } while (0)
; #define PG8_MMA(ai, bj, At, Bt) do { __builtin_amdgcn_s_setprio(1); _Pragma("unroll") for (int m = 0; m < 4; ++m) _Pragma("unroll") for (int n = 0; n < 2; ++n) _Pragma("unroll") for (int k = 0; k < 2; ++k) \
;         acc[ai][bj][m][n] = __builtin_amdgcn_mfma_f32_16x16x32_bf16(Bt[n][k], At[m][k], acc[ai][bj][m][n], 0, 0, 0); __builtin_amdgcn_s_setprio(0); } while (0)
; #define PG8_WAIT_V(n) asm volatile("s_waitcnt vmcnt(" #n ")" ::: "memory")
; #define PG8_WAIT_L(n) asm volatile("s_waitcnt lgkmcnt(" #n ")" ::: "memory")
; #define PG8_BAR __builtin_amdgcn_s_barrier()
; #define PG8_SCHED __builtin_amdgcn_sched_barrier(0)
; template <class Epi>
; __device__ __forceinline__ void gemm_phase(PG8_LAS unsigned char* lds, const Gemm g, const StaticOrder& S, const Epi& E) {
;     ...
;             PG8_BAR; PG8_WAIT_L(0); PG8_MMA(1, 0, At, B0); PG8_BAR; PG8_SCHED;
;             PG8_STAGE(PG8_SB(0, 1), b2 + hstepB, voffB);
;             PG8_WAIT_V(6); PG8_BAR; PG8_MMA(1, 1, At, B1); PG8_BAR;
;             PG8_LDB(B0, 1, 0); PG8_SCHED; PG8_LDA(At, 1, 0); PG8_STAGE(PG8_SA(0, 1), a2 + hstepA, voffA);
;             PG8_WAIT_L(8); PG8_BAR; PG8_WAIT_L(0); PG8_MMA(0, 0, At, B0); PG8_BAR; PG8_SCHED;
	s_setprio 1
	v_mfma_f32_16x16x32_bf16 v[68:71], v[0:3], v[164:167], v[68:71]
	v_mfma_f32_16x16x32_bf16 v[60:63], v[156:159], v[164:167], v[60:63]
	v_mfma_f32_16x16x32_bf16 v[52:55], v[0:3], v[182:185], v[52:55]
	v_mfma_f32_16x16x32_bf16 v[44:47], v[156:159], v[182:185], v[44:47]
	v_mfma_f32_16x16x32_bf16 v[36:39], v[0:3], v[190:193], v[36:39]
	v_mfma_f32_16x16x32_bf16 v[28:31], v[156:159], v[190:193], v[28:31]
	v_mfma_f32_16x16x32_bf16 v[0:3], v[0:3], v[198:201], v[20:23]
	v_mfma_f32_16x16x32_bf16 v[68:71], v[4:7], v[178:181], v[68:71]
	v_mfma_f32_16x16x32_bf16 v[60:63], v[160:163], v[178:181], v[60:63]
	v_mfma_f32_16x16x32_bf16 v[52:55], v[4:7], v[186:189], v[52:55]
	v_mfma_f32_16x16x32_bf16 v[44:47], v[160:163], v[186:189], v[44:47]
	v_mfma_f32_16x16x32_bf16 v[36:39], v[4:7], v[194:197], v[36:39]
	v_mfma_f32_16x16x32_bf16 v[28:31], v[160:163], v[194:197], v[28:31]
	v_mfma_f32_16x16x32_bf16 v[0:3], v[4:7], v[202:205], v[0:3]
	v_mfma_f32_16x16x32_bf16 v[4:7], v[156:159], v[198:201], v[12:15]
	v_mfma_f32_16x16x32_bf16 v[4:7], v[160:163], v[202:205], v[4:7]
	v_mfma_f32_16x16x32_bf16 v[12:15], v[206:209], v[164:167], v[64:67]
	v_mfma_f32_16x16x32_bf16 v[64:67], v[210:213], v[178:181], v[12:15]
	v_mfma_f32_16x16x32_bf16 v[12:15], v[214:217], v[164:167], v[56:59]
	v_mfma_f32_16x16x32_bf16 v[56:59], v[218:221], v[178:181], v[12:15]
	v_mfma_f32_16x16x32_bf16 v[12:15], v[206:209], v[182:185], v[48:51]
	v_mfma_f32_16x16x32_bf16 v[48:51], v[210:213], v[186:189], v[12:15]
	v_mfma_f32_16x16x32_bf16 v[12:15], v[214:217], v[182:185], v[40:43]
	v_mfma_f32_16x16x32_bf16 v[40:43], v[218:221], v[186:189], v[12:15]
	v_mfma_f32_16x16x32_bf16 v[12:15], v[206:209], v[190:193], v[32:35]
	v_mfma_f32_16x16x32_bf16 v[32:35], v[210:213], v[194:197], v[12:15]
	v_mfma_f32_16x16x32_bf16 v[12:15], v[214:217], v[190:193], v[24:27]
	v_mfma_f32_16x16x32_bf16 v[24:27], v[218:221], v[194:197], v[12:15]
	v_mfma_f32_16x16x32_bf16 v[12:15], v[206:209], v[198:201], v[16:19]
	v_mfma_f32_16x16x32_bf16 v[8:11], v[214:217], v[198:201], v[8:11]
	v_mfma_f32_16x16x32_bf16 v[16:19], v[210:213], v[202:205], v[12:15]
	v_mfma_f32_16x16x32_bf16 v[8:11], v[218:221], v[202:205], v[8:11]
	s_setprio 0
	s_add_i32 s63, 0, 0x18000
	v_add_u32_e32 v160, s63, v169
	s_barrier
	s_nop 0
	s_nop 0
	ds_read_b128 v[12:15], v160
	ds_read_b128 v[20:23], v160 offset:1024
	ds_read_b128 v[156:159], v160 offset:2048
	ds_read_b128 v[160:163], v160 offset:3072
	ds_read_b128 v[164:167], v175 offset:32768
	ds_read_b128 v[178:181], v175 offset:33792
	ds_read_b128 v[182:185], v175 offset:34816
	ds_read_b128 v[186:189], v175 offset:35840
	ds_read_b128 v[190:193], v175 offset:36864
	ds_read_b128 v[194:197], v175 offset:37888
	ds_read_b128 v[198:201], v175 offset:38912
	ds_read_b128 v[202:205], v175 offset:39936
	v_add_u32_e32 v218, 0x1c000, v169
	ds_read_b128 v[206:209], v218
	ds_read_b128 v[210:213], v218 offset:1024
	ds_read_b128 v[214:217], v218 offset:2048
	ds_read_b128 v[218:221], v218 offset:3072
	s_add_u32 s6, s6, 0x80000
	s_addc_u32 s7, s7, 0
	s_mov_b32 m0, s17
	v_lshl_add_u64 v[228:229], s[6:7], 0, v[144:145]
	global_load_lds_dwordx4 v[228:229], off
	v_lshl_add_u64 v[228:229], s[6:7], 0, v[140:141]
	s_mov_b32 m0, s22
	s_nop 0
	global_load_lds_dwordx4 v[228:229], off
	s_waitcnt lgkmcnt(0)
	s_waitcnt vmcnt(8)
	s_barrier
	s_setprio 1
	v_mfma_f32_16x16x32_bf16 v[132:135], v[12:15], v[164:167], v[132:135]
	v_mfma_f32_16x16x32_bf16 v[124:127], v[156:159], v[164:167], v[124:127]
	v_mfma_f32_16x16x32_bf16 v[116:119], v[12:15], v[182:185], v[116:119]
	v_mfma_f32_16x16x32_bf16 v[108:111], v[156:159], v[182:185], v[108:111]
	v_mfma_f32_16x16x32_bf16 v[100:103], v[12:15], v[190:193], v[100:103]
	v_mfma_f32_16x16x32_bf16 v[92:95], v[156:159], v[190:193], v[92:95]
	v_mfma_f32_16x16x32_bf16 v[84:87], v[12:15], v[198:201], v[84:87]
	v_mfma_f32_16x16x32_bf16 v[76:79], v[156:159], v[198:201], v[76:79]
	v_mfma_f32_16x16x32_bf16 v[132:135], v[20:23], v[178:181], v[132:135]
	v_mfma_f32_16x16x32_bf16 v[124:127], v[160:163], v[178:181], v[124:127]
	v_mfma_f32_16x16x32_bf16 v[116:119], v[20:23], v[186:189], v[116:119]
	v_mfma_f32_16x16x32_bf16 v[108:111], v[160:163], v[186:189], v[108:111]
	v_mfma_f32_16x16x32_bf16 v[100:103], v[20:23], v[194:197], v[100:103]
	v_mfma_f32_16x16x32_bf16 v[92:95], v[160:163], v[194:197], v[92:95]
	v_mfma_f32_16x16x32_bf16 v[84:87], v[20:23], v[202:205], v[84:87]
	v_mfma_f32_16x16x32_bf16 v[76:79], v[160:163], v[202:205], v[76:79]
	v_mfma_f32_16x16x32_bf16 v[128:131], v[206:209], v[164:167], v[128:131]
	v_mfma_f32_16x16x32_bf16 v[120:123], v[214:217], v[164:167], v[120:123]
	v_mfma_f32_16x16x32_bf16 v[112:115], v[206:209], v[182:185], v[112:115]
	v_mfma_f32_16x16x32_bf16 v[104:107], v[214:217], v[182:185], v[104:107]
	v_mfma_f32_16x16x32_bf16 v[96:99], v[206:209], v[190:193], v[96:99]
	v_mfma_f32_16x16x32_bf16 v[88:91], v[214:217], v[190:193], v[88:91]
	v_mfma_f32_16x16x32_bf16 v[80:83], v[206:209], v[198:201], v[80:83]
	v_mfma_f32_16x16x32_bf16 v[72:75], v[214:217], v[198:201], v[72:75]
	v_mfma_f32_16x16x32_bf16 v[128:131], v[210:213], v[178:181], v[128:131]
	v_mfma_f32_16x16x32_bf16 v[120:123], v[218:221], v[178:181], v[120:123]
	v_mfma_f32_16x16x32_bf16 v[112:115], v[210:213], v[186:189], v[112:115]
	v_mfma_f32_16x16x32_bf16 v[104:107], v[218:221], v[186:189], v[104:107]
	v_mfma_f32_16x16x32_bf16 v[96:99], v[210:213], v[194:197], v[96:99]
	v_mfma_f32_16x16x32_bf16 v[88:91], v[218:221], v[194:197], v[88:91]
	v_mfma_f32_16x16x32_bf16 v[80:83], v[210:213], v[202:205], v[80:83]
	v_mfma_f32_16x16x32_bf16 v[72:75], v[218:221], v[202:205], v[72:75]
	s_setprio 0
	s_barrier
; #define PG8_STAGE(bufoff, gbase, voff) do { _Pragma("unroll") for (int _i = 0; _i < 2; ++_i) \
;         __builtin_amdgcn_global_load_lds((const unsigned*)((const char*)(gbase) + (voff)[_i]), (PG8_LAS unsigned*)(lds + (bufoff) + ldsw + _i * 8192), 16, 0, 0); } while (0)
; #define PG8_LDA(dst, b, h) do { _Pragma("unroll") for (int m = 0; m < 4; ++m) _Pragma("unroll") for (int k = 0; k < 2; ++k) dst[m][k] = *(const PG8_LAS bf16x8*)(lds + PG8_SA(b, h) + aoff + m * 2048 + k * 1024); } while (0)
; #define PG8_LDB(dst, b, h) do { _Pragma("unroll") for (int n = 0; n < 2; ++n) _Pragma("unroll") for (int k = 0; k < 2; ++k) dst[n][k] = *(const PG8_LAS bf16x8*)(lds + PG8_SB(b, h) + boff + n * 2048 + k * 1024); } while (0)
; #define PG8_MMA(ai, bj, At, Bt) do { __builtin_amdgcn_s_setprio(1); _Pragma("unroll") for (int m = 0; m < 4; ++m) _Pragma("unroll") for (int n = 0; n < 2; ++n) _Pragma("unroll") for (int k = 0; k < 2; ++k) \
;         acc[ai][bj][m][n] = __builtin_amdgcn_mfma_f32_16x16x32_bf16(Bt[n][k], At[m][k], acc[ai][bj][m][n], 0, 0, 0); __builtin_amdgcn_s_setprio(0); } while (0)
; #define PG8_WAIT_V(n) asm volatile("s_waitcnt vmcnt(" #n ")" ::: "memory")
; #define PG8_WAIT_L(n) asm volatile("s_waitcnt lgkmcnt(" #n ")" ::: "memory")
; #define PG8_BAR __builtin_amdgcn_s_barrier()
; #define PG8_SCHED __builtin_amdgcn_sched_barrier(0)
; __device__ __forceinline__ void rstd8(const float* part, int row0, int fq, float (&rs)[8]) {
;     f32x4 v[8][2];
; #pragma unroll
;     for (int k = 0; k < 8; ++k) { const f32x4* p = (const f32x4*)(part + (size_t)(row0 + (k >> 2) * 128 + (k & 3) * 16) * 32 + fq * 8); v[k][0] = p[0]; v[k][1] = p[1]; }
; template <class Epi>
; __device__ __forceinline__ void gemm_phase(PG8_LAS unsigned char* lds, const Gemm g, const StaticOrder& S, const Epi& E) {
;     ...
;             PG8_LDB(B1, 1, 1); PG8_STAGE(PG8_SB(1, 0), b3, voffB);
;             PG8_BAR; PG8_WAIT_L(0); PG8_MMA(0, 1, At, B1); PG8_BAR;
;             PG8_LDA(At, 1, 1); PG8_STAGE(PG8_SA(1, 0), a3, voffA);
;             PG8_BAR; PG8_WAIT_L(0); PG8_MMA(1, 0, At, B0); PG8_BAR; PG8_SCHED;
;             PG8_STAGE(PG8_SB(1, 1), b3 + hstepB, voffB);
;             PG8_WAIT_V(6); PG8_BAR; PG8_MMA(1, 1, At, B1); PG8_BAR;
;         }
;         E(acc, cur, wr, wc, fr, fq);
;         if (!has_next) break;
	ds_read_b128 v[164:167], v175 offset:49152
	ds_read_b128 v[178:181], v175 offset:50176
	ds_read_b128 v[182:185], v175 offset:51200
	ds_read_b128 v[186:189], v175 offset:52224
	ds_read_b128 v[190:193], v175 offset:53248
	ds_read_b128 v[194:197], v175 offset:54272
	ds_read_b128 v[198:201], v175 offset:55296
	ds_read_b128 v[202:205], v175 offset:56320
	s_add_i32 s6, 0, 0x1c000
	s_add_i32 s7, s63, s11
	v_lshl_add_u64 v[170:171], v[170:171], 0, s[18:19]
	s_mov_b32 m0, s7
	s_nop 0
	global_load_lds_dwordx4 v[170:171], off
	v_lshl_add_u64 v[170:171], v[222:223], 0, s[18:19]
	s_add_i32 m0, s7, 0x2000
	s_nop 0
	global_load_lds_dwordx4 v[170:171], off
	s_mov_b32 m0, s31
	v_lshl_add_u64 v[170:171], v[224:225], 0, s[18:19]
	global_load_lds_dwordx4 v[170:171], off
	v_lshl_add_u64 v[170:171], v[226:227], 0, s[18:19]
	s_mov_b32 m0, s34
	s_nop 0
	global_load_lds_dwordx4 v[170:171], off
	s_add_u32 s4, s4, 0x80080
	s_addc_u32 s5, s5, 0
	s_add_i32 s6, s6, s11
	v_lshl_add_u64 v[228:229], s[4:5], 0, v[142:143]
	s_mov_b32 m0, s6
	s_nop 0
	global_load_lds_dwordx4 v[228:229], off
	v_lshl_add_u64 v[228:229], s[4:5], 0, v[138:139]
	s_add_i32 m0, s6, 0x2000
	s_nop 0
	global_load_lds_dwordx4 v[228:229], off
	s_waitcnt lgkmcnt(0)
	s_waitcnt vmcnt(8)
	s_barrier
	s_setprio 1
	v_mfma_f32_16x16x32_bf16 v[68:71], v[12:15], v[164:167], v[68:71]
	v_mfma_f32_16x16x32_bf16 v[52:55], v[12:15], v[182:185], v[52:55]
	v_mfma_f32_16x16x32_bf16 v[36:39], v[12:15], v[190:193], v[36:39]
	v_mfma_f32_16x16x32_bf16 v[0:3], v[12:15], v[198:201], v[0:3]
	v_mfma_f32_16x16x32_bf16 v[68:71], v[20:23], v[178:181], v[68:71]
	v_mfma_f32_16x16x32_bf16 v[60:63], v[156:159], v[164:167], v[60:63]
	v_mfma_f32_16x16x32_bf16 v[52:55], v[20:23], v[186:189], v[52:55]
	v_mfma_f32_16x16x32_bf16 v[44:47], v[156:159], v[182:185], v[44:47]
	v_mfma_f32_16x16x32_bf16 v[36:39], v[20:23], v[194:197], v[36:39]
	v_mfma_f32_16x16x32_bf16 v[28:31], v[156:159], v[190:193], v[28:31]
	v_mfma_f32_16x16x32_bf16 v[20:23], v[20:23], v[202:205], v[0:3]
	v_mfma_f32_16x16x32_bf16 v[0:3], v[156:159], v[198:201], v[4:7]
	v_mfma_f32_16x16x32_bf16 v[60:63], v[160:163], v[178:181], v[60:63]
	v_mfma_f32_16x16x32_bf16 v[44:47], v[160:163], v[186:189], v[44:47]
	v_mfma_f32_16x16x32_bf16 v[28:31], v[160:163], v[194:197], v[28:31]
	v_mfma_f32_16x16x32_bf16 v[12:15], v[160:163], v[202:205], v[0:3]
	v_mfma_f32_16x16x32_bf16 v[0:3], v[206:209], v[164:167], v[64:67]
	v_mfma_f32_16x16x32_bf16 v[64:67], v[210:213], v[178:181], v[0:3]
	v_mfma_f32_16x16x32_bf16 v[0:3], v[214:217], v[164:167], v[56:59]
	v_mfma_f32_16x16x32_bf16 v[56:59], v[218:221], v[178:181], v[0:3]
	v_mfma_f32_16x16x32_bf16 v[0:3], v[206:209], v[182:185], v[48:51]
	v_mfma_f32_16x16x32_bf16 v[48:51], v[210:213], v[186:189], v[0:3]
	v_mfma_f32_16x16x32_bf16 v[0:3], v[214:217], v[182:185], v[40:43]
	v_mfma_f32_16x16x32_bf16 v[40:43], v[218:221], v[186:189], v[0:3]
	v_mfma_f32_16x16x32_bf16 v[0:3], v[206:209], v[190:193], v[32:35]
	v_mfma_f32_16x16x32_bf16 v[32:35], v[210:213], v[194:197], v[0:3]
	v_mfma_f32_16x16x32_bf16 v[0:3], v[214:217], v[190:193], v[24:27]
	v_mfma_f32_16x16x32_bf16 v[24:27], v[218:221], v[194:197], v[0:3]
	v_mfma_f32_16x16x32_bf16 v[0:3], v[206:209], v[198:201], v[16:19]
	v_mfma_f32_16x16x32_bf16 v[16:19], v[210:213], v[202:205], v[0:3]
	v_mfma_f32_16x16x32_bf16 v[0:3], v[214:217], v[198:201], v[8:11]
	v_mfma_f32_16x16x32_bf16 v[8:11], v[218:221], v[202:205], v[0:3]
	s_setprio 0
	s_add_i32 s62, s62, 2
	s_add_u32 s0, s0, 0x100
	s_addc_u32 s1, s1, 0
	s_add_u32 s60, s60, 0x100
	s_addc_u32 s61, s61, 0
	s_cmp_gt_u32 s62, 29
	s_barrier
	s_cbranch_scc0 .LBB0_226
	v_lshl_add_u32 v166, s16, 8, v137
	v_or_b32_e32 v162, 16, v166
	v_or_b32_e32 v160, 32, v166
	v_or_b32_e32 v158, 48, v166
	s_mov_b64 s[0:1], -1
	s_cmp_lg_u32 s16, s43
	v_ashrrev_i32_e32 v167, 31, v166
	v_ashrrev_i32_e32 v163, 31, v162
	v_ashrrev_i32_e32 v161, 31, v160
	v_ashrrev_i32_e32 v159, 31, v158
	v_add_u32_e32 v170, 0x80, v166
	s_cbranch_scc0 .LBB0_229
	v_lshlrev_b64 v[0:1], 7, v[166:167]
	v_lshlrev_b64 v[4:5], 7, v[162:163]
	v_lshl_add_u64 v[6:7], v[146:147], 0, v[0:1]
	v_lshl_add_u64 v[4:5], v[146:147], 0, v[4:5]
	global_load_dwordx4 v[0:3], v[6:7], off
	global_load_dwordx4 v[178:181], v[4:5], off
	global_load_dwordx4 v[182:185], v[6:7], off offset:16
	global_load_dwordx4 v[186:189], v[4:5], off offset:16
	v_lshlrev_b64 v[4:5], 7, v[160:161]
	v_lshlrev_b64 v[156:157], 7, v[158:159]
	v_lshl_add_u64 v[4:5], v[146:147], 0, v[4:5]
	v_lshl_add_u64 v[156:157], v[146:147], 0, v[156:157]
	global_load_dwordx4 v[190:193], v[4:5], off
	global_load_dwordx4 v[194:197], v[156:157], off
	global_load_dwordx4 v[198:201], v[4:5], off offset:16
	global_load_dwordx4 v[202:205], v[156:157], off offset:16
	v_add_u32_e32 v156, 0x80, v166
	s_movk_i32 s4, 0x4000
	v_and_b32_e32 v164, 64, v177
	v_ashrrev_i32_e32 v157, 31, v156
	v_add_co_u32_e32 v206, vcc, s4, v6
	v_add_u32_e32 v221, 64, v164
	v_lshlrev_b64 v[164:165], 7, v[156:157]
	v_addc_co_u32_e32 v207, vcc, 0, v7, vcc
	v_lshl_add_u64 v[164:165], v[146:147], 0, v[164:165]
	global_load_dwordx4 v[206:209], v[206:207], off offset:2048
	s_nop 0
	global_load_dwordx4 v[210:213], v[164:165], off offset:16
	global_load_dwordx4 v[214:217], v[164:165], off
	v_add_co_u32_e32 v230, vcc, s39, v6
	v_xor_b32_e32 v171, 16, v177
	s_nop 0
	v_addc_co_u32_e32 v231, vcc, 0, v7, vcc
	v_xor_b32_e32 v220, 32, v177
	s_mov_b64 s[0:1], 0x4800
	v_cmp_lt_i32_e32 vcc, v171, v221
	v_lshl_add_u64 v[218:219], v[6:7], 0, s[0:1]
	v_lshl_add_u64 v[226:227], v[6:7], 0, s[20:21]
	v_cndmask_b32_e32 v164, v177, v171, vcc
	v_cmp_lt_i32_e32 vcc, v220, v221
	v_lshl_add_u64 v[6:7], v[6:7], 0, s[28:29]
	v_lshlrev_b32_e32 v171, 2, v164
	v_cndmask_b32_e32 v165, v177, v220, vcc
	global_load_dwordx4 v[218:221], v[218:219], off offset:16
	s_nop 0
	global_load_dwordx4 v[222:225], v[230:231], off
	s_nop 0
	global_load_dwordx4 v[226:229], v[226:227], off offset:16
	s_nop 0
	global_load_dwordx4 v[230:233], v[230:231], off offset:2048
	s_nop 0
	global_load_dwordx4 v[234:237], v[6:7], off offset:16
	v_lshlrev_b32_e32 v238, 2, v165
	v_mov_b64_e32 v[4:5], s[46:47]
	s_waitcnt vmcnt(0)
; #define PG8_LAS __attribute__((address_space(3)))
; __device__ __forceinline__ void rstd8(const float* part, int row0, int fq, float (&rs)[8]) {
;     f32x4 v[8][2];
; #pragma unroll
;     for (int k = 0; k < 8; ++k) { const f32x4* p = (const f32x4*)(part + (size_t)(row0 + (k >> 2) * 128 + (k & 3) * 16) * 32 + fq * 8); v[k][0] = p[0]; v[k][1] = p[1]; }
; #pragma unroll
;     for (int k = 0; k < 8; ++k) { float s = ((v[k][0][0] + v[k][0][1]) + (v[k][0][2] + v[k][0][3])) + ((v[k][1][0] + v[k][1][1]) + (v[k][1][2] + v[k][1][3]));
;         s += __shfl_xor(s, 16); s += __shfl_xor(s, 32); rs[k] = rsqrtf(s * (1.0f / 2048.0f) + EPS); }
; }
;     __device__ __forceinline__ void operator()(const f32x4 (&acc)[2][2][4][2], const pg8::Unit& u, int wr, int wc, int fr, int fq) const {
;         const int row0 = u.pm * 256 + wr * 64 + fr, col0 = u.pn * 128 + wc * 32 + 8 * fq;
;         float rsv[8]; PG8_LAS float* mine = rs_lds + (wr * 4 + wc) * 512 + fq * 16 + fr;
;         if (u.pm != cached_pm) { rstd8(part, row0, fq, rsv);
; #pragma unroll
;             for (int k = 0; k < 8; ++k) mine[k * 64] = rsv[k];
;             cached_pm = u.pm; }
	v_mov_b32_e32 v7, v178
	v_mov_b32_e32 v6, v0
	v_mov_b32_e32 v178, v1
	v_mov_b32_e32 v0, v2
	v_mov_b32_e32 v1, v180
	v_mov_b32_e32 v180, v3
	v_mov_b32_e32 v2, v182
	v_mov_b32_e32 v3, v186
	v_mov_b32_e32 v186, v183
	v_mov_b32_e32 v164, v184
	v_mov_b32_e32 v165, v188
	v_mov_b32_e32 v188, v185
	v_pk_add_f32 v[6:7], v[6:7], v[178:179]
	v_pk_add_f32 v[0:1], v[0:1], v[180:181]
	v_pk_add_f32 v[2:3], v[2:3], v[186:187]
	v_pk_add_f32 v[164:165], v[164:165], v[188:189]
	v_pk_add_f32 v[0:1], v[6:7], v[0:1]
	v_pk_add_f32 v[2:3], v[2:3], v[164:165]
	v_mov_b32_e32 v182, v190
	v_pk_add_f32 v[0:1], v[0:1], v[2:3]
	ds_bpermute_b32 v2, v171, v0
	ds_bpermute_b32 v3, v171, v1
	v_mov_b32_e32 v183, v194
	v_mov_b32_e32 v194, v191
	v_mov_b32_e32 v184, v192
	v_mov_b32_e32 v185, v196
	v_mov_b32_e32 v196, v193
	v_mov_b32_e32 v190, v198
	v_mov_b32_e32 v191, v202
	v_mov_b32_e32 v202, v199
	v_mov_b32_e32 v192, v200
	v_mov_b32_e32 v193, v204
	v_mov_b32_e32 v204, v201
	s_waitcnt lgkmcnt(0)
	v_pk_add_f32 v[0:1], v[0:1], v[2:3]
	v_pk_add_f32 v[178:179], v[182:183], v[194:195]
	v_pk_add_f32 v[6:7], v[184:185], v[196:197]
	v_pk_add_f32 v[164:165], v[190:191], v[202:203]
	v_pk_add_f32 v[180:181], v[192:193], v[204:205]
	ds_bpermute_b32 v2, v238, v0
	ds_bpermute_b32 v3, v238, v1
	v_pk_add_f32 v[6:7], v[178:179], v[6:7]
	v_pk_add_f32 v[164:165], v[164:165], v[180:181]
	v_mov_b32_e32 v178, v216
	v_pk_add_f32 v[6:7], v[6:7], v[164:165]
	ds_bpermute_b32 v164, v171, v6
	ds_bpermute_b32 v165, v171, v7
	s_waitcnt lgkmcnt(2)
	v_pk_add_f32 v[0:1], v[0:1], v[2:3]
	v_mov_b32_e32 v179, v208
	v_pk_fma_f32 v[0:1], v[0:1], s[30:31], v[4:5] op_sel_hi:[1,0,0]
	v_mov_b32_e32 v208, v217
	v_mul_f32_e32 v2, 0x4b800000, v0
	v_mul_f32_e32 v3, 0x4b800000, v1
	v_cmp_gt_f32_e32 vcc, s40, v0
	v_cmp_gt_f32_e64 s[0:1], s40, v1
	v_pk_add_f32 v[178:179], v[178:179], v[208:209]
	v_cndmask_b32_e32 v0, v0, v2, vcc
	v_cndmask_b32_e64 v1, v1, v3, s[0:1]
	s_waitcnt lgkmcnt(0)
	v_pk_add_f32 v[2:3], v[6:7], v[164:165]
	ds_bpermute_b32 v6, v238, v2
	ds_bpermute_b32 v7, v238, v3
	v_rsq_f32_e32 v0, v0
	v_rsq_f32_e32 v1, v1
	v_mov_b32_e32 v180, v212
	v_mov_b32_e32 v181, v220
	s_waitcnt lgkmcnt(0)
	v_pk_add_f32 v[2:3], v[2:3], v[6:7]
	v_pk_mul_f32 v[164:165], v[0:1], s[48:49] op_sel_hi:[1,0]
	v_pk_fma_f32 v[2:3], v[2:3], s[30:31], v[4:5] op_sel_hi:[1,0,0]
	v_cndmask_b32_e64 v1, v1, v165, s[0:1]
	v_mul_f32_e32 v6, 0x4b800000, v2
	v_cmp_gt_f32_e64 s[0:1], s40, v2
	v_mov_b32_e32 v7, v206
	v_mov_b32_e32 v206, v215
	v_cndmask_b32_e64 v2, v2, v6, s[0:1]
	v_mov_b32_e32 v6, v214
	v_pk_add_f32 v[6:7], v[6:7], v[206:207]
	v_mov_b32_e32 v220, v213
	v_pk_add_f32 v[6:7], v[6:7], v[178:179]
	v_mov_b32_e32 v178, v210
	v_mov_b32_e32 v179, v218
	v_mov_b32_e32 v218, v211
	v_pk_add_f32 v[178:179], v[178:179], v[218:219]
	v_pk_add_f32 v[180:181], v[180:181], v[220:221]
	v_mul_f32_e32 v165, 0x4b800000, v3
	v_pk_add_f32 v[178:179], v[178:179], v[180:181]
	v_cmp_gt_f32_e64 s[4:5], s40, v3
	v_pk_add_f32 v[6:7], v[6:7], v[178:179]
	ds_bpermute_b32 v178, v171, v6
	ds_bpermute_b32 v179, v171, v7
	v_cndmask_b32_e64 v3, v3, v165, s[4:5]
	v_rsq_f32_e32 v2, v2
	v_rsq_f32_e32 v3, v3
	v_cndmask_b32_e32 v0, v0, v164, vcc
	s_waitcnt lgkmcnt(0)
	v_pk_add_f32 v[6:7], v[6:7], v[178:179]
	ds_bpermute_b32 v178, v238, v6
	ds_bpermute_b32 v179, v238, v7
	v_pk_mul_f32 v[164:165], v[2:3], s[48:49] op_sel_hi:[1,0]
	v_mov_b32_e32 v180, v230
	v_cndmask_b32_e64 v3, v3, v165, s[4:5]
	v_cndmask_b32_e64 v2, v2, v164, s[0:1]
	s_waitcnt lgkmcnt(0)
	v_pk_add_f32 v[6:7], v[6:7], v[178:179]
	v_mov_b32_e32 v164, v223
	v_mov_b32_e32 v165, v224
	v_mov_b32_e32 v223, v225
	v_mov_b32_e32 v178, v227
	v_mov_b32_e32 v179, v228
	v_mov_b32_e32 v227, v229
	v_mov_b32_e32 v181, v234
	v_mov_b32_e32 v234, v231
	v_mov_b32_e32 v182, v232
	v_mov_b32_e32 v183, v236
	v_mov_b32_e32 v236, v233
	v_pk_add_f32 v[164:165], v[164:165], v[222:223]
	v_pk_add_f32 v[178:179], v[178:179], v[226:227]
	v_pk_add_f32 v[180:181], v[180:181], v[234:235]
	v_pk_add_f32 v[182:183], v[182:183], v[236:237]
	v_pk_add_f32 v[164:165], v[164:165], v[164:165] op_sel:[0,1] op_sel_hi:[1,0]
	v_pk_add_f32 v[178:179], v[178:179], v[178:179] op_sel:[0,1] op_sel_hi:[1,0]
	v_pk_add_f32 v[180:181], v[180:181], v[182:183]
	v_pk_fma_f32 v[6:7], v[6:7], s[30:31], v[4:5] op_sel_hi:[1,0,0]
	v_mov_b32_e32 v165, v180
	v_mov_b32_e32 v179, v181
	v_pk_add_f32 v[164:165], v[164:165], v[178:179]
	ds_bpermute_b32 v178, v171, v164
	ds_bpermute_b32 v179, v171, v165
	v_mul_f32_e32 v171, 0x4b800000, v6
	v_cmp_gt_f32_e32 vcc, s40, v6
	v_cmp_gt_f32_e64 s[0:1], s40, v7
	s_waitcnt lgkmcnt(0)
	v_pk_add_f32 v[164:165], v[164:165], v[178:179]
	ds_bpermute_b32 v178, v238, v164
	ds_bpermute_b32 v179, v238, v165
	v_cndmask_b32_e32 v6, v6, v171, vcc
	v_mul_f32_e32 v171, 0x4b800000, v7
	v_cndmask_b32_e64 v7, v7, v171, s[0:1]
	v_rsq_f32_e32 v6, v6
	s_waitcnt lgkmcnt(0)
	v_pk_add_f32 v[164:165], v[164:165], v[178:179]
	v_rsq_f32_e32 v7, v7
	v_pk_fma_f32 v[4:5], v[164:165], s[30:31], v[4:5] op_sel_hi:[1,0,0]
	s_nop 0
	v_mul_f32_e32 v164, 0x4b800000, v4
	v_cmp_gt_f32_e64 s[4:5], s40, v4
	v_cmp_gt_f32_e64 s[6:7], s40, v5
	s_nop 0
	v_cndmask_b32_e64 v4, v4, v164, s[4:5]
	v_rsq_f32_e32 v164, v4
	v_mul_f32_e32 v4, 0x4b800000, v5
	v_cndmask_b32_e64 v4, v5, v4, s[6:7]
	v_rsq_f32_e32 v165, v4
	v_pk_mul_f32 v[4:5], v[6:7], s[48:49] op_sel_hi:[1,0]
	s_nop 0
	v_cndmask_b32_e64 v5, v7, v5, s[0:1]
	v_cndmask_b32_e32 v4, v6, v4, vcc
	v_pk_mul_f32 v[6:7], v[164:165], s[48:49] op_sel_hi:[1,0]
	s_mov_b64 s[0:1], 0
	v_cndmask_b32_e64 v7, v165, v7, s[6:7]
	v_cndmask_b32_e64 v6, v164, v6, s[4:5]
	ds_write2st64_b32 v172, v0, v1 offset1:1
	ds_write2st64_b32 v172, v2, v3 offset0:2 offset1:3
	ds_write2st64_b32 v172, v4, v5 offset0:4 offset1:5
	ds_write2st64_b32 v172, v6, v7 offset0:6 offset1:7
	v_mov_b64_e32 v[164:165], v[156:157]

; #define PG8_STAGE(bufoff, gbase, voff) do { _Pragma("unroll") for (int _i = 0; _i < 2; ++_i) \
;         __builtin_amdgcn_global_load_lds((const unsigned*)((const char*)(gbase) + (voff)[_i]), (PG8_LAS unsigned*)(lds + (bufoff) + ldsw + _i * 8192), 16, 0, 0); } while (0)
; #define PG8_LDA(dst, b, h) do { _Pragma("unroll") for (int m = 0; m < 4; ++m) _Pragma("unroll") for (int k = 0; k < 2; ++k) dst[m][k] = *(const PG8_LAS bf16x8*)(lds + PG8_SA(b, h) + aoff + m * 2048 + k * 1024); } while (0)
; #define PG8_LDB(dst, b, h) do { _Pragma("unroll") for (int n = 0; n < 2; ++n) _Pragma("unroll") for (int k = 0; k < 2; ++k) dst[n][k] = *(const PG8_LAS bf16x8*)(lds + PG8_SB(b, h) + boff + n * 2048 + k * 1024); } while (0)
; #define PG8_WAIT_V(n) asm volatile("s_waitcnt vmcnt(" #n ")" ::: "memory")
; #define PG8_WAIT_L(n) asm volatile("s_waitcnt lgkmcnt(" #n ")" ::: "memory")
; #define PG8_BAR __builtin_amdgcn_s_barrier()
; #define PG8_SCHED __builtin_amdgcn_sched_barrier(0)
; template <class Epi>
; __device__ __forceinline__ void gemm_phase(PG8_LAS unsigned char* lds, const Gemm g, const StaticOrder& S, const Epi& E) {
;     ...
;     for (;;) {
;         const bool has_next = S.next(ui + 1, nxt);
;         const char* nA = has_next ? (const char*)g.A + (size_t)nxt.pm * tstepA : cA; const char* nB = has_next ? (const char*)g.Bt + (size_t)nxt.pn * tstepB : cB;
;         for (int t = 0; t < nt; t += 2) {
;             const bool last = (t == nt - 2);
;             const char* a1 = cA + (size_t)(t + 1) * kstep;
;             const char* a2 = last ? nA : cA + (size_t)(t + 2) * kstep; const char* b2 = last ? nB : cB + (size_t)(t + 2) * kstep;
;             const char* a3 = a2 + kstep; const char* b3 = b2 + kstep;
;             PG8_LDB(B0, 0, 0); PG8_SCHED; PG8_LDA(At, 0, 0); PG8_STAGE(PG8_SA(1, 1), a1 + hstepA, voffA);
;             PG8_WAIT_L(8); PG8_BAR; PG8_WAIT_L(0); PG8_MMA(0, 0, At, B0); PG8_BAR; PG8_SCHED;
;             PG8_LDB(B1, 0, 1); PG8_STAGE(PG8_SB(0, 0), b2, voffB);
;             PG8_BAR; PG8_WAIT_L(0); PG8_MMA(0, 1, At, B1); PG8_BAR;
;             PG8_LDA(At, 0, 1); PG8_STAGE(PG8_SA(0, 0), a2, voffA);
;             PG8_BAR; PG8_WAIT_L(0); PG8_MMA(1, 0, At, B0); PG8_BAR; PG8_SCHED;
;             PG8_STAGE(PG8_SB(0, 1), b2 + hstepB, voffB);
;             PG8_WAIT_V(6); PG8_BAR; PG8_MMA(1, 1, At, B1); PG8_BAR;
.LBB0_317:
	ds_read_b128 v[128:131], v191
	ds_read_b128 v[132:135], v191 offset:1024
	ds_read_b128 v[136:139], v191 offset:2048
	ds_read_b128 v[140:143], v191 offset:3072
	ds_read_b128 v[144:147], v192
	ds_read_b128 v[148:151], v192 offset:1024
	ds_read_b128 v[170:173], v192 offset:2048
	ds_read_b128 v[174:177], v192 offset:3072
	ds_read_b128 v[178:181], v192 offset:4096
	ds_read_b128 v[182:185], v192 offset:5120
	ds_read_b128 v[196:199], v192 offset:6144
	ds_read_b128 v[200:203], v192 offset:7168
	ds_read_b128 v[204:207], v193
	ds_read_b128 v[208:211], v193 offset:1024
	ds_read_b128 v[212:215], v193 offset:2048
	ds_read_b128 v[216:219], v193 offset:3072
	s_add_u32 s10, s20, 0xffea0080
	s_addc_u32 s11, s21, -1
	s_cmpk_eq_i32 s50, 0x54
	s_cselect_b32 s13, s1, s11
	s_cselect_b32 s12, s0, s10
	s_cselect_b32 s11, s7, s49
	s_cselect_b32 s10, s6, s48
	v_lshl_add_u64 v[186:187], s[20:21], 0, v[160:161]
	s_add_i32 m0, s28, 0xc000
	s_nop 0
	global_load_lds_dwordx4 v[186:187], off
	v_lshl_add_u64 v[186:187], s[20:21], 0, v[162:163]
	s_add_i32 m0, s28, 0xe000
	s_nop 0
	global_load_lds_dwordx4 v[186:187], off
	s_waitcnt lgkmcnt(0)
	s_waitcnt vmcnt(8)
	s_barrier
	s_setprio 1
	v_mfma_f32_16x16x32_bf16 v[124:127], v[128:131], v[144:147], v[124:127]
	v_mfma_f32_16x16x32_bf16 v[120:123], v[136:139], v[144:147], v[120:123]
	v_mfma_f32_16x16x32_bf16 v[104:107], v[128:131], v[170:173], v[104:107]
	v_mfma_f32_16x16x32_bf16 v[108:111], v[136:139], v[170:173], v[108:111]
	v_mfma_f32_16x16x32_bf16 v[88:91], v[128:131], v[178:181], v[88:91]
	v_mfma_f32_16x16x32_bf16 v[92:95], v[136:139], v[178:181], v[92:95]
	v_mfma_f32_16x16x32_bf16 v[72:75], v[128:131], v[196:199], v[72:75]
	v_mfma_f32_16x16x32_bf16 v[76:79], v[136:139], v[196:199], v[76:79]
	v_mfma_f32_16x16x32_bf16 v[124:127], v[132:135], v[148:151], v[124:127]
	v_mfma_f32_16x16x32_bf16 v[120:123], v[140:143], v[148:151], v[120:123]
	v_mfma_f32_16x16x32_bf16 v[104:107], v[132:135], v[174:177], v[104:107]
	v_mfma_f32_16x16x32_bf16 v[108:111], v[140:143], v[174:177], v[108:111]
	v_mfma_f32_16x16x32_bf16 v[88:91], v[132:135], v[182:185], v[88:91]
	v_mfma_f32_16x16x32_bf16 v[92:95], v[140:143], v[182:185], v[92:95]
	v_mfma_f32_16x16x32_bf16 v[72:75], v[132:135], v[200:203], v[72:75]
	v_mfma_f32_16x16x32_bf16 v[76:79], v[140:143], v[200:203], v[76:79]
	v_mfma_f32_16x16x32_bf16 v[116:119], v[204:207], v[144:147], v[116:119]
	v_mfma_f32_16x16x32_bf16 v[112:115], v[212:215], v[144:147], v[112:115]
	v_mfma_f32_16x16x32_bf16 v[100:103], v[204:207], v[170:173], v[100:103]
	v_mfma_f32_16x16x32_bf16 v[96:99], v[212:215], v[170:173], v[96:99]
	v_mfma_f32_16x16x32_bf16 v[84:87], v[204:207], v[178:181], v[84:87]
	v_mfma_f32_16x16x32_bf16 v[80:83], v[212:215], v[178:181], v[80:83]
	v_mfma_f32_16x16x32_bf16 v[68:71], v[204:207], v[196:199], v[68:71]
	v_mfma_f32_16x16x32_bf16 v[64:67], v[212:215], v[196:199], v[64:67]
	v_mfma_f32_16x16x32_bf16 v[116:119], v[208:211], v[148:151], v[116:119]
	v_mfma_f32_16x16x32_bf16 v[112:115], v[216:219], v[148:151], v[112:115]
	v_mfma_f32_16x16x32_bf16 v[100:103], v[208:211], v[174:177], v[100:103]
	v_mfma_f32_16x16x32_bf16 v[96:99], v[216:219], v[174:177], v[96:99]
	v_mfma_f32_16x16x32_bf16 v[84:87], v[208:211], v[182:185], v[84:87]
	v_mfma_f32_16x16x32_bf16 v[80:83], v[216:219], v[182:185], v[80:83]
	v_mfma_f32_16x16x32_bf16 v[68:71], v[208:211], v[200:203], v[68:71]
	v_mfma_f32_16x16x32_bf16 v[64:67], v[216:219], v[200:203], v[64:67]
	s_setprio 0
	s_barrier
	ds_read_b128 v[144:147], v192 offset:16384
	ds_read_b128 v[148:151], v192 offset:17408
	ds_read_b128 v[170:173], v192 offset:18432
	ds_read_b128 v[174:177], v192 offset:19456
	ds_read_b128 v[178:181], v192 offset:20480
	ds_read_b128 v[182:185], v192 offset:21504
	ds_read_b128 v[196:199], v192 offset:22528
	ds_read_b128 v[200:203], v192 offset:23552
	s_add_i32 s51, s40, s23
	v_lshl_add_u64 v[186:187], s[10:11], 0, v[154:155]
	s_mov_b32 m0, s51
	s_nop 0
	global_load_lds_dwordx4 v[186:187], off
	v_lshl_add_u64 v[220:221], s[10:11], 0, v[158:159]
	s_add_i32 m0, s51, 0x2000
	s_nop 0
	global_load_lds_dwordx4 v[220:221], off
	s_mov_b32 m0, s28
	v_lshl_add_u64 v[222:223], s[12:13], 0, v[152:153]
	global_load_lds_dwordx4 v[222:223], off
	v_lshl_add_u64 v[224:225], s[12:13], 0, v[156:157]
	s_mov_b32 m0, s29
	s_nop 0
	global_load_lds_dwordx4 v[224:225], off
	s_add_u32 s52, s10, 0x160000
	s_addc_u32 s53, s11, 0
	s_add_i32 s51, s41, s23
	v_lshl_add_u64 v[226:227], s[52:53], 0, v[154:155]
	s_mov_b32 m0, s51
	s_nop 0
	global_load_lds_dwordx4 v[226:227], off
	v_lshl_add_u64 v[226:227], s[52:53], 0, v[158:159]
	s_add_i32 m0, s51, 0x2000
	s_nop 0
	global_load_lds_dwordx4 v[226:227], off
	s_waitcnt lgkmcnt(0)
	s_waitcnt vmcnt(8)
	s_barrier
; #define PG8_STAGE(bufoff, gbase, voff) do { _Pragma("unroll") for (int _i = 0; _i < 2; ++_i) \
;         __builtin_amdgcn_global_load_lds((const unsigned*)((const char*)(gbase) + (voff)[_i]), (PG8_LAS unsigned*)(lds + (bufoff) + ldsw + _i * 8192), 16, 0, 0); } while (0)
; #define PG8_LDA(dst, b, h) do { _Pragma("unroll") for (int m = 0; m < 4; ++m) _Pragma("unroll") for (int k = 0; k < 2; ++k) dst[m][k] = *(const PG8_LAS bf16x8*)(lds + PG8_SA(b, h) + aoff + m * 2048 + k * 1024); } while (0)
; #define PG8_LDB(dst, b, h) do { _Pragma("unroll") for (int n = 0; n < 2; ++n) _Pragma("unroll") for (int k = 0; k < 2; ++k) dst[n][k] = *(const PG8_LAS bf16x8*)(lds + PG8_SB(b, h) + boff + n * 2048 + k * 1024); } while (0)
; #define PG8_MMA(ai, bj, At, Bt) do { __builtin_amdgcn_s_setprio(1); _Pragma("unroll") for (int m = 0; m < 4; ++m) _Pragma("unroll") for (int n = 0; n < 2; ++n) _Pragma("unroll") for (int k = 0; k < 2; ++k) \
;         acc[ai][bj][m][n] = __builtin_amdgcn_mfma_f32_16x16x32_bf16(Bt[n][k], At[m][k], acc[ai][bj][m][n], 0, 0, 0); __builtin_amdgcn_s_setprio(0); } while (0)
; #define PG8_WAIT_V(n) asm volatile("s_waitcnt vmcnt(" #n ")" ::: "memory")
; #define PG8_WAIT_L(n) asm volatile("s_waitcnt lgkmcnt(" #n ")" ::: "memory")
; #define PG8_BAR __builtin_amdgcn_s_barrier()
; #define PG8_SCHED __builtin_amdgcn_sched_barrier(0)
; template <class Epi>
; __device__ __forceinline__ void gemm_phase(PG8_LAS unsigned char* lds, const Gemm g, const StaticOrder& S, const Epi& E) {
;     ...
;             PG8_BAR; PG8_WAIT_L(0); PG8_MMA(1, 0, At, B0); PG8_BAR; PG8_SCHED;
;             PG8_STAGE(PG8_SB(0, 1), b2 + hstepB, voffB);
;             PG8_WAIT_V(6); PG8_BAR; PG8_MMA(1, 1, At, B1); PG8_BAR;
;             PG8_LDB(B0, 1, 0); PG8_SCHED; PG8_LDA(At, 1, 0); PG8_STAGE(PG8_SA(0, 1), a2 + hstepA, voffA);
;             PG8_WAIT_L(8); PG8_BAR; PG8_WAIT_L(0); PG8_MMA(0, 0, At, B0); PG8_BAR; PG8_SCHED;
	s_setprio 1
	v_mfma_f32_16x16x32_bf16 v[60:63], v[128:131], v[144:147], v[60:63]
	v_mfma_f32_16x16x32_bf16 v[56:59], v[136:139], v[144:147], v[56:59]
	v_mfma_f32_16x16x32_bf16 v[40:43], v[128:131], v[170:173], v[40:43]
	v_mfma_f32_16x16x32_bf16 v[44:47], v[136:139], v[170:173], v[44:47]
	v_mfma_f32_16x16x32_bf16 v[24:27], v[128:131], v[178:181], v[24:27]
	v_mfma_f32_16x16x32_bf16 v[28:31], v[136:139], v[178:181], v[28:31]
	v_mfma_f32_16x16x32_bf16 v[8:11], v[128:131], v[196:199], v[8:11]
	v_mfma_f32_16x16x32_bf16 v[12:15], v[136:139], v[196:199], v[12:15]
	v_mfma_f32_16x16x32_bf16 v[60:63], v[132:135], v[148:151], v[60:63]
	v_mfma_f32_16x16x32_bf16 v[56:59], v[140:143], v[148:151], v[56:59]
	v_mfma_f32_16x16x32_bf16 v[40:43], v[132:135], v[174:177], v[40:43]
	v_mfma_f32_16x16x32_bf16 v[44:47], v[140:143], v[174:177], v[44:47]
	v_mfma_f32_16x16x32_bf16 v[24:27], v[132:135], v[182:185], v[24:27]
	v_mfma_f32_16x16x32_bf16 v[28:31], v[140:143], v[182:185], v[28:31]
	v_mfma_f32_16x16x32_bf16 v[8:11], v[132:135], v[200:203], v[8:11]
	v_mfma_f32_16x16x32_bf16 v[12:15], v[140:143], v[200:203], v[12:15]
	v_mfma_f32_16x16x32_bf16 v[52:55], v[204:207], v[144:147], v[52:55]
	v_mfma_f32_16x16x32_bf16 v[48:51], v[212:215], v[144:147], v[48:51]
	v_mfma_f32_16x16x32_bf16 v[36:39], v[204:207], v[170:173], v[36:39]
	v_mfma_f32_16x16x32_bf16 v[32:35], v[212:215], v[170:173], v[32:35]
	v_mfma_f32_16x16x32_bf16 v[20:23], v[204:207], v[178:181], v[20:23]
	v_mfma_f32_16x16x32_bf16 v[16:19], v[212:215], v[178:181], v[16:19]
	v_mfma_f32_16x16x32_bf16 v[4:7], v[204:207], v[196:199], v[4:7]
	v_mfma_f32_16x16x32_bf16 v[0:3], v[212:215], v[196:199], v[0:3]
	v_mfma_f32_16x16x32_bf16 v[52:55], v[208:211], v[148:151], v[52:55]
	v_mfma_f32_16x16x32_bf16 v[48:51], v[216:219], v[148:151], v[48:51]
	v_mfma_f32_16x16x32_bf16 v[36:39], v[208:211], v[174:177], v[36:39]
	v_mfma_f32_16x16x32_bf16 v[32:35], v[216:219], v[174:177], v[32:35]
	v_mfma_f32_16x16x32_bf16 v[20:23], v[208:211], v[182:185], v[20:23]
	v_mfma_f32_16x16x32_bf16 v[16:19], v[216:219], v[182:185], v[16:19]
	v_mfma_f32_16x16x32_bf16 v[4:7], v[208:211], v[200:203], v[4:7]
	v_mfma_f32_16x16x32_bf16 v[0:3], v[216:219], v[200:203], v[0:3]
	s_setprio 0
	s_add_i32 s51, 0, 0x18000
	v_add_u32_e32 v140, s51, v189
	s_barrier
	ds_read_b128 v[128:131], v140
	ds_read_b128 v[132:135], v140 offset:1024
	ds_read_b128 v[136:139], v140 offset:2048
	ds_read_b128 v[140:143], v140 offset:3072
	ds_read_b128 v[144:147], v192 offset:32768
	ds_read_b128 v[148:151], v192 offset:33792
	ds_read_b128 v[170:173], v192 offset:34816
	ds_read_b128 v[174:177], v192 offset:35840
	ds_read_b128 v[178:181], v192 offset:36864
	ds_read_b128 v[182:185], v192 offset:37888
	ds_read_b128 v[196:199], v192 offset:38912
	ds_read_b128 v[200:203], v192 offset:39936
	v_add_u32_e32 v195, 0x1c000, v189
	ds_read_b128 v[204:207], v195
	ds_read_b128 v[208:211], v195 offset:1024
	ds_read_b128 v[212:215], v195 offset:2048
	ds_read_b128 v[216:219], v195 offset:3072
	s_add_u32 s12, s12, 0x160000
	s_addc_u32 s13, s13, 0
	s_mov_b32 m0, s30
	v_lshl_add_u64 v[226:227], s[12:13], 0, v[152:153]
	global_load_lds_dwordx4 v[226:227], off
	v_lshl_add_u64 v[226:227], s[12:13], 0, v[156:157]
	s_mov_b32 m0, s31
	s_nop 0
	global_load_lds_dwordx4 v[226:227], off
	s_waitcnt lgkmcnt(0)
	s_waitcnt vmcnt(8)
	s_barrier
	s_setprio 1
	v_mfma_f32_16x16x32_bf16 v[124:127], v[128:131], v[144:147], v[124:127]
	v_mfma_f32_16x16x32_bf16 v[120:123], v[136:139], v[144:147], v[120:123]
	v_mfma_f32_16x16x32_bf16 v[104:107], v[128:131], v[170:173], v[104:107]
	v_mfma_f32_16x16x32_bf16 v[108:111], v[136:139], v[170:173], v[108:111]
	v_mfma_f32_16x16x32_bf16 v[88:91], v[128:131], v[178:181], v[88:91]
	v_mfma_f32_16x16x32_bf16 v[92:95], v[136:139], v[178:181], v[92:95]
	v_mfma_f32_16x16x32_bf16 v[72:75], v[128:131], v[196:199], v[72:75]
	v_mfma_f32_16x16x32_bf16 v[76:79], v[136:139], v[196:199], v[76:79]
	v_mfma_f32_16x16x32_bf16 v[124:127], v[132:135], v[148:151], v[124:127]
	v_mfma_f32_16x16x32_bf16 v[120:123], v[140:143], v[148:151], v[120:123]
	v_mfma_f32_16x16x32_bf16 v[104:107], v[132:135], v[174:177], v[104:107]
	v_mfma_f32_16x16x32_bf16 v[108:111], v[140:143], v[174:177], v[108:111]
	v_mfma_f32_16x16x32_bf16 v[88:91], v[132:135], v[182:185], v[88:91]
	v_mfma_f32_16x16x32_bf16 v[92:95], v[140:143], v[182:185], v[92:95]
	v_mfma_f32_16x16x32_bf16 v[72:75], v[132:135], v[200:203], v[72:75]
	v_mfma_f32_16x16x32_bf16 v[76:79], v[140:143], v[200:203], v[76:79]
	v_mfma_f32_16x16x32_bf16 v[116:119], v[204:207], v[144:147], v[116:119]
	v_mfma_f32_16x16x32_bf16 v[112:115], v[212:215], v[144:147], v[112:115]
	v_mfma_f32_16x16x32_bf16 v[100:103], v[204:207], v[170:173], v[100:103]
	v_mfma_f32_16x16x32_bf16 v[96:99], v[212:215], v[170:173], v[96:99]
	v_mfma_f32_16x16x32_bf16 v[84:87], v[204:207], v[178:181], v[84:87]
	v_mfma_f32_16x16x32_bf16 v[80:83], v[212:215], v[178:181], v[80:83]
	v_mfma_f32_16x16x32_bf16 v[68:71], v[204:207], v[196:199], v[68:71]
	v_mfma_f32_16x16x32_bf16 v[64:67], v[212:215], v[196:199], v[64:67]
	v_mfma_f32_16x16x32_bf16 v[116:119], v[208:211], v[148:151], v[116:119]
	v_mfma_f32_16x16x32_bf16 v[112:115], v[216:219], v[148:151], v[112:115]
	v_mfma_f32_16x16x32_bf16 v[100:103], v[208:211], v[174:177], v[100:103]
	v_mfma_f32_16x16x32_bf16 v[96:99], v[216:219], v[174:177], v[96:99]
	v_mfma_f32_16x16x32_bf16 v[84:87], v[208:211], v[182:185], v[84:87]
	v_mfma_f32_16x16x32_bf16 v[80:83], v[216:219], v[182:185], v[80:83]
	v_mfma_f32_16x16x32_bf16 v[68:71], v[208:211], v[200:203], v[68:71]
	v_mfma_f32_16x16x32_bf16 v[64:67], v[216:219], v[200:203], v[64:67]
	s_setprio 0
	s_barrier
; #define PG8_STAGE(bufoff, gbase, voff) do { _Pragma("unroll") for (int _i = 0; _i < 2; ++_i) \
;         __builtin_amdgcn_global_load_lds((const unsigned*)((const char*)(gbase) + (voff)[_i]), (PG8_LAS unsigned*)(lds + (bufoff) + ldsw + _i * 8192), 16, 0, 0); } while (0)
; #define PG8_LDA(dst, b, h) do { _Pragma("unroll") for (int m = 0; m < 4; ++m) _Pragma("unroll") for (int k = 0; k < 2; ++k) dst[m][k] = *(const PG8_LAS bf16x8*)(lds + PG8_SA(b, h) + aoff + m * 2048 + k * 1024); } while (0)
; #define PG8_LDB(dst, b, h) do { _Pragma("unroll") for (int n = 0; n < 2; ++n) _Pragma("unroll") for (int k = 0; k < 2; ++k) dst[n][k] = *(const PG8_LAS bf16x8*)(lds + PG8_SB(b, h) + boff + n * 2048 + k * 1024); } while (0)
; #define PG8_MMA(ai, bj, At, Bt) do { __builtin_amdgcn_s_setprio(1); _Pragma("unroll") for (int m = 0; m < 4; ++m) _Pragma("unroll") for (int n = 0; n < 2; ++n) _Pragma("unroll") for (int k = 0; k < 2; ++k) \
;         acc[ai][bj][m][n] = __builtin_amdgcn_mfma_f32_16x16x32_bf16(Bt[n][k], At[m][k], acc[ai][bj][m][n], 0, 0, 0); __builtin_amdgcn_s_setprio(0); } while (0)
; #define PG8_WAIT_V(n) asm volatile("s_waitcnt vmcnt(" #n ")" ::: "memory")
; #define PG8_WAIT_L(n) asm volatile("s_waitcnt lgkmcnt(" #n ")" ::: "memory")
; #define PG8_BAR __builtin_amdgcn_s_barrier()
; #define PG8_SCHED __builtin_amdgcn_sched_barrier(0)
; template <class Epi>
; __device__ __forceinline__ void gemm_phase(PG8_LAS unsigned char* lds, const Gemm g, const StaticOrder& S, const Epi& E) {
;     ...
;             PG8_LDB(B1, 1, 1); PG8_STAGE(PG8_SB(1, 0), b3, voffB);
;             PG8_BAR; PG8_WAIT_L(0); PG8_MMA(0, 1, At, B1); PG8_BAR;
;             PG8_LDA(At, 1, 1); PG8_STAGE(PG8_SA(1, 0), a3, voffA);
;             PG8_BAR; PG8_WAIT_L(0); PG8_MMA(1, 0, At, B0); PG8_BAR; PG8_SCHED;
;             PG8_STAGE(PG8_SB(1, 1), b3 + hstepB, voffB);
;             PG8_WAIT_V(6); PG8_BAR; PG8_MMA(1, 1, At, B1); PG8_BAR;
;         }
	ds_read_b128 v[144:147], v192 offset:49152
	ds_read_b128 v[148:151], v192 offset:50176
	ds_read_b128 v[170:173], v192 offset:51200
	ds_read_b128 v[174:177], v192 offset:52224
	ds_read_b128 v[178:181], v192 offset:53248
	ds_read_b128 v[182:185], v192 offset:54272
	ds_read_b128 v[196:199], v192 offset:55296
	ds_read_b128 v[200:203], v192 offset:56320
	s_add_i32 s12, 0, 0x1c000
	s_add_i32 s13, s51, s23
	v_lshl_add_u64 v[186:187], v[186:187], 0, s[18:19]
	s_mov_b32 m0, s13
	s_nop 0
	global_load_lds_dwordx4 v[186:187], off
	v_lshl_add_u64 v[186:187], v[220:221], 0, s[18:19]
	s_add_i32 m0, s13, 0x2000
	s_nop 0
	global_load_lds_dwordx4 v[186:187], off
	s_mov_b32 m0, s35
	v_lshl_add_u64 v[186:187], v[222:223], 0, s[18:19]
	global_load_lds_dwordx4 v[186:187], off
	v_lshl_add_u64 v[186:187], v[224:225], 0, s[18:19]
	s_mov_b32 m0, s36
	s_nop 0
	global_load_lds_dwordx4 v[186:187], off
	s_add_u32 s10, s10, 0x160080
	s_addc_u32 s11, s11, 0
	s_add_i32 s12, s12, s23
	v_lshl_add_u64 v[226:227], s[10:11], 0, v[154:155]
	s_mov_b32 m0, s12
	s_nop 0
	global_load_lds_dwordx4 v[226:227], off
	v_lshl_add_u64 v[226:227], s[10:11], 0, v[158:159]
	s_add_i32 m0, s12, 0x2000
	s_nop 0
	global_load_lds_dwordx4 v[226:227], off
	s_waitcnt lgkmcnt(0)
	s_waitcnt vmcnt(8)
	s_barrier
	s_setprio 1
	v_mfma_f32_16x16x32_bf16 v[60:63], v[128:131], v[144:147], v[60:63]
	v_mfma_f32_16x16x32_bf16 v[56:59], v[136:139], v[144:147], v[56:59]
	v_mfma_f32_16x16x32_bf16 v[40:43], v[128:131], v[170:173], v[40:43]
	v_mfma_f32_16x16x32_bf16 v[44:47], v[136:139], v[170:173], v[44:47]
	v_mfma_f32_16x16x32_bf16 v[24:27], v[128:131], v[178:181], v[24:27]
	v_mfma_f32_16x16x32_bf16 v[28:31], v[136:139], v[178:181], v[28:31]
	v_mfma_f32_16x16x32_bf16 v[8:11], v[128:131], v[196:199], v[8:11]
	v_mfma_f32_16x16x32_bf16 v[12:15], v[136:139], v[196:199], v[12:15]
	v_mfma_f32_16x16x32_bf16 v[60:63], v[132:135], v[148:151], v[60:63]
	v_mfma_f32_16x16x32_bf16 v[56:59], v[140:143], v[148:151], v[56:59]
	v_mfma_f32_16x16x32_bf16 v[40:43], v[132:135], v[174:177], v[40:43]
	v_mfma_f32_16x16x32_bf16 v[44:47], v[140:143], v[174:177], v[44:47]
	v_mfma_f32_16x16x32_bf16 v[24:27], v[132:135], v[182:185], v[24:27]
	v_mfma_f32_16x16x32_bf16 v[28:31], v[140:143], v[182:185], v[28:31]
	v_mfma_f32_16x16x32_bf16 v[8:11], v[132:135], v[200:203], v[8:11]
	v_mfma_f32_16x16x32_bf16 v[12:15], v[140:143], v[200:203], v[12:15]
	v_mfma_f32_16x16x32_bf16 v[52:55], v[204:207], v[144:147], v[52:55]
	v_mfma_f32_16x16x32_bf16 v[48:51], v[212:215], v[144:147], v[48:51]
	v_mfma_f32_16x16x32_bf16 v[36:39], v[204:207], v[170:173], v[36:39]
	v_mfma_f32_16x16x32_bf16 v[32:35], v[212:215], v[170:173], v[32:35]
	v_mfma_f32_16x16x32_bf16 v[20:23], v[204:207], v[178:181], v[20:23]
	v_mfma_f32_16x16x32_bf16 v[16:19], v[212:215], v[178:181], v[16:19]
	v_mfma_f32_16x16x32_bf16 v[4:7], v[204:207], v[196:199], v[4:7]
	v_mfma_f32_16x16x32_bf16 v[0:3], v[212:215], v[196:199], v[0:3]
	v_mfma_f32_16x16x32_bf16 v[52:55], v[208:211], v[148:151], v[52:55]
	v_mfma_f32_16x16x32_bf16 v[48:51], v[216:219], v[148:151], v[48:51]
	v_mfma_f32_16x16x32_bf16 v[36:39], v[208:211], v[174:177], v[36:39]
	v_mfma_f32_16x16x32_bf16 v[32:35], v[216:219], v[174:177], v[32:35]
	v_mfma_f32_16x16x32_bf16 v[20:23], v[208:211], v[182:185], v[20:23]
	v_mfma_f32_16x16x32_bf16 v[16:19], v[216:219], v[182:185], v[16:19]
	v_mfma_f32_16x16x32_bf16 v[4:7], v[208:211], v[200:203], v[4:7]
	v_mfma_f32_16x16x32_bf16 v[0:3], v[216:219], v[200:203], v[0:3]
	s_setprio 0
	s_add_i32 s50, s50, 2
	s_add_u32 s20, s20, 0x100
	s_addc_u32 s21, s21, 0
	s_add_u32 s48, s48, 0x100
	s_addc_u32 s49, s49, 0
	s_cmpk_gt_u32 s50, 0x55
	s_barrier
	s_cbranch_scc0 .LBB0_317
; __device__ __forceinline__ u32x4 pack8(const float (&f)[8]) { u32x4 w; w.x = cvt_pk_bf16(f[0], f[1]); w.y = cvt_pk_bf16(f[2], f[3]); w.z = cvt_pk_bf16(f[4], f[5]); w.w = cvt_pk_bf16(f[6], f[7]); return w; }
;     __device__ __forceinline__ void operator()(const f32x4 (&acc)[2][2][4][2], const pg8::Unit& u, int wr, int wc, int fr, int fq) const {
;         const int row0 = u.pm * 256 + wr * 64 + fr, col0 = u.pn * 256 + wc * 32 + 8 * fq;
; #pragma unroll
;         for (int ai = 0; ai < 2; ++ai) {
;             u32x4 rb[4][2];
; #pragma unroll
;             for (int m = 0; m < 4; ++m)
; #pragma unroll
;                 for (int bj = 0; bj < 2; ++bj) rb[m][bj] = *(const u32x4*)(resb + (size_t)(row0 + ai * 128 + m * 16) * DM + col0 + bj * 128);
; #pragma unroll
;             for (int m = 0; m < 4; ++m) {
;                 const int r = row0 + ai * 128 + m * 16; float ss = 0.f;
; #pragma unroll
;                 for (int bj = 0; bj < 2; ++bj) {
;                     const size_t off = (size_t)r * DM + col0 + bj * 128;
;                     float rv[8], o[8]; unpack8(rb[m][bj], rv);
; #pragma unroll
;                     for (int n = 0; n < 2; ++n)
; #pragma unroll
;                         for (int i = 0; i < 4; ++i) o[n * 4 + i] = rv[n * 4 + i] + coef * acc[ai][bj][m][n][i];
;                     if (outf) { *(f32x4*)(outf + off) = (f32x4){o[0], o[1], o[2], o[3]}; *(f32x4*)(outf + off + 4) = (f32x4){o[4], o[5], o[6], o[7]}; }
;                     if (hb) { *(u32x4*)(hb + off) = pack8(o);
; #pragma unroll
;                         for (int i = 0; i < 8; ++i) ss += o[i] * o[i]; }
;                 }
;                 if (hb) { ss += __shfl_xor(ss, 16); ss += __shfl_xor(ss, 32); if (fq == 0) part[(size_t)r * 32 + u.pn * 4 + wc] = ss; }
	v_lshl_or_b32 v170, s16, 8, v190
	v_lshl_add_u32 v172, s47, 8, v188
	v_ashrrev_i32_e32 v171, 31, v170
	v_lshlrev_b64 v[204:205], 1, v[170:171]
	v_ashrrev_i32_e32 v173, 31, v172
	v_lshl_add_u64 v[174:175], s[76:77], 0, v[204:205]
	v_lshlrev_b64 v[206:207], 12, v[172:173]
	v_lshl_add_u64 v[128:129], v[174:175], 0, v[206:207]
	global_load_dwordx4 v[196:199], v[128:129], off
	global_load_dwordx4 v[200:203], v[128:129], off offset:256
	v_or_b32_e32 v184, 16, v172
	v_or_b32_e32 v180, 32, v172
	v_or_b32_e32 v176, 48, v172
	v_ashrrev_i32_e32 v185, 31, v184
	v_ashrrev_i32_e32 v181, 31, v180
	v_ashrrev_i32_e32 v177, 31, v176
	v_lshlrev_b64 v[186:187], 12, v[184:185]
	v_lshlrev_b64 v[182:183], 12, v[180:181]
	v_lshlrev_b64 v[178:179], 12, v[176:177]
	v_lshl_add_u64 v[128:129], v[174:175], 0, v[186:187]
	v_lshl_add_u64 v[130:131], v[174:175], 0, v[182:183]
	v_lshl_add_u64 v[208:209], v[174:175], 0, v[178:179]
	global_load_dwordx4 v[148:151], v[128:129], off
	global_load_dwordx4 v[144:147], v[128:129], off offset:256
	global_load_dwordx4 v[140:143], v[130:131], off
	global_load_dwordx4 v[136:139], v[130:131], off offset:256
	global_load_dwordx4 v[132:135], v[208:209], off
	s_nop 0
	global_load_dwordx4 v[128:131], v[208:209], off offset:256
	v_lshl_add_u64 v[206:207], s[76:77], 0, v[206:207]
	v_and_b32_e32 v208, 64, v194
	v_lshl_add_u64 v[204:205], v[206:207], 0, v[204:205]
	v_xor_b32_e32 v195, 16, v194
	v_add_u32_e32 v208, 64, v208
	v_xor_b32_e32 v209, 32, v194
	v_cmp_lt_i32_e32 vcc, v195, v208
	s_lshl_b32 s20, s16, 2
	s_ashr_i32 s21, s20, 31
	v_cndmask_b32_e32 v195, v194, v195, vcc
	v_cmp_lt_i32_e32 vcc, v209, v208
	v_lshlrev_b32_e32 v195, 2, v195
	s_waitcnt vmcnt(0)
	v_lshlrev_b32_e32 v206, 16, v196
	v_and_b32_e32 v196, 0xffff0000, v196
	v_lshlrev_b32_e32 v211, 16, v200
	v_and_b32_e32 v200, 0xffff0000, v200
	v_fmac_f32_e32 v196, 0.5, v125
	v_lshlrev_b32_e32 v207, 16, v197
	v_fmac_f32_e32 v206, 0.5, v124
	v_fmac_f32_e32 v200, 0.5, v117
	v_mul_f32_e32 v117, v196, v196
	v_and_b32_e32 v197, 0xffff0000, v197
	v_fmac_f32_e32 v207, 0.5, v126
	v_fmac_f32_e32 v117, v206, v206
	v_cndmask_b32_e32 v208, v194, v209, vcc
	v_lshlrev_b32_e32 v209, 16, v198
	v_fmac_f32_e32 v197, 0.5, v127
	v_fmac_f32_e32 v117, v207, v207
	v_and_b32_e32 v198, 0xffff0000, v198
	v_fmac_f32_e32 v209, 0.5, v120
	v_fmac_f32_e32 v117, v197, v197
	v_lshlrev_b32_e32 v210, 16, v199
	v_fmac_f32_e32 v198, 0.5, v121
	v_fmac_f32_e32 v117, v209, v209
	v_and_b32_e32 v199, 0xffff0000, v199
	v_fmac_f32_e32 v210, 0.5, v122
	v_fmac_f32_e32 v117, v198, v198
	v_fmac_f32_e32 v199, 0.5, v123
	v_fmac_f32_e32 v117, v210, v210
	v_fmac_f32_e32 v211, 0.5, v116
	v_fmac_f32_e32 v117, v199, v199
	v_lshlrev_b32_e32 v212, 16, v201
	v_fmac_f32_e32 v117, v211, v211
	v_and_b32_e32 v201, 0xffff0000, v201
	v_fmac_f32_e32 v212, 0.5, v118
	v_fmac_f32_e32 v117, v200, v200
	v_lshlrev_b32_e32 v213, 16, v202
	v_fmac_f32_e32 v201, 0.5, v119
	v_fmac_f32_e32 v117, v212, v212
	v_and_b32_e32 v202, 0xffff0000, v202
	v_fmac_f32_e32 v213, 0.5, v112
	v_fmac_f32_e32 v117, v201, v201
	v_lshlrev_b32_e32 v214, 16, v203
	v_fmac_f32_e32 v202, 0.5, v113
	v_fmac_f32_e32 v117, v213, v213
	v_and_b32_e32 v203, 0xffff0000, v203
	v_fmac_f32_e32 v214, 0.5, v114
	v_fmac_f32_e32 v117, v202, v202
	v_fmac_f32_e32 v203, 0.5, v115
	v_fmac_f32_e32 v117, v214, v214
	v_fmac_f32_e32 v117, v203, v203
	ds_bpermute_b32 v118, v195, v117
	v_cvt_pk_bf16_f32 v112, v206, v196
	v_cvt_pk_bf16_f32 v113, v207, v197
	v_cvt_pk_bf16_f32 v114, v209, v198
	v_cvt_pk_bf16_f32 v115, v210, v199
	global_store_dwordx4 v[204:205], v[112:115], off
	v_cvt_pk_bf16_f32 v116, v211, v200
	s_waitcnt lgkmcnt(0)
	s_nop 0
	v_add_f32_e32 v113, v117, v118
	v_lshlrev_b32_e32 v112, 2, v208
	ds_bpermute_b32 v114, v112, v113
	v_cvt_pk_bf16_f32 v117, v212, v201
	v_cvt_pk_bf16_f32 v118, v213, v202
	v_cvt_pk_bf16_f32 v119, v214, v203
	global_store_dwordx4 v[204:205], v[116:119], off offset:256
	s_and_saveexec_b64 s[10:11], s[2:3]
	s_cbranch_execz .LBB0_320
	v_lshlrev_b64 v[116:117], 7, v[172:173]
	v_lshl_add_u64 v[116:117], s[8:9], 0, v[116:117]
	v_lshl_add_u64 v[116:117], s[20:21], 2, v[116:117]
	s_lshl_b32 s16, s34, 2
	v_lshl_add_u64 v[116:117], v[116:117], 0, s[16:17]
	s_waitcnt lgkmcnt(0)
	v_add_f32_e32 v113, v113, v114
	global_store_dword v[116:117], v113, off

; #define PG8_STAGE(bufoff, gbase, voff) do { _Pragma("unroll") for (int _i = 0; _i < 2; ++_i) \
;         __builtin_amdgcn_global_load_lds((const unsigned*)((const char*)(gbase) + (voff)[_i]), (PG8_LAS unsigned*)(lds + (bufoff) + ldsw + _i * 8192), 16, 0, 0); } while (0)
; #define PG8_LDA(dst, b, h) do { _Pragma("unroll") for (int m = 0; m < 4; ++m) _Pragma("unroll") for (int k = 0; k < 2; ++k) dst[m][k] = *(const PG8_LAS bf16x8*)(lds + PG8_SA(b, h) + aoff + m * 2048 + k * 1024); } while (0)
; #define PG8_LDB(dst, b, h) do { _Pragma("unroll") for (int n = 0; n < 2; ++n) _Pragma("unroll") for (int k = 0; k < 2; ++k) dst[n][k] = *(const PG8_LAS bf16x8*)(lds + PG8_SB(b, h) + boff + n * 2048 + k * 1024); } while (0)
; #define PG8_WAIT_V(n) asm volatile("s_waitcnt vmcnt(" #n ")" ::: "memory")
; #define PG8_WAIT_L(n) asm volatile("s_waitcnt lgkmcnt(" #n ")" ::: "memory")
; #define PG8_BAR __builtin_amdgcn_s_barrier()
; #define PG8_SCHED __builtin_amdgcn_sched_barrier(0)
; template <class Epi>
; __device__ __forceinline__ void gemm_phase(PG8_LAS unsigned char* lds, const Gemm g, const StaticOrder& S, const Epi& E) {
;     ...
;     for (;;) {
;         const bool has_next = S.next(ui + 1, nxt);
;         const char* nA = has_next ? (const char*)g.A + (size_t)nxt.pm * tstepA : cA; const char* nB = has_next ? (const char*)g.Bt + (size_t)nxt.pn * tstepB : cB;
;         for (int t = 0; t < nt; t += 2) {
;             const bool last = (t == nt - 2);
;             const char* a1 = cA + (size_t)(t + 1) * kstep;
;             const char* a2 = last ? nA : cA + (size_t)(t + 2) * kstep; const char* b2 = last ? nB : cB + (size_t)(t + 2) * kstep;
;             const char* a3 = a2 + kstep; const char* b3 = b2 + kstep;
;             PG8_LDB(B0, 0, 0); PG8_SCHED; PG8_LDA(At, 0, 0); PG8_STAGE(PG8_SA(1, 1), a1 + hstepA, voffA);
;             PG8_WAIT_L(8); PG8_BAR; PG8_WAIT_L(0); PG8_MMA(0, 0, At, B0); PG8_BAR; PG8_SCHED;
;             PG8_LDB(B1, 0, 1); PG8_STAGE(PG8_SB(0, 0), b2, voffB);
;             PG8_BAR; PG8_WAIT_L(0); PG8_MMA(0, 1, At, B1); PG8_BAR;
;             PG8_LDA(At, 0, 1); PG8_STAGE(PG8_SA(0, 0), a2, voffA);
;             PG8_BAR; PG8_WAIT_L(0); PG8_MMA(1, 0, At, B0); PG8_BAR; PG8_SCHED;
;             PG8_STAGE(PG8_SB(0, 1), b2 + hstepB, voffB);
;             PG8_WAIT_V(6); PG8_BAR; PG8_MMA(1, 1, At, B1); PG8_BAR;
.LBB0_413:
	ds_read_b128 v[148:151], v166
	ds_read_b128 v[152:155], v166 offset:1024
	ds_read_b128 v[156:159], v166 offset:2048
	ds_read_b128 v[172:175], v166 offset:3072
	ds_read_b128 v[176:179], v167
	ds_read_b128 v[180:183], v167 offset:1024
	ds_read_b128 v[184:187], v167 offset:2048
	ds_read_b128 v[188:191], v167 offset:3072
	ds_read_b128 v[192:195], v167 offset:4096
	ds_read_b128 v[196:199], v167 offset:5120
	ds_read_b128 v[200:203], v167 offset:6144
	ds_read_b128 v[204:207], v167 offset:7168
	ds_read_b128 v[208:211], v169
	ds_read_b128 v[212:215], v169 offset:1024
	ds_read_b128 v[216:219], v169 offset:2048
	ds_read_b128 v[220:223], v169 offset:3072
	s_add_u32 s4, s0, 0xfff80080
	s_addc_u32 s5, s1, -1
	s_cmp_eq_u32 s67, 28
	s_cselect_b32 s7, s53, s5
	s_cselect_b32 s6, s57, s4
	s_cselect_b32 s5, s55, s66
	s_cselect_b32 s4, s63, s65
	v_lshl_add_u64 v[160:161], s[0:1], 0, v[140:141]
	s_add_i32 m0, s11, 0xc000
	s_nop 0
	global_load_lds_dwordx4 v[160:161], off
	v_lshl_add_u64 v[160:161], s[0:1], 0, v[142:143]
	s_add_i32 m0, s11, 0xe000
	s_nop 0
	global_load_lds_dwordx4 v[160:161], off
	s_waitcnt lgkmcnt(0)
	s_waitcnt vmcnt(8)
	s_barrier
	s_setprio 1
	v_mfma_f32_16x16x32_bf16 v[124:127], v[148:151], v[176:179], v[124:127]
	v_mfma_f32_16x16x32_bf16 v[120:123], v[156:159], v[176:179], v[120:123]
	v_mfma_f32_16x16x32_bf16 v[108:111], v[148:151], v[184:187], v[108:111]
	v_mfma_f32_16x16x32_bf16 v[104:107], v[156:159], v[184:187], v[104:107]
	v_mfma_f32_16x16x32_bf16 v[92:95], v[148:151], v[192:195], v[92:95]
	v_mfma_f32_16x16x32_bf16 v[88:91], v[156:159], v[192:195], v[88:91]
	v_mfma_f32_16x16x32_bf16 v[76:79], v[148:151], v[200:203], v[76:79]
	v_mfma_f32_16x16x32_bf16 v[72:75], v[156:159], v[200:203], v[72:75]
	v_mfma_f32_16x16x32_bf16 v[124:127], v[152:155], v[180:183], v[124:127]
	v_mfma_f32_16x16x32_bf16 v[120:123], v[172:175], v[180:183], v[120:123]
	v_mfma_f32_16x16x32_bf16 v[108:111], v[152:155], v[188:191], v[108:111]
	v_mfma_f32_16x16x32_bf16 v[104:107], v[172:175], v[188:191], v[104:107]
	v_mfma_f32_16x16x32_bf16 v[92:95], v[152:155], v[196:199], v[92:95]
	v_mfma_f32_16x16x32_bf16 v[88:91], v[172:175], v[196:199], v[88:91]
	v_mfma_f32_16x16x32_bf16 v[76:79], v[152:155], v[204:207], v[76:79]
	v_mfma_f32_16x16x32_bf16 v[72:75], v[172:175], v[204:207], v[72:75]
	v_mfma_f32_16x16x32_bf16 v[116:119], v[208:211], v[176:179], v[116:119]
	v_mfma_f32_16x16x32_bf16 v[112:115], v[216:219], v[176:179], v[112:115]
	v_mfma_f32_16x16x32_bf16 v[100:103], v[208:211], v[184:187], v[100:103]
	v_mfma_f32_16x16x32_bf16 v[96:99], v[216:219], v[184:187], v[96:99]
	v_mfma_f32_16x16x32_bf16 v[84:87], v[208:211], v[192:195], v[84:87]
	v_mfma_f32_16x16x32_bf16 v[80:83], v[216:219], v[192:195], v[80:83]
	v_mfma_f32_16x16x32_bf16 v[68:71], v[208:211], v[200:203], v[68:71]
	v_mfma_f32_16x16x32_bf16 v[64:67], v[216:219], v[200:203], v[64:67]
	v_mfma_f32_16x16x32_bf16 v[116:119], v[212:215], v[180:183], v[116:119]
	v_mfma_f32_16x16x32_bf16 v[112:115], v[220:223], v[180:183], v[112:115]
	v_mfma_f32_16x16x32_bf16 v[100:103], v[212:215], v[188:191], v[100:103]
	v_mfma_f32_16x16x32_bf16 v[96:99], v[220:223], v[188:191], v[96:99]
	v_mfma_f32_16x16x32_bf16 v[84:87], v[212:215], v[196:199], v[84:87]
	v_mfma_f32_16x16x32_bf16 v[80:83], v[220:223], v[196:199], v[80:83]
	v_mfma_f32_16x16x32_bf16 v[68:71], v[212:215], v[204:207], v[68:71]
	v_mfma_f32_16x16x32_bf16 v[64:67], v[220:223], v[204:207], v[64:67]
	s_setprio 0
	s_barrier
	ds_read_b128 v[176:179], v167 offset:16384
	ds_read_b128 v[180:183], v167 offset:17408
	ds_read_b128 v[184:187], v167 offset:18432
	ds_read_b128 v[188:191], v167 offset:19456
	ds_read_b128 v[192:195], v167 offset:20480
	ds_read_b128 v[196:199], v167 offset:21504
	ds_read_b128 v[200:203], v167 offset:22528
	ds_read_b128 v[204:207], v167 offset:23552
	s_add_i32 s68, s9, s10
	v_lshl_add_u64 v[160:161], s[4:5], 0, v[130:131]
	s_mov_b32 m0, s68
	s_nop 0
	global_load_lds_dwordx4 v[160:161], off
	v_lshl_add_u64 v[224:225], s[4:5], 0, v[134:135]
	s_add_i32 m0, s68, 0x2000
	s_nop 0
	global_load_lds_dwordx4 v[224:225], off
	s_mov_b32 m0, s11
	v_lshl_add_u64 v[226:227], s[6:7], 0, v[128:129]
	global_load_lds_dwordx4 v[226:227], off
	v_lshl_add_u64 v[228:229], s[6:7], 0, v[132:133]
	s_mov_b32 m0, s19
	s_nop 0
	global_load_lds_dwordx4 v[228:229], off
	s_add_u32 s68, s4, 0x80000
	s_addc_u32 s69, s5, 0
	s_add_i32 s70, s40, s10
	v_lshl_add_u64 v[230:231], s[68:69], 0, v[130:131]
	s_mov_b32 m0, s70
	s_nop 0
	global_load_lds_dwordx4 v[230:231], off
	v_lshl_add_u64 v[230:231], s[68:69], 0, v[134:135]
	s_add_i32 m0, s70, 0x2000
	s_nop 0
	global_load_lds_dwordx4 v[230:231], off
	s_waitcnt lgkmcnt(0)
	s_waitcnt vmcnt(8)
	s_barrier
; #define PG8_STAGE(bufoff, gbase, voff) do { _Pragma("unroll") for (int _i = 0; _i < 2; ++_i) \
;         __builtin_amdgcn_global_load_lds((const unsigned*)((const char*)(gbase) + (voff)[_i]), (PG8_LAS unsigned*)(lds + (bufoff) + ldsw + _i * 8192), 16, 0, 0); } while (0)
; #define PG8_LDA(dst, b, h) do { _Pragma("unroll") for (int m = 0; m < 4; ++m) _Pragma("unroll") for (int k = 0; k < 2; ++k) dst[m][k] = *(const PG8_LAS bf16x8*)(lds + PG8_SA(b, h) + aoff + m * 2048 + k * 1024); } while (0)
; #define PG8_LDB(dst, b, h) do { _Pragma("unroll") for (int n = 0; n < 2; ++n) _Pragma("unroll") for (int k = 0; k < 2; ++k) dst[n][k] = *(const PG8_LAS bf16x8*)(lds + PG8_SB(b, h) + boff + n * 2048 + k * 1024); } while (0)
; #define PG8_MMA(ai, bj, At, Bt) do { __builtin_amdgcn_s_setprio(1); _Pragma("unroll") for (int m = 0; m < 4; ++m) _Pragma("unroll") for (int n = 0; n < 2; ++n) _Pragma("unroll") for (int k = 0; k < 2; ++k) \
;         acc[ai][bj][m][n] = __builtin_amdgcn_mfma_f32_16x16x32_bf16(Bt[n][k], At[m][k], acc[ai][bj][m][n], 0, 0, 0); __builtin_amdgcn_s_setprio(0); } while (0)
; #define PG8_WAIT_V(n) asm volatile("s_waitcnt vmcnt(" #n ")" ::: "memory")
; #define PG8_WAIT_L(n) asm volatile("s_waitcnt lgkmcnt(" #n ")" ::: "memory")
; #define PG8_BAR __builtin_amdgcn_s_barrier()
; #define PG8_SCHED __builtin_amdgcn_sched_barrier(0)
; template <class Epi>
; __device__ __forceinline__ void gemm_phase(PG8_LAS unsigned char* lds, const Gemm g, const StaticOrder& S, const Epi& E) {
;     ...
;             PG8_BAR; PG8_WAIT_L(0); PG8_MMA(1, 0, At, B0); PG8_BAR; PG8_SCHED;
;             PG8_STAGE(PG8_SB(0, 1), b2 + hstepB, voffB);
;             PG8_WAIT_V(6); PG8_BAR; PG8_MMA(1, 1, At, B1); PG8_BAR;
;             PG8_LDB(B0, 1, 0); PG8_SCHED; PG8_LDA(At, 1, 0); PG8_STAGE(PG8_SA(0, 1), a2 + hstepA, voffA);
;             PG8_WAIT_L(8); PG8_BAR; PG8_WAIT_L(0); PG8_MMA(0, 0, At, B0); PG8_BAR; PG8_SCHED;
	s_setprio 1
	v_mfma_f32_16x16x32_bf16 v[60:63], v[148:151], v[176:179], v[60:63]
	v_mfma_f32_16x16x32_bf16 v[56:59], v[156:159], v[176:179], v[56:59]
	v_mfma_f32_16x16x32_bf16 v[44:47], v[148:151], v[184:187], v[44:47]
	v_mfma_f32_16x16x32_bf16 v[40:43], v[156:159], v[184:187], v[40:43]
	v_mfma_f32_16x16x32_bf16 v[28:31], v[148:151], v[192:195], v[28:31]
	v_mfma_f32_16x16x32_bf16 v[24:27], v[156:159], v[192:195], v[24:27]
	v_mfma_f32_16x16x32_bf16 v[12:15], v[148:151], v[200:203], v[12:15]
	v_mfma_f32_16x16x32_bf16 v[8:11], v[156:159], v[200:203], v[8:11]
	v_mfma_f32_16x16x32_bf16 v[60:63], v[152:155], v[180:183], v[60:63]
	v_mfma_f32_16x16x32_bf16 v[56:59], v[172:175], v[180:183], v[56:59]
	v_mfma_f32_16x16x32_bf16 v[44:47], v[152:155], v[188:191], v[44:47]
	v_mfma_f32_16x16x32_bf16 v[40:43], v[172:175], v[188:191], v[40:43]
	v_mfma_f32_16x16x32_bf16 v[28:31], v[152:155], v[196:199], v[28:31]
	v_mfma_f32_16x16x32_bf16 v[24:27], v[172:175], v[196:199], v[24:27]
	v_mfma_f32_16x16x32_bf16 v[12:15], v[152:155], v[204:207], v[12:15]
	v_mfma_f32_16x16x32_bf16 v[8:11], v[172:175], v[204:207], v[8:11]
	v_mfma_f32_16x16x32_bf16 v[52:55], v[208:211], v[176:179], v[52:55]
	v_mfma_f32_16x16x32_bf16 v[48:51], v[216:219], v[176:179], v[48:51]
	v_mfma_f32_16x16x32_bf16 v[36:39], v[208:211], v[184:187], v[36:39]
	v_mfma_f32_16x16x32_bf16 v[32:35], v[216:219], v[184:187], v[32:35]
	v_mfma_f32_16x16x32_bf16 v[20:23], v[208:211], v[192:195], v[20:23]
	v_mfma_f32_16x16x32_bf16 v[16:19], v[216:219], v[192:195], v[16:19]
	v_mfma_f32_16x16x32_bf16 v[4:7], v[208:211], v[200:203], v[4:7]
	v_mfma_f32_16x16x32_bf16 v[0:3], v[216:219], v[200:203], v[0:3]
	v_mfma_f32_16x16x32_bf16 v[52:55], v[212:215], v[180:183], v[52:55]
	v_mfma_f32_16x16x32_bf16 v[48:51], v[220:223], v[180:183], v[48:51]
	v_mfma_f32_16x16x32_bf16 v[36:39], v[212:215], v[188:191], v[36:39]
	v_mfma_f32_16x16x32_bf16 v[32:35], v[220:223], v[188:191], v[32:35]
	v_mfma_f32_16x16x32_bf16 v[20:23], v[212:215], v[196:199], v[20:23]
	v_mfma_f32_16x16x32_bf16 v[16:19], v[220:223], v[196:199], v[16:19]
	v_mfma_f32_16x16x32_bf16 v[4:7], v[212:215], v[204:207], v[4:7]
	v_mfma_f32_16x16x32_bf16 v[0:3], v[220:223], v[204:207], v[0:3]
	s_setprio 0
	s_add_i32 s68, 0, 0x18000
	v_add_u32_e32 v172, s68, v163
	s_barrier
	ds_read_b128 v[148:151], v172
	ds_read_b128 v[152:155], v172 offset:1024
	ds_read_b128 v[156:159], v172 offset:2048
	ds_read_b128 v[172:175], v172 offset:3072
	ds_read_b128 v[176:179], v167 offset:32768
	ds_read_b128 v[180:183], v167 offset:33792
	ds_read_b128 v[184:187], v167 offset:34816
	ds_read_b128 v[188:191], v167 offset:35840
	ds_read_b128 v[192:195], v167 offset:36864
	ds_read_b128 v[196:199], v167 offset:37888
	ds_read_b128 v[200:203], v167 offset:38912
	ds_read_b128 v[204:207], v167 offset:39936
	v_add_u32_e32 v220, 0x1c000, v163
	ds_read_b128 v[208:211], v220
	ds_read_b128 v[212:215], v220 offset:1024
	ds_read_b128 v[216:219], v220 offset:2048
	ds_read_b128 v[220:223], v220 offset:3072
	s_add_u32 s6, s6, 0x80000
	s_addc_u32 s7, s7, 0
	s_mov_b32 m0, s22
	v_lshl_add_u64 v[230:231], s[6:7], 0, v[128:129]
	global_load_lds_dwordx4 v[230:231], off
	v_lshl_add_u64 v[230:231], s[6:7], 0, v[132:133]
	s_mov_b32 m0, s23
	s_nop 0
	global_load_lds_dwordx4 v[230:231], off
	s_waitcnt lgkmcnt(0)
	s_waitcnt vmcnt(8)
	s_barrier
	s_setprio 1
	v_mfma_f32_16x16x32_bf16 v[124:127], v[148:151], v[176:179], v[124:127]
	v_mfma_f32_16x16x32_bf16 v[120:123], v[156:159], v[176:179], v[120:123]
	v_mfma_f32_16x16x32_bf16 v[108:111], v[148:151], v[184:187], v[108:111]
	v_mfma_f32_16x16x32_bf16 v[104:107], v[156:159], v[184:187], v[104:107]
	v_mfma_f32_16x16x32_bf16 v[92:95], v[148:151], v[192:195], v[92:95]
	v_mfma_f32_16x16x32_bf16 v[88:91], v[156:159], v[192:195], v[88:91]
	v_mfma_f32_16x16x32_bf16 v[76:79], v[148:151], v[200:203], v[76:79]
	v_mfma_f32_16x16x32_bf16 v[72:75], v[156:159], v[200:203], v[72:75]
	v_mfma_f32_16x16x32_bf16 v[124:127], v[152:155], v[180:183], v[124:127]
	v_mfma_f32_16x16x32_bf16 v[120:123], v[172:175], v[180:183], v[120:123]
	v_mfma_f32_16x16x32_bf16 v[108:111], v[152:155], v[188:191], v[108:111]
	v_mfma_f32_16x16x32_bf16 v[104:107], v[172:175], v[188:191], v[104:107]
	v_mfma_f32_16x16x32_bf16 v[92:95], v[152:155], v[196:199], v[92:95]
	v_mfma_f32_16x16x32_bf16 v[88:91], v[172:175], v[196:199], v[88:91]
	v_mfma_f32_16x16x32_bf16 v[76:79], v[152:155], v[204:207], v[76:79]
	v_mfma_f32_16x16x32_bf16 v[72:75], v[172:175], v[204:207], v[72:75]
	v_mfma_f32_16x16x32_bf16 v[116:119], v[208:211], v[176:179], v[116:119]
	v_mfma_f32_16x16x32_bf16 v[112:115], v[216:219], v[176:179], v[112:115]
	v_mfma_f32_16x16x32_bf16 v[100:103], v[208:211], v[184:187], v[100:103]
	v_mfma_f32_16x16x32_bf16 v[96:99], v[216:219], v[184:187], v[96:99]
	v_mfma_f32_16x16x32_bf16 v[84:87], v[208:211], v[192:195], v[84:87]
	v_mfma_f32_16x16x32_bf16 v[80:83], v[216:219], v[192:195], v[80:83]
	v_mfma_f32_16x16x32_bf16 v[68:71], v[208:211], v[200:203], v[68:71]
	v_mfma_f32_16x16x32_bf16 v[64:67], v[216:219], v[200:203], v[64:67]
	v_mfma_f32_16x16x32_bf16 v[116:119], v[212:215], v[180:183], v[116:119]
	v_mfma_f32_16x16x32_bf16 v[112:115], v[220:223], v[180:183], v[112:115]
	v_mfma_f32_16x16x32_bf16 v[100:103], v[212:215], v[188:191], v[100:103]
	v_mfma_f32_16x16x32_bf16 v[96:99], v[220:223], v[188:191], v[96:99]
	v_mfma_f32_16x16x32_bf16 v[84:87], v[212:215], v[196:199], v[84:87]
	v_mfma_f32_16x16x32_bf16 v[80:83], v[220:223], v[196:199], v[80:83]
	v_mfma_f32_16x16x32_bf16 v[68:71], v[212:215], v[204:207], v[68:71]
	v_mfma_f32_16x16x32_bf16 v[64:67], v[220:223], v[204:207], v[64:67]
	s_setprio 0
	s_barrier
; #define PG8_STAGE(bufoff, gbase, voff) do { _Pragma("unroll") for (int _i = 0; _i < 2; ++_i) \
;         __builtin_amdgcn_global_load_lds((const unsigned*)((const char*)(gbase) + (voff)[_i]), (PG8_LAS unsigned*)(lds + (bufoff) + ldsw + _i * 8192), 16, 0, 0); } while (0)
; #define PG8_LDA(dst, b, h) do { _Pragma("unroll") for (int m = 0; m < 4; ++m) _Pragma("unroll") for (int k = 0; k < 2; ++k) dst[m][k] = *(const PG8_LAS bf16x8*)(lds + PG8_SA(b, h) + aoff + m * 2048 + k * 1024); } while (0)
; #define PG8_LDB(dst, b, h) do { _Pragma("unroll") for (int n = 0; n < 2; ++n) _Pragma("unroll") for (int k = 0; k < 2; ++k) dst[n][k] = *(const PG8_LAS bf16x8*)(lds + PG8_SB(b, h) + boff + n * 2048 + k * 1024); } while (0)
; #define PG8_MMA(ai, bj, At, Bt) do { __builtin_amdgcn_s_setprio(1); _Pragma("unroll") for (int m = 0; m < 4; ++m) _Pragma("unroll") for (int n = 0; n < 2; ++n) _Pragma("unroll") for (int k = 0; k < 2; ++k) \
;         acc[ai][bj][m][n] = __builtin_amdgcn_mfma_f32_16x16x32_bf16(Bt[n][k], At[m][k], acc[ai][bj][m][n], 0, 0, 0); __builtin_amdgcn_s_setprio(0); } while (0)
; #define PG8_WAIT_V(n) asm volatile("s_waitcnt vmcnt(" #n ")" ::: "memory")
; #define PG8_WAIT_L(n) asm volatile("s_waitcnt lgkmcnt(" #n ")" ::: "memory")
; template <class Epi>
; __device__ __forceinline__ void gemm_phase(PG8_LAS unsigned char* lds, const Gemm g, const StaticOrder& S, const Epi& E) {
;     ...
;             PG8_LDB(B1, 1, 1); PG8_STAGE(PG8_SB(1, 0), b3, voffB);
;             PG8_BAR; PG8_WAIT_L(0); PG8_MMA(0, 1, At, B1); PG8_BAR;
;             PG8_LDA(At, 1, 1); PG8_STAGE(PG8_SA(1, 0), a3, voffA);
;             PG8_BAR; PG8_WAIT_L(0); PG8_MMA(1, 0, At, B0); PG8_BAR; PG8_SCHED;
;             PG8_STAGE(PG8_SB(1, 1), b3 + hstepB, voffB);
;             PG8_WAIT_V(6); PG8_BAR; PG8_MMA(1, 1, At, B1); PG8_BAR;
;         }
;     __device__ __forceinline__ void operator()(const f32x4 (&acc)[2][2][4][2], const pg8::Unit& u, int wr, int wc, int fr, int fq) const {
;         const int row0 = u.pm * 256 + wr * 64 + fr; const int pn = u.pn;
;         bf16_t* base; int ld, cb; const bool paired = (pn >= 11 && pn < 19);
;         if (pn < 11) { base = Z1; ld = LDZ; cb = pn * 256; } else if (pn < 19) { base = XCC; ld = LDX; cb = (pn - 11) * 128; } else if (pn < 23) { base = BB; ld = LDX; cb = (pn - 19) * 256; } else { base = G; ld = LDG; cb = (pn - 23) * 256; }
	ds_read_b128 v[176:179], v167 offset:49152
	ds_read_b128 v[180:183], v167 offset:50176
	ds_read_b128 v[184:187], v167 offset:51200
	ds_read_b128 v[188:191], v167 offset:52224
	ds_read_b128 v[192:195], v167 offset:53248
	ds_read_b128 v[196:199], v167 offset:54272
	ds_read_b128 v[200:203], v167 offset:55296
	ds_read_b128 v[204:207], v167 offset:56320
	s_add_i32 s6, 0, 0x1c000
	s_add_i32 s7, s68, s10
	v_lshl_add_u64 v[160:161], v[160:161], 0, s[14:15]
	s_mov_b32 m0, s7
	s_nop 0
	global_load_lds_dwordx4 v[160:161], off
	v_lshl_add_u64 v[160:161], v[224:225], 0, s[14:15]
	s_add_i32 m0, s7, 0x2000
	s_nop 0
	global_load_lds_dwordx4 v[160:161], off
	s_mov_b32 m0, s35
	v_lshl_add_u64 v[160:161], v[226:227], 0, s[14:15]
	global_load_lds_dwordx4 v[160:161], off
	v_lshl_add_u64 v[160:161], v[228:229], 0, s[14:15]
	s_mov_b32 m0, s36
	s_nop 0
	global_load_lds_dwordx4 v[160:161], off
	s_add_u32 s4, s4, 0x80080
	s_addc_u32 s5, s5, 0
	s_add_i32 s6, s6, s10
	v_lshl_add_u64 v[230:231], s[4:5], 0, v[130:131]
	s_mov_b32 m0, s6
	s_nop 0
	global_load_lds_dwordx4 v[230:231], off
	v_lshl_add_u64 v[230:231], s[4:5], 0, v[134:135]
	s_add_i32 m0, s6, 0x2000
	s_nop 0
	global_load_lds_dwordx4 v[230:231], off
	s_waitcnt lgkmcnt(0)
	s_waitcnt vmcnt(8)
	s_barrier
	s_setprio 1
	v_mfma_f32_16x16x32_bf16 v[60:63], v[148:151], v[176:179], v[60:63]
	v_mfma_f32_16x16x32_bf16 v[56:59], v[156:159], v[176:179], v[56:59]
	v_mfma_f32_16x16x32_bf16 v[44:47], v[148:151], v[184:187], v[44:47]
	v_mfma_f32_16x16x32_bf16 v[40:43], v[156:159], v[184:187], v[40:43]
	v_mfma_f32_16x16x32_bf16 v[28:31], v[148:151], v[192:195], v[28:31]
	v_mfma_f32_16x16x32_bf16 v[24:27], v[156:159], v[192:195], v[24:27]
	v_mfma_f32_16x16x32_bf16 v[12:15], v[148:151], v[200:203], v[12:15]
	v_mfma_f32_16x16x32_bf16 v[8:11], v[156:159], v[200:203], v[8:11]
	v_mfma_f32_16x16x32_bf16 v[60:63], v[152:155], v[180:183], v[60:63]
	v_mfma_f32_16x16x32_bf16 v[56:59], v[172:175], v[180:183], v[56:59]
	v_mfma_f32_16x16x32_bf16 v[44:47], v[152:155], v[188:191], v[44:47]
	v_mfma_f32_16x16x32_bf16 v[40:43], v[172:175], v[188:191], v[40:43]
	v_mfma_f32_16x16x32_bf16 v[28:31], v[152:155], v[196:199], v[28:31]
	v_mfma_f32_16x16x32_bf16 v[24:27], v[172:175], v[196:199], v[24:27]
	v_mfma_f32_16x16x32_bf16 v[12:15], v[152:155], v[204:207], v[12:15]
	v_mfma_f32_16x16x32_bf16 v[8:11], v[172:175], v[204:207], v[8:11]
	v_mfma_f32_16x16x32_bf16 v[52:55], v[208:211], v[176:179], v[52:55]
	v_mfma_f32_16x16x32_bf16 v[48:51], v[216:219], v[176:179], v[48:51]
	v_mfma_f32_16x16x32_bf16 v[36:39], v[208:211], v[184:187], v[36:39]
	v_mfma_f32_16x16x32_bf16 v[32:35], v[216:219], v[184:187], v[32:35]
	v_mfma_f32_16x16x32_bf16 v[20:23], v[208:211], v[192:195], v[20:23]
	v_mfma_f32_16x16x32_bf16 v[16:19], v[216:219], v[192:195], v[16:19]
	v_mfma_f32_16x16x32_bf16 v[4:7], v[208:211], v[200:203], v[4:7]
	v_mfma_f32_16x16x32_bf16 v[0:3], v[216:219], v[200:203], v[0:3]
	v_mfma_f32_16x16x32_bf16 v[52:55], v[212:215], v[180:183], v[52:55]
	v_mfma_f32_16x16x32_bf16 v[48:51], v[220:223], v[180:183], v[48:51]
	v_mfma_f32_16x16x32_bf16 v[36:39], v[212:215], v[188:191], v[36:39]
	v_mfma_f32_16x16x32_bf16 v[32:35], v[220:223], v[188:191], v[32:35]
	v_mfma_f32_16x16x32_bf16 v[20:23], v[212:215], v[196:199], v[20:23]
	v_mfma_f32_16x16x32_bf16 v[16:19], v[220:223], v[196:199], v[16:19]
	v_mfma_f32_16x16x32_bf16 v[4:7], v[212:215], v[204:207], v[4:7]
	v_mfma_f32_16x16x32_bf16 v[0:3], v[220:223], v[204:207], v[0:3]
	s_setprio 0
	s_add_i32 s67, s67, 2
	s_add_u32 s0, s0, 0x100
	s_addc_u32 s1, s1, 0
	s_add_u32 s65, s65, 0x100
	s_addc_u32 s66, s66, 0
	s_cmp_gt_u32 s67, 29
	s_barrier
	s_cbranch_scc0 .LBB0_413
	s_cmp_gt_i32 s62, 10
	s_mov_b64 s[0:1], -1
	s_cbranch_scc0 .LBB0_424
	s_cmp_gt_u32 s62, 18
	s_cbranch_scc0 .LBB0_421
	s_lshl_b32 s4, s62, 8
	s_cmp_gt_u32 s62, 22
	s_cbranch_scc0 .LBB0_418
	s_add_i32 s53, s4, 0xffffe900
	s_mov_b64 s[0:1], 0

; #define PG8_STAGE(bufoff, gbase, voff) do { _Pragma("unroll") for (int _i = 0; _i < 2; ++_i) \
;         __builtin_amdgcn_global_load_lds((const unsigned*)((const char*)(gbase) + (voff)[_i]), (PG8_LAS unsigned*)(lds + (bufoff) + ldsw + _i * 8192), 16, 0, 0); } while (0)
; #define PG8_LDA(dst, b, h) do { _Pragma("unroll") for (int m = 0; m < 4; ++m) _Pragma("unroll") for (int k = 0; k < 2; ++k) dst[m][k] = *(const PG8_LAS bf16x8*)(lds + PG8_SA(b, h) + aoff + m * 2048 + k * 1024); } while (0)
; #define PG8_LDB(dst, b, h) do { _Pragma("unroll") for (int n = 0; n < 2; ++n) _Pragma("unroll") for (int k = 0; k < 2; ++k) dst[n][k] = *(const PG8_LAS bf16x8*)(lds + PG8_SB(b, h) + boff + n * 2048 + k * 1024); } while (0)
; #define PG8_WAIT_V(n) asm volatile("s_waitcnt vmcnt(" #n ")" ::: "memory")
; #define PG8_WAIT_L(n) asm volatile("s_waitcnt lgkmcnt(" #n ")" ::: "memory")
; #define PG8_BAR __builtin_amdgcn_s_barrier()
; #define PG8_SCHED __builtin_amdgcn_sched_barrier(0)
; template <class Epi>
; __device__ __forceinline__ void gemm_phase(PG8_LAS unsigned char* lds, const Gemm g, const StaticOrder& S, const Epi& E) {
;     ...
;     for (;;) {
;         const bool has_next = S.next(ui + 1, nxt);
;         const char* nA = has_next ? (const char*)g.A + (size_t)nxt.pm * tstepA : cA; const char* nB = has_next ? (const char*)g.Bt + (size_t)nxt.pn * tstepB : cB;
;         for (int t = 0; t < nt; t += 2) {
;             const bool last = (t == nt - 2);
;             const char* a1 = cA + (size_t)(t + 1) * kstep;
;             const char* a2 = last ? nA : cA + (size_t)(t + 2) * kstep; const char* b2 = last ? nB : cB + (size_t)(t + 2) * kstep;
;             const char* a3 = a2 + kstep; const char* b3 = b2 + kstep;
;             PG8_LDB(B0, 0, 0); PG8_SCHED; PG8_LDA(At, 0, 0); PG8_STAGE(PG8_SA(1, 1), a1 + hstepA, voffA);
;             PG8_WAIT_L(8); PG8_BAR; PG8_WAIT_L(0); PG8_MMA(0, 0, At, B0); PG8_BAR; PG8_SCHED;
;             PG8_LDB(B1, 0, 1); PG8_STAGE(PG8_SB(0, 0), b2, voffB);
;             PG8_BAR; PG8_WAIT_L(0); PG8_MMA(0, 1, At, B1); PG8_BAR;
;             PG8_LDA(At, 0, 1); PG8_STAGE(PG8_SA(0, 0), a2, voffA);
;             PG8_BAR; PG8_WAIT_L(0); PG8_MMA(1, 0, At, B0); PG8_BAR; PG8_SCHED;
;             PG8_STAGE(PG8_SB(0, 1), b2 + hstepB, voffB);
;             PG8_WAIT_V(6); PG8_BAR; PG8_MMA(1, 1, At, B1); PG8_BAR;
.LBB0_904:
	ds_read_b128 v[128:131], v178
	ds_read_b128 v[132:135], v178 offset:1024
	ds_read_b128 v[136:139], v178 offset:2048
	ds_read_b128 v[140:143], v178 offset:3072
	ds_read_b128 v[144:147], v179
	ds_read_b128 v[164:167], v179 offset:1024
	ds_read_b128 v[170:173], v179 offset:2048
	ds_read_b128 v[182:185], v179 offset:3072
	ds_read_b128 v[186:189], v179 offset:4096
	ds_read_b128 v[190:193], v179 offset:5120
	ds_read_b128 v[194:197], v179 offset:6144
	ds_read_b128 v[198:201], v179 offset:7168
	ds_read_b128 v[202:205], v180
	ds_read_b128 v[206:209], v180 offset:1024
	ds_read_b128 v[210:213], v180 offset:2048
	ds_read_b128 v[214:217], v180 offset:3072
	s_add_u32 s22, s28, 0xfffc0080
	s_addc_u32 s23, s29, -1
	s_cmp_eq_u32 s58, 12
	s_cselect_b32 s31, s15, s23
	s_cselect_b32 s30, s54, s22
	s_cselect_b32 s23, s13, s57
	s_cselect_b32 s22, s55, s56
	v_lshl_add_u64 v[174:175], s[28:29], 0, v[156:157]
	s_add_i32 m0, s21, 0xc000
	s_nop 0
	global_load_lds_dwordx4 v[174:175], off
	v_lshl_add_u64 v[174:175], s[28:29], 0, v[158:159]
	s_add_i32 m0, s21, 0xe000
	s_nop 0
	global_load_lds_dwordx4 v[174:175], off
	s_waitcnt lgkmcnt(0)
	s_waitcnt vmcnt(8)
	s_barrier
	s_setprio 1
	v_mfma_f32_16x16x32_bf16 v[124:127], v[128:131], v[144:147], v[124:127]
	v_mfma_f32_16x16x32_bf16 v[120:123], v[136:139], v[144:147], v[120:123]
	v_mfma_f32_16x16x32_bf16 v[108:111], v[128:131], v[170:173], v[108:111]
	v_mfma_f32_16x16x32_bf16 v[104:107], v[136:139], v[170:173], v[104:107]
	v_mfma_f32_16x16x32_bf16 v[92:95], v[128:131], v[186:189], v[92:95]
	v_mfma_f32_16x16x32_bf16 v[88:91], v[136:139], v[186:189], v[88:91]
	v_mfma_f32_16x16x32_bf16 v[76:79], v[128:131], v[194:197], v[76:79]
	v_mfma_f32_16x16x32_bf16 v[72:75], v[136:139], v[194:197], v[72:75]
	v_mfma_f32_16x16x32_bf16 v[124:127], v[132:135], v[164:167], v[124:127]
	v_mfma_f32_16x16x32_bf16 v[120:123], v[140:143], v[164:167], v[120:123]
	v_mfma_f32_16x16x32_bf16 v[108:111], v[132:135], v[182:185], v[108:111]
	v_mfma_f32_16x16x32_bf16 v[104:107], v[140:143], v[182:185], v[104:107]
	v_mfma_f32_16x16x32_bf16 v[92:95], v[132:135], v[190:193], v[92:95]
	v_mfma_f32_16x16x32_bf16 v[88:91], v[140:143], v[190:193], v[88:91]
	v_mfma_f32_16x16x32_bf16 v[76:79], v[132:135], v[198:201], v[76:79]
	v_mfma_f32_16x16x32_bf16 v[72:75], v[140:143], v[198:201], v[72:75]
	v_mfma_f32_16x16x32_bf16 v[116:119], v[202:205], v[144:147], v[116:119]
	v_mfma_f32_16x16x32_bf16 v[112:115], v[210:213], v[144:147], v[112:115]
	v_mfma_f32_16x16x32_bf16 v[100:103], v[202:205], v[170:173], v[100:103]
	v_mfma_f32_16x16x32_bf16 v[96:99], v[210:213], v[170:173], v[96:99]
	v_mfma_f32_16x16x32_bf16 v[84:87], v[202:205], v[186:189], v[84:87]
	v_mfma_f32_16x16x32_bf16 v[80:83], v[210:213], v[186:189], v[80:83]
	v_mfma_f32_16x16x32_bf16 v[68:71], v[202:205], v[194:197], v[68:71]
	v_mfma_f32_16x16x32_bf16 v[64:67], v[210:213], v[194:197], v[64:67]
	v_mfma_f32_16x16x32_bf16 v[116:119], v[206:209], v[164:167], v[116:119]
	v_mfma_f32_16x16x32_bf16 v[112:115], v[214:217], v[164:167], v[112:115]
	v_mfma_f32_16x16x32_bf16 v[100:103], v[206:209], v[182:185], v[100:103]
	v_mfma_f32_16x16x32_bf16 v[96:99], v[214:217], v[182:185], v[96:99]
	v_mfma_f32_16x16x32_bf16 v[84:87], v[206:209], v[190:193], v[84:87]
	v_mfma_f32_16x16x32_bf16 v[80:83], v[214:217], v[190:193], v[80:83]
	v_mfma_f32_16x16x32_bf16 v[68:71], v[206:209], v[198:201], v[68:71]
	v_mfma_f32_16x16x32_bf16 v[64:67], v[214:217], v[198:201], v[64:67]
	s_setprio 0
	s_barrier
	ds_read_b128 v[144:147], v179 offset:16384
	ds_read_b128 v[164:167], v179 offset:17408
	ds_read_b128 v[170:173], v179 offset:18432
	ds_read_b128 v[182:185], v179 offset:19456
	ds_read_b128 v[186:189], v179 offset:20480
	ds_read_b128 v[190:193], v179 offset:21504
	ds_read_b128 v[194:197], v179 offset:22528
	ds_read_b128 v[198:201], v179 offset:23552
	s_add_i32 s59, s51, s36
	v_lshl_add_u64 v[174:175], s[22:23], 0, v[150:151]
	s_mov_b32 m0, s59
	s_nop 0
	global_load_lds_dwordx4 v[174:175], off
	v_lshl_add_u64 v[218:219], s[22:23], 0, v[154:155]
	s_add_i32 m0, s59, 0x2000
	s_nop 0
	global_load_lds_dwordx4 v[218:219], off
	s_mov_b32 m0, s21
	v_lshl_add_u64 v[220:221], s[30:31], 0, v[148:149]
	global_load_lds_dwordx4 v[220:221], off
	v_lshl_add_u64 v[222:223], s[30:31], 0, v[152:153]
	s_mov_b32 m0, s37
	s_nop 0
	global_load_lds_dwordx4 v[222:223], off
	s_add_u32 s60, s22, 0x40000
	s_addc_u32 s61, s23, 0
	s_add_i32 s59, s52, s36
	v_lshl_add_u64 v[224:225], s[60:61], 0, v[150:151]
	s_mov_b32 m0, s59
	s_nop 0
	global_load_lds_dwordx4 v[224:225], off
	v_lshl_add_u64 v[224:225], s[60:61], 0, v[154:155]
	s_add_i32 m0, s59, 0x2000
	s_nop 0
	global_load_lds_dwordx4 v[224:225], off
	s_waitcnt lgkmcnt(0)
	s_waitcnt vmcnt(8)
	s_barrier
; #define PG8_STAGE(bufoff, gbase, voff) do { _Pragma("unroll") for (int _i = 0; _i < 2; ++_i) \
;         __builtin_amdgcn_global_load_lds((const unsigned*)((const char*)(gbase) + (voff)[_i]), (PG8_LAS unsigned*)(lds + (bufoff) + ldsw + _i * 8192), 16, 0, 0); } while (0)
; #define PG8_LDA(dst, b, h) do { _Pragma("unroll") for (int m = 0; m < 4; ++m) _Pragma("unroll") for (int k = 0; k < 2; ++k) dst[m][k] = *(const PG8_LAS bf16x8*)(lds + PG8_SA(b, h) + aoff + m * 2048 + k * 1024); } while (0)
; #define PG8_LDB(dst, b, h) do { _Pragma("unroll") for (int n = 0; n < 2; ++n) _Pragma("unroll") for (int k = 0; k < 2; ++k) dst[n][k] = *(const PG8_LAS bf16x8*)(lds + PG8_SB(b, h) + boff + n * 2048 + k * 1024); } while (0)
; #define PG8_MMA(ai, bj, At, Bt) do { __builtin_amdgcn_s_setprio(1); _Pragma("unroll") for (int m = 0; m < 4; ++m) _Pragma("unroll") for (int n = 0; n < 2; ++n) _Pragma("unroll") for (int k = 0; k < 2; ++k) \
;         acc[ai][bj][m][n] = __builtin_amdgcn_mfma_f32_16x16x32_bf16(Bt[n][k], At[m][k], acc[ai][bj][m][n], 0, 0, 0); __builtin_amdgcn_s_setprio(0); } while (0)
; #define PG8_WAIT_V(n) asm volatile("s_waitcnt vmcnt(" #n ")" ::: "memory")
; #define PG8_WAIT_L(n) asm volatile("s_waitcnt lgkmcnt(" #n ")" ::: "memory")
; #define PG8_BAR __builtin_amdgcn_s_barrier()
; #define PG8_SCHED __builtin_amdgcn_sched_barrier(0)
; template <class Epi>
; __device__ __forceinline__ void gemm_phase(PG8_LAS unsigned char* lds, const Gemm g, const StaticOrder& S, const Epi& E) {
;     ...
;             PG8_BAR; PG8_WAIT_L(0); PG8_MMA(1, 0, At, B0); PG8_BAR; PG8_SCHED;
;             PG8_STAGE(PG8_SB(0, 1), b2 + hstepB, voffB);
;             PG8_WAIT_V(6); PG8_BAR; PG8_MMA(1, 1, At, B1); PG8_BAR;
;             PG8_LDB(B0, 1, 0); PG8_SCHED; PG8_LDA(At, 1, 0); PG8_STAGE(PG8_SA(0, 1), a2 + hstepA, voffA);
;             PG8_WAIT_L(8); PG8_BAR; PG8_WAIT_L(0); PG8_MMA(0, 0, At, B0); PG8_BAR; PG8_SCHED;
	s_setprio 1
	v_mfma_f32_16x16x32_bf16 v[60:63], v[128:131], v[144:147], v[60:63]
	v_mfma_f32_16x16x32_bf16 v[56:59], v[136:139], v[144:147], v[56:59]
	v_mfma_f32_16x16x32_bf16 v[44:47], v[128:131], v[170:173], v[44:47]
	v_mfma_f32_16x16x32_bf16 v[40:43], v[136:139], v[170:173], v[40:43]
	v_mfma_f32_16x16x32_bf16 v[28:31], v[128:131], v[186:189], v[28:31]
	v_mfma_f32_16x16x32_bf16 v[24:27], v[136:139], v[186:189], v[24:27]
	v_mfma_f32_16x16x32_bf16 v[12:15], v[128:131], v[194:197], v[12:15]
	v_mfma_f32_16x16x32_bf16 v[8:11], v[136:139], v[194:197], v[8:11]
	v_mfma_f32_16x16x32_bf16 v[60:63], v[132:135], v[164:167], v[60:63]
	v_mfma_f32_16x16x32_bf16 v[56:59], v[140:143], v[164:167], v[56:59]
	v_mfma_f32_16x16x32_bf16 v[44:47], v[132:135], v[182:185], v[44:47]
	v_mfma_f32_16x16x32_bf16 v[40:43], v[140:143], v[182:185], v[40:43]
	v_mfma_f32_16x16x32_bf16 v[28:31], v[132:135], v[190:193], v[28:31]
	v_mfma_f32_16x16x32_bf16 v[24:27], v[140:143], v[190:193], v[24:27]
	v_mfma_f32_16x16x32_bf16 v[12:15], v[132:135], v[198:201], v[12:15]
	v_mfma_f32_16x16x32_bf16 v[8:11], v[140:143], v[198:201], v[8:11]
	v_mfma_f32_16x16x32_bf16 v[52:55], v[202:205], v[144:147], v[52:55]
	v_mfma_f32_16x16x32_bf16 v[48:51], v[210:213], v[144:147], v[48:51]
	v_mfma_f32_16x16x32_bf16 v[36:39], v[202:205], v[170:173], v[36:39]
	v_mfma_f32_16x16x32_bf16 v[32:35], v[210:213], v[170:173], v[32:35]
	v_mfma_f32_16x16x32_bf16 v[20:23], v[202:205], v[186:189], v[20:23]
	v_mfma_f32_16x16x32_bf16 v[16:19], v[210:213], v[186:189], v[16:19]
	v_mfma_f32_16x16x32_bf16 v[4:7], v[202:205], v[194:197], v[4:7]
	v_mfma_f32_16x16x32_bf16 v[0:3], v[210:213], v[194:197], v[0:3]
	v_mfma_f32_16x16x32_bf16 v[52:55], v[206:209], v[164:167], v[52:55]
	v_mfma_f32_16x16x32_bf16 v[48:51], v[214:217], v[164:167], v[48:51]
	v_mfma_f32_16x16x32_bf16 v[36:39], v[206:209], v[182:185], v[36:39]
	v_mfma_f32_16x16x32_bf16 v[32:35], v[214:217], v[182:185], v[32:35]
	v_mfma_f32_16x16x32_bf16 v[20:23], v[206:209], v[190:193], v[20:23]
	v_mfma_f32_16x16x32_bf16 v[16:19], v[214:217], v[190:193], v[16:19]
	v_mfma_f32_16x16x32_bf16 v[4:7], v[206:209], v[198:201], v[4:7]
	v_mfma_f32_16x16x32_bf16 v[0:3], v[214:217], v[198:201], v[0:3]
	s_setprio 0
	s_add_i32 s59, 0, 0x18000
	v_add_u32_e32 v140, s59, v176
	s_barrier
	ds_read_b128 v[128:131], v140
	ds_read_b128 v[132:135], v140 offset:1024
	ds_read_b128 v[136:139], v140 offset:2048
	ds_read_b128 v[140:143], v140 offset:3072
	ds_read_b128 v[144:147], v179 offset:32768
	ds_read_b128 v[164:167], v179 offset:33792
	ds_read_b128 v[170:173], v179 offset:34816
	ds_read_b128 v[182:185], v179 offset:35840
	ds_read_b128 v[186:189], v179 offset:36864
	ds_read_b128 v[190:193], v179 offset:37888
	ds_read_b128 v[194:197], v179 offset:38912
	ds_read_b128 v[198:201], v179 offset:39936
	v_add_u32_e32 v181, 0x1c000, v176
	ds_read_b128 v[202:205], v181
	ds_read_b128 v[206:209], v181 offset:1024
	ds_read_b128 v[210:213], v181 offset:2048
	ds_read_b128 v[214:217], v181 offset:3072
	s_add_u32 s30, s30, 0x40000
	s_addc_u32 s31, s31, 0
	s_mov_b32 m0, s38
	v_lshl_add_u64 v[224:225], s[30:31], 0, v[148:149]
	global_load_lds_dwordx4 v[224:225], off
	v_lshl_add_u64 v[224:225], s[30:31], 0, v[152:153]
	s_mov_b32 m0, s39
	s_nop 0
	global_load_lds_dwordx4 v[224:225], off
	s_waitcnt lgkmcnt(0)
	s_waitcnt vmcnt(8)
	s_barrier
	s_setprio 1
	v_mfma_f32_16x16x32_bf16 v[124:127], v[128:131], v[144:147], v[124:127]
	v_mfma_f32_16x16x32_bf16 v[120:123], v[136:139], v[144:147], v[120:123]
	v_mfma_f32_16x16x32_bf16 v[108:111], v[128:131], v[170:173], v[108:111]
	v_mfma_f32_16x16x32_bf16 v[104:107], v[136:139], v[170:173], v[104:107]
	v_mfma_f32_16x16x32_bf16 v[92:95], v[128:131], v[186:189], v[92:95]
	v_mfma_f32_16x16x32_bf16 v[88:91], v[136:139], v[186:189], v[88:91]
	v_mfma_f32_16x16x32_bf16 v[76:79], v[128:131], v[194:197], v[76:79]
	v_mfma_f32_16x16x32_bf16 v[72:75], v[136:139], v[194:197], v[72:75]
	v_mfma_f32_16x16x32_bf16 v[124:127], v[132:135], v[164:167], v[124:127]
	v_mfma_f32_16x16x32_bf16 v[120:123], v[140:143], v[164:167], v[120:123]
	v_mfma_f32_16x16x32_bf16 v[108:111], v[132:135], v[182:185], v[108:111]
	v_mfma_f32_16x16x32_bf16 v[104:107], v[140:143], v[182:185], v[104:107]
	v_mfma_f32_16x16x32_bf16 v[92:95], v[132:135], v[190:193], v[92:95]
	v_mfma_f32_16x16x32_bf16 v[88:91], v[140:143], v[190:193], v[88:91]
	v_mfma_f32_16x16x32_bf16 v[76:79], v[132:135], v[198:201], v[76:79]
	v_mfma_f32_16x16x32_bf16 v[72:75], v[140:143], v[198:201], v[72:75]
	v_mfma_f32_16x16x32_bf16 v[116:119], v[202:205], v[144:147], v[116:119]
	v_mfma_f32_16x16x32_bf16 v[112:115], v[210:213], v[144:147], v[112:115]
	v_mfma_f32_16x16x32_bf16 v[100:103], v[202:205], v[170:173], v[100:103]
	v_mfma_f32_16x16x32_bf16 v[96:99], v[210:213], v[170:173], v[96:99]
	v_mfma_f32_16x16x32_bf16 v[84:87], v[202:205], v[186:189], v[84:87]
	v_mfma_f32_16x16x32_bf16 v[80:83], v[210:213], v[186:189], v[80:83]
	v_mfma_f32_16x16x32_bf16 v[68:71], v[202:205], v[194:197], v[68:71]
	v_mfma_f32_16x16x32_bf16 v[64:67], v[210:213], v[194:197], v[64:67]
	v_mfma_f32_16x16x32_bf16 v[116:119], v[206:209], v[164:167], v[116:119]
	v_mfma_f32_16x16x32_bf16 v[112:115], v[214:217], v[164:167], v[112:115]
	v_mfma_f32_16x16x32_bf16 v[100:103], v[206:209], v[182:185], v[100:103]
	v_mfma_f32_16x16x32_bf16 v[96:99], v[214:217], v[182:185], v[96:99]
	v_mfma_f32_16x16x32_bf16 v[84:87], v[206:209], v[190:193], v[84:87]
	v_mfma_f32_16x16x32_bf16 v[80:83], v[214:217], v[190:193], v[80:83]
	v_mfma_f32_16x16x32_bf16 v[68:71], v[206:209], v[198:201], v[68:71]
	v_mfma_f32_16x16x32_bf16 v[64:67], v[214:217], v[198:201], v[64:67]
	s_setprio 0
	s_barrier
; #define PG8_STAGE(bufoff, gbase, voff) do { _Pragma("unroll") for (int _i = 0; _i < 2; ++_i) \
;         __builtin_amdgcn_global_load_lds((const unsigned*)((const char*)(gbase) + (voff)[_i]), (PG8_LAS unsigned*)(lds + (bufoff) + ldsw + _i * 8192), 16, 0, 0); } while (0)
; #define PG8_LDA(dst, b, h) do { _Pragma("unroll") for (int m = 0; m < 4; ++m) _Pragma("unroll") for (int k = 0; k < 2; ++k) dst[m][k] = *(const PG8_LAS bf16x8*)(lds + PG8_SA(b, h) + aoff + m * 2048 + k * 1024); } while (0)
; #define PG8_LDB(dst, b, h) do { _Pragma("unroll") for (int n = 0; n < 2; ++n) _Pragma("unroll") for (int k = 0; k < 2; ++k) dst[n][k] = *(const PG8_LAS bf16x8*)(lds + PG8_SB(b, h) + boff + n * 2048 + k * 1024); } while (0)
; #define PG8_MMA(ai, bj, At, Bt) do { __builtin_amdgcn_s_setprio(1); _Pragma("unroll") for (int m = 0; m < 4; ++m) _Pragma("unroll") for (int n = 0; n < 2; ++n) _Pragma("unroll") for (int k = 0; k < 2; ++k) \
;         acc[ai][bj][m][n] = __builtin_amdgcn_mfma_f32_16x16x32_bf16(Bt[n][k], At[m][k], acc[ai][bj][m][n], 0, 0, 0); __builtin_amdgcn_s_setprio(0); } while (0)
; template <class Epi>
; __device__ __forceinline__ void gemm_phase(PG8_LAS unsigned char* lds, const Gemm g, const StaticOrder& S, const Epi& E) {
;     ...
;             PG8_LDB(B1, 1, 1); PG8_STAGE(PG8_SB(1, 0), b3, voffB);
;             PG8_BAR; PG8_WAIT_L(0); PG8_MMA(0, 1, At, B1); PG8_BAR;
;             PG8_LDA(At, 1, 1); PG8_STAGE(PG8_SA(1, 0), a3, voffA);
;             PG8_BAR; PG8_WAIT_L(0); PG8_MMA(1, 0, At, B0); PG8_BAR; PG8_SCHED;
;             PG8_STAGE(PG8_SB(1, 1), b3 + hstepB, voffB);
;             PG8_WAIT_V(6); PG8_BAR; PG8_MMA(1, 1, At, B1); PG8_BAR;
;         }
;         E(acc, cur, wr, wc, fr, fq);
;     __device__ __forceinline__ void operator()(const f32x4 (&acc)[2][2][4][2], const pg8::Unit& u, int wr, int wc, int fr, int fq) const {
;         const int row0 = u.pm * 256 + wr * 64 + fr, col0 = u.pn * 256 + wc * 32 + 8 * fq;
; #pragma unroll
;         for (int ai = 0; ai < 2; ++ai) {
;             u32x4 la[4][2], lg[4][2];
; #pragma unroll
;             for (int m = 0; m < 4; ++m)
; #pragma unroll
;                 for (int bj = 0; bj < 2; ++bj) { const bf16_t* p = G + (size_t)(row0 + ai * 128 + m * 16) * LDG + col0 + bj * 128;
;                     la[m][bj] = *(const u32x4*)p; if (mode != 0) lg[m][bj] = *(const u32x4*)(p + 2048); else lg[m][bj] = la[m][bj]; }
	ds_read_b128 v[144:147], v179 offset:49152
	ds_read_b128 v[164:167], v179 offset:50176
	ds_read_b128 v[170:173], v179 offset:51200
	ds_read_b128 v[182:185], v179 offset:52224
	ds_read_b128 v[186:189], v179 offset:53248
	ds_read_b128 v[190:193], v179 offset:54272
	ds_read_b128 v[194:197], v179 offset:55296
	ds_read_b128 v[198:201], v179 offset:56320
	s_add_i32 s30, 0, 0x1c000
	s_add_i32 s31, s59, s36
	v_lshl_add_u64 v[174:175], v[174:175], 0, s[0:1]
	s_mov_b32 m0, s31
	s_nop 0
	global_load_lds_dwordx4 v[174:175], off
	v_lshl_add_u64 v[174:175], v[218:219], 0, s[0:1]
	s_add_i32 m0, s31, 0x2000
	s_nop 0
	global_load_lds_dwordx4 v[174:175], off
	s_mov_b32 m0, s41
	v_lshl_add_u64 v[174:175], v[220:221], 0, s[0:1]
	global_load_lds_dwordx4 v[174:175], off
	v_lshl_add_u64 v[174:175], v[222:223], 0, s[0:1]
	s_mov_b32 m0, s42
	s_nop 0
	global_load_lds_dwordx4 v[174:175], off
	s_add_u32 s22, s22, 0x40080
	s_addc_u32 s23, s23, 0
	s_add_i32 s30, s30, s36
	v_lshl_add_u64 v[224:225], s[22:23], 0, v[150:151]
	s_mov_b32 m0, s30
	s_nop 0
	global_load_lds_dwordx4 v[224:225], off
	v_lshl_add_u64 v[224:225], s[22:23], 0, v[154:155]
	s_add_i32 m0, s30, 0x2000
	s_nop 0
	global_load_lds_dwordx4 v[224:225], off
	s_waitcnt lgkmcnt(0)
	s_waitcnt vmcnt(8)
	s_barrier
	s_setprio 1
	v_mfma_f32_16x16x32_bf16 v[60:63], v[128:131], v[144:147], v[60:63]
	v_mfma_f32_16x16x32_bf16 v[56:59], v[136:139], v[144:147], v[56:59]
	v_mfma_f32_16x16x32_bf16 v[44:47], v[128:131], v[170:173], v[44:47]
	v_mfma_f32_16x16x32_bf16 v[40:43], v[136:139], v[170:173], v[40:43]
	v_mfma_f32_16x16x32_bf16 v[28:31], v[128:131], v[186:189], v[28:31]
	v_mfma_f32_16x16x32_bf16 v[24:27], v[136:139], v[186:189], v[24:27]
	v_mfma_f32_16x16x32_bf16 v[12:15], v[128:131], v[194:197], v[12:15]
	v_mfma_f32_16x16x32_bf16 v[8:11], v[136:139], v[194:197], v[8:11]
	v_mfma_f32_16x16x32_bf16 v[60:63], v[132:135], v[164:167], v[60:63]
	v_mfma_f32_16x16x32_bf16 v[56:59], v[140:143], v[164:167], v[56:59]
	v_mfma_f32_16x16x32_bf16 v[44:47], v[132:135], v[182:185], v[44:47]
	v_mfma_f32_16x16x32_bf16 v[40:43], v[140:143], v[182:185], v[40:43]
	v_mfma_f32_16x16x32_bf16 v[28:31], v[132:135], v[190:193], v[28:31]
	v_mfma_f32_16x16x32_bf16 v[24:27], v[140:143], v[190:193], v[24:27]
	v_mfma_f32_16x16x32_bf16 v[12:15], v[132:135], v[198:201], v[12:15]
	v_mfma_f32_16x16x32_bf16 v[8:11], v[140:143], v[198:201], v[8:11]
	v_mfma_f32_16x16x32_bf16 v[52:55], v[202:205], v[144:147], v[52:55]
	v_mfma_f32_16x16x32_bf16 v[48:51], v[210:213], v[144:147], v[48:51]
	v_mfma_f32_16x16x32_bf16 v[36:39], v[202:205], v[170:173], v[36:39]
	v_mfma_f32_16x16x32_bf16 v[32:35], v[210:213], v[170:173], v[32:35]
	v_mfma_f32_16x16x32_bf16 v[20:23], v[202:205], v[186:189], v[20:23]
	v_mfma_f32_16x16x32_bf16 v[16:19], v[210:213], v[186:189], v[16:19]
	v_mfma_f32_16x16x32_bf16 v[4:7], v[202:205], v[194:197], v[4:7]
	v_mfma_f32_16x16x32_bf16 v[0:3], v[210:213], v[194:197], v[0:3]
	v_mfma_f32_16x16x32_bf16 v[52:55], v[206:209], v[164:167], v[52:55]
	v_mfma_f32_16x16x32_bf16 v[48:51], v[214:217], v[164:167], v[48:51]
	v_mfma_f32_16x16x32_bf16 v[36:39], v[206:209], v[182:185], v[36:39]
	v_mfma_f32_16x16x32_bf16 v[32:35], v[214:217], v[182:185], v[32:35]
	v_mfma_f32_16x16x32_bf16 v[20:23], v[206:209], v[190:193], v[20:23]
	v_mfma_f32_16x16x32_bf16 v[16:19], v[214:217], v[190:193], v[16:19]
	v_mfma_f32_16x16x32_bf16 v[4:7], v[206:209], v[198:201], v[4:7]
	v_mfma_f32_16x16x32_bf16 v[0:3], v[214:217], v[198:201], v[0:3]
	s_setprio 0
	s_add_i32 s58, s58, 2
	s_add_u32 s28, s28, 0x100
	s_addc_u32 s29, s29, 0
	s_add_u32 s56, s56, 0x100
	s_addc_u32 s57, s57, 0
	s_cmp_gt_u32 s58, 13
	s_barrier
	s_cbranch_scc0 .LBB0_904
	v_lshl_or_b32 v130, s53, 8, v177
	v_lshl_add_u32 v128, s20, 8, v169
	v_ashrrev_i32_e32 v131, 31, v130
	v_lshlrev_b64 v[164:165], 1, v[130:131]
	v_ashrrev_i32_e32 v129, 31, v128
	v_lshl_add_u64 v[166:167], s[46:47], 0, v[164:165]
	v_lshlrev_b64 v[170:171], 13, v[128:129]
	v_lshl_add_u64 v[130:131], v[166:167], 0, v[170:171]
	global_load_dwordx4 v[182:185], v[130:131], off
	global_load_dwordx4 v[186:189], v[130:131], off offset:256
	v_or_b32_e32 v130, 16, v128
	v_or_b32_e32 v132, 32, v128
	v_or_b32_e32 v128, 48, v128
	v_ashrrev_i32_e32 v131, 31, v130
	v_ashrrev_i32_e32 v133, 31, v132
	v_ashrrev_i32_e32 v129, 31, v128
	v_lshlrev_b64 v[194:195], 13, v[130:131]
	v_lshlrev_b64 v[174:175], 13, v[132:133]
	v_lshlrev_b64 v[172:173], 13, v[128:129]
	v_lshl_add_u64 v[128:129], s[46:47], 0, v[170:171]
	v_lshl_add_u64 v[130:131], v[166:167], 0, v[194:195]
	v_lshl_add_u64 v[132:133], v[166:167], 0, v[174:175]
	v_lshl_add_u64 v[196:197], v[166:167], 0, v[172:173]
	v_lshl_add_u64 v[198:199], v[128:129], 0, v[164:165]
	global_load_dwordx4 v[190:193], v[130:131], off
	global_load_dwordx4 v[144:147], v[130:131], off offset:256
	global_load_dwordx4 v[140:143], v[132:133], off
	global_load_dwordx4 v[136:139], v[132:133], off offset:256
	s_nop 0
	global_load_dwordx4 v[132:135], v[196:197], off
	global_load_dwordx4 v[128:131], v[196:197], off offset:256
	s_and_b64 vcc, exec, s[2:3]
	s_mov_b32 s53, s12
	s_mov_b32 s20, s14
	s_mov_b64 s[22:23], s[18:19]
	s_mov_b64 s[28:29], s[16:17]
	s_waitcnt vmcnt(0)
; __device__ __forceinline__ float sigmoidf_(float x) { return __builtin_amdgcn_rcpf(1.0f + __expf(-x)); }
; __device__ __forceinline__ u32x4 pack8(const float (&f)[8]) { u32x4 w; w.x = cvt_pk_bf16(f[0], f[1]); w.y = cvt_pk_bf16(f[2], f[3]); w.z = cvt_pk_bf16(f[4], f[5]); w.w = cvt_pk_bf16(f[6], f[7]); return w; }
;     __device__ __forceinline__ void operator()(const f32x4 (&acc)[2][2][4][2], const pg8::Unit& u, int wr, int wc, int fr, int fq) const {
;     ...
;             for (int m = 0; m < 4; ++m)
; #pragma unroll
;                 for (int bj = 0; bj < 2; ++bj) {
;                     bf16_t* p = G + (size_t)(row0 + ai * 128 + m * 16) * LDG + col0 + bj * 128;
;                     float a[8], gt[8], o[8];
;                     unpack8(la[m][bj], a);
;                     if (mode == 0) {
; #pragma unroll
;                         for (int n = 0; n < 2; ++n)
; #pragma unroll
;                             for (int i = 0; i < 4; ++i) o[n * 4 + i] = sigmoidf_(a[n * 4 + i]) * acc[ai][bj][m][n][i];
;                     } else {
;                         unpack8(lg[m][bj], gt);
; #pragma unroll
;                         for (int n = 0; n < 2; ++n)
; #pragma unroll
;                             for (int i = 0; i < 4; ++i) o[n * 4 + i] = a[n * 4 + i] + sigmoidf_(gt[n * 4 + i]) * acc[ai][bj][m][n][i];
;                     }
;                     *(u32x4*)p = pack8(o);
	v_lshlrev_b32_e32 v181, 16, v182
	v_and_b32_e32 v182, 0xffff0000, v182
	v_lshlrev_b32_e32 v196, 16, v183
	v_and_b32_e32 v183, 0xffff0000, v183
	v_lshlrev_b32_e32 v197, 16, v184
	v_and_b32_e32 v184, 0xffff0000, v184
	v_lshlrev_b32_e32 v200, 16, v185
	v_and_b32_e32 v185, 0xffff0000, v185
	v_mul_f32_e32 v181, 0xbfb8aa3b, v181
	v_mul_f32_e32 v182, 0xbfb8aa3b, v182
	v_mul_f32_e32 v196, 0xbfb8aa3b, v196
	v_mul_f32_e32 v183, 0xbfb8aa3b, v183
	v_mul_f32_e32 v197, 0xbfb8aa3b, v197
	v_mul_f32_e32 v184, 0xbfb8aa3b, v184
	v_mul_f32_e32 v200, 0xbfb8aa3b, v200
	v_mul_f32_e32 v185, 0xbfb8aa3b, v185
	v_exp_f32_e32 v181, v181
	v_exp_f32_e32 v182, v182
	v_exp_f32_e32 v196, v196
	v_exp_f32_e32 v183, v183
	v_exp_f32_e32 v197, v197
	v_exp_f32_e32 v184, v184
	v_exp_f32_e32 v200, v200
	v_exp_f32_e32 v185, v185
	v_lshlrev_b32_e32 v201, 16, v186
	v_and_b32_e32 v186, 0xffff0000, v186
	v_lshlrev_b32_e32 v202, 16, v187
	v_add_f32_e32 v181, 1.0, v181
	v_add_f32_e32 v182, 1.0, v182
	v_add_f32_e32 v196, 1.0, v196
	v_add_f32_e32 v183, 1.0, v183
	v_add_f32_e32 v197, 1.0, v197
	v_add_f32_e32 v184, 1.0, v184
	v_add_f32_e32 v200, 1.0, v200
	v_add_f32_e32 v185, 1.0, v185
	v_mul_f32_e32 v186, 0xbfb8aa3b, v186
	v_mul_f32_e32 v202, 0xbfb8aa3b, v202
	v_rcp_f32_e32 v181, v181
	v_rcp_f32_e32 v182, v182
	v_rcp_f32_e32 v196, v196
	v_rcp_f32_e32 v183, v183
	v_rcp_f32_e32 v197, v197
	v_rcp_f32_e32 v184, v184
	v_rcp_f32_e32 v200, v200
	v_rcp_f32_e32 v185, v185
	v_exp_f32_e32 v186, v186
	v_exp_f32_e32 v202, v202
	v_and_b32_e32 v187, 0xffff0000, v187
	v_mul_f32_e32 v124, v124, v181
	v_mul_f32_e32 v125, v125, v182
	v_mul_f32_e32 v126, v126, v196
	v_mul_f32_e32 v127, v127, v183
	v_mul_f32_e32 v181, v120, v197
	v_mul_f32_e32 v182, v121, v184
	v_mul_f32_e32 v183, v122, v200
	v_mul_f32_e32 v123, v123, v185
	v_cvt_pk_bf16_f32 v120, v124, v125
	v_cvt_pk_bf16_f32 v121, v126, v127
	v_cvt_pk_bf16_f32 v122, v181, v182
	v_cvt_pk_bf16_f32 v123, v183, v123
	global_store_dwordx4 v[198:199], v[120:123], off
	v_lshlrev_b32_e32 v203, 16, v188
	v_and_b32_e32 v188, 0xffff0000, v188
	v_add_f32_e32 v120, 1.0, v186
	v_add_f32_e32 v121, 1.0, v202
	v_mul_f32_e32 v122, 0xbfb8aa3b, v187
	v_rcp_f32_e32 v120, v120
	v_rcp_f32_e32 v121, v121
	v_exp_f32_e32 v122, v122
	v_lshlrev_b32_e32 v204, 16, v189
	v_mul_f32_e32 v117, v117, v120
	v_mul_f32_e32 v118, v118, v121
	v_add_f32_e32 v120, 1.0, v122
	v_mul_f32_e32 v121, 0xbfb8aa3b, v203
	v_mul_f32_e32 v122, 0xbfb8aa3b, v188
	v_rcp_f32_e32 v120, v120
	v_exp_f32_e32 v121, v121
	v_exp_f32_e32 v122, v122
	v_and_b32_e32 v189, 0xffff0000, v189
	v_mul_f32_e32 v123, 0xbfb8aa3b, v189
	v_mul_f32_e32 v201, 0xbfb8aa3b, v201
	v_mul_f32_e32 v119, v119, v120
	v_add_f32_e32 v120, 1.0, v121
	v_add_f32_e32 v121, 1.0, v122
	v_mul_f32_e32 v122, 0xbfb8aa3b, v204
	v_exp_f32_e32 v123, v123
	v_exp_f32_e32 v201, v201
	v_exp_f32_e32 v122, v122
	v_rcp_f32_e32 v120, v120
	v_add_f32_e32 v123, 1.0, v123
	v_add_f32_e32 v201, 1.0, v201
	v_add_f32_e32 v122, 1.0, v122
	v_rcp_f32_e32 v123, v123
	v_rcp_f32_e32 v201, v201
	v_rcp_f32_e32 v121, v121
	v_rcp_f32_e32 v122, v122
	v_mul_f32_e32 v115, v115, v123
	v_mul_f32_e32 v116, v116, v201
	v_mul_f32_e32 v120, v112, v120
	v_mul_f32_e32 v121, v113, v121
	v_mul_f32_e32 v122, v114, v122
	v_cvt_pk_bf16_f32 v112, v116, v117
	v_cvt_pk_bf16_f32 v113, v118, v119
	v_cvt_pk_bf16_f32 v114, v120, v121
	v_cvt_pk_bf16_f32 v115, v122, v115
	global_store_dwordx4 v[198:199], v[112:115], off offset:256
	v_lshlrev_b32_e32 v116, 16, v191
	v_mul_f32_e32 v116, 0xbfb8aa3b, v116
	v_lshlrev_b32_e32 v114, 16, v190
	v_and_b32_e32 v115, 0xffff0000, v190
	v_mul_f32_e32 v114, 0xbfb8aa3b, v114
	v_mul_f32_e32 v115, 0xbfb8aa3b, v115
	v_exp_f32_e32 v114, v114
	v_exp_f32_e32 v115, v115
	v_exp_f32_e32 v116, v116
	v_and_b32_e32 v117, 0xffff0000, v191
	v_add_f32_e32 v114, 1.0, v114
	v_add_f32_e32 v115, 1.0, v115
	v_add_f32_e32 v116, 1.0, v116
	v_mul_f32_e32 v117, 0xbfb8aa3b, v117
	v_rcp_f32_e32 v114, v114
	v_rcp_f32_e32 v115, v115
	v_rcp_f32_e32 v116, v116
	v_exp_f32_e32 v117, v117
	v_lshlrev_b32_e32 v118, 16, v192
	v_and_b32_e32 v119, 0xffff0000, v192
	v_mul_f32_e32 v108, v108, v114
	v_mul_f32_e32 v109, v109, v115
	v_mul_f32_e32 v110, v110, v116
	v_add_f32_e32 v114, 1.0, v117
	v_mul_f32_e32 v115, 0xbfb8aa3b, v118
	v_mul_f32_e32 v116, 0xbfb8aa3b, v119
	v_rcp_f32_e32 v114, v114
	v_exp_f32_e32 v115, v115
	v_exp_f32_e32 v116, v116
	v_lshlrev_b32_e32 v120, 16, v193
	v_and_b32_e32 v121, 0xffff0000, v193
	v_mul_f32_e32 v111, v111, v114
	v_add_f32_e32 v114, 1.0, v115
	v_add_f32_e32 v115, 1.0, v116
	v_mul_f32_e32 v116, 0xbfb8aa3b, v120
	v_mul_f32_e32 v117, 0xbfb8aa3b, v121
	v_exp_f32_e32 v116, v116
	v_exp_f32_e32 v117, v117
	v_rcp_f32_e32 v114, v114
	v_rcp_f32_e32 v115, v115
	v_add_f32_e32 v116, 1.0, v116
	v_add_f32_e32 v117, 1.0, v117
	v_rcp_f32_e32 v116, v116
	v_rcp_f32_e32 v117, v117
	v_lshl_add_u64 v[112:113], s[46:47], 0, v[194:195]
	v_lshl_add_u64 v[112:113], v[112:113], 0, v[164:165]
	v_mul_f32_e32 v114, v104, v114
	v_mul_f32_e32 v115, v105, v115
	v_mul_f32_e32 v116, v106, v116
	v_mul_f32_e32 v107, v107, v117
	v_cvt_pk_bf16_f32 v104, v108, v109
	v_cvt_pk_bf16_f32 v105, v110, v111
	v_cvt_pk_bf16_f32 v106, v114, v115
	v_cvt_pk_bf16_f32 v107, v116, v107
	global_store_dwordx4 v[112:113], v[104:107], off
	v_lshlrev_b32_e32 v108, 16, v146
	v_and_b32_e32 v109, 0xffff0000, v146
	v_lshlrev_b32_e32 v104, 16, v144
	v_and_b32_e32 v105, 0xffff0000, v144
	v_lshlrev_b32_e32 v106, 16, v145
	v_mul_f32_e32 v104, 0xbfb8aa3b, v104
	v_mul_f32_e32 v105, 0xbfb8aa3b, v105
	v_mul_f32_e32 v106, 0xbfb8aa3b, v106
	v_exp_f32_e32 v104, v104
	v_exp_f32_e32 v105, v105
	v_exp_f32_e32 v106, v106
	v_and_b32_e32 v107, 0xffff0000, v145
; __device__ __forceinline__ float sigmoidf_(float x) { return __builtin_amdgcn_rcpf(1.0f + __expf(-x)); }
; __device__ __forceinline__ u32x4 pack8(const float (&f)[8]) { u32x4 w; w.x = cvt_pk_bf16(f[0], f[1]); w.y = cvt_pk_bf16(f[2], f[3]); w.z = cvt_pk_bf16(f[4], f[5]); w.w = cvt_pk_bf16(f[6], f[7]); return w; }
;     __device__ __forceinline__ void operator()(const f32x4 (&acc)[2][2][4][2], const pg8::Unit& u, int wr, int wc, int fr, int fq) const {
;     ...
;             for (int m = 0; m < 4; ++m)
; #pragma unroll
;                 for (int bj = 0; bj < 2; ++bj) {
;                     bf16_t* p = G + (size_t)(row0 + ai * 128 + m * 16) * LDG + col0 + bj * 128;
;                     float a[8], gt[8], o[8];
;                     unpack8(la[m][bj], a);
;                     if (mode == 0) {
; #pragma unroll
;                         for (int n = 0; n < 2; ++n)
; #pragma unroll
;                             for (int i = 0; i < 4; ++i) o[n * 4 + i] = sigmoidf_(a[n * 4 + i]) * acc[ai][bj][m][n][i];
;                     } else {
;                         unpack8(lg[m][bj], gt);
; #pragma unroll
;                         for (int n = 0; n < 2; ++n)
; #pragma unroll
;                             for (int i = 0; i < 4; ++i) o[n * 4 + i] = a[n * 4 + i] + sigmoidf_(gt[n * 4 + i]) * acc[ai][bj][m][n][i];
;                     }
;                     *(u32x4*)p = pack8(o);
	v_add_f32_e32 v104, 1.0, v104
	v_add_f32_e32 v105, 1.0, v105
	v_add_f32_e32 v106, 1.0, v106
	v_mul_f32_e32 v107, 0xbfb8aa3b, v107
	v_rcp_f32_e32 v104, v104
	v_rcp_f32_e32 v105, v105
	v_rcp_f32_e32 v106, v106
	v_exp_f32_e32 v107, v107
	v_mul_f32_e32 v100, v100, v104
	v_mul_f32_e32 v101, v101, v105
	v_mul_f32_e32 v102, v102, v106
	v_add_f32_e32 v104, 1.0, v107
	v_mul_f32_e32 v105, 0xbfb8aa3b, v108
	v_mul_f32_e32 v106, 0xbfb8aa3b, v109
	v_rcp_f32_e32 v104, v104
	v_exp_f32_e32 v105, v105
	v_exp_f32_e32 v106, v106
	v_and_b32_e32 v111, 0xffff0000, v147
	v_lshlrev_b32_e32 v110, 16, v147
	v_mul_f32_e32 v107, 0xbfb8aa3b, v111
	v_mul_f32_e32 v103, v103, v104
	v_add_f32_e32 v104, 1.0, v105
	v_add_f32_e32 v105, 1.0, v106
	v_mul_f32_e32 v106, 0xbfb8aa3b, v110
	v_exp_f32_e32 v107, v107
	v_exp_f32_e32 v106, v106
	v_rcp_f32_e32 v104, v104
	v_rcp_f32_e32 v105, v105
	v_add_f32_e32 v107, 1.0, v107
	v_add_f32_e32 v106, 1.0, v106
	v_rcp_f32_e32 v107, v107
	v_rcp_f32_e32 v106, v106
	v_mul_f32_e32 v104, v96, v104
	v_mul_f32_e32 v105, v97, v105
	v_mul_f32_e32 v99, v99, v107
	v_mul_f32_e32 v106, v98, v106
	v_cvt_pk_bf16_f32 v96, v100, v101
	v_cvt_pk_bf16_f32 v97, v102, v103
	v_cvt_pk_bf16_f32 v98, v104, v105
	v_cvt_pk_bf16_f32 v99, v106, v99
	global_store_dwordx4 v[112:113], v[96:99], off offset:256
	v_lshlrev_b32_e32 v100, 16, v141
	v_mul_f32_e32 v100, 0xbfb8aa3b, v100
	v_lshlrev_b32_e32 v98, 16, v140
	v_and_b32_e32 v99, 0xffff0000, v140
	v_mul_f32_e32 v98, 0xbfb8aa3b, v98
	v_mul_f32_e32 v99, 0xbfb8aa3b, v99
	v_exp_f32_e32 v98, v98
	v_exp_f32_e32 v99, v99
	v_exp_f32_e32 v100, v100
	v_and_b32_e32 v101, 0xffff0000, v141
	v_add_f32_e32 v98, 1.0, v98
	v_add_f32_e32 v99, 1.0, v99
	v_add_f32_e32 v100, 1.0, v100
	v_mul_f32_e32 v101, 0xbfb8aa3b, v101
	v_rcp_f32_e32 v98, v98
	v_rcp_f32_e32 v99, v99
	v_rcp_f32_e32 v100, v100
	v_exp_f32_e32 v101, v101
	v_lshlrev_b32_e32 v102, 16, v142
	v_and_b32_e32 v103, 0xffff0000, v142
	v_mul_f32_e32 v92, v92, v98
	v_mul_f32_e32 v93, v93, v99
	v_mul_f32_e32 v94, v94, v100
	v_add_f32_e32 v98, 1.0, v101
	v_mul_f32_e32 v99, 0xbfb8aa3b, v102
	v_mul_f32_e32 v100, 0xbfb8aa3b, v103
	v_rcp_f32_e32 v98, v98
	v_exp_f32_e32 v99, v99
	v_exp_f32_e32 v100, v100
	v_lshlrev_b32_e32 v104, 16, v143
	v_and_b32_e32 v105, 0xffff0000, v143
	v_mul_f32_e32 v95, v95, v98
	v_add_f32_e32 v98, 1.0, v99
	v_add_f32_e32 v99, 1.0, v100
	v_mul_f32_e32 v100, 0xbfb8aa3b, v104
	v_mul_f32_e32 v101, 0xbfb8aa3b, v105
	v_exp_f32_e32 v100, v100
	v_exp_f32_e32 v101, v101
	v_rcp_f32_e32 v98, v98
	v_rcp_f32_e32 v99, v99
	v_add_f32_e32 v100, 1.0, v100
	v_add_f32_e32 v101, 1.0, v101
	v_rcp_f32_e32 v100, v100
	v_rcp_f32_e32 v101, v101
	v_lshl_add_u64 v[96:97], s[46:47], 0, v[174:175]
	v_lshl_add_u64 v[96:97], v[96:97], 0, v[164:165]
	v_mul_f32_e32 v98, v88, v98
	v_mul_f32_e32 v99, v89, v99
	v_mul_f32_e32 v100, v90, v100
	v_mul_f32_e32 v91, v91, v101
	v_cvt_pk_bf16_f32 v88, v92, v93
	v_cvt_pk_bf16_f32 v89, v94, v95
	v_cvt_pk_bf16_f32 v90, v98, v99
	v_cvt_pk_bf16_f32 v91, v100, v91
	global_store_dwordx4 v[96:97], v[88:91], off
	v_lshlrev_b32_e32 v92, 16, v138
	v_and_b32_e32 v93, 0xffff0000, v138
	v_lshlrev_b32_e32 v88, 16, v136
	v_and_b32_e32 v89, 0xffff0000, v136
	v_lshlrev_b32_e32 v90, 16, v137
	v_mul_f32_e32 v88, 0xbfb8aa3b, v88
	v_mul_f32_e32 v89, 0xbfb8aa3b, v89
	v_mul_f32_e32 v90, 0xbfb8aa3b, v90
	v_exp_f32_e32 v88, v88
	v_exp_f32_e32 v89, v89
	v_exp_f32_e32 v90, v90
	v_and_b32_e32 v91, 0xffff0000, v137
	v_add_f32_e32 v88, 1.0, v88
	v_add_f32_e32 v89, 1.0, v89
	v_add_f32_e32 v90, 1.0, v90
	v_mul_f32_e32 v91, 0xbfb8aa3b, v91
	v_rcp_f32_e32 v88, v88
	v_rcp_f32_e32 v89, v89
	v_rcp_f32_e32 v90, v90
	v_exp_f32_e32 v91, v91
	v_mul_f32_e32 v84, v84, v88
	v_mul_f32_e32 v85, v85, v89
	v_mul_f32_e32 v86, v86, v90
	v_add_f32_e32 v88, 1.0, v91
	v_mul_f32_e32 v89, 0xbfb8aa3b, v92
	v_mul_f32_e32 v90, 0xbfb8aa3b, v93
	v_rcp_f32_e32 v88, v88
	v_exp_f32_e32 v89, v89
	v_exp_f32_e32 v90, v90
	v_and_b32_e32 v95, 0xffff0000, v139
	v_lshlrev_b32_e32 v94, 16, v139
	v_mul_f32_e32 v91, 0xbfb8aa3b, v95
	v_mul_f32_e32 v87, v87, v88
	v_add_f32_e32 v88, 1.0, v89
	v_add_f32_e32 v89, 1.0, v90
	v_mul_f32_e32 v90, 0xbfb8aa3b, v94
	v_exp_f32_e32 v91, v91
	v_exp_f32_e32 v90, v90
	v_rcp_f32_e32 v88, v88
	v_rcp_f32_e32 v89, v89
	v_add_f32_e32 v91, 1.0, v91
	v_add_f32_e32 v90, 1.0, v90
	v_rcp_f32_e32 v91, v91
	v_rcp_f32_e32 v90, v90
	v_mul_f32_e32 v88, v80, v88
	v_mul_f32_e32 v89, v81, v89
	v_mul_f32_e32 v83, v83, v91
	v_mul_f32_e32 v90, v82, v90
	v_cvt_pk_bf16_f32 v80, v84, v85
	v_cvt_pk_bf16_f32 v81, v86, v87
	v_cvt_pk_bf16_f32 v82, v88, v89
	v_cvt_pk_bf16_f32 v83, v90, v83
	global_store_dwordx4 v[96:97], v[80:83], off offset:256
	v_lshlrev_b32_e32 v84, 16, v133
	v_mul_f32_e32 v84, 0xbfb8aa3b, v84
	v_lshlrev_b32_e32 v82, 16, v132
	v_and_b32_e32 v83, 0xffff0000, v132
	v_mul_f32_e32 v82, 0xbfb8aa3b, v82
	v_mul_f32_e32 v83, 0xbfb8aa3b, v83
	v_exp_f32_e32 v82, v82
	v_exp_f32_e32 v83, v83
	v_exp_f32_e32 v84, v84
	v_and_b32_e32 v85, 0xffff0000, v133
	v_add_f32_e32 v82, 1.0, v82
	v_add_f32_e32 v83, 1.0, v83
	v_add_f32_e32 v84, 1.0, v84
	v_mul_f32_e32 v85, 0xbfb8aa3b, v85
	v_rcp_f32_e32 v82, v82
	v_rcp_f32_e32 v83, v83
	v_rcp_f32_e32 v84, v84
	v_exp_f32_e32 v85, v85
	v_lshlrev_b32_e32 v86, 16, v134
	v_and_b32_e32 v87, 0xffff0000, v134
	v_mul_f32_e32 v76, v76, v82
	v_mul_f32_e32 v77, v77, v83
	v_mul_f32_e32 v78, v78, v84
	v_add_f32_e32 v82, 1.0, v85
	v_mul_f32_e32 v83, 0xbfb8aa3b, v86
	v_mul_f32_e32 v84, 0xbfb8aa3b, v87
	v_rcp_f32_e32 v82, v82
	v_exp_f32_e32 v83, v83
	v_exp_f32_e32 v84, v84
	v_lshlrev_b32_e32 v88, 16, v135
	v_and_b32_e32 v89, 0xffff0000, v135
	v_mul_f32_e32 v79, v79, v82
	v_add_f32_e32 v82, 1.0, v83
; __device__ __forceinline__ float sigmoidf_(float x) { return __builtin_amdgcn_rcpf(1.0f + __expf(-x)); }
; __device__ __forceinline__ u32x4 pack8(const float (&f)[8]) { u32x4 w; w.x = cvt_pk_bf16(f[0], f[1]); w.y = cvt_pk_bf16(f[2], f[3]); w.z = cvt_pk_bf16(f[4], f[5]); w.w = cvt_pk_bf16(f[6], f[7]); return w; }
;     __device__ __forceinline__ void operator()(const f32x4 (&acc)[2][2][4][2], const pg8::Unit& u, int wr, int wc, int fr, int fq) const {
;         const int row0 = u.pm * 256 + wr * 64 + fr, col0 = u.pn * 256 + wc * 32 + 8 * fq;
; #pragma unroll
;         for (int ai = 0; ai < 2; ++ai) {
;             u32x4 la[4][2], lg[4][2];
; #pragma unroll
;             for (int m = 0; m < 4; ++m)
; #pragma unroll
;                 for (int bj = 0; bj < 2; ++bj) { const bf16_t* p = G + (size_t)(row0 + ai * 128 + m * 16) * LDG + col0 + bj * 128;
;                     la[m][bj] = *(const u32x4*)p; if (mode != 0) lg[m][bj] = *(const u32x4*)(p + 2048); else lg[m][bj] = la[m][bj]; }
; #pragma unroll
;             for (int m = 0; m < 4; ++m)
; #pragma unroll
;                 for (int bj = 0; bj < 2; ++bj) {
;                     bf16_t* p = G + (size_t)(row0 + ai * 128 + m * 16) * LDG + col0 + bj * 128;
;                     float a[8], gt[8], o[8];
;                     unpack8(la[m][bj], a);
;                     if (mode == 0) {
; #pragma unroll
;                         for (int n = 0; n < 2; ++n)
; #pragma unroll
;                             for (int i = 0; i < 4; ++i) o[n * 4 + i] = sigmoidf_(a[n * 4 + i]) * acc[ai][bj][m][n][i];
;                     } else {
;                         unpack8(lg[m][bj], gt);
; #pragma unroll
;                         for (int n = 0; n < 2; ++n)
; #pragma unroll
;                             for (int i = 0; i < 4; ++i) o[n * 4 + i] = a[n * 4 + i] + sigmoidf_(gt[n * 4 + i]) * acc[ai][bj][m][n][i];
;                     }
;                     *(u32x4*)p = pack8(o);
	v_add_f32_e32 v83, 1.0, v84
	v_mul_f32_e32 v84, 0xbfb8aa3b, v88
	v_mul_f32_e32 v85, 0xbfb8aa3b, v89
	v_exp_f32_e32 v84, v84
	v_exp_f32_e32 v85, v85
	v_rcp_f32_e32 v82, v82
	v_rcp_f32_e32 v83, v83
	v_add_f32_e32 v84, 1.0, v84
	v_add_f32_e32 v85, 1.0, v85
	v_rcp_f32_e32 v84, v84
	v_rcp_f32_e32 v85, v85
	v_lshl_add_u64 v[80:81], s[46:47], 0, v[172:173]
	v_lshl_add_u64 v[80:81], v[80:81], 0, v[164:165]
	v_mul_f32_e32 v82, v72, v82
	v_mul_f32_e32 v83, v73, v83
	v_mul_f32_e32 v84, v74, v84
	v_mul_f32_e32 v75, v75, v85
	v_cvt_pk_bf16_f32 v72, v76, v77
	v_cvt_pk_bf16_f32 v73, v78, v79
	v_cvt_pk_bf16_f32 v74, v82, v83
	v_cvt_pk_bf16_f32 v75, v84, v75
	global_store_dwordx4 v[80:81], v[72:75], off
	v_lshlrev_b32_e32 v76, 16, v130
	v_and_b32_e32 v77, 0xffff0000, v130
	v_lshlrev_b32_e32 v72, 16, v128
	v_and_b32_e32 v73, 0xffff0000, v128
	v_lshlrev_b32_e32 v74, 16, v129
	v_mul_f32_e32 v72, 0xbfb8aa3b, v72
	v_mul_f32_e32 v73, 0xbfb8aa3b, v73
	v_mul_f32_e32 v74, 0xbfb8aa3b, v74
	v_exp_f32_e32 v72, v72
	v_exp_f32_e32 v73, v73
	v_exp_f32_e32 v74, v74
	v_and_b32_e32 v75, 0xffff0000, v129
	v_add_f32_e32 v72, 1.0, v72
	v_add_f32_e32 v73, 1.0, v73
	v_add_f32_e32 v74, 1.0, v74
	v_mul_f32_e32 v75, 0xbfb8aa3b, v75
	v_rcp_f32_e32 v72, v72
	v_rcp_f32_e32 v73, v73
	v_rcp_f32_e32 v74, v74
	v_exp_f32_e32 v75, v75
	v_mul_f32_e32 v68, v68, v72
	v_mul_f32_e32 v69, v69, v73
	v_mul_f32_e32 v70, v70, v74
	v_add_f32_e32 v72, 1.0, v75
	v_mul_f32_e32 v73, 0xbfb8aa3b, v76
	v_mul_f32_e32 v74, 0xbfb8aa3b, v77
	v_rcp_f32_e32 v72, v72
	v_exp_f32_e32 v73, v73
	v_exp_f32_e32 v74, v74
	v_and_b32_e32 v79, 0xffff0000, v131
	v_lshlrev_b32_e32 v78, 16, v131
	v_mul_f32_e32 v75, 0xbfb8aa3b, v79
	v_mul_f32_e32 v71, v71, v72
	v_add_f32_e32 v72, 1.0, v73
	v_add_f32_e32 v73, 1.0, v74
	v_mul_f32_e32 v74, 0xbfb8aa3b, v78
	v_exp_f32_e32 v75, v75
	v_exp_f32_e32 v74, v74
	v_rcp_f32_e32 v72, v72
	v_rcp_f32_e32 v73, v73
	v_add_f32_e32 v75, 1.0, v75
	v_add_f32_e32 v74, 1.0, v74
	v_rcp_f32_e32 v75, v75
	v_rcp_f32_e32 v74, v74
	v_lshl_add_u64 v[100:101], v[170:171], 0, s[4:5]
	v_mul_f32_e32 v72, v64, v72
	v_mul_f32_e32 v67, v67, v75
	v_cvt_pk_bf16_f32 v64, v68, v69
	v_lshl_add_u64 v[68:69], v[166:167], 0, v[100:101]
	v_mul_f32_e32 v73, v65, v73
	v_mul_f32_e32 v74, v66, v74
	v_cvt_pk_bf16_f32 v65, v70, v71
	v_cvt_pk_bf16_f32 v66, v72, v73
	v_cvt_pk_bf16_f32 v67, v74, v67
	global_load_dwordx4 v[84:87], v[68:69], off
	global_load_dwordx4 v[88:91], v[68:69], off offset:256
	v_lshl_add_u64 v[102:103], v[170:171], 0, s[6:7]
	global_store_dwordx4 v[80:81], v[64:67], off offset:256
	v_lshl_add_u64 v[82:83], v[170:171], 0, s[8:9]
	v_lshl_add_u64 v[80:81], v[170:171], 0, s[10:11]
	v_lshl_add_u64 v[64:65], v[166:167], 0, v[102:103]
	global_load_dwordx4 v[92:95], v[64:65], off
	global_load_dwordx4 v[96:99], v[64:65], off offset:256
	v_lshl_add_u64 v[64:65], v[166:167], 0, v[82:83]
	global_load_dwordx4 v[76:79], v[64:65], off
	global_load_dwordx4 v[72:75], v[64:65], off offset:256
	v_lshl_add_u64 v[64:65], v[166:167], 0, v[80:81]
	v_lshl_add_u64 v[100:101], s[46:47], 0, v[100:101]
	global_load_dwordx4 v[68:71], v[64:65], off
	s_nop 0
	global_load_dwordx4 v[64:67], v[64:65], off offset:256
	v_lshl_add_u64 v[100:101], v[100:101], 0, v[164:165]
	s_waitcnt vmcnt(0)
	v_lshlrev_b32_e32 v104, 16, v84
	v_and_b32_e32 v84, 0xffff0000, v84
	v_mul_f32_e32 v84, 0xbfb8aa3b, v84
	v_exp_f32_e32 v84, v84
	v_lshlrev_b32_e32 v105, 16, v85
	v_and_b32_e32 v85, 0xffff0000, v85
	v_mul_f32_e32 v85, 0xbfb8aa3b, v85
	v_add_f32_e32 v84, 1.0, v84
	v_rcp_f32_e32 v84, v84
	v_exp_f32_e32 v85, v85
	v_lshlrev_b32_e32 v106, 16, v86
	v_and_b32_e32 v86, 0xffff0000, v86
	v_mul_f32_e32 v61, v61, v84
	v_add_f32_e32 v84, 1.0, v85
	v_mul_f32_e32 v85, 0xbfb8aa3b, v106
	v_mul_f32_e32 v86, 0xbfb8aa3b, v86
	v_rcp_f32_e32 v84, v84
	v_exp_f32_e32 v85, v85
	v_exp_f32_e32 v86, v86
	v_lshlrev_b32_e32 v107, 16, v87
	v_and_b32_e32 v87, 0xffff0000, v87
	v_mul_f32_e32 v104, 0xbfb8aa3b, v104
	v_mul_f32_e32 v105, 0xbfb8aa3b, v105
	v_mul_f32_e32 v63, v63, v84
	v_add_f32_e32 v84, 1.0, v85
	v_add_f32_e32 v85, 1.0, v86
	v_mul_f32_e32 v86, 0xbfb8aa3b, v107
	v_mul_f32_e32 v87, 0xbfb8aa3b, v87
	v_exp_f32_e32 v104, v104
	v_exp_f32_e32 v105, v105
	v_exp_f32_e32 v86, v86
	v_exp_f32_e32 v87, v87
	v_add_f32_e32 v104, 1.0, v104
	v_add_f32_e32 v105, 1.0, v105
	v_add_f32_e32 v86, 1.0, v86
	v_add_f32_e32 v87, 1.0, v87
	v_rcp_f32_e32 v104, v104
	v_rcp_f32_e32 v105, v105
	v_rcp_f32_e32 v84, v84
	v_rcp_f32_e32 v85, v85
	v_rcp_f32_e32 v86, v86
	v_rcp_f32_e32 v87, v87
	v_mul_f32_e32 v60, v60, v104
	v_mul_f32_e32 v62, v62, v105
	v_mul_f32_e32 v84, v56, v84
	v_mul_f32_e32 v85, v57, v85
	v_mul_f32_e32 v86, v58, v86
	v_mul_f32_e32 v59, v59, v87
	v_cvt_pk_bf16_f32 v56, v60, v61
	v_cvt_pk_bf16_f32 v57, v62, v63
	v_cvt_pk_bf16_f32 v58, v84, v85
	v_cvt_pk_bf16_f32 v59, v86, v59
	global_store_dwordx4 v[100:101], v[56:59], off
	v_lshlrev_b32_e32 v60, 16, v90
	v_and_b32_e32 v61, 0xffff0000, v90
	v_lshlrev_b32_e32 v56, 16, v88
	v_and_b32_e32 v57, 0xffff0000, v88
	v_lshlrev_b32_e32 v58, 16, v89
	v_mul_f32_e32 v56, 0xbfb8aa3b, v56
	v_mul_f32_e32 v57, 0xbfb8aa3b, v57
	v_mul_f32_e32 v58, 0xbfb8aa3b, v58
	v_exp_f32_e32 v56, v56
	v_exp_f32_e32 v57, v57
	v_exp_f32_e32 v58, v58
	v_and_b32_e32 v59, 0xffff0000, v89
	v_add_f32_e32 v56, 1.0, v56
	v_add_f32_e32 v57, 1.0, v57
	v_add_f32_e32 v58, 1.0, v58
	v_mul_f32_e32 v59, 0xbfb8aa3b, v59
	v_rcp_f32_e32 v56, v56
	v_rcp_f32_e32 v57, v57
	v_rcp_f32_e32 v58, v58
	v_exp_f32_e32 v59, v59
	v_mul_f32_e32 v52, v52, v56
	v_mul_f32_e32 v53, v53, v57
	v_mul_f32_e32 v54, v54, v58
	v_add_f32_e32 v56, 1.0, v59
	v_mul_f32_e32 v57, 0xbfb8aa3b, v60
	v_mul_f32_e32 v58, 0xbfb8aa3b, v61
; __device__ __forceinline__ float sigmoidf_(float x) { return __builtin_amdgcn_rcpf(1.0f + __expf(-x)); }
; __device__ __forceinline__ u32x4 pack8(const float (&f)[8]) { u32x4 w; w.x = cvt_pk_bf16(f[0], f[1]); w.y = cvt_pk_bf16(f[2], f[3]); w.z = cvt_pk_bf16(f[4], f[5]); w.w = cvt_pk_bf16(f[6], f[7]); return w; }
;     __device__ __forceinline__ void operator()(const f32x4 (&acc)[2][2][4][2], const pg8::Unit& u, int wr, int wc, int fr, int fq) const {
;     ...
;             for (int m = 0; m < 4; ++m)
; #pragma unroll
;                 for (int bj = 0; bj < 2; ++bj) {
;                     bf16_t* p = G + (size_t)(row0 + ai * 128 + m * 16) * LDG + col0 + bj * 128;
;                     float a[8], gt[8], o[8];
;                     unpack8(la[m][bj], a);
;                     if (mode == 0) {
; #pragma unroll
;                         for (int n = 0; n < 2; ++n)
; #pragma unroll
;                             for (int i = 0; i < 4; ++i) o[n * 4 + i] = sigmoidf_(a[n * 4 + i]) * acc[ai][bj][m][n][i];
;                     } else {
;                         unpack8(lg[m][bj], gt);
; #pragma unroll
;                         for (int n = 0; n < 2; ++n)
; #pragma unroll
;                             for (int i = 0; i < 4; ++i) o[n * 4 + i] = a[n * 4 + i] + sigmoidf_(gt[n * 4 + i]) * acc[ai][bj][m][n][i];
;                     }
;                     *(u32x4*)p = pack8(o);
	v_rcp_f32_e32 v56, v56
	v_exp_f32_e32 v57, v57
	v_exp_f32_e32 v58, v58
	v_and_b32_e32 v63, 0xffff0000, v91
	v_lshlrev_b32_e32 v62, 16, v91
	v_mul_f32_e32 v59, 0xbfb8aa3b, v63
	v_mul_f32_e32 v55, v55, v56
	v_add_f32_e32 v56, 1.0, v57
	v_add_f32_e32 v57, 1.0, v58
	v_mul_f32_e32 v58, 0xbfb8aa3b, v62
	v_exp_f32_e32 v59, v59
	v_exp_f32_e32 v58, v58
	v_rcp_f32_e32 v56, v56
	v_rcp_f32_e32 v57, v57
	v_add_f32_e32 v59, 1.0, v59
	v_add_f32_e32 v58, 1.0, v58
	v_rcp_f32_e32 v59, v59
	v_rcp_f32_e32 v58, v58
	v_mul_f32_e32 v56, v48, v56
	v_mul_f32_e32 v57, v49, v57
	v_mul_f32_e32 v51, v51, v59
	v_mul_f32_e32 v58, v50, v58
	v_cvt_pk_bf16_f32 v48, v52, v53
	v_cvt_pk_bf16_f32 v49, v54, v55
	v_cvt_pk_bf16_f32 v50, v56, v57
	v_cvt_pk_bf16_f32 v51, v58, v51
	global_store_dwordx4 v[100:101], v[48:51], off offset:256
	v_lshlrev_b32_e32 v52, 16, v93
	v_mul_f32_e32 v52, 0xbfb8aa3b, v52
	v_lshlrev_b32_e32 v50, 16, v92
	v_and_b32_e32 v51, 0xffff0000, v92
	v_mul_f32_e32 v50, 0xbfb8aa3b, v50
	v_mul_f32_e32 v51, 0xbfb8aa3b, v51
	v_exp_f32_e32 v50, v50
	v_exp_f32_e32 v51, v51
	v_exp_f32_e32 v52, v52
	v_and_b32_e32 v53, 0xffff0000, v93
	v_add_f32_e32 v50, 1.0, v50
	v_add_f32_e32 v51, 1.0, v51
	v_add_f32_e32 v52, 1.0, v52
	v_mul_f32_e32 v53, 0xbfb8aa3b, v53
	v_rcp_f32_e32 v50, v50
	v_rcp_f32_e32 v51, v51
	v_rcp_f32_e32 v52, v52
	v_exp_f32_e32 v53, v53
	v_lshlrev_b32_e32 v54, 16, v94
	v_and_b32_e32 v55, 0xffff0000, v94
	v_mul_f32_e32 v44, v44, v50
	v_mul_f32_e32 v45, v45, v51
	v_mul_f32_e32 v46, v46, v52
	v_add_f32_e32 v50, 1.0, v53
	v_mul_f32_e32 v51, 0xbfb8aa3b, v54
	v_mul_f32_e32 v52, 0xbfb8aa3b, v55
	v_rcp_f32_e32 v50, v50
	v_exp_f32_e32 v51, v51
	v_exp_f32_e32 v52, v52
	v_lshlrev_b32_e32 v56, 16, v95
	v_and_b32_e32 v57, 0xffff0000, v95
	v_mul_f32_e32 v47, v47, v50
	v_add_f32_e32 v50, 1.0, v51
	v_add_f32_e32 v51, 1.0, v52
	v_mul_f32_e32 v52, 0xbfb8aa3b, v56
	v_mul_f32_e32 v53, 0xbfb8aa3b, v57
	v_exp_f32_e32 v52, v52
	v_exp_f32_e32 v53, v53
	v_rcp_f32_e32 v50, v50
	v_rcp_f32_e32 v51, v51
	v_add_f32_e32 v52, 1.0, v52
	v_add_f32_e32 v53, 1.0, v53
	v_rcp_f32_e32 v52, v52
	v_rcp_f32_e32 v53, v53
	v_lshl_add_u64 v[48:49], s[46:47], 0, v[102:103]
	v_lshl_add_u64 v[48:49], v[48:49], 0, v[164:165]
	v_mul_f32_e32 v50, v40, v50
	v_mul_f32_e32 v51, v41, v51
	v_mul_f32_e32 v52, v42, v52
	v_mul_f32_e32 v43, v43, v53
	v_cvt_pk_bf16_f32 v40, v44, v45
	v_cvt_pk_bf16_f32 v41, v46, v47
	v_cvt_pk_bf16_f32 v42, v50, v51
	v_cvt_pk_bf16_f32 v43, v52, v43
	global_store_dwordx4 v[48:49], v[40:43], off
	v_lshlrev_b32_e32 v44, 16, v98
	v_and_b32_e32 v45, 0xffff0000, v98
	v_lshlrev_b32_e32 v40, 16, v96
	v_and_b32_e32 v41, 0xffff0000, v96
	v_lshlrev_b32_e32 v42, 16, v97
	v_mul_f32_e32 v40, 0xbfb8aa3b, v40
	v_mul_f32_e32 v41, 0xbfb8aa3b, v41
	v_mul_f32_e32 v42, 0xbfb8aa3b, v42
	v_exp_f32_e32 v40, v40
	v_exp_f32_e32 v41, v41
	v_exp_f32_e32 v42, v42
	v_and_b32_e32 v43, 0xffff0000, v97
	v_add_f32_e32 v40, 1.0, v40
	v_add_f32_e32 v41, 1.0, v41
	v_add_f32_e32 v42, 1.0, v42
	v_mul_f32_e32 v43, 0xbfb8aa3b, v43
	v_rcp_f32_e32 v40, v40
	v_rcp_f32_e32 v41, v41
	v_rcp_f32_e32 v42, v42
	v_exp_f32_e32 v43, v43
	v_mul_f32_e32 v36, v36, v40
	v_mul_f32_e32 v37, v37, v41
	v_mul_f32_e32 v38, v38, v42
	v_add_f32_e32 v40, 1.0, v43
	v_mul_f32_e32 v41, 0xbfb8aa3b, v44
	v_mul_f32_e32 v42, 0xbfb8aa3b, v45
	v_rcp_f32_e32 v40, v40
	v_exp_f32_e32 v41, v41
	v_exp_f32_e32 v42, v42
	v_and_b32_e32 v47, 0xffff0000, v99
	v_lshlrev_b32_e32 v46, 16, v99
	v_mul_f32_e32 v43, 0xbfb8aa3b, v47
	v_mul_f32_e32 v39, v39, v40
	v_add_f32_e32 v40, 1.0, v41
	v_add_f32_e32 v41, 1.0, v42
	v_mul_f32_e32 v42, 0xbfb8aa3b, v46
	v_exp_f32_e32 v43, v43
	v_exp_f32_e32 v42, v42
	v_rcp_f32_e32 v40, v40
	v_rcp_f32_e32 v41, v41
	v_add_f32_e32 v43, 1.0, v43
	v_add_f32_e32 v42, 1.0, v42
	v_rcp_f32_e32 v43, v43
	v_rcp_f32_e32 v42, v42
	v_mul_f32_e32 v40, v32, v40
	v_mul_f32_e32 v41, v33, v41
	v_mul_f32_e32 v35, v35, v43
	v_mul_f32_e32 v42, v34, v42
	v_cvt_pk_bf16_f32 v32, v36, v37
	v_cvt_pk_bf16_f32 v33, v38, v39
	v_cvt_pk_bf16_f32 v34, v40, v41
	v_cvt_pk_bf16_f32 v35, v42, v35
	global_store_dwordx4 v[48:49], v[32:35], off offset:256
	v_lshlrev_b32_e32 v36, 16, v77
	v_mul_f32_e32 v36, 0xbfb8aa3b, v36
	v_lshlrev_b32_e32 v34, 16, v76
	v_and_b32_e32 v35, 0xffff0000, v76
	v_mul_f32_e32 v34, 0xbfb8aa3b, v34
	v_mul_f32_e32 v35, 0xbfb8aa3b, v35
	v_exp_f32_e32 v34, v34
	v_exp_f32_e32 v35, v35
	v_exp_f32_e32 v36, v36
	v_and_b32_e32 v37, 0xffff0000, v77
	v_add_f32_e32 v34, 1.0, v34
	v_add_f32_e32 v35, 1.0, v35
	v_add_f32_e32 v36, 1.0, v36
	v_mul_f32_e32 v37, 0xbfb8aa3b, v37
	v_rcp_f32_e32 v34, v34
	v_rcp_f32_e32 v35, v35
	v_rcp_f32_e32 v36, v36
	v_exp_f32_e32 v37, v37
	v_lshlrev_b32_e32 v38, 16, v78
	v_and_b32_e32 v39, 0xffff0000, v78
	v_mul_f32_e32 v28, v28, v34
	v_mul_f32_e32 v29, v29, v35
	v_mul_f32_e32 v30, v30, v36
	v_add_f32_e32 v34, 1.0, v37
	v_mul_f32_e32 v35, 0xbfb8aa3b, v38
	v_mul_f32_e32 v36, 0xbfb8aa3b, v39
	v_rcp_f32_e32 v34, v34
	v_exp_f32_e32 v35, v35
	v_exp_f32_e32 v36, v36
	v_lshlrev_b32_e32 v40, 16, v79
	v_and_b32_e32 v41, 0xffff0000, v79
	v_mul_f32_e32 v31, v31, v34
	v_add_f32_e32 v34, 1.0, v35
	v_add_f32_e32 v35, 1.0, v36
	v_mul_f32_e32 v36, 0xbfb8aa3b, v40
	v_mul_f32_e32 v37, 0xbfb8aa3b, v41
	v_exp_f32_e32 v36, v36
	v_exp_f32_e32 v37, v37
	v_rcp_f32_e32 v34, v34
	v_rcp_f32_e32 v35, v35
	v_add_f32_e32 v36, 1.0, v36
	v_add_f32_e32 v37, 1.0, v37
; __device__ __forceinline__ float sigmoidf_(float x) { return __builtin_amdgcn_rcpf(1.0f + __expf(-x)); }
; __device__ __forceinline__ u32x4 pack8(const float (&f)[8]) { u32x4 w; w.x = cvt_pk_bf16(f[0], f[1]); w.y = cvt_pk_bf16(f[2], f[3]); w.z = cvt_pk_bf16(f[4], f[5]); w.w = cvt_pk_bf16(f[6], f[7]); return w; }
; #define PG8_WAIT_V(n) asm volatile("s_waitcnt vmcnt(" #n ")" ::: "memory")
; #define PG8_BAR __builtin_amdgcn_s_barrier()
; template <class Epi>
; __device__ __forceinline__ void gemm_phase(PG8_LAS unsigned char* lds, const Gemm g, const StaticOrder& S, const Epi& E) {
;     ...
;     PG8_WAIT_V(0);
;     if (wr == 0) PG8_BAR;
;     PG8_BAR;
;     __device__ __forceinline__ void operator()(const f32x4 (&acc)[2][2][4][2], const pg8::Unit& u, int wr, int wc, int fr, int fq) const {
;     ...
;             for (int m = 0; m < 4; ++m)
; #pragma unroll
;                 for (int bj = 0; bj < 2; ++bj) {
;                     bf16_t* p = G + (size_t)(row0 + ai * 128 + m * 16) * LDG + col0 + bj * 128;
;                     float a[8], gt[8], o[8];
;                     unpack8(la[m][bj], a);
;                     if (mode == 0) {
; #pragma unroll
;                         for (int n = 0; n < 2; ++n)
; #pragma unroll
;                             for (int i = 0; i < 4; ++i) o[n * 4 + i] = sigmoidf_(a[n * 4 + i]) * acc[ai][bj][m][n][i];
;                     } else {
;                         unpack8(lg[m][bj], gt);
; #pragma unroll
;                         for (int n = 0; n < 2; ++n)
; #pragma unroll
;                             for (int i = 0; i < 4; ++i) o[n * 4 + i] = a[n * 4 + i] + sigmoidf_(gt[n * 4 + i]) * acc[ai][bj][m][n][i];
;                     }
;                     *(u32x4*)p = pack8(o);
	v_rcp_f32_e32 v36, v36
	v_rcp_f32_e32 v37, v37
	v_lshl_add_u64 v[32:33], s[46:47], 0, v[82:83]
	v_lshl_add_u64 v[32:33], v[32:33], 0, v[164:165]
	v_mul_f32_e32 v34, v24, v34
	v_mul_f32_e32 v35, v25, v35
	v_mul_f32_e32 v36, v26, v36
	v_mul_f32_e32 v27, v27, v37
	v_cvt_pk_bf16_f32 v24, v28, v29
	v_cvt_pk_bf16_f32 v25, v30, v31
	v_cvt_pk_bf16_f32 v26, v34, v35
	v_cvt_pk_bf16_f32 v27, v36, v27
	global_store_dwordx4 v[32:33], v[24:27], off
	v_lshlrev_b32_e32 v28, 16, v74
	v_and_b32_e32 v29, 0xffff0000, v74
	v_lshlrev_b32_e32 v24, 16, v72
	v_and_b32_e32 v25, 0xffff0000, v72
	v_lshlrev_b32_e32 v26, 16, v73
	v_mul_f32_e32 v24, 0xbfb8aa3b, v24
	v_mul_f32_e32 v25, 0xbfb8aa3b, v25
	v_mul_f32_e32 v26, 0xbfb8aa3b, v26
	v_exp_f32_e32 v24, v24
	v_exp_f32_e32 v25, v25
	v_exp_f32_e32 v26, v26
	v_and_b32_e32 v27, 0xffff0000, v73
	v_add_f32_e32 v24, 1.0, v24
	v_add_f32_e32 v25, 1.0, v25
	v_add_f32_e32 v26, 1.0, v26
	v_mul_f32_e32 v27, 0xbfb8aa3b, v27
	v_rcp_f32_e32 v24, v24
	v_rcp_f32_e32 v25, v25
	v_rcp_f32_e32 v26, v26
	v_exp_f32_e32 v27, v27
	v_mul_f32_e32 v20, v20, v24
	v_mul_f32_e32 v21, v21, v25
	v_mul_f32_e32 v22, v22, v26
	v_add_f32_e32 v24, 1.0, v27
	v_mul_f32_e32 v25, 0xbfb8aa3b, v28
	v_mul_f32_e32 v26, 0xbfb8aa3b, v29
	v_rcp_f32_e32 v24, v24
	v_exp_f32_e32 v25, v25
	v_exp_f32_e32 v26, v26
	v_and_b32_e32 v31, 0xffff0000, v75
	v_lshlrev_b32_e32 v30, 16, v75
	v_mul_f32_e32 v27, 0xbfb8aa3b, v31
	v_mul_f32_e32 v23, v23, v24
	v_add_f32_e32 v24, 1.0, v25
	v_add_f32_e32 v25, 1.0, v26
	v_mul_f32_e32 v26, 0xbfb8aa3b, v30
	v_exp_f32_e32 v27, v27
	v_exp_f32_e32 v26, v26
	v_rcp_f32_e32 v24, v24
	v_rcp_f32_e32 v25, v25
	v_add_f32_e32 v27, 1.0, v27
	v_add_f32_e32 v26, 1.0, v26
	v_rcp_f32_e32 v27, v27
	v_rcp_f32_e32 v26, v26
	v_mul_f32_e32 v24, v16, v24
	v_mul_f32_e32 v25, v17, v25
	v_mul_f32_e32 v19, v19, v27
	v_mul_f32_e32 v26, v18, v26
	v_cvt_pk_bf16_f32 v16, v20, v21
	v_cvt_pk_bf16_f32 v17, v22, v23
	v_cvt_pk_bf16_f32 v18, v24, v25
	v_cvt_pk_bf16_f32 v19, v26, v19
	global_store_dwordx4 v[32:33], v[16:19], off offset:256
	v_lshlrev_b32_e32 v20, 16, v69
	v_mul_f32_e32 v20, 0xbfb8aa3b, v20
	v_lshlrev_b32_e32 v18, 16, v68
	v_and_b32_e32 v19, 0xffff0000, v68
	v_mul_f32_e32 v18, 0xbfb8aa3b, v18
	v_mul_f32_e32 v19, 0xbfb8aa3b, v19
	v_exp_f32_e32 v18, v18
	v_exp_f32_e32 v19, v19
	v_exp_f32_e32 v20, v20
	v_and_b32_e32 v21, 0xffff0000, v69
	v_add_f32_e32 v18, 1.0, v18
	v_add_f32_e32 v19, 1.0, v19
	v_add_f32_e32 v20, 1.0, v20
	v_mul_f32_e32 v21, 0xbfb8aa3b, v21
	v_rcp_f32_e32 v18, v18
	v_rcp_f32_e32 v19, v19
	v_rcp_f32_e32 v20, v20
	v_exp_f32_e32 v21, v21
	v_lshlrev_b32_e32 v22, 16, v70
	v_and_b32_e32 v23, 0xffff0000, v70
	v_mul_f32_e32 v12, v12, v18
	v_mul_f32_e32 v13, v13, v19
	v_mul_f32_e32 v14, v14, v20
	v_add_f32_e32 v18, 1.0, v21
	v_mul_f32_e32 v19, 0xbfb8aa3b, v22
	v_mul_f32_e32 v20, 0xbfb8aa3b, v23
	v_rcp_f32_e32 v18, v18
	v_exp_f32_e32 v19, v19
	v_exp_f32_e32 v20, v20
	v_lshlrev_b32_e32 v24, 16, v71
	v_and_b32_e32 v25, 0xffff0000, v71
	v_mul_f32_e32 v15, v15, v18
	v_add_f32_e32 v18, 1.0, v19
	v_add_f32_e32 v19, 1.0, v20
	v_mul_f32_e32 v20, 0xbfb8aa3b, v24
	v_mul_f32_e32 v21, 0xbfb8aa3b, v25
	v_exp_f32_e32 v20, v20
	v_exp_f32_e32 v21, v21
	v_rcp_f32_e32 v18, v18
	v_rcp_f32_e32 v19, v19
	v_add_f32_e32 v20, 1.0, v20
	v_add_f32_e32 v21, 1.0, v21
	v_rcp_f32_e32 v20, v20
	v_rcp_f32_e32 v21, v21
	v_lshl_add_u64 v[16:17], s[46:47], 0, v[80:81]
	v_lshl_add_u64 v[16:17], v[16:17], 0, v[164:165]
	v_mul_f32_e32 v18, v8, v18
	v_mul_f32_e32 v19, v9, v19
	v_mul_f32_e32 v20, v10, v20
	v_mul_f32_e32 v11, v11, v21
	v_cvt_pk_bf16_f32 v8, v12, v13
	v_cvt_pk_bf16_f32 v9, v14, v15
	v_cvt_pk_bf16_f32 v10, v18, v19
	v_cvt_pk_bf16_f32 v11, v20, v11
	global_store_dwordx4 v[16:17], v[8:11], off
	v_lshlrev_b32_e32 v12, 16, v66
	v_and_b32_e32 v13, 0xffff0000, v66
	v_lshlrev_b32_e32 v8, 16, v64
	v_and_b32_e32 v9, 0xffff0000, v64
	v_lshlrev_b32_e32 v10, 16, v65
	v_mul_f32_e32 v8, 0xbfb8aa3b, v8
	v_mul_f32_e32 v9, 0xbfb8aa3b, v9
	v_mul_f32_e32 v10, 0xbfb8aa3b, v10
	v_exp_f32_e32 v8, v8
	v_exp_f32_e32 v9, v9
	v_exp_f32_e32 v10, v10
	v_and_b32_e32 v11, 0xffff0000, v65
	v_add_f32_e32 v8, 1.0, v8
	v_add_f32_e32 v9, 1.0, v9
	v_add_f32_e32 v10, 1.0, v10
	v_mul_f32_e32 v11, 0xbfb8aa3b, v11
	v_rcp_f32_e32 v8, v8
	v_rcp_f32_e32 v9, v9
	v_rcp_f32_e32 v10, v10
	v_exp_f32_e32 v11, v11
	v_mul_f32_e32 v4, v4, v8
	v_mul_f32_e32 v5, v5, v9
	v_mul_f32_e32 v6, v6, v10
	v_add_f32_e32 v8, 1.0, v11
	v_mul_f32_e32 v9, 0xbfb8aa3b, v12
	v_mul_f32_e32 v10, 0xbfb8aa3b, v13
	v_rcp_f32_e32 v8, v8
	v_exp_f32_e32 v9, v9
	v_exp_f32_e32 v10, v10
	v_and_b32_e32 v15, 0xffff0000, v67
	v_lshlrev_b32_e32 v14, 16, v67
	v_mul_f32_e32 v11, 0xbfb8aa3b, v15
	v_mul_f32_e32 v7, v7, v8
	v_add_f32_e32 v8, 1.0, v9
	v_add_f32_e32 v9, 1.0, v10
	v_mul_f32_e32 v10, 0xbfb8aa3b, v14
	v_exp_f32_e32 v11, v11
	v_exp_f32_e32 v10, v10
	v_rcp_f32_e32 v8, v8
	v_rcp_f32_e32 v9, v9
	v_add_f32_e32 v11, 1.0, v11
	v_add_f32_e32 v10, 1.0, v10
	v_rcp_f32_e32 v11, v11
	v_rcp_f32_e32 v10, v10
	v_mul_f32_e32 v8, v0, v8
	v_mul_f32_e32 v9, v1, v9
	v_mul_f32_e32 v3, v3, v11
	v_mul_f32_e32 v10, v2, v10
	v_cvt_pk_bf16_f32 v0, v4, v5
	v_cvt_pk_bf16_f32 v1, v6, v7
	v_cvt_pk_bf16_f32 v2, v8, v9
	v_cvt_pk_bf16_f32 v3, v10, v3
	global_store_dwordx4 v[16:17], v[0:3], off offset:256
	s_cbranch_vccz .LBB0_897
	s_waitcnt vmcnt(0)
	s_cmpk_gt_u32 s34, 0xff
	s_cbranch_scc1 .LBB0_908
	s_barrier

; #define PG8_STAGE(bufoff, gbase, voff) do { _Pragma("unroll") for (int _i = 0; _i < 2; ++_i) \
;         __builtin_amdgcn_global_load_lds((const unsigned*)((const char*)(gbase) + (voff)[_i]), (PG8_LAS unsigned*)(lds + (bufoff) + ldsw + _i * 8192), 16, 0, 0); } while (0)
; #define PG8_LDA(dst, b, h) do { _Pragma("unroll") for (int m = 0; m < 4; ++m) _Pragma("unroll") for (int k = 0; k < 2; ++k) dst[m][k] = *(const PG8_LAS bf16x8*)(lds + PG8_SA(b, h) + aoff + m * 2048 + k * 1024); } while (0)
; #define PG8_LDB(dst, b, h) do { _Pragma("unroll") for (int n = 0; n < 2; ++n) _Pragma("unroll") for (int k = 0; k < 2; ++k) dst[n][k] = *(const PG8_LAS bf16x8*)(lds + PG8_SB(b, h) + boff + n * 2048 + k * 1024); } while (0)
; #define PG8_WAIT_V(n) asm volatile("s_waitcnt vmcnt(" #n ")" ::: "memory")
; #define PG8_WAIT_L(n) asm volatile("s_waitcnt lgkmcnt(" #n ")" ::: "memory")
; #define PG8_BAR __builtin_amdgcn_s_barrier()
; #define PG8_SCHED __builtin_amdgcn_sched_barrier(0)
; template <class Epi>
; __device__ __forceinline__ void gemm_phase(PG8_LAS unsigned char* lds, const Gemm g, const StaticOrder& S, const Epi& E) {
;     ...
;     for (;;) {
;         const bool has_next = S.next(ui + 1, nxt);
;         const char* nA = has_next ? (const char*)g.A + (size_t)nxt.pm * tstepA : cA; const char* nB = has_next ? (const char*)g.Bt + (size_t)nxt.pn * tstepB : cB;
;         for (int t = 0; t < nt; t += 2) {
;             const bool last = (t == nt - 2);
;             const char* a1 = cA + (size_t)(t + 1) * kstep;
;             const char* a2 = last ? nA : cA + (size_t)(t + 2) * kstep; const char* b2 = last ? nB : cB + (size_t)(t + 2) * kstep;
;             const char* a3 = a2 + kstep; const char* b3 = b2 + kstep;
;             PG8_LDB(B0, 0, 0); PG8_SCHED; PG8_LDA(At, 0, 0); PG8_STAGE(PG8_SA(1, 1), a1 + hstepA, voffA);
;             PG8_WAIT_L(8); PG8_BAR; PG8_WAIT_L(0); PG8_MMA(0, 0, At, B0); PG8_BAR; PG8_SCHED;
;             PG8_LDB(B1, 0, 1); PG8_STAGE(PG8_SB(0, 0), b2, voffB);
;             PG8_BAR; PG8_WAIT_L(0); PG8_MMA(0, 1, At, B1); PG8_BAR;
;             PG8_LDA(At, 0, 1); PG8_STAGE(PG8_SA(0, 0), a2, voffA);
;             PG8_BAR; PG8_WAIT_L(0); PG8_MMA(1, 0, At, B0); PG8_BAR; PG8_SCHED;
;             PG8_STAGE(PG8_SB(0, 1), b2 + hstepB, voffB);
;             PG8_WAIT_V(6); PG8_BAR; PG8_MMA(1, 1, At, B1); PG8_BAR;
.LBB0_925:
	ds_read_b128 v[128:131], v198
	ds_read_b128 v[132:135], v198 offset:1024
	ds_read_b128 v[136:139], v198 offset:2048
	ds_read_b128 v[140:143], v198 offset:3072
	ds_read_b128 v[144:147], v199
	ds_read_b128 v[148:151], v199 offset:1024
	ds_read_b128 v[152:155], v199 offset:2048
	ds_read_b128 v[156:159], v199 offset:3072
	ds_read_b128 v[160:163], v199 offset:4096
	ds_read_b128 v[164:167], v199 offset:5120
	ds_read_b128 v[186:189], v199 offset:6144
	ds_read_b128 v[190:193], v199 offset:7168
	ds_read_b128 v[202:205], v200
	ds_read_b128 v[206:209], v200 offset:1024
	ds_read_b128 v[210:213], v200 offset:2048
	ds_read_b128 v[214:217], v200 offset:3072
	s_add_u32 s22, s30, 0xfffc0080
	s_addc_u32 s23, s31, -1
	s_cmp_eq_u32 s61, 12
	s_cselect_b32 s35, s17, s23
	s_cselect_b32 s34, s57, s22
	s_cselect_b32 s23, s15, s60
	s_cselect_b32 s22, s58, s59
	v_lshl_add_u64 v[194:195], s[30:31], 0, v[178:179]
	s_add_i32 m0, s29, 0xc000
	s_nop 0
	global_load_lds_dwordx4 v[194:195], off
	v_lshl_add_u64 v[194:195], s[30:31], 0, v[180:181]
	s_add_i32 m0, s29, 0xe000
	s_nop 0
	global_load_lds_dwordx4 v[194:195], off
	s_waitcnt lgkmcnt(0)
	s_waitcnt vmcnt(8)
	s_barrier
	s_setprio 1
	v_mfma_f32_16x16x32_bf16 v[124:127], v[128:131], v[144:147], v[124:127]
	v_mfma_f32_16x16x32_bf16 v[120:123], v[136:139], v[144:147], v[120:123]
	v_mfma_f32_16x16x32_bf16 v[108:111], v[128:131], v[152:155], v[108:111]
	v_mfma_f32_16x16x32_bf16 v[104:107], v[136:139], v[152:155], v[104:107]
	v_mfma_f32_16x16x32_bf16 v[92:95], v[128:131], v[160:163], v[92:95]
	v_mfma_f32_16x16x32_bf16 v[88:91], v[136:139], v[160:163], v[88:91]
	v_mfma_f32_16x16x32_bf16 v[76:79], v[128:131], v[186:189], v[76:79]
	v_mfma_f32_16x16x32_bf16 v[72:75], v[136:139], v[186:189], v[72:75]
	v_mfma_f32_16x16x32_bf16 v[124:127], v[132:135], v[148:151], v[124:127]
	v_mfma_f32_16x16x32_bf16 v[120:123], v[140:143], v[148:151], v[120:123]
	v_mfma_f32_16x16x32_bf16 v[108:111], v[132:135], v[156:159], v[108:111]
	v_mfma_f32_16x16x32_bf16 v[104:107], v[140:143], v[156:159], v[104:107]
	v_mfma_f32_16x16x32_bf16 v[92:95], v[132:135], v[164:167], v[92:95]
	v_mfma_f32_16x16x32_bf16 v[88:91], v[140:143], v[164:167], v[88:91]
	v_mfma_f32_16x16x32_bf16 v[76:79], v[132:135], v[190:193], v[76:79]
	v_mfma_f32_16x16x32_bf16 v[72:75], v[140:143], v[190:193], v[72:75]
	v_mfma_f32_16x16x32_bf16 v[116:119], v[202:205], v[144:147], v[116:119]
	v_mfma_f32_16x16x32_bf16 v[112:115], v[210:213], v[144:147], v[112:115]
	v_mfma_f32_16x16x32_bf16 v[100:103], v[202:205], v[152:155], v[100:103]
	v_mfma_f32_16x16x32_bf16 v[96:99], v[210:213], v[152:155], v[96:99]
	v_mfma_f32_16x16x32_bf16 v[84:87], v[202:205], v[160:163], v[84:87]
	v_mfma_f32_16x16x32_bf16 v[80:83], v[210:213], v[160:163], v[80:83]
	v_mfma_f32_16x16x32_bf16 v[68:71], v[202:205], v[186:189], v[68:71]
	v_mfma_f32_16x16x32_bf16 v[64:67], v[210:213], v[186:189], v[64:67]
	v_mfma_f32_16x16x32_bf16 v[116:119], v[206:209], v[148:151], v[116:119]
	v_mfma_f32_16x16x32_bf16 v[112:115], v[214:217], v[148:151], v[112:115]
	v_mfma_f32_16x16x32_bf16 v[100:103], v[206:209], v[156:159], v[100:103]
	v_mfma_f32_16x16x32_bf16 v[96:99], v[214:217], v[156:159], v[96:99]
	v_mfma_f32_16x16x32_bf16 v[84:87], v[206:209], v[164:167], v[84:87]
	v_mfma_f32_16x16x32_bf16 v[80:83], v[214:217], v[164:167], v[80:83]
	v_mfma_f32_16x16x32_bf16 v[68:71], v[206:209], v[190:193], v[68:71]
	v_mfma_f32_16x16x32_bf16 v[64:67], v[214:217], v[190:193], v[64:67]
	s_setprio 0
	s_barrier
	ds_read_b128 v[144:147], v199 offset:16384
	ds_read_b128 v[148:151], v199 offset:17408
	ds_read_b128 v[152:155], v199 offset:18432
	ds_read_b128 v[156:159], v199 offset:19456
	ds_read_b128 v[160:163], v199 offset:20480
	ds_read_b128 v[164:167], v199 offset:21504
	ds_read_b128 v[186:189], v199 offset:22528
	ds_read_b128 v[190:193], v199 offset:23552
	s_add_i32 s62, s53, s38
	v_lshl_add_u64 v[194:195], s[22:23], 0, v[172:173]
	s_mov_b32 m0, s62
	s_nop 0
	global_load_lds_dwordx4 v[194:195], off
	v_lshl_add_u64 v[218:219], s[22:23], 0, v[176:177]
	s_add_i32 m0, s62, 0x2000
	s_nop 0
	global_load_lds_dwordx4 v[218:219], off
	s_mov_b32 m0, s29
	v_lshl_add_u64 v[220:221], s[34:35], 0, v[170:171]
	global_load_lds_dwordx4 v[220:221], off
	v_lshl_add_u64 v[222:223], s[34:35], 0, v[174:175]
	s_mov_b32 m0, s39
	s_nop 0
	global_load_lds_dwordx4 v[222:223], off
	s_add_u32 s62, s22, 0x40000
	s_addc_u32 s63, s23, 0
	s_add_i32 s64, s54, s38
	v_lshl_add_u64 v[224:225], s[62:63], 0, v[172:173]
	s_mov_b32 m0, s64
	s_nop 0
	global_load_lds_dwordx4 v[224:225], off
	v_lshl_add_u64 v[224:225], s[62:63], 0, v[176:177]
	s_add_i32 m0, s64, 0x2000
	s_nop 0
	global_load_lds_dwordx4 v[224:225], off
	s_waitcnt lgkmcnt(0)
	s_waitcnt vmcnt(8)
	s_barrier
; #define PG8_STAGE(bufoff, gbase, voff) do { _Pragma("unroll") for (int _i = 0; _i < 2; ++_i) \
;         __builtin_amdgcn_global_load_lds((const unsigned*)((const char*)(gbase) + (voff)[_i]), (PG8_LAS unsigned*)(lds + (bufoff) + ldsw + _i * 8192), 16, 0, 0); } while (0)
; #define PG8_LDA(dst, b, h) do { _Pragma("unroll") for (int m = 0; m < 4; ++m) _Pragma("unroll") for (int k = 0; k < 2; ++k) dst[m][k] = *(const PG8_LAS bf16x8*)(lds + PG8_SA(b, h) + aoff + m * 2048 + k * 1024); } while (0)
; #define PG8_LDB(dst, b, h) do { _Pragma("unroll") for (int n = 0; n < 2; ++n) _Pragma("unroll") for (int k = 0; k < 2; ++k) dst[n][k] = *(const PG8_LAS bf16x8*)(lds + PG8_SB(b, h) + boff + n * 2048 + k * 1024); } while (0)
; #define PG8_MMA(ai, bj, At, Bt) do { __builtin_amdgcn_s_setprio(1); _Pragma("unroll") for (int m = 0; m < 4; ++m) _Pragma("unroll") for (int n = 0; n < 2; ++n) _Pragma("unroll") for (int k = 0; k < 2; ++k) \
;         acc[ai][bj][m][n] = __builtin_amdgcn_mfma_f32_16x16x32_bf16(Bt[n][k], At[m][k], acc[ai][bj][m][n], 0, 0, 0); __builtin_amdgcn_s_setprio(0); } while (0)
; #define PG8_WAIT_V(n) asm volatile("s_waitcnt vmcnt(" #n ")" ::: "memory")
; #define PG8_WAIT_L(n) asm volatile("s_waitcnt lgkmcnt(" #n ")" ::: "memory")
; #define PG8_BAR __builtin_amdgcn_s_barrier()
; #define PG8_SCHED __builtin_amdgcn_sched_barrier(0)
; template <class Epi>
; __device__ __forceinline__ void gemm_phase(PG8_LAS unsigned char* lds, const Gemm g, const StaticOrder& S, const Epi& E) {
;     ...
;             PG8_BAR; PG8_WAIT_L(0); PG8_MMA(1, 0, At, B0); PG8_BAR; PG8_SCHED;
;             PG8_STAGE(PG8_SB(0, 1), b2 + hstepB, voffB);
;             PG8_WAIT_V(6); PG8_BAR; PG8_MMA(1, 1, At, B1); PG8_BAR;
;             PG8_LDB(B0, 1, 0); PG8_SCHED; PG8_LDA(At, 1, 0); PG8_STAGE(PG8_SA(0, 1), a2 + hstepA, voffA);
;             PG8_WAIT_L(8); PG8_BAR; PG8_WAIT_L(0); PG8_MMA(0, 0, At, B0); PG8_BAR; PG8_SCHED;
	s_setprio 1
	v_mfma_f32_16x16x32_bf16 v[60:63], v[128:131], v[144:147], v[60:63]
	v_mfma_f32_16x16x32_bf16 v[56:59], v[136:139], v[144:147], v[56:59]
	v_mfma_f32_16x16x32_bf16 v[44:47], v[128:131], v[152:155], v[44:47]
	v_mfma_f32_16x16x32_bf16 v[40:43], v[136:139], v[152:155], v[40:43]
	v_mfma_f32_16x16x32_bf16 v[28:31], v[128:131], v[160:163], v[28:31]
	v_mfma_f32_16x16x32_bf16 v[24:27], v[136:139], v[160:163], v[24:27]
	v_mfma_f32_16x16x32_bf16 v[12:15], v[128:131], v[186:189], v[12:15]
	v_mfma_f32_16x16x32_bf16 v[8:11], v[136:139], v[186:189], v[8:11]
	v_mfma_f32_16x16x32_bf16 v[60:63], v[132:135], v[148:151], v[60:63]
	v_mfma_f32_16x16x32_bf16 v[56:59], v[140:143], v[148:151], v[56:59]
	v_mfma_f32_16x16x32_bf16 v[44:47], v[132:135], v[156:159], v[44:47]
	v_mfma_f32_16x16x32_bf16 v[40:43], v[140:143], v[156:159], v[40:43]
	v_mfma_f32_16x16x32_bf16 v[28:31], v[132:135], v[164:167], v[28:31]
	v_mfma_f32_16x16x32_bf16 v[24:27], v[140:143], v[164:167], v[24:27]
	v_mfma_f32_16x16x32_bf16 v[12:15], v[132:135], v[190:193], v[12:15]
	v_mfma_f32_16x16x32_bf16 v[8:11], v[140:143], v[190:193], v[8:11]
	v_mfma_f32_16x16x32_bf16 v[52:55], v[202:205], v[144:147], v[52:55]
	v_mfma_f32_16x16x32_bf16 v[48:51], v[210:213], v[144:147], v[48:51]
	v_mfma_f32_16x16x32_bf16 v[36:39], v[202:205], v[152:155], v[36:39]
	v_mfma_f32_16x16x32_bf16 v[32:35], v[210:213], v[152:155], v[32:35]
	v_mfma_f32_16x16x32_bf16 v[20:23], v[202:205], v[160:163], v[20:23]
	v_mfma_f32_16x16x32_bf16 v[16:19], v[210:213], v[160:163], v[16:19]
	v_mfma_f32_16x16x32_bf16 v[4:7], v[202:205], v[186:189], v[4:7]
	v_mfma_f32_16x16x32_bf16 v[0:3], v[210:213], v[186:189], v[0:3]
	v_mfma_f32_16x16x32_bf16 v[52:55], v[206:209], v[148:151], v[52:55]
	v_mfma_f32_16x16x32_bf16 v[48:51], v[214:217], v[148:151], v[48:51]
	v_mfma_f32_16x16x32_bf16 v[36:39], v[206:209], v[156:159], v[36:39]
	v_mfma_f32_16x16x32_bf16 v[32:35], v[214:217], v[156:159], v[32:35]
	v_mfma_f32_16x16x32_bf16 v[20:23], v[206:209], v[164:167], v[20:23]
	v_mfma_f32_16x16x32_bf16 v[16:19], v[214:217], v[164:167], v[16:19]
	v_mfma_f32_16x16x32_bf16 v[4:7], v[206:209], v[190:193], v[4:7]
	v_mfma_f32_16x16x32_bf16 v[0:3], v[214:217], v[190:193], v[0:3]
	s_setprio 0
	s_add_i32 s62, 0, 0x18000
	v_add_u32_e32 v140, s62, v196
	s_barrier
	ds_read_b128 v[128:131], v140
	ds_read_b128 v[132:135], v140 offset:1024
	ds_read_b128 v[136:139], v140 offset:2048
	ds_read_b128 v[140:143], v140 offset:3072
	ds_read_b128 v[144:147], v199 offset:32768
	ds_read_b128 v[148:151], v199 offset:33792
	ds_read_b128 v[152:155], v199 offset:34816
	ds_read_b128 v[156:159], v199 offset:35840
	ds_read_b128 v[160:163], v199 offset:36864
	ds_read_b128 v[164:167], v199 offset:37888
	ds_read_b128 v[186:189], v199 offset:38912
	ds_read_b128 v[190:193], v199 offset:39936
	v_add_u32_e32 v201, 0x1c000, v196
	ds_read_b128 v[202:205], v201
	ds_read_b128 v[206:209], v201 offset:1024
	ds_read_b128 v[210:213], v201 offset:2048
	ds_read_b128 v[214:217], v201 offset:3072
	s_add_u32 s34, s34, 0x40000
	s_addc_u32 s35, s35, 0
	s_mov_b32 m0, s40
	v_lshl_add_u64 v[224:225], s[34:35], 0, v[170:171]
	global_load_lds_dwordx4 v[224:225], off
	v_lshl_add_u64 v[224:225], s[34:35], 0, v[174:175]
	s_mov_b32 m0, s41
	s_nop 0
	global_load_lds_dwordx4 v[224:225], off
	s_waitcnt lgkmcnt(0)
	s_waitcnt vmcnt(8)
	s_barrier
	s_setprio 1
	v_mfma_f32_16x16x32_bf16 v[124:127], v[128:131], v[144:147], v[124:127]
	v_mfma_f32_16x16x32_bf16 v[120:123], v[136:139], v[144:147], v[120:123]
	v_mfma_f32_16x16x32_bf16 v[108:111], v[128:131], v[152:155], v[108:111]
	v_mfma_f32_16x16x32_bf16 v[104:107], v[136:139], v[152:155], v[104:107]
	v_mfma_f32_16x16x32_bf16 v[92:95], v[128:131], v[160:163], v[92:95]
	v_mfma_f32_16x16x32_bf16 v[88:91], v[136:139], v[160:163], v[88:91]
	v_mfma_f32_16x16x32_bf16 v[76:79], v[128:131], v[186:189], v[76:79]
	v_mfma_f32_16x16x32_bf16 v[72:75], v[136:139], v[186:189], v[72:75]
	v_mfma_f32_16x16x32_bf16 v[124:127], v[132:135], v[148:151], v[124:127]
	v_mfma_f32_16x16x32_bf16 v[120:123], v[140:143], v[148:151], v[120:123]
	v_mfma_f32_16x16x32_bf16 v[108:111], v[132:135], v[156:159], v[108:111]
	v_mfma_f32_16x16x32_bf16 v[104:107], v[140:143], v[156:159], v[104:107]
	v_mfma_f32_16x16x32_bf16 v[92:95], v[132:135], v[164:167], v[92:95]
	v_mfma_f32_16x16x32_bf16 v[88:91], v[140:143], v[164:167], v[88:91]
	v_mfma_f32_16x16x32_bf16 v[76:79], v[132:135], v[190:193], v[76:79]
	v_mfma_f32_16x16x32_bf16 v[72:75], v[140:143], v[190:193], v[72:75]
	v_mfma_f32_16x16x32_bf16 v[116:119], v[202:205], v[144:147], v[116:119]
	v_mfma_f32_16x16x32_bf16 v[112:115], v[210:213], v[144:147], v[112:115]
	v_mfma_f32_16x16x32_bf16 v[100:103], v[202:205], v[152:155], v[100:103]
	v_mfma_f32_16x16x32_bf16 v[96:99], v[210:213], v[152:155], v[96:99]
	v_mfma_f32_16x16x32_bf16 v[84:87], v[202:205], v[160:163], v[84:87]
	v_mfma_f32_16x16x32_bf16 v[80:83], v[210:213], v[160:163], v[80:83]
	v_mfma_f32_16x16x32_bf16 v[68:71], v[202:205], v[186:189], v[68:71]
	v_mfma_f32_16x16x32_bf16 v[64:67], v[210:213], v[186:189], v[64:67]
	v_mfma_f32_16x16x32_bf16 v[116:119], v[206:209], v[148:151], v[116:119]
	v_mfma_f32_16x16x32_bf16 v[112:115], v[214:217], v[148:151], v[112:115]
	v_mfma_f32_16x16x32_bf16 v[100:103], v[206:209], v[156:159], v[100:103]
	v_mfma_f32_16x16x32_bf16 v[96:99], v[214:217], v[156:159], v[96:99]
	v_mfma_f32_16x16x32_bf16 v[84:87], v[206:209], v[164:167], v[84:87]
	v_mfma_f32_16x16x32_bf16 v[80:83], v[214:217], v[164:167], v[80:83]
	v_mfma_f32_16x16x32_bf16 v[68:71], v[206:209], v[190:193], v[68:71]
	v_mfma_f32_16x16x32_bf16 v[64:67], v[214:217], v[190:193], v[64:67]
	s_setprio 0
	s_barrier
; #define PG8_STAGE(bufoff, gbase, voff) do { _Pragma("unroll") for (int _i = 0; _i < 2; ++_i) \
;         __builtin_amdgcn_global_load_lds((const unsigned*)((const char*)(gbase) + (voff)[_i]), (PG8_LAS unsigned*)(lds + (bufoff) + ldsw + _i * 8192), 16, 0, 0); } while (0)
; #define PG8_LDA(dst, b, h) do { _Pragma("unroll") for (int m = 0; m < 4; ++m) _Pragma("unroll") for (int k = 0; k < 2; ++k) dst[m][k] = *(const PG8_LAS bf16x8*)(lds + PG8_SA(b, h) + aoff + m * 2048 + k * 1024); } while (0)
; #define PG8_LDB(dst, b, h) do { _Pragma("unroll") for (int n = 0; n < 2; ++n) _Pragma("unroll") for (int k = 0; k < 2; ++k) dst[n][k] = *(const PG8_LAS bf16x8*)(lds + PG8_SB(b, h) + boff + n * 2048 + k * 1024); } while (0)
; #define PG8_MMA(ai, bj, At, Bt) do { __builtin_amdgcn_s_setprio(1); _Pragma("unroll") for (int m = 0; m < 4; ++m) _Pragma("unroll") for (int n = 0; n < 2; ++n) _Pragma("unroll") for (int k = 0; k < 2; ++k) \
;         acc[ai][bj][m][n] = __builtin_amdgcn_mfma_f32_16x16x32_bf16(Bt[n][k], At[m][k], acc[ai][bj][m][n], 0, 0, 0); __builtin_amdgcn_s_setprio(0); } while (0)
; template <class Epi>
; __device__ __forceinline__ void gemm_phase(PG8_LAS unsigned char* lds, const Gemm g, const StaticOrder& S, const Epi& E) {
;     ...
;             PG8_LDB(B1, 1, 1); PG8_STAGE(PG8_SB(1, 0), b3, voffB);
;             PG8_BAR; PG8_WAIT_L(0); PG8_MMA(0, 1, At, B1); PG8_BAR;
;             PG8_LDA(At, 1, 1); PG8_STAGE(PG8_SA(1, 0), a3, voffA);
;             PG8_BAR; PG8_WAIT_L(0); PG8_MMA(1, 0, At, B0); PG8_BAR; PG8_SCHED;
;             PG8_STAGE(PG8_SB(1, 1), b3 + hstepB, voffB);
;             PG8_WAIT_V(6); PG8_BAR; PG8_MMA(1, 1, At, B1); PG8_BAR;
;         }
;         E(acc, cur, wr, wc, fr, fq);
;     __device__ __forceinline__ void operator()(const f32x4 (&acc)[2][2][4][2], const pg8::Unit& u, int wr, int wc, int fr, int fq) const {
;         const int row0 = u.pm * 256 + wr * 64 + fr, col0 = u.pn * 256 + wc * 32 + 8 * fq;
; #pragma unroll
;         for (int ai = 0; ai < 2; ++ai) {
;             u32x4 la[4][2], lg[4][2];
; #pragma unroll
;             for (int m = 0; m < 4; ++m)
; #pragma unroll
;                 for (int bj = 0; bj < 2; ++bj) { const bf16_t* p = G + (size_t)(row0 + ai * 128 + m * 16) * LDG + col0 + bj * 128;
;                     la[m][bj] = *(const u32x4*)p; if (mode != 0) lg[m][bj] = *(const u32x4*)(p + 2048); else lg[m][bj] = la[m][bj]; }
	ds_read_b128 v[144:147], v199 offset:49152
	ds_read_b128 v[148:151], v199 offset:50176
	ds_read_b128 v[152:155], v199 offset:51200
	ds_read_b128 v[156:159], v199 offset:52224
	ds_read_b128 v[160:163], v199 offset:53248
	ds_read_b128 v[164:167], v199 offset:54272
	ds_read_b128 v[186:189], v199 offset:55296
	ds_read_b128 v[190:193], v199 offset:56320
	s_add_i32 s34, 0, 0x1c000
	s_add_i32 s35, s62, s38
	v_lshl_add_u64 v[194:195], v[194:195], 0, s[4:5]
	s_mov_b32 m0, s35
	s_nop 0
	global_load_lds_dwordx4 v[194:195], off
	v_lshl_add_u64 v[194:195], v[218:219], 0, s[4:5]
	s_add_i32 m0, s35, 0x2000
	s_nop 0
	global_load_lds_dwordx4 v[194:195], off
	s_mov_b32 m0, s43
	v_lshl_add_u64 v[194:195], v[220:221], 0, s[4:5]
	global_load_lds_dwordx4 v[194:195], off
	v_lshl_add_u64 v[194:195], v[222:223], 0, s[4:5]
	s_mov_b32 m0, s50
	s_nop 0
	global_load_lds_dwordx4 v[194:195], off
	s_add_u32 s22, s22, 0x40080
	s_addc_u32 s23, s23, 0
	s_add_i32 s34, s34, s38
	v_lshl_add_u64 v[224:225], s[22:23], 0, v[172:173]
	s_mov_b32 m0, s34
	s_nop 0
	global_load_lds_dwordx4 v[224:225], off
	v_lshl_add_u64 v[224:225], s[22:23], 0, v[176:177]
	s_add_i32 m0, s34, 0x2000
	s_nop 0
	global_load_lds_dwordx4 v[224:225], off
	s_waitcnt lgkmcnt(0)
	s_waitcnt vmcnt(8)
	s_barrier
	s_setprio 1
	v_mfma_f32_16x16x32_bf16 v[60:63], v[128:131], v[144:147], v[60:63]
	v_mfma_f32_16x16x32_bf16 v[56:59], v[136:139], v[144:147], v[56:59]
	v_mfma_f32_16x16x32_bf16 v[44:47], v[128:131], v[152:155], v[44:47]
	v_mfma_f32_16x16x32_bf16 v[40:43], v[136:139], v[152:155], v[40:43]
	v_mfma_f32_16x16x32_bf16 v[28:31], v[128:131], v[160:163], v[28:31]
	v_mfma_f32_16x16x32_bf16 v[24:27], v[136:139], v[160:163], v[24:27]
	v_mfma_f32_16x16x32_bf16 v[12:15], v[128:131], v[186:189], v[12:15]
	v_mfma_f32_16x16x32_bf16 v[8:11], v[136:139], v[186:189], v[8:11]
	v_mfma_f32_16x16x32_bf16 v[60:63], v[132:135], v[148:151], v[60:63]
	v_mfma_f32_16x16x32_bf16 v[56:59], v[140:143], v[148:151], v[56:59]
	v_mfma_f32_16x16x32_bf16 v[44:47], v[132:135], v[156:159], v[44:47]
	v_mfma_f32_16x16x32_bf16 v[40:43], v[140:143], v[156:159], v[40:43]
	v_mfma_f32_16x16x32_bf16 v[28:31], v[132:135], v[164:167], v[28:31]
	v_mfma_f32_16x16x32_bf16 v[24:27], v[140:143], v[164:167], v[24:27]
	v_mfma_f32_16x16x32_bf16 v[12:15], v[132:135], v[190:193], v[12:15]
	v_mfma_f32_16x16x32_bf16 v[8:11], v[140:143], v[190:193], v[8:11]
	v_mfma_f32_16x16x32_bf16 v[52:55], v[202:205], v[144:147], v[52:55]
	v_mfma_f32_16x16x32_bf16 v[48:51], v[210:213], v[144:147], v[48:51]
	v_mfma_f32_16x16x32_bf16 v[36:39], v[202:205], v[152:155], v[36:39]
	v_mfma_f32_16x16x32_bf16 v[32:35], v[210:213], v[152:155], v[32:35]
	v_mfma_f32_16x16x32_bf16 v[20:23], v[202:205], v[160:163], v[20:23]
	v_mfma_f32_16x16x32_bf16 v[16:19], v[210:213], v[160:163], v[16:19]
	v_mfma_f32_16x16x32_bf16 v[4:7], v[202:205], v[186:189], v[4:7]
	v_mfma_f32_16x16x32_bf16 v[0:3], v[210:213], v[186:189], v[0:3]
	v_mfma_f32_16x16x32_bf16 v[52:55], v[206:209], v[148:151], v[52:55]
	v_mfma_f32_16x16x32_bf16 v[48:51], v[214:217], v[148:151], v[48:51]
	v_mfma_f32_16x16x32_bf16 v[36:39], v[206:209], v[156:159], v[36:39]
	v_mfma_f32_16x16x32_bf16 v[32:35], v[214:217], v[156:159], v[32:35]
	v_mfma_f32_16x16x32_bf16 v[20:23], v[206:209], v[164:167], v[20:23]
	v_mfma_f32_16x16x32_bf16 v[16:19], v[214:217], v[164:167], v[16:19]
	v_mfma_f32_16x16x32_bf16 v[4:7], v[206:209], v[190:193], v[4:7]
	v_mfma_f32_16x16x32_bf16 v[0:3], v[214:217], v[190:193], v[0:3]
	s_setprio 0
	s_add_i32 s61, s61, 2
	s_add_u32 s30, s30, 0x100
	s_addc_u32 s31, s31, 0
	s_add_u32 s59, s59, 0x100
	s_addc_u32 s60, s60, 0
	s_cmp_gt_u32 s61, 13
	s_barrier
	s_cbranch_scc0 .LBB0_925
	v_lshl_or_b32 v130, s56, 8, v197
	v_lshl_add_u32 v128, s28, 8, v169
	v_ashrrev_i32_e32 v131, 31, v130
	v_lshlrev_b64 v[186:187], 1, v[130:131]
	v_ashrrev_i32_e32 v129, 31, v128
	v_lshl_add_u64 v[188:189], s[46:47], 0, v[186:187]
	v_lshlrev_b64 v[190:191], 13, v[128:129]
	v_lshl_add_u64 v[130:131], v[188:189], 0, v[190:191]
	v_add_co_u32_e32 v132, vcc, 0x1000, v130
	global_load_dwordx4 v[202:205], v[130:131], off
	s_nop 0
	v_addc_co_u32_e32 v133, vcc, 0, v131, vcc
	global_load_dwordx4 v[206:209], v[132:133], off
	v_or_b32_e32 v134, 16, v128
	v_or_b32_e32 v136, 32, v128
	v_or_b32_e32 v128, 48, v128
	v_ashrrev_i32_e32 v135, 31, v134
	v_ashrrev_i32_e32 v137, 31, v136
	v_ashrrev_i32_e32 v129, 31, v128
	v_lshlrev_b64 v[226:227], 13, v[134:135]
	v_lshlrev_b64 v[194:195], 13, v[136:137]
	v_lshlrev_b64 v[192:193], 13, v[128:129]
	v_lshl_add_u64 v[128:129], s[46:47], 0, v[190:191]
	v_lshl_add_u64 v[134:135], v[188:189], 0, v[226:227]
	v_lshl_add_u64 v[140:141], v[188:189], 0, v[194:195]
	v_lshl_add_u64 v[142:143], v[188:189], 0, v[192:193]
	v_lshl_add_u64 v[228:229], v[128:129], 0, v[186:187]
	global_load_dwordx4 v[210:213], v[130:131], off offset:256
	global_load_dwordx4 v[214:217], v[134:135], off
	global_load_dwordx4 v[164:167], v[134:135], off offset:256
	global_load_dwordx4 v[152:155], v[140:141], off
	global_load_dwordx4 v[144:147], v[140:141], off offset:256
	global_load_dwordx4 v[136:139], v[142:143], off
	global_load_dwordx4 v[128:131], v[142:143], off offset:256
	global_load_dwordx4 v[218:221], v[132:133], off offset:256
	v_add_co_u32_e32 v134, vcc, 0x1000, v134
	s_mov_b32 s56, s14
	s_nop 0
	v_addc_co_u32_e32 v135, vcc, 0, v135, vcc
	global_load_dwordx4 v[222:225], v[134:135], off
	global_load_dwordx4 v[160:163], v[134:135], off offset:256
	v_add_co_u32_e32 v132, vcc, 0x1000, v140
	s_mov_b32 s28, s16
	s_nop 0
	v_addc_co_u32_e32 v133, vcc, 0, v141, vcc
	global_load_dwordx4 v[156:159], v[132:133], off
	global_load_dwordx4 v[148:151], v[132:133], off offset:256
	v_add_co_u32_e32 v134, vcc, 0x1000, v142
	s_mov_b64 s[22:23], s[20:21]
	s_nop 0
	v_addc_co_u32_e32 v135, vcc, 0, v143, vcc
	global_load_dwordx4 v[140:143], v[134:135], off
	s_nop 0
	global_load_dwordx4 v[132:135], v[134:135], off offset:256
	s_mov_b64 s[30:31], s[18:19]
	s_waitcnt vmcnt(0)
; __device__ __forceinline__ float sigmoidf_(float x) { return __builtin_amdgcn_rcpf(1.0f + __expf(-x)); }
; __device__ __forceinline__ u32x4 pack8(const float (&f)[8]) { u32x4 w; w.x = cvt_pk_bf16(f[0], f[1]); w.y = cvt_pk_bf16(f[2], f[3]); w.z = cvt_pk_bf16(f[4], f[5]); w.w = cvt_pk_bf16(f[6], f[7]); return w; }
;     __device__ __forceinline__ void operator()(const f32x4 (&acc)[2][2][4][2], const pg8::Unit& u, int wr, int wc, int fr, int fq) const {
;     ...
;             for (int m = 0; m < 4; ++m)
; #pragma unroll
;                 for (int bj = 0; bj < 2; ++bj) {
;                     bf16_t* p = G + (size_t)(row0 + ai * 128 + m * 16) * LDG + col0 + bj * 128;
;                     float a[8], gt[8], o[8];
;                     unpack8(la[m][bj], a);
;                     if (mode == 0) {
; #pragma unroll
;                         for (int n = 0; n < 2; ++n)
; #pragma unroll
;                             for (int i = 0; i < 4; ++i) o[n * 4 + i] = sigmoidf_(a[n * 4 + i]) * acc[ai][bj][m][n][i];
;                     } else {
;                         unpack8(lg[m][bj], gt);
; #pragma unroll
;                         for (int n = 0; n < 2; ++n)
; #pragma unroll
;                             for (int i = 0; i < 4; ++i) o[n * 4 + i] = a[n * 4 + i] + sigmoidf_(gt[n * 4 + i]) * acc[ai][bj][m][n][i];
;                     }
;                     *(u32x4*)p = pack8(o);
	v_lshlrev_b32_e32 v201, 16, v202
	v_and_b32_e32 v202, 0xffff0000, v202
	v_lshlrev_b32_e32 v230, 16, v203
	v_lshlrev_b32_e32 v233, 16, v206
	v_and_b32_e32 v206, 0xffff0000, v206
	v_lshlrev_b32_e32 v234, 16, v207
	v_mul_f32_e32 v206, 0xbfb8aa3b, v206
	v_mul_f32_e32 v234, 0xbfb8aa3b, v234
	v_mul_f32_e32 v233, 0xbfb8aa3b, v233
	v_exp_f32_e32 v206, v206
	v_exp_f32_e32 v234, v234
	v_exp_f32_e32 v233, v233
	v_and_b32_e32 v207, 0xffff0000, v207
	v_lshlrev_b32_e32 v235, 16, v208
	v_and_b32_e32 v208, 0xffff0000, v208
	v_mul_f32_e32 v207, 0xbfb8aa3b, v207
	v_mul_f32_e32 v235, 0xbfb8aa3b, v235
	v_mul_f32_e32 v208, 0xbfb8aa3b, v208
	v_exp_f32_e32 v207, v207
	v_add_f32_e32 v206, 1.0, v206
	v_add_f32_e32 v234, 1.0, v234
	v_exp_f32_e32 v235, v235
	v_exp_f32_e32 v208, v208
	v_add_f32_e32 v233, 1.0, v233
	v_rcp_f32_e32 v206, v206
	v_rcp_f32_e32 v234, v234
	v_rcp_f32_e32 v233, v233
	v_lshlrev_b32_e32 v236, 16, v209
	v_add_f32_e32 v207, 1.0, v207
	v_add_f32_e32 v235, 1.0, v235
	v_rcp_f32_e32 v207, v207
	v_fmac_f32_e32 v202, v125, v206
	v_fmac_f32_e32 v230, v126, v234
	v_add_f32_e32 v125, 1.0, v208
	v_mul_f32_e32 v126, 0xbfb8aa3b, v236
	v_fmac_f32_e32 v201, v124, v233
	v_rcp_f32_e32 v124, v235
	v_exp_f32_e32 v126, v126
	v_rcp_f32_e32 v125, v125
	v_and_b32_e32 v203, 0xffff0000, v203
	v_and_b32_e32 v209, 0xffff0000, v209
	v_lshlrev_b32_e32 v231, 16, v204
	v_and_b32_e32 v204, 0xffff0000, v204
	v_fmac_f32_e32 v203, v127, v207
	v_mul_f32_e32 v127, 0xbfb8aa3b, v209
	v_exp_f32_e32 v127, v127
	v_add_f32_e32 v126, 1.0, v126
	v_fmac_f32_e32 v231, v120, v124
	v_fmac_f32_e32 v204, v121, v125
	v_cvt_pk_bf16_f32 v120, v201, v202
	v_cvt_pk_bf16_f32 v121, v230, v203
	v_lshlrev_b32_e32 v201, 16, v218
	v_and_b32_e32 v202, 0xffff0000, v218
	v_lshlrev_b32_e32 v203, 16, v219
	v_rcp_f32_e32 v126, v126
	v_mul_f32_e32 v201, 0xbfb8aa3b, v201
	v_mul_f32_e32 v202, 0xbfb8aa3b, v202
	v_mul_f32_e32 v203, 0xbfb8aa3b, v203
	v_exp_f32_e32 v201, v201
	v_exp_f32_e32 v202, v202
	v_exp_f32_e32 v203, v203
	v_lshlrev_b32_e32 v232, 16, v205
	v_add_f32_e32 v127, 1.0, v127
	v_rcp_f32_e32 v127, v127
	v_fmac_f32_e32 v232, v122, v126
	v_cvt_pk_bf16_f32 v122, v231, v204
	v_and_b32_e32 v204, 0xffff0000, v219
	v_add_f32_e32 v201, 1.0, v201
	v_add_f32_e32 v202, 1.0, v202
	v_add_f32_e32 v203, 1.0, v203
	v_mul_f32_e32 v204, 0xbfb8aa3b, v204
	v_rcp_f32_e32 v201, v201
	v_rcp_f32_e32 v202, v202
	v_rcp_f32_e32 v203, v203
	v_exp_f32_e32 v204, v204
	v_and_b32_e32 v205, 0xffff0000, v205
	v_fmac_f32_e32 v205, v123, v127
	v_cvt_pk_bf16_f32 v123, v232, v205
	global_store_dwordx4 v[228:229], v[120:123], off
	v_lshlrev_b32_e32 v205, 16, v220
	v_and_b32_e32 v206, 0xffff0000, v220
	v_lshlrev_b32_e32 v120, 16, v210
	v_and_b32_e32 v121, 0xffff0000, v210
	v_lshlrev_b32_e32 v122, 16, v211
	v_fmac_f32_e32 v120, v116, v201
	v_fmac_f32_e32 v121, v117, v202
	v_fmac_f32_e32 v122, v118, v203
	v_add_f32_e32 v116, 1.0, v204
	v_mul_f32_e32 v117, 0xbfb8aa3b, v205
	v_mul_f32_e32 v118, 0xbfb8aa3b, v206
	v_rcp_f32_e32 v116, v116
	v_exp_f32_e32 v117, v117
	v_exp_f32_e32 v118, v118
	v_and_b32_e32 v123, 0xffff0000, v211
	v_lshlrev_b32_e32 v207, 16, v221
	v_fmac_f32_e32 v123, v119, v116
	v_add_f32_e32 v116, 1.0, v117
	v_add_f32_e32 v117, 1.0, v118
	v_mul_f32_e32 v118, 0xbfb8aa3b, v207
	v_exp_f32_e32 v118, v118
	v_rcp_f32_e32 v116, v116
	v_rcp_f32_e32 v117, v117
	v_lshlrev_b32_e32 v124, 16, v212
	v_add_f32_e32 v118, 1.0, v118
	v_rcp_f32_e32 v118, v118
	v_and_b32_e32 v208, 0xffff0000, v221
	v_and_b32_e32 v125, 0xffff0000, v212
	v_lshlrev_b32_e32 v126, 16, v213
	v_mul_f32_e32 v119, 0xbfb8aa3b, v208
	v_fmac_f32_e32 v124, v112, v116
	v_exp_f32_e32 v119, v119
	v_fmac_f32_e32 v125, v113, v117
	v_fmac_f32_e32 v126, v114, v118
	v_cvt_pk_bf16_f32 v112, v120, v121
	v_cvt_pk_bf16_f32 v113, v122, v123
	v_cvt_pk_bf16_f32 v114, v124, v125
	v_lshlrev_b32_e32 v122, 16, v222
	v_and_b32_e32 v123, 0xffff0000, v222
	v_lshlrev_b32_e32 v124, 16, v223
	v_mul_f32_e32 v122, 0xbfb8aa3b, v122
	v_mul_f32_e32 v123, 0xbfb8aa3b, v123
	v_mul_f32_e32 v124, 0xbfb8aa3b, v124
	v_exp_f32_e32 v122, v122
	v_exp_f32_e32 v123, v123
	v_exp_f32_e32 v124, v124
	v_add_f32_e32 v119, 1.0, v119
	v_rcp_f32_e32 v119, v119
	v_and_b32_e32 v125, 0xffff0000, v223
	v_add_f32_e32 v122, 1.0, v122
	v_add_f32_e32 v123, 1.0, v123
	v_add_f32_e32 v124, 1.0, v124
	v_mul_f32_e32 v125, 0xbfb8aa3b, v125
	v_rcp_f32_e32 v122, v122
	v_rcp_f32_e32 v123, v123
	v_rcp_f32_e32 v124, v124
	v_exp_f32_e32 v125, v125
	v_and_b32_e32 v127, 0xffff0000, v213
	v_fmac_f32_e32 v127, v115, v119
	v_cvt_pk_bf16_f32 v115, v126, v127
	global_store_dwordx4 v[228:229], v[112:115], off offset:256
	v_lshlrev_b32_e32 v116, 16, v215
	v_lshlrev_b32_e32 v126, 16, v224
	v_lshlrev_b32_e32 v114, 16, v214
	v_and_b32_e32 v115, 0xffff0000, v214
	v_and_b32_e32 v127, 0xffff0000, v224
	v_fmac_f32_e32 v114, v108, v122
	v_fmac_f32_e32 v115, v109, v123
	v_fmac_f32_e32 v116, v110, v124
	v_add_f32_e32 v108, 1.0, v125
	v_mul_f32_e32 v109, 0xbfb8aa3b, v126
	v_mul_f32_e32 v110, 0xbfb8aa3b, v127
	v_rcp_f32_e32 v108, v108
	v_exp_f32_e32 v109, v109
	v_exp_f32_e32 v110, v110
	v_and_b32_e32 v117, 0xffff0000, v215
	v_fmac_f32_e32 v117, v111, v108
	v_add_f32_e32 v108, 1.0, v109
	v_add_f32_e32 v109, 1.0, v110
	v_rcp_f32_e32 v108, v108
	v_rcp_f32_e32 v109, v109
	v_lshlrev_b32_e32 v201, 16, v225
	v_lshlrev_b32_e32 v118, 16, v216
	v_and_b32_e32 v119, 0xffff0000, v216
	v_and_b32_e32 v202, 0xffff0000, v225
	v_mul_f32_e32 v110, 0xbfb8aa3b, v201
	v_exp_f32_e32 v110, v110
	v_mul_f32_e32 v111, 0xbfb8aa3b, v202
	v_fmac_f32_e32 v118, v104, v108
	v_fmac_f32_e32 v119, v105, v109
	v_cvt_pk_bf16_f32 v104, v114, v115
	v_cvt_pk_bf16_f32 v105, v116, v117
	v_lshlrev_b32_e32 v114, 16, v160
; __device__ __forceinline__ float sigmoidf_(float x) { return __builtin_amdgcn_rcpf(1.0f + __expf(-x)); }
; __device__ __forceinline__ u32x4 pack8(const float (&f)[8]) { u32x4 w; w.x = cvt_pk_bf16(f[0], f[1]); w.y = cvt_pk_bf16(f[2], f[3]); w.z = cvt_pk_bf16(f[4], f[5]); w.w = cvt_pk_bf16(f[6], f[7]); return w; }
;     __device__ __forceinline__ void operator()(const f32x4 (&acc)[2][2][4][2], const pg8::Unit& u, int wr, int wc, int fr, int fq) const {
;     ...
;                 for (int bj = 0; bj < 2; ++bj) { const bf16_t* p = G + (size_t)(row0 + ai * 128 + m * 16) * LDG + col0 + bj * 128;
;                     la[m][bj] = *(const u32x4*)p; if (mode != 0) lg[m][bj] = *(const u32x4*)(p + 2048); else lg[m][bj] = la[m][bj]; }
; #pragma unroll
;             for (int m = 0; m < 4; ++m)
; #pragma unroll
;                 for (int bj = 0; bj < 2; ++bj) {
;                     bf16_t* p = G + (size_t)(row0 + ai * 128 + m * 16) * LDG + col0 + bj * 128;
;                     float a[8], gt[8], o[8];
;                     unpack8(la[m][bj], a);
;                     if (mode == 0) {
; #pragma unroll
;                         for (int n = 0; n < 2; ++n)
; #pragma unroll
;                             for (int i = 0; i < 4; ++i) o[n * 4 + i] = sigmoidf_(a[n * 4 + i]) * acc[ai][bj][m][n][i];
;                     } else {
;                         unpack8(lg[m][bj], gt);
; #pragma unroll
;                         for (int n = 0; n < 2; ++n)
; #pragma unroll
;                             for (int i = 0; i < 4; ++i) o[n * 4 + i] = a[n * 4 + i] + sigmoidf_(gt[n * 4 + i]) * acc[ai][bj][m][n][i];
;                     }
;                     *(u32x4*)p = pack8(o);
	v_and_b32_e32 v115, 0xffff0000, v160
	v_lshlrev_b32_e32 v116, 16, v161
	v_exp_f32_e32 v111, v111
	v_mul_f32_e32 v114, 0xbfb8aa3b, v114
	v_mul_f32_e32 v115, 0xbfb8aa3b, v115
	v_mul_f32_e32 v116, 0xbfb8aa3b, v116
	v_exp_f32_e32 v114, v114
	v_exp_f32_e32 v115, v115
	v_exp_f32_e32 v116, v116
	v_add_f32_e32 v110, 1.0, v110
	v_rcp_f32_e32 v110, v110
	v_add_f32_e32 v111, 1.0, v111
	v_and_b32_e32 v117, 0xffff0000, v161
	v_rcp_f32_e32 v111, v111
	v_add_f32_e32 v114, 1.0, v114
	v_add_f32_e32 v115, 1.0, v115
	v_add_f32_e32 v116, 1.0, v116
	v_mul_f32_e32 v117, 0xbfb8aa3b, v117
	v_rcp_f32_e32 v114, v114
	v_rcp_f32_e32 v115, v115
	v_rcp_f32_e32 v116, v116
	v_exp_f32_e32 v117, v117
	v_lshl_add_u64 v[112:113], s[46:47], 0, v[226:227]
	v_lshlrev_b32_e32 v120, 16, v217
	v_lshl_add_u64 v[112:113], v[112:113], 0, v[186:187]
	v_and_b32_e32 v121, 0xffff0000, v217
	v_fmac_f32_e32 v120, v106, v110
	v_cvt_pk_bf16_f32 v106, v118, v119
	v_fmac_f32_e32 v121, v107, v111
	v_cvt_pk_bf16_f32 v107, v120, v121
	global_store_dwordx4 v[112:113], v[104:107], off
	v_lshlrev_b32_e32 v118, 16, v162
	v_and_b32_e32 v119, 0xffff0000, v162
	v_lshlrev_b32_e32 v104, 16, v164
	v_and_b32_e32 v105, 0xffff0000, v164
	v_lshlrev_b32_e32 v106, 16, v165
	v_fmac_f32_e32 v104, v100, v114
	v_fmac_f32_e32 v105, v101, v115
	v_fmac_f32_e32 v106, v102, v116
	v_add_f32_e32 v100, 1.0, v117
	v_mul_f32_e32 v101, 0xbfb8aa3b, v118
	v_mul_f32_e32 v102, 0xbfb8aa3b, v119
	v_rcp_f32_e32 v100, v100
	v_exp_f32_e32 v101, v101
	v_exp_f32_e32 v102, v102
	v_and_b32_e32 v107, 0xffff0000, v165
	v_lshlrev_b32_e32 v120, 16, v163
	v_fmac_f32_e32 v107, v103, v100
	v_add_f32_e32 v100, 1.0, v101
	v_add_f32_e32 v101, 1.0, v102
	v_mul_f32_e32 v102, 0xbfb8aa3b, v120
	v_exp_f32_e32 v102, v102
	v_rcp_f32_e32 v100, v100
	v_rcp_f32_e32 v101, v101
	v_lshlrev_b32_e32 v108, 16, v166
	v_add_f32_e32 v102, 1.0, v102
	v_rcp_f32_e32 v102, v102
	v_and_b32_e32 v121, 0xffff0000, v163
	v_and_b32_e32 v109, 0xffff0000, v166
	v_lshlrev_b32_e32 v110, 16, v167
	v_mul_f32_e32 v103, 0xbfb8aa3b, v121
	v_fmac_f32_e32 v108, v96, v100
	v_exp_f32_e32 v103, v103
	v_fmac_f32_e32 v109, v97, v101
	v_fmac_f32_e32 v110, v98, v102
	v_cvt_pk_bf16_f32 v96, v104, v105
	v_cvt_pk_bf16_f32 v97, v106, v107
	v_cvt_pk_bf16_f32 v98, v108, v109
	v_lshlrev_b32_e32 v106, 16, v156
	v_and_b32_e32 v107, 0xffff0000, v156
	v_lshlrev_b32_e32 v108, 16, v157
	v_mul_f32_e32 v106, 0xbfb8aa3b, v106
	v_mul_f32_e32 v107, 0xbfb8aa3b, v107
	v_mul_f32_e32 v108, 0xbfb8aa3b, v108
	v_exp_f32_e32 v106, v106
	v_exp_f32_e32 v107, v107
	v_exp_f32_e32 v108, v108
	v_add_f32_e32 v103, 1.0, v103
	v_rcp_f32_e32 v103, v103
	v_and_b32_e32 v109, 0xffff0000, v157
	v_add_f32_e32 v106, 1.0, v106
	v_add_f32_e32 v107, 1.0, v107
	v_add_f32_e32 v108, 1.0, v108
	v_mul_f32_e32 v109, 0xbfb8aa3b, v109
	v_rcp_f32_e32 v106, v106
	v_rcp_f32_e32 v107, v107
	v_rcp_f32_e32 v108, v108
	v_exp_f32_e32 v109, v109
	v_and_b32_e32 v111, 0xffff0000, v167
	v_fmac_f32_e32 v111, v99, v103
	v_cvt_pk_bf16_f32 v99, v110, v111
	global_store_dwordx4 v[112:113], v[96:99], off offset:256
	v_lshlrev_b32_e32 v100, 16, v153
	v_lshlrev_b32_e32 v110, 16, v158
	v_lshlrev_b32_e32 v98, 16, v152
	v_and_b32_e32 v99, 0xffff0000, v152
	v_and_b32_e32 v111, 0xffff0000, v158
	v_fmac_f32_e32 v98, v92, v106
	v_fmac_f32_e32 v99, v93, v107
	v_fmac_f32_e32 v100, v94, v108
	v_add_f32_e32 v92, 1.0, v109
	v_mul_f32_e32 v93, 0xbfb8aa3b, v110
	v_mul_f32_e32 v94, 0xbfb8aa3b, v111
	v_rcp_f32_e32 v92, v92
	v_exp_f32_e32 v93, v93
	v_exp_f32_e32 v94, v94
	v_and_b32_e32 v101, 0xffff0000, v153
	v_fmac_f32_e32 v101, v95, v92
	v_add_f32_e32 v92, 1.0, v93
	v_add_f32_e32 v93, 1.0, v94
	v_rcp_f32_e32 v92, v92
	v_rcp_f32_e32 v93, v93
	v_lshlrev_b32_e32 v112, 16, v159
	v_lshlrev_b32_e32 v102, 16, v154
	v_and_b32_e32 v103, 0xffff0000, v154
	v_and_b32_e32 v113, 0xffff0000, v159
	v_mul_f32_e32 v94, 0xbfb8aa3b, v112
	v_exp_f32_e32 v94, v94
	v_mul_f32_e32 v95, 0xbfb8aa3b, v113
	v_fmac_f32_e32 v102, v88, v92
	v_fmac_f32_e32 v103, v89, v93
	v_cvt_pk_bf16_f32 v88, v98, v99
	v_cvt_pk_bf16_f32 v89, v100, v101
	v_lshlrev_b32_e32 v98, 16, v148
	v_and_b32_e32 v99, 0xffff0000, v148
	v_lshlrev_b32_e32 v100, 16, v149
	v_exp_f32_e32 v95, v95
	v_mul_f32_e32 v98, 0xbfb8aa3b, v98
	v_mul_f32_e32 v99, 0xbfb8aa3b, v99
	v_mul_f32_e32 v100, 0xbfb8aa3b, v100
	v_exp_f32_e32 v98, v98
	v_exp_f32_e32 v99, v99
	v_exp_f32_e32 v100, v100
	v_add_f32_e32 v94, 1.0, v94
	v_rcp_f32_e32 v94, v94
	v_add_f32_e32 v95, 1.0, v95
	v_and_b32_e32 v101, 0xffff0000, v149
	v_rcp_f32_e32 v95, v95
	v_add_f32_e32 v98, 1.0, v98
	v_add_f32_e32 v99, 1.0, v99
	v_add_f32_e32 v100, 1.0, v100
	v_mul_f32_e32 v101, 0xbfb8aa3b, v101
	v_rcp_f32_e32 v98, v98
	v_rcp_f32_e32 v99, v99
	v_rcp_f32_e32 v100, v100
	v_exp_f32_e32 v101, v101
	v_lshl_add_u64 v[96:97], s[46:47], 0, v[194:195]
	v_lshlrev_b32_e32 v104, 16, v155
	v_lshl_add_u64 v[96:97], v[96:97], 0, v[186:187]
	v_and_b32_e32 v105, 0xffff0000, v155
	v_fmac_f32_e32 v104, v90, v94
	v_cvt_pk_bf16_f32 v90, v102, v103
	v_fmac_f32_e32 v105, v91, v95
	v_cvt_pk_bf16_f32 v91, v104, v105
	global_store_dwordx4 v[96:97], v[88:91], off
	v_lshlrev_b32_e32 v102, 16, v150
	v_and_b32_e32 v103, 0xffff0000, v150
	v_lshlrev_b32_e32 v88, 16, v144
	v_and_b32_e32 v89, 0xffff0000, v144
	v_lshlrev_b32_e32 v90, 16, v145
	v_fmac_f32_e32 v88, v84, v98
	v_fmac_f32_e32 v89, v85, v99
	v_fmac_f32_e32 v90, v86, v100
	v_add_f32_e32 v84, 1.0, v101
	v_mul_f32_e32 v85, 0xbfb8aa3b, v102
	v_mul_f32_e32 v86, 0xbfb8aa3b, v103
	v_rcp_f32_e32 v84, v84
	v_exp_f32_e32 v85, v85
	v_exp_f32_e32 v86, v86
	v_and_b32_e32 v91, 0xffff0000, v145
	v_lshlrev_b32_e32 v104, 16, v151
	v_fmac_f32_e32 v91, v87, v84
	v_add_f32_e32 v84, 1.0, v85
; __device__ __forceinline__ float sigmoidf_(float x) { return __builtin_amdgcn_rcpf(1.0f + __expf(-x)); }
; __device__ __forceinline__ u32x4 pack8(const float (&f)[8]) { u32x4 w; w.x = cvt_pk_bf16(f[0], f[1]); w.y = cvt_pk_bf16(f[2], f[3]); w.z = cvt_pk_bf16(f[4], f[5]); w.w = cvt_pk_bf16(f[6], f[7]); return w; }
;     __device__ __forceinline__ void operator()(const f32x4 (&acc)[2][2][4][2], const pg8::Unit& u, int wr, int wc, int fr, int fq) const {
;     ...
;                 for (int bj = 0; bj < 2; ++bj) { const bf16_t* p = G + (size_t)(row0 + ai * 128 + m * 16) * LDG + col0 + bj * 128;
;                     la[m][bj] = *(const u32x4*)p; if (mode != 0) lg[m][bj] = *(const u32x4*)(p + 2048); else lg[m][bj] = la[m][bj]; }
; #pragma unroll
;             for (int m = 0; m < 4; ++m)
; #pragma unroll
;                 for (int bj = 0; bj < 2; ++bj) {
;                     bf16_t* p = G + (size_t)(row0 + ai * 128 + m * 16) * LDG + col0 + bj * 128;
;                     float a[8], gt[8], o[8];
;                     unpack8(la[m][bj], a);
;                     if (mode == 0) {
; #pragma unroll
;                         for (int n = 0; n < 2; ++n)
; #pragma unroll
;                             for (int i = 0; i < 4; ++i) o[n * 4 + i] = sigmoidf_(a[n * 4 + i]) * acc[ai][bj][m][n][i];
;                     } else {
;                         unpack8(lg[m][bj], gt);
; #pragma unroll
;                         for (int n = 0; n < 2; ++n)
; #pragma unroll
;                             for (int i = 0; i < 4; ++i) o[n * 4 + i] = a[n * 4 + i] + sigmoidf_(gt[n * 4 + i]) * acc[ai][bj][m][n][i];
;                     }
;                     *(u32x4*)p = pack8(o);
	v_add_f32_e32 v85, 1.0, v86
	v_mul_f32_e32 v86, 0xbfb8aa3b, v104
	v_exp_f32_e32 v86, v86
	v_rcp_f32_e32 v84, v84
	v_rcp_f32_e32 v85, v85
	v_lshlrev_b32_e32 v92, 16, v146
	v_add_f32_e32 v86, 1.0, v86
	v_rcp_f32_e32 v86, v86
	v_and_b32_e32 v105, 0xffff0000, v151
	v_and_b32_e32 v93, 0xffff0000, v146
	v_lshlrev_b32_e32 v94, 16, v147
	v_mul_f32_e32 v87, 0xbfb8aa3b, v105
	v_fmac_f32_e32 v92, v80, v84
	v_exp_f32_e32 v87, v87
	v_fmac_f32_e32 v93, v81, v85
	v_fmac_f32_e32 v94, v82, v86
	v_cvt_pk_bf16_f32 v80, v88, v89
	v_cvt_pk_bf16_f32 v81, v90, v91
	v_cvt_pk_bf16_f32 v82, v92, v93
	v_lshlrev_b32_e32 v90, 16, v140
	v_and_b32_e32 v91, 0xffff0000, v140
	v_lshlrev_b32_e32 v92, 16, v141
	v_mul_f32_e32 v90, 0xbfb8aa3b, v90
	v_mul_f32_e32 v91, 0xbfb8aa3b, v91
	v_mul_f32_e32 v92, 0xbfb8aa3b, v92
	v_exp_f32_e32 v90, v90
	v_exp_f32_e32 v91, v91
	v_exp_f32_e32 v92, v92
	v_add_f32_e32 v87, 1.0, v87
	v_rcp_f32_e32 v87, v87
	v_and_b32_e32 v93, 0xffff0000, v141
	v_add_f32_e32 v90, 1.0, v90
	v_add_f32_e32 v91, 1.0, v91
	v_add_f32_e32 v92, 1.0, v92
	v_mul_f32_e32 v93, 0xbfb8aa3b, v93
	v_rcp_f32_e32 v90, v90
	v_rcp_f32_e32 v91, v91
	v_rcp_f32_e32 v92, v92
	v_exp_f32_e32 v93, v93
	v_and_b32_e32 v95, 0xffff0000, v147
	v_fmac_f32_e32 v95, v83, v87
	v_cvt_pk_bf16_f32 v83, v94, v95
	global_store_dwordx4 v[96:97], v[80:83], off offset:256
	v_lshlrev_b32_e32 v84, 16, v137
	v_lshlrev_b32_e32 v94, 16, v142
	v_lshlrev_b32_e32 v82, 16, v136
	v_and_b32_e32 v83, 0xffff0000, v136
	v_and_b32_e32 v95, 0xffff0000, v142
	v_fmac_f32_e32 v82, v76, v90
	v_fmac_f32_e32 v83, v77, v91
	v_fmac_f32_e32 v84, v78, v92
	v_add_f32_e32 v76, 1.0, v93
	v_mul_f32_e32 v77, 0xbfb8aa3b, v94
	v_mul_f32_e32 v78, 0xbfb8aa3b, v95
	v_rcp_f32_e32 v76, v76
	v_exp_f32_e32 v77, v77
	v_exp_f32_e32 v78, v78
	v_and_b32_e32 v85, 0xffff0000, v137
	v_fmac_f32_e32 v85, v79, v76
	v_add_f32_e32 v76, 1.0, v77
	v_add_f32_e32 v77, 1.0, v78
	v_rcp_f32_e32 v76, v76
	v_rcp_f32_e32 v77, v77
	v_lshlrev_b32_e32 v96, 16, v143
	v_lshlrev_b32_e32 v86, 16, v138
	v_and_b32_e32 v87, 0xffff0000, v138
	v_and_b32_e32 v97, 0xffff0000, v143
	v_mul_f32_e32 v78, 0xbfb8aa3b, v96
	v_exp_f32_e32 v78, v78
	v_mul_f32_e32 v79, 0xbfb8aa3b, v97
	v_fmac_f32_e32 v86, v72, v76
	v_fmac_f32_e32 v87, v73, v77
	v_cvt_pk_bf16_f32 v72, v82, v83
	v_cvt_pk_bf16_f32 v73, v84, v85
	v_lshlrev_b32_e32 v82, 16, v132
	v_and_b32_e32 v83, 0xffff0000, v132
	v_lshlrev_b32_e32 v84, 16, v133
	v_exp_f32_e32 v79, v79
	v_mul_f32_e32 v82, 0xbfb8aa3b, v82
	v_mul_f32_e32 v83, 0xbfb8aa3b, v83
	v_mul_f32_e32 v84, 0xbfb8aa3b, v84
	v_exp_f32_e32 v82, v82
	v_exp_f32_e32 v83, v83
	v_exp_f32_e32 v84, v84
	v_add_f32_e32 v78, 1.0, v78
	v_rcp_f32_e32 v78, v78
	v_add_f32_e32 v79, 1.0, v79
	v_and_b32_e32 v85, 0xffff0000, v133
	v_rcp_f32_e32 v79, v79
	v_add_f32_e32 v82, 1.0, v82
	v_add_f32_e32 v83, 1.0, v83
	v_add_f32_e32 v84, 1.0, v84
	v_mul_f32_e32 v85, 0xbfb8aa3b, v85
	v_rcp_f32_e32 v82, v82
	v_rcp_f32_e32 v83, v83
	v_rcp_f32_e32 v84, v84
	v_exp_f32_e32 v85, v85
	v_lshl_add_u64 v[80:81], s[46:47], 0, v[192:193]
	v_lshlrev_b32_e32 v88, 16, v139
	v_lshl_add_u64 v[80:81], v[80:81], 0, v[186:187]
	v_and_b32_e32 v89, 0xffff0000, v139
	v_fmac_f32_e32 v88, v74, v78
	v_cvt_pk_bf16_f32 v74, v86, v87
	v_fmac_f32_e32 v89, v75, v79
	v_cvt_pk_bf16_f32 v75, v88, v89
	global_store_dwordx4 v[80:81], v[72:75], off
	v_lshlrev_b32_e32 v86, 16, v134
	v_and_b32_e32 v87, 0xffff0000, v134
	v_lshlrev_b32_e32 v72, 16, v128
	v_and_b32_e32 v73, 0xffff0000, v128
	v_lshlrev_b32_e32 v74, 16, v129
	v_fmac_f32_e32 v72, v68, v82
	v_fmac_f32_e32 v73, v69, v83
	v_fmac_f32_e32 v74, v70, v84
	v_add_f32_e32 v68, 1.0, v85
	v_mul_f32_e32 v69, 0xbfb8aa3b, v86
	v_mul_f32_e32 v70, 0xbfb8aa3b, v87
	v_rcp_f32_e32 v68, v68
	v_exp_f32_e32 v69, v69
	v_exp_f32_e32 v70, v70
	v_and_b32_e32 v75, 0xffff0000, v129
	v_lshlrev_b32_e32 v88, 16, v135
	v_and_b32_e32 v89, 0xffff0000, v135
	v_fmac_f32_e32 v75, v71, v68
	v_add_f32_e32 v68, 1.0, v69
	v_add_f32_e32 v69, 1.0, v70
	v_mul_f32_e32 v70, 0xbfb8aa3b, v88
	v_exp_f32_e32 v70, v70
	v_mul_f32_e32 v71, 0xbfb8aa3b, v89
	v_exp_f32_e32 v71, v71
	v_rcp_f32_e32 v68, v68
	v_rcp_f32_e32 v69, v69
	v_add_f32_e32 v70, 1.0, v70
	v_rcp_f32_e32 v70, v70
	v_add_f32_e32 v71, 1.0, v71
	v_rcp_f32_e32 v71, v71
	v_lshlrev_b32_e32 v76, 16, v130
	v_and_b32_e32 v77, 0xffff0000, v130
	v_lshl_add_u64 v[132:133], v[190:191], 0, s[6:7]
	v_lshlrev_b32_e32 v78, 16, v131
	v_fmac_f32_e32 v76, v64, v68
	v_fmac_f32_e32 v77, v65, v69
	v_lshl_add_u64 v[68:69], v[188:189], 0, v[132:133]
	v_and_b32_e32 v79, 0xffff0000, v131
	v_fmac_f32_e32 v78, v66, v70
	v_add_co_u32_e32 v70, vcc, s55, v68
	v_fmac_f32_e32 v79, v67, v71
	s_nop 0
	v_addc_co_u32_e32 v71, vcc, 0, v69, vcc
	v_cvt_pk_bf16_f32 v64, v72, v73
	v_cvt_pk_bf16_f32 v65, v74, v75
	v_cvt_pk_bf16_f32 v66, v76, v77
	v_cvt_pk_bf16_f32 v67, v78, v79
	global_load_dwordx4 v[108:111], v[68:69], off
	global_load_dwordx4 v[112:115], v[70:71], off
	v_lshl_add_u64 v[134:135], v[190:191], 0, s[8:9]
	global_store_dwordx4 v[80:81], v[64:67], off offset:256
	global_load_dwordx4 v[116:119], v[68:69], off offset:256
	global_load_dwordx4 v[120:123], v[70:71], off offset:256
	v_lshl_add_u64 v[64:65], v[188:189], 0, v[134:135]
	v_add_co_u32_e32 v66, vcc, s55, v64
	v_lshl_add_u64 v[106:107], v[190:191], 0, s[10:11]
	s_nop 0
	v_addc_co_u32_e32 v67, vcc, 0, v65, vcc
	global_load_dwordx4 v[124:127], v[64:65], off
	global_load_dwordx4 v[100:103], v[64:65], off offset:256
	global_load_dwordx4 v[128:131], v[66:67], off
	global_load_dwordx4 v[96:99], v[66:67], off offset:256
	v_lshl_add_u64 v[64:65], v[188:189], 0, v[106:107]
	v_add_co_u32_e32 v66, vcc, s55, v64
	v_lshl_add_u64 v[104:105], v[190:191], 0, s[12:13]
	s_nop 0
	v_addc_co_u32_e32 v67, vcc, 0, v65, vcc
	global_load_dwordx4 v[92:95], v[64:65], off
	global_load_dwordx4 v[84:87], v[64:65], off offset:256
	global_load_dwordx4 v[88:91], v[66:67], off
	global_load_dwordx4 v[80:83], v[66:67], off offset:256
	v_lshl_add_u64 v[64:65], v[188:189], 0, v[104:105]
	v_add_co_u32_e32 v66, vcc, s55, v64
	v_lshl_add_u64 v[132:133], s[46:47], 0, v[132:133]
	s_nop 0
	v_addc_co_u32_e32 v67, vcc, 0, v65, vcc
	global_load_dwordx4 v[76:79], v[64:65], off
	global_load_dwordx4 v[68:71], v[64:65], off offset:256
	global_load_dwordx4 v[72:75], v[66:67], off
	s_nop 0
	global_load_dwordx4 v[64:67], v[66:67], off offset:256
	v_lshl_add_u64 v[132:133], v[132:133], 0, v[186:187]
	s_and_b64 vcc, exec, s[2:3]
	s_waitcnt vmcnt(0)
; __device__ __forceinline__ float sigmoidf_(float x) { return __builtin_amdgcn_rcpf(1.0f + __expf(-x)); }
; __device__ __forceinline__ u32x4 pack8(const float (&f)[8]) { u32x4 w; w.x = cvt_pk_bf16(f[0], f[1]); w.y = cvt_pk_bf16(f[2], f[3]); w.z = cvt_pk_bf16(f[4], f[5]); w.w = cvt_pk_bf16(f[6], f[7]); return w; }
;     __device__ __forceinline__ void operator()(const f32x4 (&acc)[2][2][4][2], const pg8::Unit& u, int wr, int wc, int fr, int fq) const {
;     ...
;                 for (int bj = 0; bj < 2; ++bj) { const bf16_t* p = G + (size_t)(row0 + ai * 128 + m * 16) * LDG + col0 + bj * 128;
;                     la[m][bj] = *(const u32x4*)p; if (mode != 0) lg[m][bj] = *(const u32x4*)(p + 2048); else lg[m][bj] = la[m][bj]; }
; #pragma unroll
;             for (int m = 0; m < 4; ++m)
; #pragma unroll
;                 for (int bj = 0; bj < 2; ++bj) {
;                     bf16_t* p = G + (size_t)(row0 + ai * 128 + m * 16) * LDG + col0 + bj * 128;
;                     float a[8], gt[8], o[8];
;                     unpack8(la[m][bj], a);
;                     if (mode == 0) {
; #pragma unroll
;                         for (int n = 0; n < 2; ++n)
; #pragma unroll
;                             for (int i = 0; i < 4; ++i) o[n * 4 + i] = sigmoidf_(a[n * 4 + i]) * acc[ai][bj][m][n][i];
;                     } else {
;                         unpack8(lg[m][bj], gt);
; #pragma unroll
;                         for (int n = 0; n < 2; ++n)
; #pragma unroll
;                             for (int i = 0; i < 4; ++i) o[n * 4 + i] = a[n * 4 + i] + sigmoidf_(gt[n * 4 + i]) * acc[ai][bj][m][n][i];
;                     }
;                     *(u32x4*)p = pack8(o);
	v_lshlrev_b32_e32 v136, 16, v108
	v_lshlrev_b32_e32 v140, 16, v112
	v_and_b32_e32 v112, 0xffff0000, v112
	v_lshlrev_b32_e32 v141, 16, v113
	v_mul_f32_e32 v140, 0xbfb8aa3b, v140
	v_mul_f32_e32 v112, 0xbfb8aa3b, v112
	v_mul_f32_e32 v141, 0xbfb8aa3b, v141
	v_exp_f32_e32 v140, v140
	v_exp_f32_e32 v112, v112
	v_exp_f32_e32 v141, v141
	v_and_b32_e32 v113, 0xffff0000, v113
	v_add_f32_e32 v140, 1.0, v140
	v_add_f32_e32 v112, 1.0, v112
	v_add_f32_e32 v141, 1.0, v141
	v_mul_f32_e32 v113, 0xbfb8aa3b, v113
	v_rcp_f32_e32 v140, v140
	v_rcp_f32_e32 v112, v112
	v_rcp_f32_e32 v141, v141
	v_exp_f32_e32 v113, v113
	v_and_b32_e32 v108, 0xffff0000, v108
	v_lshlrev_b32_e32 v137, 16, v109
	v_lshlrev_b32_e32 v142, 16, v114
	v_and_b32_e32 v114, 0xffff0000, v114
	v_fmac_f32_e32 v136, v60, v140
	v_fmac_f32_e32 v108, v61, v112
	v_fmac_f32_e32 v137, v62, v141
	v_add_f32_e32 v60, 1.0, v113
	v_mul_f32_e32 v61, 0xbfb8aa3b, v142
	v_mul_f32_e32 v62, 0xbfb8aa3b, v114
	v_rcp_f32_e32 v60, v60
	v_exp_f32_e32 v61, v61
	v_exp_f32_e32 v62, v62
	v_and_b32_e32 v109, 0xffff0000, v109
	v_lshlrev_b32_e32 v143, 16, v115
	v_fmac_f32_e32 v109, v63, v60
	v_add_f32_e32 v60, 1.0, v61
	v_add_f32_e32 v61, 1.0, v62
	v_mul_f32_e32 v62, 0xbfb8aa3b, v143
	v_exp_f32_e32 v62, v62
	v_and_b32_e32 v115, 0xffff0000, v115
	v_mul_f32_e32 v63, 0xbfb8aa3b, v115
	v_exp_f32_e32 v63, v63
	v_rcp_f32_e32 v61, v61
	v_add_f32_e32 v62, 1.0, v62
	v_rcp_f32_e32 v60, v60
	v_rcp_f32_e32 v62, v62
	v_lshlrev_b32_e32 v138, 16, v110
	v_and_b32_e32 v110, 0xffff0000, v110
	v_lshlrev_b32_e32 v139, 16, v111
	v_add_f32_e32 v63, 1.0, v63
	v_fmac_f32_e32 v110, v57, v61
	v_rcp_f32_e32 v63, v63
	v_fmac_f32_e32 v138, v56, v60
	v_fmac_f32_e32 v139, v58, v62
	v_cvt_pk_bf16_f32 v56, v136, v108
	v_cvt_pk_bf16_f32 v57, v137, v109
	v_cvt_pk_bf16_f32 v58, v138, v110
	v_lshlrev_b32_e32 v108, 16, v120
	v_and_b32_e32 v109, 0xffff0000, v120
	v_lshlrev_b32_e32 v110, 16, v121
	v_mul_f32_e32 v108, 0xbfb8aa3b, v108
	v_mul_f32_e32 v109, 0xbfb8aa3b, v109
	v_mul_f32_e32 v110, 0xbfb8aa3b, v110
	v_exp_f32_e32 v108, v108
	v_exp_f32_e32 v109, v109
	v_exp_f32_e32 v110, v110
	v_and_b32_e32 v111, 0xffff0000, v111
	v_fmac_f32_e32 v111, v59, v63
	v_cvt_pk_bf16_f32 v59, v139, v111
	v_and_b32_e32 v111, 0xffff0000, v121
	v_add_f32_e32 v108, 1.0, v108
	v_add_f32_e32 v109, 1.0, v109
	v_add_f32_e32 v110, 1.0, v110
	v_mul_f32_e32 v111, 0xbfb8aa3b, v111
	v_rcp_f32_e32 v108, v108
	v_rcp_f32_e32 v109, v109
	v_rcp_f32_e32 v110, v110
	v_exp_f32_e32 v111, v111
	global_store_dwordx4 v[132:133], v[56:59], off
	v_lshlrev_b32_e32 v112, 16, v122
	v_and_b32_e32 v113, 0xffff0000, v122
	v_lshlrev_b32_e32 v56, 16, v116
	v_and_b32_e32 v57, 0xffff0000, v116
	v_lshlrev_b32_e32 v58, 16, v117
	v_fmac_f32_e32 v56, v52, v108
	v_fmac_f32_e32 v57, v53, v109
	v_fmac_f32_e32 v58, v54, v110
	v_add_f32_e32 v52, 1.0, v111
	v_mul_f32_e32 v53, 0xbfb8aa3b, v112
	v_mul_f32_e32 v54, 0xbfb8aa3b, v113
	v_rcp_f32_e32 v52, v52
	v_exp_f32_e32 v53, v53
	v_exp_f32_e32 v54, v54
	v_and_b32_e32 v59, 0xffff0000, v117
	v_lshlrev_b32_e32 v114, 16, v123
	v_fmac_f32_e32 v59, v55, v52
	v_add_f32_e32 v52, 1.0, v53
	v_add_f32_e32 v53, 1.0, v54
	v_mul_f32_e32 v54, 0xbfb8aa3b, v114
	v_exp_f32_e32 v54, v54
	v_rcp_f32_e32 v52, v52
	v_rcp_f32_e32 v53, v53
	v_lshlrev_b32_e32 v60, 16, v118
	v_add_f32_e32 v54, 1.0, v54
	v_rcp_f32_e32 v54, v54
	v_and_b32_e32 v115, 0xffff0000, v123
	v_and_b32_e32 v61, 0xffff0000, v118
	v_lshlrev_b32_e32 v62, 16, v119
	v_mul_f32_e32 v55, 0xbfb8aa3b, v115
	v_fmac_f32_e32 v60, v48, v52
	v_exp_f32_e32 v55, v55
	v_fmac_f32_e32 v61, v49, v53
	v_fmac_f32_e32 v62, v50, v54
	v_cvt_pk_bf16_f32 v48, v56, v57
	v_cvt_pk_bf16_f32 v49, v58, v59
	v_cvt_pk_bf16_f32 v50, v60, v61
	v_lshlrev_b32_e32 v58, 16, v128
	v_and_b32_e32 v59, 0xffff0000, v128
	v_lshlrev_b32_e32 v60, 16, v129
	v_mul_f32_e32 v58, 0xbfb8aa3b, v58
	v_mul_f32_e32 v59, 0xbfb8aa3b, v59
	v_mul_f32_e32 v60, 0xbfb8aa3b, v60
	v_exp_f32_e32 v58, v58
	v_exp_f32_e32 v59, v59
	v_exp_f32_e32 v60, v60
	v_add_f32_e32 v55, 1.0, v55
	v_rcp_f32_e32 v55, v55
	v_and_b32_e32 v61, 0xffff0000, v129
	v_add_f32_e32 v58, 1.0, v58
	v_add_f32_e32 v59, 1.0, v59
	v_add_f32_e32 v60, 1.0, v60
	v_mul_f32_e32 v61, 0xbfb8aa3b, v61
	v_rcp_f32_e32 v58, v58
	v_rcp_f32_e32 v59, v59
	v_rcp_f32_e32 v60, v60
	v_exp_f32_e32 v61, v61
	v_and_b32_e32 v63, 0xffff0000, v119
	v_fmac_f32_e32 v63, v51, v55
	v_cvt_pk_bf16_f32 v51, v62, v63
	global_store_dwordx4 v[132:133], v[48:51], off offset:256
	v_lshlrev_b32_e32 v52, 16, v125
	v_lshlrev_b32_e32 v62, 16, v130
	v_lshlrev_b32_e32 v50, 16, v124
	v_and_b32_e32 v51, 0xffff0000, v124
	v_and_b32_e32 v63, 0xffff0000, v130
	v_fmac_f32_e32 v50, v44, v58
	v_fmac_f32_e32 v51, v45, v59
	v_fmac_f32_e32 v52, v46, v60
	v_add_f32_e32 v44, 1.0, v61
	v_mul_f32_e32 v45, 0xbfb8aa3b, v62
	v_mul_f32_e32 v46, 0xbfb8aa3b, v63
	v_rcp_f32_e32 v44, v44
	v_exp_f32_e32 v45, v45
	v_exp_f32_e32 v46, v46
	v_and_b32_e32 v53, 0xffff0000, v125
	v_fmac_f32_e32 v53, v47, v44
	v_add_f32_e32 v44, 1.0, v45
	v_add_f32_e32 v45, 1.0, v46
	v_rcp_f32_e32 v44, v44
	v_rcp_f32_e32 v45, v45
	v_lshlrev_b32_e32 v108, 16, v131
	v_lshlrev_b32_e32 v54, 16, v126
	v_and_b32_e32 v55, 0xffff0000, v126
	v_and_b32_e32 v109, 0xffff0000, v131
	v_mul_f32_e32 v46, 0xbfb8aa3b, v108
	v_exp_f32_e32 v46, v46
	v_mul_f32_e32 v47, 0xbfb8aa3b, v109
	v_fmac_f32_e32 v54, v40, v44
	v_fmac_f32_e32 v55, v41, v45
	v_cvt_pk_bf16_f32 v40, v50, v51
	v_cvt_pk_bf16_f32 v41, v52, v53
	v_lshlrev_b32_e32 v50, 16, v96
	v_and_b32_e32 v51, 0xffff0000, v96
	v_lshlrev_b32_e32 v52, 16, v97
	v_exp_f32_e32 v47, v47
	v_mul_f32_e32 v50, 0xbfb8aa3b, v50
	v_mul_f32_e32 v51, 0xbfb8aa3b, v51
	v_mul_f32_e32 v52, 0xbfb8aa3b, v52
; __device__ __forceinline__ float sigmoidf_(float x) { return __builtin_amdgcn_rcpf(1.0f + __expf(-x)); }
; __device__ __forceinline__ u32x4 pack8(const float (&f)[8]) { u32x4 w; w.x = cvt_pk_bf16(f[0], f[1]); w.y = cvt_pk_bf16(f[2], f[3]); w.z = cvt_pk_bf16(f[4], f[5]); w.w = cvt_pk_bf16(f[6], f[7]); return w; }
;     __device__ __forceinline__ void operator()(const f32x4 (&acc)[2][2][4][2], const pg8::Unit& u, int wr, int wc, int fr, int fq) const {
;     ...
;                 for (int bj = 0; bj < 2; ++bj) { const bf16_t* p = G + (size_t)(row0 + ai * 128 + m * 16) * LDG + col0 + bj * 128;
;                     la[m][bj] = *(const u32x4*)p; if (mode != 0) lg[m][bj] = *(const u32x4*)(p + 2048); else lg[m][bj] = la[m][bj]; }
; #pragma unroll
;             for (int m = 0; m < 4; ++m)
; #pragma unroll
;                 for (int bj = 0; bj < 2; ++bj) {
;                     bf16_t* p = G + (size_t)(row0 + ai * 128 + m * 16) * LDG + col0 + bj * 128;
;                     float a[8], gt[8], o[8];
;                     unpack8(la[m][bj], a);
;                     if (mode == 0) {
; #pragma unroll
;                         for (int n = 0; n < 2; ++n)
; #pragma unroll
;                             for (int i = 0; i < 4; ++i) o[n * 4 + i] = sigmoidf_(a[n * 4 + i]) * acc[ai][bj][m][n][i];
;                     } else {
;                         unpack8(lg[m][bj], gt);
; #pragma unroll
;                         for (int n = 0; n < 2; ++n)
; #pragma unroll
;                             for (int i = 0; i < 4; ++i) o[n * 4 + i] = a[n * 4 + i] + sigmoidf_(gt[n * 4 + i]) * acc[ai][bj][m][n][i];
;                     }
;                     *(u32x4*)p = pack8(o);
	v_exp_f32_e32 v50, v50
	v_exp_f32_e32 v51, v51
	v_exp_f32_e32 v52, v52
	v_add_f32_e32 v46, 1.0, v46
	v_rcp_f32_e32 v46, v46
	v_add_f32_e32 v47, 1.0, v47
	v_and_b32_e32 v53, 0xffff0000, v97
	v_rcp_f32_e32 v47, v47
	v_add_f32_e32 v50, 1.0, v50
	v_add_f32_e32 v51, 1.0, v51
	v_add_f32_e32 v52, 1.0, v52
	v_mul_f32_e32 v53, 0xbfb8aa3b, v53
	v_rcp_f32_e32 v50, v50
	v_rcp_f32_e32 v51, v51
	v_rcp_f32_e32 v52, v52
	v_exp_f32_e32 v53, v53
	v_lshl_add_u64 v[48:49], s[46:47], 0, v[134:135]
	v_lshlrev_b32_e32 v56, 16, v127
	v_lshl_add_u64 v[48:49], v[48:49], 0, v[186:187]
	v_and_b32_e32 v57, 0xffff0000, v127
	v_fmac_f32_e32 v56, v42, v46
	v_cvt_pk_bf16_f32 v42, v54, v55
	v_fmac_f32_e32 v57, v43, v47
	v_cvt_pk_bf16_f32 v43, v56, v57
	global_store_dwordx4 v[48:49], v[40:43], off
	v_lshlrev_b32_e32 v54, 16, v98
	v_and_b32_e32 v55, 0xffff0000, v98
	v_lshlrev_b32_e32 v40, 16, v100
	v_and_b32_e32 v41, 0xffff0000, v100
	v_lshlrev_b32_e32 v42, 16, v101
	v_fmac_f32_e32 v40, v36, v50
	v_fmac_f32_e32 v41, v37, v51
	v_fmac_f32_e32 v42, v38, v52
	v_add_f32_e32 v36, 1.0, v53
	v_mul_f32_e32 v37, 0xbfb8aa3b, v54
	v_mul_f32_e32 v38, 0xbfb8aa3b, v55
	v_rcp_f32_e32 v36, v36
	v_exp_f32_e32 v37, v37
	v_exp_f32_e32 v38, v38
	v_and_b32_e32 v43, 0xffff0000, v101
	v_lshlrev_b32_e32 v56, 16, v99
	v_fmac_f32_e32 v43, v39, v36
	v_add_f32_e32 v36, 1.0, v37
	v_add_f32_e32 v37, 1.0, v38
	v_mul_f32_e32 v38, 0xbfb8aa3b, v56
	v_exp_f32_e32 v38, v38
	v_rcp_f32_e32 v36, v36
	v_rcp_f32_e32 v37, v37
	v_lshlrev_b32_e32 v44, 16, v102
	v_add_f32_e32 v38, 1.0, v38
	v_rcp_f32_e32 v38, v38
	v_and_b32_e32 v57, 0xffff0000, v99
	v_and_b32_e32 v45, 0xffff0000, v102
	v_lshlrev_b32_e32 v46, 16, v103
	v_mul_f32_e32 v39, 0xbfb8aa3b, v57
	v_fmac_f32_e32 v44, v32, v36
	v_exp_f32_e32 v39, v39
	v_fmac_f32_e32 v45, v33, v37
	v_fmac_f32_e32 v46, v34, v38
	v_cvt_pk_bf16_f32 v32, v40, v41
	v_cvt_pk_bf16_f32 v33, v42, v43
	v_cvt_pk_bf16_f32 v34, v44, v45
	v_lshlrev_b32_e32 v42, 16, v88
	v_and_b32_e32 v43, 0xffff0000, v88
	v_lshlrev_b32_e32 v44, 16, v89
	v_mul_f32_e32 v42, 0xbfb8aa3b, v42
	v_mul_f32_e32 v43, 0xbfb8aa3b, v43
	v_mul_f32_e32 v44, 0xbfb8aa3b, v44
	v_exp_f32_e32 v42, v42
	v_exp_f32_e32 v43, v43
	v_exp_f32_e32 v44, v44
	v_add_f32_e32 v39, 1.0, v39
	v_rcp_f32_e32 v39, v39
	v_and_b32_e32 v45, 0xffff0000, v89
	v_add_f32_e32 v42, 1.0, v42
	v_add_f32_e32 v43, 1.0, v43
	v_add_f32_e32 v44, 1.0, v44
	v_mul_f32_e32 v45, 0xbfb8aa3b, v45
	v_rcp_f32_e32 v42, v42
	v_rcp_f32_e32 v43, v43
	v_rcp_f32_e32 v44, v44
	v_exp_f32_e32 v45, v45
	v_and_b32_e32 v47, 0xffff0000, v103
	v_fmac_f32_e32 v47, v35, v39
	v_cvt_pk_bf16_f32 v35, v46, v47
	global_store_dwordx4 v[48:49], v[32:35], off offset:256
	v_lshlrev_b32_e32 v36, 16, v93
	v_lshlrev_b32_e32 v46, 16, v90
	v_lshlrev_b32_e32 v34, 16, v92
	v_and_b32_e32 v35, 0xffff0000, v92
	v_and_b32_e32 v47, 0xffff0000, v90
	v_fmac_f32_e32 v34, v28, v42
	v_fmac_f32_e32 v35, v29, v43
	v_fmac_f32_e32 v36, v30, v44
	v_add_f32_e32 v28, 1.0, v45
	v_mul_f32_e32 v29, 0xbfb8aa3b, v46
	v_mul_f32_e32 v30, 0xbfb8aa3b, v47
	v_rcp_f32_e32 v28, v28
	v_exp_f32_e32 v29, v29
	v_exp_f32_e32 v30, v30
	v_and_b32_e32 v37, 0xffff0000, v93
	v_fmac_f32_e32 v37, v31, v28
	v_add_f32_e32 v28, 1.0, v29
	v_add_f32_e32 v29, 1.0, v30
	v_rcp_f32_e32 v28, v28
	v_rcp_f32_e32 v29, v29
	v_lshlrev_b32_e32 v48, 16, v91
	v_lshlrev_b32_e32 v38, 16, v94
	v_and_b32_e32 v39, 0xffff0000, v94
	v_and_b32_e32 v49, 0xffff0000, v91
	v_mul_f32_e32 v30, 0xbfb8aa3b, v48
	v_exp_f32_e32 v30, v30
	v_mul_f32_e32 v31, 0xbfb8aa3b, v49
	v_fmac_f32_e32 v38, v24, v28
	v_fmac_f32_e32 v39, v25, v29
	v_cvt_pk_bf16_f32 v24, v34, v35
	v_cvt_pk_bf16_f32 v25, v36, v37
	v_lshlrev_b32_e32 v34, 16, v80
	v_and_b32_e32 v35, 0xffff0000, v80
	v_lshlrev_b32_e32 v36, 16, v81
	v_exp_f32_e32 v31, v31
	v_mul_f32_e32 v34, 0xbfb8aa3b, v34
	v_mul_f32_e32 v35, 0xbfb8aa3b, v35
	v_mul_f32_e32 v36, 0xbfb8aa3b, v36
	v_exp_f32_e32 v34, v34
	v_exp_f32_e32 v35, v35
	v_exp_f32_e32 v36, v36
	v_add_f32_e32 v30, 1.0, v30
	v_rcp_f32_e32 v30, v30
	v_add_f32_e32 v31, 1.0, v31
	v_and_b32_e32 v37, 0xffff0000, v81
	v_rcp_f32_e32 v31, v31
	v_add_f32_e32 v34, 1.0, v34
	v_add_f32_e32 v35, 1.0, v35
	v_add_f32_e32 v36, 1.0, v36
	v_mul_f32_e32 v37, 0xbfb8aa3b, v37
	v_rcp_f32_e32 v34, v34
	v_rcp_f32_e32 v35, v35
	v_rcp_f32_e32 v36, v36
	v_exp_f32_e32 v37, v37
	v_lshl_add_u64 v[32:33], s[46:47], 0, v[106:107]
	v_lshlrev_b32_e32 v40, 16, v95
	v_lshl_add_u64 v[32:33], v[32:33], 0, v[186:187]
	v_and_b32_e32 v41, 0xffff0000, v95
	v_fmac_f32_e32 v40, v26, v30
	v_cvt_pk_bf16_f32 v26, v38, v39
	v_fmac_f32_e32 v41, v27, v31
	v_cvt_pk_bf16_f32 v27, v40, v41
	global_store_dwordx4 v[32:33], v[24:27], off
	v_lshlrev_b32_e32 v38, 16, v82
	v_and_b32_e32 v39, 0xffff0000, v82
	v_lshlrev_b32_e32 v24, 16, v84
	v_and_b32_e32 v25, 0xffff0000, v84
	v_lshlrev_b32_e32 v26, 16, v85
	v_fmac_f32_e32 v24, v20, v34
	v_fmac_f32_e32 v25, v21, v35
	v_fmac_f32_e32 v26, v22, v36
	v_add_f32_e32 v20, 1.0, v37
; __device__ __forceinline__ float sigmoidf_(float x) { return __builtin_amdgcn_rcpf(1.0f + __expf(-x)); }
; __device__ __forceinline__ u32x4 pack8(const float (&f)[8]) { u32x4 w; w.x = cvt_pk_bf16(f[0], f[1]); w.y = cvt_pk_bf16(f[2], f[3]); w.z = cvt_pk_bf16(f[4], f[5]); w.w = cvt_pk_bf16(f[6], f[7]); return w; }
; #define PG8_WAIT_V(n) asm volatile("s_waitcnt vmcnt(" #n ")" ::: "memory")
; #define PG8_BAR __builtin_amdgcn_s_barrier()
; template <class Epi>
; __device__ __forceinline__ void gemm_phase(PG8_LAS unsigned char* lds, const Gemm g, const StaticOrder& S, const Epi& E) {
;     ...
;     PG8_WAIT_V(0);
;     if (wr == 0) PG8_BAR;
;     PG8_BAR;
;     __device__ __forceinline__ void operator()(const f32x4 (&acc)[2][2][4][2], const pg8::Unit& u, int wr, int wc, int fr, int fq) const {
;     ...
;                 for (int bj = 0; bj < 2; ++bj) { const bf16_t* p = G + (size_t)(row0 + ai * 128 + m * 16) * LDG + col0 + bj * 128;
;                     la[m][bj] = *(const u32x4*)p; if (mode != 0) lg[m][bj] = *(const u32x4*)(p + 2048); else lg[m][bj] = la[m][bj]; }
; #pragma unroll
;             for (int m = 0; m < 4; ++m)
; #pragma unroll
;                 for (int bj = 0; bj < 2; ++bj) {
;                     bf16_t* p = G + (size_t)(row0 + ai * 128 + m * 16) * LDG + col0 + bj * 128;
;                     float a[8], gt[8], o[8];
;                     unpack8(la[m][bj], a);
;                     if (mode == 0) {
; #pragma unroll
;                         for (int n = 0; n < 2; ++n)
; #pragma unroll
;                             for (int i = 0; i < 4; ++i) o[n * 4 + i] = sigmoidf_(a[n * 4 + i]) * acc[ai][bj][m][n][i];
;                     } else {
;                         unpack8(lg[m][bj], gt);
; #pragma unroll
;                         for (int n = 0; n < 2; ++n)
; #pragma unroll
;                             for (int i = 0; i < 4; ++i) o[n * 4 + i] = a[n * 4 + i] + sigmoidf_(gt[n * 4 + i]) * acc[ai][bj][m][n][i];
;                     }
;                     *(u32x4*)p = pack8(o);
	v_mul_f32_e32 v21, 0xbfb8aa3b, v38
	v_mul_f32_e32 v22, 0xbfb8aa3b, v39
	v_rcp_f32_e32 v20, v20
	v_exp_f32_e32 v21, v21
	v_exp_f32_e32 v22, v22
	v_and_b32_e32 v27, 0xffff0000, v85
	v_lshlrev_b32_e32 v40, 16, v83
	v_fmac_f32_e32 v27, v23, v20
	v_add_f32_e32 v20, 1.0, v21
	v_add_f32_e32 v21, 1.0, v22
	v_mul_f32_e32 v22, 0xbfb8aa3b, v40
	v_exp_f32_e32 v22, v22
	v_rcp_f32_e32 v20, v20
	v_rcp_f32_e32 v21, v21
	v_lshlrev_b32_e32 v28, 16, v86
	v_add_f32_e32 v22, 1.0, v22
	v_rcp_f32_e32 v22, v22
	v_and_b32_e32 v41, 0xffff0000, v83
	v_and_b32_e32 v29, 0xffff0000, v86
	v_lshlrev_b32_e32 v30, 16, v87
	v_mul_f32_e32 v23, 0xbfb8aa3b, v41
	v_fmac_f32_e32 v28, v16, v20
	v_exp_f32_e32 v23, v23
	v_fmac_f32_e32 v29, v17, v21
	v_fmac_f32_e32 v30, v18, v22
	v_cvt_pk_bf16_f32 v16, v24, v25
	v_cvt_pk_bf16_f32 v17, v26, v27
	v_cvt_pk_bf16_f32 v18, v28, v29
	v_lshlrev_b32_e32 v26, 16, v72
	v_and_b32_e32 v27, 0xffff0000, v72
	v_lshlrev_b32_e32 v28, 16, v73
	v_mul_f32_e32 v26, 0xbfb8aa3b, v26
	v_mul_f32_e32 v27, 0xbfb8aa3b, v27
	v_mul_f32_e32 v28, 0xbfb8aa3b, v28
	v_exp_f32_e32 v26, v26
	v_exp_f32_e32 v27, v27
	v_exp_f32_e32 v28, v28
	v_add_f32_e32 v23, 1.0, v23
	v_rcp_f32_e32 v23, v23
	v_and_b32_e32 v29, 0xffff0000, v73
	v_add_f32_e32 v26, 1.0, v26
	v_add_f32_e32 v27, 1.0, v27
	v_add_f32_e32 v28, 1.0, v28
	v_mul_f32_e32 v29, 0xbfb8aa3b, v29
	v_rcp_f32_e32 v26, v26
	v_rcp_f32_e32 v27, v27
	v_rcp_f32_e32 v28, v28
	v_exp_f32_e32 v29, v29
	v_and_b32_e32 v31, 0xffff0000, v87
	v_fmac_f32_e32 v31, v19, v23
	v_cvt_pk_bf16_f32 v19, v30, v31
	global_store_dwordx4 v[32:33], v[16:19], off offset:256
	v_lshlrev_b32_e32 v20, 16, v77
	v_lshlrev_b32_e32 v30, 16, v74
	v_lshlrev_b32_e32 v18, 16, v76
	v_and_b32_e32 v19, 0xffff0000, v76
	v_and_b32_e32 v31, 0xffff0000, v74
	v_fmac_f32_e32 v18, v12, v26
	v_fmac_f32_e32 v19, v13, v27
	v_fmac_f32_e32 v20, v14, v28
	v_add_f32_e32 v12, 1.0, v29
	v_mul_f32_e32 v13, 0xbfb8aa3b, v30
	v_mul_f32_e32 v14, 0xbfb8aa3b, v31
	v_rcp_f32_e32 v12, v12
	v_exp_f32_e32 v13, v13
	v_exp_f32_e32 v14, v14
	v_and_b32_e32 v21, 0xffff0000, v77
	v_fmac_f32_e32 v21, v15, v12
	v_add_f32_e32 v12, 1.0, v13
	v_add_f32_e32 v13, 1.0, v14
	v_rcp_f32_e32 v12, v12
	v_rcp_f32_e32 v13, v13
	v_lshlrev_b32_e32 v32, 16, v75
	v_lshlrev_b32_e32 v22, 16, v78
	v_and_b32_e32 v23, 0xffff0000, v78
	v_and_b32_e32 v33, 0xffff0000, v75
	v_mul_f32_e32 v14, 0xbfb8aa3b, v32
	v_exp_f32_e32 v14, v14
	v_mul_f32_e32 v15, 0xbfb8aa3b, v33
	v_fmac_f32_e32 v22, v8, v12
	v_fmac_f32_e32 v23, v9, v13
	v_cvt_pk_bf16_f32 v8, v18, v19
	v_cvt_pk_bf16_f32 v9, v20, v21
	v_lshlrev_b32_e32 v18, 16, v64
	v_and_b32_e32 v19, 0xffff0000, v64
	v_lshlrev_b32_e32 v20, 16, v65
	v_exp_f32_e32 v15, v15
	v_mul_f32_e32 v18, 0xbfb8aa3b, v18
	v_mul_f32_e32 v19, 0xbfb8aa3b, v19
	v_mul_f32_e32 v20, 0xbfb8aa3b, v20
	v_exp_f32_e32 v18, v18
	v_exp_f32_e32 v19, v19
	v_exp_f32_e32 v20, v20
	v_add_f32_e32 v14, 1.0, v14
	v_rcp_f32_e32 v14, v14
	v_add_f32_e32 v15, 1.0, v15
	v_and_b32_e32 v21, 0xffff0000, v65
	v_rcp_f32_e32 v15, v15
	v_add_f32_e32 v18, 1.0, v18
	v_add_f32_e32 v19, 1.0, v19
	v_add_f32_e32 v20, 1.0, v20
	v_mul_f32_e32 v21, 0xbfb8aa3b, v21
	v_rcp_f32_e32 v18, v18
	v_rcp_f32_e32 v19, v19
	v_rcp_f32_e32 v20, v20
	v_exp_f32_e32 v21, v21
	v_lshl_add_u64 v[16:17], s[46:47], 0, v[104:105]
	v_lshlrev_b32_e32 v24, 16, v79
	v_lshl_add_u64 v[16:17], v[16:17], 0, v[186:187]
	v_and_b32_e32 v25, 0xffff0000, v79
	v_fmac_f32_e32 v24, v10, v14
	v_cvt_pk_bf16_f32 v10, v22, v23
	v_fmac_f32_e32 v25, v11, v15
	v_cvt_pk_bf16_f32 v11, v24, v25
	global_store_dwordx4 v[16:17], v[8:11], off
	v_lshlrev_b32_e32 v22, 16, v66
	v_and_b32_e32 v23, 0xffff0000, v66
	v_lshlrev_b32_e32 v8, 16, v68
	v_and_b32_e32 v9, 0xffff0000, v68
	v_lshlrev_b32_e32 v10, 16, v69
	v_fmac_f32_e32 v8, v4, v18
	v_fmac_f32_e32 v9, v5, v19
	v_fmac_f32_e32 v10, v6, v20
	v_add_f32_e32 v4, 1.0, v21
	v_mul_f32_e32 v5, 0xbfb8aa3b, v22
	v_mul_f32_e32 v6, 0xbfb8aa3b, v23
	v_rcp_f32_e32 v4, v4
	v_exp_f32_e32 v5, v5
	v_exp_f32_e32 v6, v6
	v_and_b32_e32 v11, 0xffff0000, v69
	v_lshlrev_b32_e32 v24, 16, v67
	v_and_b32_e32 v25, 0xffff0000, v67
	v_fmac_f32_e32 v11, v7, v4
	v_add_f32_e32 v4, 1.0, v5
	v_add_f32_e32 v5, 1.0, v6
	v_mul_f32_e32 v6, 0xbfb8aa3b, v24
	v_mul_f32_e32 v7, 0xbfb8aa3b, v25
	v_exp_f32_e32 v6, v6
	v_exp_f32_e32 v7, v7
	v_rcp_f32_e32 v4, v4
	v_rcp_f32_e32 v5, v5
	v_add_f32_e32 v6, 1.0, v6
	v_add_f32_e32 v7, 1.0, v7
	v_rcp_f32_e32 v6, v6
	v_rcp_f32_e32 v7, v7
	v_lshlrev_b32_e32 v12, 16, v70
	v_and_b32_e32 v13, 0xffff0000, v70
	v_lshlrev_b32_e32 v14, 16, v71
	v_and_b32_e32 v15, 0xffff0000, v71
	v_fmac_f32_e32 v12, v0, v4
	v_fmac_f32_e32 v13, v1, v5
	v_fmac_f32_e32 v14, v2, v6
	v_fmac_f32_e32 v15, v3, v7
	v_cvt_pk_bf16_f32 v0, v8, v9
	v_cvt_pk_bf16_f32 v1, v10, v11
	v_cvt_pk_bf16_f32 v2, v12, v13
	v_cvt_pk_bf16_f32 v3, v14, v15
	global_store_dwordx4 v[16:17], v[0:3], off offset:256
	s_cbranch_vccz .LBB0_918
	s_waitcnt vmcnt(0)
	s_cmpk_gt_u32 s36, 0xff
	s_cbranch_scc1 .LBB0_929
	s_barrier

; #define PG8_STAGE(bufoff, gbase, voff) do { _Pragma("unroll") for (int _i = 0; _i < 2; ++_i) \
;         __builtin_amdgcn_global_load_lds((const unsigned*)((const char*)(gbase) + (voff)[_i]), (PG8_LAS unsigned*)(lds + (bufoff) + ldsw + _i * 8192), 16, 0, 0); } while (0)
; #define PG8_LDA(dst, b, h) do { _Pragma("unroll") for (int m = 0; m < 4; ++m) _Pragma("unroll") for (int k = 0; k < 2; ++k) dst[m][k] = *(const PG8_LAS bf16x8*)(lds + PG8_SA(b, h) + aoff + m * 2048 + k * 1024); } while (0)
; #define PG8_LDB(dst, b, h) do { _Pragma("unroll") for (int n = 0; n < 2; ++n) _Pragma("unroll") for (int k = 0; k < 2; ++k) dst[n][k] = *(const PG8_LAS bf16x8*)(lds + PG8_SB(b, h) + boff + n * 2048 + k * 1024); } while (0)
; #define PG8_MMA(ai, bj, At, Bt) do { __builtin_amdgcn_s_setprio(1); _Pragma("unroll") for (int m = 0; m < 4; ++m) _Pragma("unroll") for (int n = 0; n < 2; ++n) _Pragma("unroll") for (int k = 0; k < 2; ++k) \
;         acc[ai][bj][m][n] = __builtin_amdgcn_mfma_f32_16x16x32_bf16(Bt[n][k], At[m][k], acc[ai][bj][m][n], 0, 0, 0); __builtin_amdgcn_s_setprio(0); } while (0)
; #define PG8_WAIT_V(n) asm volatile("s_waitcnt vmcnt(" #n ")" ::: "memory")
; #define PG8_WAIT_L(n) asm volatile("s_waitcnt lgkmcnt(" #n ")" ::: "memory")
; template <class Epi>
; __device__ __forceinline__ void gemm_phase(PG8_LAS unsigned char* lds, const Gemm g, const StaticOrder& S, const Epi& E) {
;     ...
;         for (int t = 0; t < nt; t += 2) {
;             const bool last = (t == nt - 2);
;             const char* a1 = cA + (size_t)(t + 1) * kstep;
;             const char* a2 = last ? nA : cA + (size_t)(t + 2) * kstep; const char* b2 = last ? nB : cB + (size_t)(t + 2) * kstep;
;             const char* a3 = a2 + kstep; const char* b3 = b2 + kstep;
;             PG8_LDB(B0, 0, 0); PG8_SCHED; PG8_LDA(At, 0, 0); PG8_STAGE(PG8_SA(1, 1), a1 + hstepA, voffA);
;             PG8_WAIT_L(8); PG8_BAR; PG8_WAIT_L(0); PG8_MMA(0, 0, At, B0); PG8_BAR; PG8_SCHED;
;             PG8_LDB(B1, 0, 1); PG8_STAGE(PG8_SB(0, 0), b2, voffB);
;             PG8_BAR; PG8_WAIT_L(0); PG8_MMA(0, 1, At, B1); PG8_BAR;
;             PG8_LDA(At, 0, 1); PG8_STAGE(PG8_SA(0, 0), a2, voffA);
;             PG8_BAR; PG8_WAIT_L(0); PG8_MMA(1, 0, At, B0); PG8_BAR; PG8_SCHED;
;             PG8_STAGE(PG8_SB(0, 1), b2 + hstepB, voffB);
;             PG8_WAIT_V(6); PG8_BAR; PG8_MMA(1, 1, At, B1); PG8_BAR;
.LBB0_1003:
	ds_read_b128 v[128:131], v190
	ds_read_b128 v[132:135], v190 offset:1024
	ds_read_b128 v[136:139], v190 offset:2048
	ds_read_b128 v[140:143], v190 offset:3072
	ds_read_b128 v[144:147], v191
	ds_read_b128 v[148:151], v191 offset:1024
	ds_read_b128 v[170:173], v191 offset:2048
	ds_read_b128 v[174:177], v191 offset:3072
	ds_read_b128 v[178:181], v191 offset:4096
	ds_read_b128 v[182:185], v191 offset:5120
	ds_read_b128 v[194:197], v191 offset:6144
	ds_read_b128 v[198:201], v191 offset:7168
	ds_read_b128 v[202:205], v192
	ds_read_b128 v[206:209], v192 offset:1024
	ds_read_b128 v[210:213], v192 offset:2048
	ds_read_b128 v[214:217], v192 offset:3072
	s_add_u32 s22, s28, 0xfff00080
	s_addc_u32 s23, s29, -1
	s_cmp_eq_u32 s56, 28
	s_cselect_b32 s31, s15, s23
	s_cselect_b32 s30, s21, s22
	s_cselect_b32 s23, s13, s55
	s_cselect_b32 s22, s53, s54
	v_lshl_add_u64 v[186:187], s[28:29], 0, v[160:161]
	s_add_i32 m0, s36, 0xc000
	s_nop 0
	global_load_lds_dwordx4 v[186:187], off
	v_lshl_add_u64 v[186:187], s[28:29], 0, v[162:163]
	s_add_i32 m0, s36, 0xe000
	s_nop 0
	global_load_lds_dwordx4 v[186:187], off
	s_waitcnt lgkmcnt(0)
	s_waitcnt vmcnt(8)
	s_barrier
	s_setprio 1
	v_mfma_f32_16x16x32_bf16 v[124:127], v[128:131], v[144:147], v[124:127]
	v_mfma_f32_16x16x32_bf16 v[120:123], v[136:139], v[144:147], v[120:123]
	v_mfma_f32_16x16x32_bf16 v[104:107], v[128:131], v[170:173], v[104:107]
	v_mfma_f32_16x16x32_bf16 v[108:111], v[136:139], v[170:173], v[108:111]
	v_mfma_f32_16x16x32_bf16 v[88:91], v[128:131], v[178:181], v[88:91]
	v_mfma_f32_16x16x32_bf16 v[92:95], v[136:139], v[178:181], v[92:95]
	v_mfma_f32_16x16x32_bf16 v[72:75], v[128:131], v[194:197], v[72:75]
	v_mfma_f32_16x16x32_bf16 v[76:79], v[136:139], v[194:197], v[76:79]
	v_mfma_f32_16x16x32_bf16 v[124:127], v[132:135], v[148:151], v[124:127]
	v_mfma_f32_16x16x32_bf16 v[120:123], v[140:143], v[148:151], v[120:123]
	v_mfma_f32_16x16x32_bf16 v[104:107], v[132:135], v[174:177], v[104:107]
	v_mfma_f32_16x16x32_bf16 v[108:111], v[140:143], v[174:177], v[108:111]
	v_mfma_f32_16x16x32_bf16 v[88:91], v[132:135], v[182:185], v[88:91]
	v_mfma_f32_16x16x32_bf16 v[92:95], v[140:143], v[182:185], v[92:95]
	v_mfma_f32_16x16x32_bf16 v[72:75], v[132:135], v[198:201], v[72:75]
	v_mfma_f32_16x16x32_bf16 v[76:79], v[140:143], v[198:201], v[76:79]
	v_mfma_f32_16x16x32_bf16 v[116:119], v[202:205], v[144:147], v[116:119]
	v_mfma_f32_16x16x32_bf16 v[112:115], v[210:213], v[144:147], v[112:115]
	v_mfma_f32_16x16x32_bf16 v[100:103], v[202:205], v[170:173], v[100:103]
	v_mfma_f32_16x16x32_bf16 v[96:99], v[210:213], v[170:173], v[96:99]
	v_mfma_f32_16x16x32_bf16 v[84:87], v[202:205], v[178:181], v[84:87]
	v_mfma_f32_16x16x32_bf16 v[80:83], v[210:213], v[178:181], v[80:83]
	v_mfma_f32_16x16x32_bf16 v[68:71], v[202:205], v[194:197], v[68:71]
	v_mfma_f32_16x16x32_bf16 v[64:67], v[210:213], v[194:197], v[64:67]
	v_mfma_f32_16x16x32_bf16 v[116:119], v[206:209], v[148:151], v[116:119]
	v_mfma_f32_16x16x32_bf16 v[112:115], v[214:217], v[148:151], v[112:115]
	v_mfma_f32_16x16x32_bf16 v[100:103], v[206:209], v[174:177], v[100:103]
	v_mfma_f32_16x16x32_bf16 v[96:99], v[214:217], v[174:177], v[96:99]
	v_mfma_f32_16x16x32_bf16 v[84:87], v[206:209], v[182:185], v[84:87]
	v_mfma_f32_16x16x32_bf16 v[80:83], v[214:217], v[182:185], v[80:83]
	v_mfma_f32_16x16x32_bf16 v[68:71], v[206:209], v[198:201], v[68:71]
	v_mfma_f32_16x16x32_bf16 v[64:67], v[214:217], v[198:201], v[64:67]
	s_setprio 0
	s_barrier
	ds_read_b128 v[144:147], v191 offset:16384
	ds_read_b128 v[148:151], v191 offset:17408
	ds_read_b128 v[170:173], v191 offset:18432
	ds_read_b128 v[174:177], v191 offset:19456
	ds_read_b128 v[178:181], v191 offset:20480
	ds_read_b128 v[182:185], v191 offset:21504
	ds_read_b128 v[194:197], v191 offset:22528
	ds_read_b128 v[198:201], v191 offset:23552
	s_add_i32 s57, s50, s35
	v_lshl_add_u64 v[186:187], s[22:23], 0, v[154:155]
	s_mov_b32 m0, s57
	s_nop 0
	global_load_lds_dwordx4 v[186:187], off
	v_lshl_add_u64 v[218:219], s[22:23], 0, v[158:159]
	s_add_i32 m0, s57, 0x2000
	s_nop 0
	global_load_lds_dwordx4 v[218:219], off
	s_mov_b32 m0, s36
	v_lshl_add_u64 v[220:221], s[30:31], 0, v[152:153]
	global_load_lds_dwordx4 v[220:221], off
	v_lshl_add_u64 v[222:223], s[30:31], 0, v[156:157]
	s_mov_b32 m0, s37
	s_nop 0
	global_load_lds_dwordx4 v[222:223], off
	s_add_u32 s58, s22, 0x80000
	s_addc_u32 s59, s23, 0
	s_add_i32 s57, s51, s35
	v_lshl_add_u64 v[224:225], s[58:59], 0, v[154:155]
	s_mov_b32 m0, s57
	s_nop 0
	global_load_lds_dwordx4 v[224:225], off
	v_lshl_add_u64 v[224:225], s[58:59], 0, v[158:159]
	s_add_i32 m0, s57, 0x2000
	s_nop 0
	global_load_lds_dwordx4 v[224:225], off
	s_waitcnt lgkmcnt(0)
	s_waitcnt vmcnt(8)
	s_barrier
; #define PG8_STAGE(bufoff, gbase, voff) do { _Pragma("unroll") for (int _i = 0; _i < 2; ++_i) \
;         __builtin_amdgcn_global_load_lds((const unsigned*)((const char*)(gbase) + (voff)[_i]), (PG8_LAS unsigned*)(lds + (bufoff) + ldsw + _i * 8192), 16, 0, 0); } while (0)
; #define PG8_LDA(dst, b, h) do { _Pragma("unroll") for (int m = 0; m < 4; ++m) _Pragma("unroll") for (int k = 0; k < 2; ++k) dst[m][k] = *(const PG8_LAS bf16x8*)(lds + PG8_SA(b, h) + aoff + m * 2048 + k * 1024); } while (0)
; #define PG8_LDB(dst, b, h) do { _Pragma("unroll") for (int n = 0; n < 2; ++n) _Pragma("unroll") for (int k = 0; k < 2; ++k) dst[n][k] = *(const PG8_LAS bf16x8*)(lds + PG8_SB(b, h) + boff + n * 2048 + k * 1024); } while (0)
; #define PG8_MMA(ai, bj, At, Bt) do { __builtin_amdgcn_s_setprio(1); _Pragma("unroll") for (int m = 0; m < 4; ++m) _Pragma("unroll") for (int n = 0; n < 2; ++n) _Pragma("unroll") for (int k = 0; k < 2; ++k) \
;         acc[ai][bj][m][n] = __builtin_amdgcn_mfma_f32_16x16x32_bf16(Bt[n][k], At[m][k], acc[ai][bj][m][n], 0, 0, 0); __builtin_amdgcn_s_setprio(0); } while (0)
; #define PG8_WAIT_V(n) asm volatile("s_waitcnt vmcnt(" #n ")" ::: "memory")
; #define PG8_WAIT_L(n) asm volatile("s_waitcnt lgkmcnt(" #n ")" ::: "memory")
; #define PG8_BAR __builtin_amdgcn_s_barrier()
; #define PG8_SCHED __builtin_amdgcn_sched_barrier(0)
; template <class Epi>
; __device__ __forceinline__ void gemm_phase(PG8_LAS unsigned char* lds, const Gemm g, const StaticOrder& S, const Epi& E) {
;     ...
;             PG8_BAR; PG8_WAIT_L(0); PG8_MMA(0, 1, At, B1); PG8_BAR;
;             PG8_LDA(At, 0, 1); PG8_STAGE(PG8_SA(0, 0), a2, voffA);
;             PG8_BAR; PG8_WAIT_L(0); PG8_MMA(1, 0, At, B0); PG8_BAR; PG8_SCHED;
;             PG8_STAGE(PG8_SB(0, 1), b2 + hstepB, voffB);
;             PG8_WAIT_V(6); PG8_BAR; PG8_MMA(1, 1, At, B1); PG8_BAR;
;             PG8_LDB(B0, 1, 0); PG8_SCHED; PG8_LDA(At, 1, 0); PG8_STAGE(PG8_SA(0, 1), a2 + hstepA, voffA);
;             PG8_WAIT_L(8); PG8_BAR; PG8_WAIT_L(0); PG8_MMA(0, 0, At, B0); PG8_BAR; PG8_SCHED;
;             PG8_LDB(B1, 1, 1); PG8_STAGE(PG8_SB(1, 0), b3, voffB);
;             PG8_BAR; PG8_WAIT_L(0); PG8_MMA(0, 1, At, B1); PG8_BAR;
	s_setprio 1
	v_mfma_f32_16x16x32_bf16 v[60:63], v[128:131], v[144:147], v[60:63]
	v_mfma_f32_16x16x32_bf16 v[56:59], v[136:139], v[144:147], v[56:59]
	v_mfma_f32_16x16x32_bf16 v[40:43], v[128:131], v[170:173], v[40:43]
	v_mfma_f32_16x16x32_bf16 v[44:47], v[136:139], v[170:173], v[44:47]
	v_mfma_f32_16x16x32_bf16 v[24:27], v[128:131], v[178:181], v[24:27]
	v_mfma_f32_16x16x32_bf16 v[28:31], v[136:139], v[178:181], v[28:31]
	v_mfma_f32_16x16x32_bf16 v[8:11], v[128:131], v[194:197], v[8:11]
	v_mfma_f32_16x16x32_bf16 v[12:15], v[136:139], v[194:197], v[12:15]
	v_mfma_f32_16x16x32_bf16 v[60:63], v[132:135], v[148:151], v[60:63]
	v_mfma_f32_16x16x32_bf16 v[56:59], v[140:143], v[148:151], v[56:59]
	v_mfma_f32_16x16x32_bf16 v[40:43], v[132:135], v[174:177], v[40:43]
	v_mfma_f32_16x16x32_bf16 v[44:47], v[140:143], v[174:177], v[44:47]
	v_mfma_f32_16x16x32_bf16 v[24:27], v[132:135], v[182:185], v[24:27]
	v_mfma_f32_16x16x32_bf16 v[28:31], v[140:143], v[182:185], v[28:31]
	v_mfma_f32_16x16x32_bf16 v[8:11], v[132:135], v[198:201], v[8:11]
	v_mfma_f32_16x16x32_bf16 v[12:15], v[140:143], v[198:201], v[12:15]
	v_mfma_f32_16x16x32_bf16 v[52:55], v[202:205], v[144:147], v[52:55]
	v_mfma_f32_16x16x32_bf16 v[48:51], v[210:213], v[144:147], v[48:51]
	v_mfma_f32_16x16x32_bf16 v[36:39], v[202:205], v[170:173], v[36:39]
	v_mfma_f32_16x16x32_bf16 v[32:35], v[210:213], v[170:173], v[32:35]
	v_mfma_f32_16x16x32_bf16 v[20:23], v[202:205], v[178:181], v[20:23]
	v_mfma_f32_16x16x32_bf16 v[16:19], v[210:213], v[178:181], v[16:19]
	v_mfma_f32_16x16x32_bf16 v[4:7], v[202:205], v[194:197], v[4:7]
	v_mfma_f32_16x16x32_bf16 v[0:3], v[210:213], v[194:197], v[0:3]
	v_mfma_f32_16x16x32_bf16 v[52:55], v[206:209], v[148:151], v[52:55]
	v_mfma_f32_16x16x32_bf16 v[48:51], v[214:217], v[148:151], v[48:51]
	v_mfma_f32_16x16x32_bf16 v[36:39], v[206:209], v[174:177], v[36:39]
	v_mfma_f32_16x16x32_bf16 v[32:35], v[214:217], v[174:177], v[32:35]
	v_mfma_f32_16x16x32_bf16 v[20:23], v[206:209], v[182:185], v[20:23]
	v_mfma_f32_16x16x32_bf16 v[16:19], v[214:217], v[182:185], v[16:19]
	v_mfma_f32_16x16x32_bf16 v[4:7], v[206:209], v[198:201], v[4:7]
	v_mfma_f32_16x16x32_bf16 v[0:3], v[214:217], v[198:201], v[0:3]
	s_setprio 0
	s_add_i32 s57, 0, 0x18000
	v_add_u32_e32 v140, s57, v188
	s_barrier
	ds_read_b128 v[128:131], v140
	ds_read_b128 v[132:135], v140 offset:1024
	ds_read_b128 v[136:139], v140 offset:2048
	ds_read_b128 v[140:143], v140 offset:3072
	ds_read_b128 v[144:147], v191 offset:32768
	ds_read_b128 v[148:151], v191 offset:33792
	ds_read_b128 v[170:173], v191 offset:34816
	ds_read_b128 v[174:177], v191 offset:35840
	ds_read_b128 v[178:181], v191 offset:36864
	ds_read_b128 v[182:185], v191 offset:37888
	ds_read_b128 v[194:197], v191 offset:38912
	ds_read_b128 v[198:201], v191 offset:39936
	v_add_u32_e32 v214, 0x1c000, v188
	ds_read_b128 v[202:205], v214
	ds_read_b128 v[206:209], v214 offset:1024
	ds_read_b128 v[210:213], v214 offset:2048
	ds_read_b128 v[214:217], v214 offset:3072
	s_add_u32 s30, s30, 0x100000
	s_addc_u32 s31, s31, 0
	s_mov_b32 m0, s38
	v_lshl_add_u64 v[224:225], s[30:31], 0, v[152:153]
	global_load_lds_dwordx4 v[224:225], off
	v_lshl_add_u64 v[224:225], s[30:31], 0, v[156:157]
	s_mov_b32 m0, s39
	s_nop 0
	global_load_lds_dwordx4 v[224:225], off
	s_waitcnt lgkmcnt(0)
	s_waitcnt vmcnt(8)
	s_barrier
	s_setprio 1
	v_mfma_f32_16x16x32_bf16 v[124:127], v[128:131], v[144:147], v[124:127]
	v_mfma_f32_16x16x32_bf16 v[120:123], v[136:139], v[144:147], v[120:123]
	v_mfma_f32_16x16x32_bf16 v[104:107], v[128:131], v[170:173], v[104:107]
	v_mfma_f32_16x16x32_bf16 v[108:111], v[136:139], v[170:173], v[108:111]
	v_mfma_f32_16x16x32_bf16 v[88:91], v[128:131], v[178:181], v[88:91]
	v_mfma_f32_16x16x32_bf16 v[92:95], v[136:139], v[178:181], v[92:95]
	v_mfma_f32_16x16x32_bf16 v[72:75], v[128:131], v[194:197], v[72:75]
	v_mfma_f32_16x16x32_bf16 v[76:79], v[136:139], v[194:197], v[76:79]
	v_mfma_f32_16x16x32_bf16 v[124:127], v[132:135], v[148:151], v[124:127]
	v_mfma_f32_16x16x32_bf16 v[120:123], v[140:143], v[148:151], v[120:123]
	v_mfma_f32_16x16x32_bf16 v[104:107], v[132:135], v[174:177], v[104:107]
	v_mfma_f32_16x16x32_bf16 v[108:111], v[140:143], v[174:177], v[108:111]
	v_mfma_f32_16x16x32_bf16 v[88:91], v[132:135], v[182:185], v[88:91]
	v_mfma_f32_16x16x32_bf16 v[92:95], v[140:143], v[182:185], v[92:95]
	v_mfma_f32_16x16x32_bf16 v[72:75], v[132:135], v[198:201], v[72:75]
	v_mfma_f32_16x16x32_bf16 v[76:79], v[140:143], v[198:201], v[76:79]
	v_mfma_f32_16x16x32_bf16 v[116:119], v[202:205], v[144:147], v[116:119]
	v_mfma_f32_16x16x32_bf16 v[112:115], v[210:213], v[144:147], v[112:115]
	v_mfma_f32_16x16x32_bf16 v[100:103], v[202:205], v[170:173], v[100:103]
	v_mfma_f32_16x16x32_bf16 v[96:99], v[210:213], v[170:173], v[96:99]
	v_mfma_f32_16x16x32_bf16 v[84:87], v[202:205], v[178:181], v[84:87]
	v_mfma_f32_16x16x32_bf16 v[80:83], v[210:213], v[178:181], v[80:83]
	v_mfma_f32_16x16x32_bf16 v[68:71], v[202:205], v[194:197], v[68:71]
	v_mfma_f32_16x16x32_bf16 v[64:67], v[210:213], v[194:197], v[64:67]
	v_mfma_f32_16x16x32_bf16 v[116:119], v[206:209], v[148:151], v[116:119]
	v_mfma_f32_16x16x32_bf16 v[112:115], v[214:217], v[148:151], v[112:115]
	v_mfma_f32_16x16x32_bf16 v[100:103], v[206:209], v[174:177], v[100:103]
	v_mfma_f32_16x16x32_bf16 v[96:99], v[214:217], v[174:177], v[96:99]
	v_mfma_f32_16x16x32_bf16 v[84:87], v[206:209], v[182:185], v[84:87]
	v_mfma_f32_16x16x32_bf16 v[80:83], v[214:217], v[182:185], v[80:83]
	v_mfma_f32_16x16x32_bf16 v[68:71], v[206:209], v[198:201], v[68:71]
	v_mfma_f32_16x16x32_bf16 v[64:67], v[214:217], v[198:201], v[64:67]
	s_setprio 0
	s_barrier
; #define PG8_STAGE(bufoff, gbase, voff) do { _Pragma("unroll") for (int _i = 0; _i < 2; ++_i) \
;         __builtin_amdgcn_global_load_lds((const unsigned*)((const char*)(gbase) + (voff)[_i]), (PG8_LAS unsigned*)(lds + (bufoff) + ldsw + _i * 8192), 16, 0, 0); } while (0)
; #define PG8_LDA(dst, b, h) do { _Pragma("unroll") for (int m = 0; m < 4; ++m) _Pragma("unroll") for (int k = 0; k < 2; ++k) dst[m][k] = *(const PG8_LAS bf16x8*)(lds + PG8_SA(b, h) + aoff + m * 2048 + k * 1024); } while (0)
; #define PG8_LDB(dst, b, h) do { _Pragma("unroll") for (int n = 0; n < 2; ++n) _Pragma("unroll") for (int k = 0; k < 2; ++k) dst[n][k] = *(const PG8_LAS bf16x8*)(lds + PG8_SB(b, h) + boff + n * 2048 + k * 1024); } while (0)
; #define PG8_MMA(ai, bj, At, Bt) do { __builtin_amdgcn_s_setprio(1); _Pragma("unroll") for (int m = 0; m < 4; ++m) _Pragma("unroll") for (int n = 0; n < 2; ++n) _Pragma("unroll") for (int k = 0; k < 2; ++k) \
;         acc[ai][bj][m][n] = __builtin_amdgcn_mfma_f32_16x16x32_bf16(Bt[n][k], At[m][k], acc[ai][bj][m][n], 0, 0, 0); __builtin_amdgcn_s_setprio(0); } while (0)
; #define PG8_WAIT_V(n) asm volatile("s_waitcnt vmcnt(" #n ")" ::: "memory")
; #define PG8_WAIT_L(n) asm volatile("s_waitcnt lgkmcnt(" #n ")" ::: "memory")
; #define PG8_BAR __builtin_amdgcn_s_barrier()
; #define PG8_SCHED __builtin_amdgcn_sched_barrier(0)
; template <class Epi>
; __device__ __forceinline__ void gemm_phase(PG8_LAS unsigned char* lds, const Gemm g, const StaticOrder& S, const Epi& E) {
;     ...
;             PG8_LDB(B1, 1, 1); PG8_STAGE(PG8_SB(1, 0), b3, voffB);
;             PG8_BAR; PG8_WAIT_L(0); PG8_MMA(0, 1, At, B1); PG8_BAR;
;             PG8_LDA(At, 1, 1); PG8_STAGE(PG8_SA(1, 0), a3, voffA);
;             PG8_BAR; PG8_WAIT_L(0); PG8_MMA(1, 0, At, B0); PG8_BAR; PG8_SCHED;
;             PG8_STAGE(PG8_SB(1, 1), b3 + hstepB, voffB);
;             PG8_WAIT_V(6); PG8_BAR; PG8_MMA(1, 1, At, B1); PG8_BAR;
	ds_read_b128 v[144:147], v191 offset:49152
	ds_read_b128 v[148:151], v191 offset:50176
	ds_read_b128 v[170:173], v191 offset:51200
	ds_read_b128 v[174:177], v191 offset:52224
	ds_read_b128 v[178:181], v191 offset:53248
	ds_read_b128 v[182:185], v191 offset:54272
	ds_read_b128 v[194:197], v191 offset:55296
	ds_read_b128 v[198:201], v191 offset:56320
	s_add_i32 s30, 0, 0x1c000
	s_add_i32 s31, s57, s35
	v_lshl_add_u64 v[186:187], v[186:187], 0, s[10:11]
	s_mov_b32 m0, s31
	s_nop 0
	global_load_lds_dwordx4 v[186:187], off
	v_lshl_add_u64 v[186:187], v[218:219], 0, s[10:11]
	s_add_i32 m0, s31, 0x2000
	s_nop 0
	global_load_lds_dwordx4 v[186:187], off
	s_mov_b32 m0, s41
	v_lshl_add_u64 v[186:187], v[220:221], 0, s[10:11]
	global_load_lds_dwordx4 v[186:187], off
	v_lshl_add_u64 v[186:187], v[222:223], 0, s[10:11]
	s_mov_b32 m0, s42
	s_nop 0
	global_load_lds_dwordx4 v[186:187], off
	s_add_u32 s22, s22, 0x80080
	s_addc_u32 s23, s23, 0
	s_add_i32 s30, s30, s35
	v_lshl_add_u64 v[224:225], s[22:23], 0, v[154:155]
	s_mov_b32 m0, s30
	s_nop 0
	global_load_lds_dwordx4 v[224:225], off
	v_lshl_add_u64 v[224:225], s[22:23], 0, v[158:159]
	s_add_i32 m0, s30, 0x2000
	s_nop 0
	global_load_lds_dwordx4 v[224:225], off
	s_waitcnt lgkmcnt(0)
	s_waitcnt vmcnt(8)
	s_barrier
	s_setprio 1
	v_mfma_f32_16x16x32_bf16 v[60:63], v[128:131], v[144:147], v[60:63]
	v_mfma_f32_16x16x32_bf16 v[56:59], v[136:139], v[144:147], v[56:59]
	v_mfma_f32_16x16x32_bf16 v[40:43], v[128:131], v[170:173], v[40:43]
	v_mfma_f32_16x16x32_bf16 v[44:47], v[136:139], v[170:173], v[44:47]
	v_mfma_f32_16x16x32_bf16 v[24:27], v[128:131], v[178:181], v[24:27]
	v_mfma_f32_16x16x32_bf16 v[28:31], v[136:139], v[178:181], v[28:31]
	v_mfma_f32_16x16x32_bf16 v[8:11], v[128:131], v[194:197], v[8:11]
	v_mfma_f32_16x16x32_bf16 v[12:15], v[136:139], v[194:197], v[12:15]
	v_mfma_f32_16x16x32_bf16 v[60:63], v[132:135], v[148:151], v[60:63]
	v_mfma_f32_16x16x32_bf16 v[56:59], v[140:143], v[148:151], v[56:59]
	v_mfma_f32_16x16x32_bf16 v[40:43], v[132:135], v[174:177], v[40:43]
	v_mfma_f32_16x16x32_bf16 v[44:47], v[140:143], v[174:177], v[44:47]
	v_mfma_f32_16x16x32_bf16 v[24:27], v[132:135], v[182:185], v[24:27]
	v_mfma_f32_16x16x32_bf16 v[28:31], v[140:143], v[182:185], v[28:31]
	v_mfma_f32_16x16x32_bf16 v[8:11], v[132:135], v[198:201], v[8:11]
	v_mfma_f32_16x16x32_bf16 v[12:15], v[140:143], v[198:201], v[12:15]
	v_mfma_f32_16x16x32_bf16 v[52:55], v[202:205], v[144:147], v[52:55]
	v_mfma_f32_16x16x32_bf16 v[48:51], v[210:213], v[144:147], v[48:51]
	v_mfma_f32_16x16x32_bf16 v[36:39], v[202:205], v[170:173], v[36:39]
	v_mfma_f32_16x16x32_bf16 v[32:35], v[210:213], v[170:173], v[32:35]
	v_mfma_f32_16x16x32_bf16 v[20:23], v[202:205], v[178:181], v[20:23]
	v_mfma_f32_16x16x32_bf16 v[16:19], v[210:213], v[178:181], v[16:19]
	v_mfma_f32_16x16x32_bf16 v[4:7], v[202:205], v[194:197], v[4:7]
	v_mfma_f32_16x16x32_bf16 v[0:3], v[210:213], v[194:197], v[0:3]
	v_mfma_f32_16x16x32_bf16 v[52:55], v[206:209], v[148:151], v[52:55]
	v_mfma_f32_16x16x32_bf16 v[48:51], v[214:217], v[148:151], v[48:51]
	v_mfma_f32_16x16x32_bf16 v[36:39], v[206:209], v[174:177], v[36:39]
	v_mfma_f32_16x16x32_bf16 v[32:35], v[214:217], v[174:177], v[32:35]
	v_mfma_f32_16x16x32_bf16 v[20:23], v[206:209], v[182:185], v[20:23]
	v_mfma_f32_16x16x32_bf16 v[16:19], v[214:217], v[182:185], v[16:19]
	v_mfma_f32_16x16x32_bf16 v[4:7], v[206:209], v[198:201], v[4:7]
	v_mfma_f32_16x16x32_bf16 v[0:3], v[214:217], v[198:201], v[0:3]
	s_setprio 0
	s_add_i32 s56, s56, 2
	s_add_u32 s28, s28, 0x100
	s_addc_u32 s29, s29, 0
	s_add_u32 s54, s54, 0x100
	s_addc_u32 s55, s55, 0
	s_cmp_gt_u32 s56, 29
	s_barrier
	s_cbranch_scc0 .LBB0_1003
; __device__ __forceinline__ u32x4 pack8(const float (&f)[8]) { u32x4 w; w.x = cvt_pk_bf16(f[0], f[1]); w.y = cvt_pk_bf16(f[2], f[3]); w.z = cvt_pk_bf16(f[4], f[5]); w.w = cvt_pk_bf16(f[6], f[7]); return w; }
;     __device__ __forceinline__ void operator()(const f32x4 (&acc)[2][2][4][2], const pg8::Unit& u, int wr, int wc, int fr, int fq) const {
;         const int row0 = u.pm * 256 + wr * 64 + fr, col0 = u.pn * 256 + wc * 32 + 8 * fq;
; #pragma unroll
;         for (int ai = 0; ai < 2; ++ai) {
;             u32x4 rb[4][2];
; #pragma unroll
;             for (int m = 0; m < 4; ++m)
; #pragma unroll
;                 for (int bj = 0; bj < 2; ++bj) rb[m][bj] = *(const u32x4*)(resb + (size_t)(row0 + ai * 128 + m * 16) * DM + col0 + bj * 128);
; #pragma unroll
;             for (int m = 0; m < 4; ++m) {
;                 const int r = row0 + ai * 128 + m * 16; float ss = 0.f;
; #pragma unroll
;                 for (int bj = 0; bj < 2; ++bj) {
;                     const size_t off = (size_t)r * DM + col0 + bj * 128;
;                     float rv[8], o[8]; unpack8(rb[m][bj], rv);
; #pragma unroll
;                     for (int n = 0; n < 2; ++n)
; #pragma unroll
;                         for (int i = 0; i < 4; ++i) o[n * 4 + i] = rv[n * 4 + i] + coef * acc[ai][bj][m][n][i];
;                     if (outf) { *(f32x4*)(outf + off) = (f32x4){o[0], o[1], o[2], o[3]}; *(f32x4*)(outf + off + 4) = (f32x4){o[4], o[5], o[6], o[7]}; }
;                     if (hb) { *(u32x4*)(hb + off) = pack8(o);
; #pragma unroll
;                         for (int i = 0; i < 8; ++i) ss += o[i] * o[i]; }
;                 }
;                 if (hb) { ss += __shfl_xor(ss, 16); ss += __shfl_xor(ss, 32); if (fq == 0) part[(size_t)r * 32 + u.pn * 4 + wc] = ss; }
	v_lshl_or_b32 v170, s8, 8, v189
	v_lshl_add_u32 v172, s20, 8, v169
	v_ashrrev_i32_e32 v171, 31, v170
	v_lshlrev_b64 v[204:205], 1, v[170:171]
	v_ashrrev_i32_e32 v173, 31, v172
	v_lshl_add_u64 v[174:175], s[76:77], 0, v[204:205]
	v_lshlrev_b64 v[194:195], 12, v[172:173]
	v_lshl_add_u64 v[128:129], v[174:175], 0, v[194:195]
	global_load_dwordx4 v[196:199], v[128:129], off
	global_load_dwordx4 v[200:203], v[128:129], off offset:256
	v_or_b32_e32 v184, 16, v172
	v_or_b32_e32 v180, 32, v172
	v_or_b32_e32 v176, 48, v172
	v_ashrrev_i32_e32 v185, 31, v184
	v_ashrrev_i32_e32 v181, 31, v180
	v_ashrrev_i32_e32 v177, 31, v176
	v_lshlrev_b64 v[186:187], 12, v[184:185]
	v_lshlrev_b64 v[182:183], 12, v[180:181]
	v_lshlrev_b64 v[178:179], 12, v[176:177]
	v_lshl_add_u64 v[128:129], v[174:175], 0, v[186:187]
	v_lshl_add_u64 v[130:131], v[174:175], 0, v[182:183]
	v_lshl_add_u64 v[206:207], v[174:175], 0, v[178:179]
	global_load_dwordx4 v[148:151], v[128:129], off
	global_load_dwordx4 v[144:147], v[128:129], off offset:256
	global_load_dwordx4 v[140:143], v[130:131], off
	global_load_dwordx4 v[136:139], v[130:131], off offset:256
	global_load_dwordx4 v[132:135], v[206:207], off
	s_nop 0
	global_load_dwordx4 v[128:131], v[206:207], off offset:256
	v_and_b32_e32 v207, 64, v193
	v_xor_b32_e32 v206, 16, v193
	v_add_u32_e32 v207, 64, v207
	v_xor_b32_e32 v208, 32, v193
	v_cmp_lt_i32_e32 vcc, v206, v207
	s_lshl_b32 s20, s8, 2
	s_ashr_i32 s21, s20, 31
	v_cndmask_b32_e32 v209, v193, v206, vcc
	v_cmp_lt_i32_e32 vcc, v208, v207
	v_lshl_add_u64 v[206:207], s[76:77], 0, v[194:195]
	v_lshl_add_u64 v[204:205], v[206:207], 0, v[204:205]
	v_lshlrev_b32_e32 v194, 2, v209
	v_cndmask_b32_e32 v208, v193, v208, vcc
	s_waitcnt vmcnt(0)
	v_lshlrev_b32_e32 v195, 16, v196
	v_and_b32_e32 v196, 0xffff0000, v196
	v_lshlrev_b32_e32 v212, 16, v202
	v_add_f32_e32 v125, v125, v196
	v_lshlrev_b32_e32 v206, 16, v197
	v_add_f32_e32 v124, v124, v195
	v_add_f32_e32 v195, v112, v212
	v_cvt_pk_bf16_f32 v112, v124, v125
	v_mul_f32_e32 v125, v125, v125
	v_and_b32_e32 v197, 0xffff0000, v197
	v_add_f32_e32 v126, v126, v206
	v_fmac_f32_e32 v125, v124, v124
	v_lshlrev_b32_e32 v207, 16, v198
	v_add_f32_e32 v127, v127, v197
	v_fmac_f32_e32 v125, v126, v126
	v_and_b32_e32 v198, 0xffff0000, v198
	v_add_f32_e32 v120, v120, v207
	v_fmac_f32_e32 v125, v127, v127
	v_lshlrev_b32_e32 v209, 16, v199
	v_add_f32_e32 v121, v121, v198
	v_fmac_f32_e32 v125, v120, v120
	v_and_b32_e32 v199, 0xffff0000, v199
	v_add_f32_e32 v122, v122, v209
	v_fmac_f32_e32 v125, v121, v121
	v_lshlrev_b32_e32 v210, 16, v200
	v_add_f32_e32 v123, v123, v199
	v_fmac_f32_e32 v125, v122, v122
	v_and_b32_e32 v200, 0xffff0000, v200
	v_add_f32_e32 v116, v116, v210
	v_fmac_f32_e32 v125, v123, v123
	v_lshlrev_b32_e32 v211, 16, v201
	v_add_f32_e32 v117, v117, v200
	v_fmac_f32_e32 v125, v116, v116
	v_and_b32_e32 v201, 0xffff0000, v201
	v_add_f32_e32 v118, v118, v211
	v_fmac_f32_e32 v125, v117, v117
	v_add_f32_e32 v119, v119, v201
	v_fmac_f32_e32 v125, v118, v118
	v_and_b32_e32 v202, 0xffff0000, v202
	v_fmac_f32_e32 v125, v119, v119
	v_lshlrev_b32_e32 v213, 16, v203
	v_add_f32_e32 v196, v113, v202
	v_fmac_f32_e32 v125, v195, v195
	v_and_b32_e32 v203, 0xffff0000, v203
	v_add_f32_e32 v197, v114, v213
	v_fmac_f32_e32 v125, v196, v196
	v_add_f32_e32 v198, v115, v203
	v_fmac_f32_e32 v125, v197, v197
	v_fmac_f32_e32 v125, v198, v198
	ds_bpermute_b32 v124, v194, v125
	v_cvt_pk_bf16_f32 v113, v126, v127
	v_cvt_pk_bf16_f32 v114, v120, v121
	v_cvt_pk_bf16_f32 v115, v122, v123
	global_store_dwordx4 v[204:205], v[112:115], off
	v_cvt_pk_bf16_f32 v116, v116, v117
	v_cvt_pk_bf16_f32 v117, v118, v119
	v_cvt_pk_bf16_f32 v118, v195, v196
	v_cvt_pk_bf16_f32 v119, v197, v198
	global_store_dwordx4 v[204:205], v[116:119], off offset:256
	s_waitcnt lgkmcnt(0)
	v_add_f32_e32 v113, v125, v124
	v_lshlrev_b32_e32 v112, 2, v208
	ds_bpermute_b32 v114, v112, v113
	s_and_saveexec_b64 s[22:23], s[2:3]
	s_cbranch_execz .LBB0_1006
	v_lshlrev_b64 v[116:117], 7, v[172:173]
	v_lshl_add_u64 v[116:117], s[0:1], 0, v[116:117]
	v_lshl_add_u64 v[116:117], s[20:21], 2, v[116:117]
	s_lshl_b32 s8, s40, 2
	v_lshl_add_u64 v[116:117], v[116:117], 0, s[8:9]
	s_waitcnt lgkmcnt(0)
	v_add_f32_e32 v113, v113, v114
	global_store_dword v[116:117], v113, off

; #define PG8_STAGE(bufoff, gbase, voff) do { _Pragma("unroll") for (int _i = 0; _i < 2; ++_i) \
;         __builtin_amdgcn_global_load_lds((const unsigned*)((const char*)(gbase) + (voff)[_i]), (PG8_LAS unsigned*)(lds + (bufoff) + ldsw + _i * 8192), 16, 0, 0); } while (0)
; #define PG8_LDA(dst, b, h) do { _Pragma("unroll") for (int m = 0; m < 4; ++m) _Pragma("unroll") for (int k = 0; k < 2; ++k) dst[m][k] = *(const PG8_LAS bf16x8*)(lds + PG8_SA(b, h) + aoff + m * 2048 + k * 1024); } while (0)
; #define PG8_LDB(dst, b, h) do { _Pragma("unroll") for (int n = 0; n < 2; ++n) _Pragma("unroll") for (int k = 0; k < 2; ++k) dst[n][k] = *(const PG8_LAS bf16x8*)(lds + PG8_SB(b, h) + boff + n * 2048 + k * 1024); } while (0)
; #define PG8_MMA(ai, bj, At, Bt) do { __builtin_amdgcn_s_setprio(1); _Pragma("unroll") for (int m = 0; m < 4; ++m) _Pragma("unroll") for (int n = 0; n < 2; ++n) _Pragma("unroll") for (int k = 0; k < 2; ++k) \
;         acc[ai][bj][m][n] = __builtin_amdgcn_mfma_f32_16x16x32_bf16(Bt[n][k], At[m][k], acc[ai][bj][m][n], 0, 0, 0); __builtin_amdgcn_s_setprio(0); } while (0)
; #define PG8_WAIT_V(n) asm volatile("s_waitcnt vmcnt(" #n ")" ::: "memory")
; #define PG8_WAIT_L(n) asm volatile("s_waitcnt lgkmcnt(" #n ")" ::: "memory")
; template <class Epi>
; __device__ __forceinline__ void gemm_phase(PG8_LAS unsigned char* lds, const Gemm g, const StaticOrder& S, const Epi& E) {
;     ...
;         for (int t = 0; t < nt; t += 2) {
;             const bool last = (t == nt - 2);
;             const char* a1 = cA + (size_t)(t + 1) * kstep;
;             const char* a2 = last ? nA : cA + (size_t)(t + 2) * kstep; const char* b2 = last ? nB : cB + (size_t)(t + 2) * kstep;
;             const char* a3 = a2 + kstep; const char* b3 = b2 + kstep;
;             PG8_LDB(B0, 0, 0); PG8_SCHED; PG8_LDA(At, 0, 0); PG8_STAGE(PG8_SA(1, 1), a1 + hstepA, voffA);
;             PG8_WAIT_L(8); PG8_BAR; PG8_WAIT_L(0); PG8_MMA(0, 0, At, B0); PG8_BAR; PG8_SCHED;
;             PG8_LDB(B1, 0, 1); PG8_STAGE(PG8_SB(0, 0), b2, voffB);
;             PG8_BAR; PG8_WAIT_L(0); PG8_MMA(0, 1, At, B1); PG8_BAR;
;             PG8_LDA(At, 0, 1); PG8_STAGE(PG8_SA(0, 0), a2, voffA);
;             PG8_BAR; PG8_WAIT_L(0); PG8_MMA(1, 0, At, B0); PG8_BAR; PG8_SCHED;
;             PG8_STAGE(PG8_SB(0, 1), b2 + hstepB, voffB);
;             PG8_WAIT_V(6); PG8_BAR; PG8_MMA(1, 1, At, B1); PG8_BAR;
.LBB0_1086:
	ds_read_b128 v[0:3], v173
	ds_read_b128 v[4:7], v173 offset:1024
	ds_read_b128 v[154:157], v173 offset:2048
	ds_read_b128 v[158:161], v173 offset:3072
	ds_read_b128 v[162:165], v174
	ds_read_b128 v[178:181], v174 offset:1024
	ds_read_b128 v[182:185], v174 offset:2048
	ds_read_b128 v[186:189], v174 offset:3072
	ds_read_b128 v[190:193], v174 offset:4096
	ds_read_b128 v[194:197], v174 offset:5120
	ds_read_b128 v[198:201], v174 offset:6144
	ds_read_b128 v[202:205], v174 offset:7168
	ds_read_b128 v[206:209], v175
	ds_read_b128 v[210:213], v175 offset:1024
	ds_read_b128 v[214:217], v175 offset:2048
	ds_read_b128 v[218:221], v175 offset:3072
	s_add_u32 s4, s0, 0xfff80080
	s_addc_u32 s5, s1, -1
	s_cmp_eq_u32 s63, 28
	s_cselect_b32 s7, s39, s5
	s_cselect_b32 s6, s59, s4
	s_cselect_b32 s5, s37, s62
	s_cselect_b32 s4, s60, s61
	v_lshl_add_u64 v[166:167], s[0:1], 0, v[146:147]
	s_add_i32 m0, s11, 0xc000
	s_nop 0
	global_load_lds_dwordx4 v[166:167], off
	v_lshl_add_u64 v[166:167], s[0:1], 0, v[148:149]
	s_add_i32 m0, s11, 0xe000
	s_nop 0
	global_load_lds_dwordx4 v[166:167], off
	s_waitcnt lgkmcnt(0)
	s_waitcnt vmcnt(8)
	s_barrier
	s_setprio 1
	v_mfma_f32_16x16x32_bf16 v[132:135], v[0:3], v[162:165], v[132:135]
	v_mfma_f32_16x16x32_bf16 v[124:127], v[154:157], v[162:165], v[124:127]
	v_mfma_f32_16x16x32_bf16 v[116:119], v[0:3], v[182:185], v[116:119]
	v_mfma_f32_16x16x32_bf16 v[108:111], v[154:157], v[182:185], v[108:111]
	v_mfma_f32_16x16x32_bf16 v[100:103], v[0:3], v[190:193], v[100:103]
	v_mfma_f32_16x16x32_bf16 v[92:95], v[154:157], v[190:193], v[92:95]
	v_mfma_f32_16x16x32_bf16 v[84:87], v[0:3], v[198:201], v[84:87]
	v_mfma_f32_16x16x32_bf16 v[76:79], v[154:157], v[198:201], v[76:79]
	v_mfma_f32_16x16x32_bf16 v[132:135], v[4:7], v[178:181], v[132:135]
	v_mfma_f32_16x16x32_bf16 v[124:127], v[158:161], v[178:181], v[124:127]
	v_mfma_f32_16x16x32_bf16 v[116:119], v[4:7], v[186:189], v[116:119]
	v_mfma_f32_16x16x32_bf16 v[108:111], v[158:161], v[186:189], v[108:111]
	v_mfma_f32_16x16x32_bf16 v[100:103], v[4:7], v[194:197], v[100:103]
	v_mfma_f32_16x16x32_bf16 v[92:95], v[158:161], v[194:197], v[92:95]
	v_mfma_f32_16x16x32_bf16 v[84:87], v[4:7], v[202:205], v[84:87]
	v_mfma_f32_16x16x32_bf16 v[76:79], v[158:161], v[202:205], v[76:79]
	v_mfma_f32_16x16x32_bf16 v[128:131], v[206:209], v[162:165], v[128:131]
	v_mfma_f32_16x16x32_bf16 v[120:123], v[214:217], v[162:165], v[120:123]
	v_mfma_f32_16x16x32_bf16 v[112:115], v[206:209], v[182:185], v[112:115]
	v_mfma_f32_16x16x32_bf16 v[104:107], v[214:217], v[182:185], v[104:107]
	v_mfma_f32_16x16x32_bf16 v[96:99], v[206:209], v[190:193], v[96:99]
	v_mfma_f32_16x16x32_bf16 v[88:91], v[214:217], v[190:193], v[88:91]
	v_mfma_f32_16x16x32_bf16 v[80:83], v[206:209], v[198:201], v[80:83]
	v_mfma_f32_16x16x32_bf16 v[72:75], v[214:217], v[198:201], v[72:75]
	v_mfma_f32_16x16x32_bf16 v[128:131], v[210:213], v[178:181], v[128:131]
	v_mfma_f32_16x16x32_bf16 v[120:123], v[218:221], v[178:181], v[120:123]
	v_mfma_f32_16x16x32_bf16 v[112:115], v[210:213], v[186:189], v[112:115]
	v_mfma_f32_16x16x32_bf16 v[104:107], v[218:221], v[186:189], v[104:107]
	v_mfma_f32_16x16x32_bf16 v[96:99], v[210:213], v[194:197], v[96:99]
	v_mfma_f32_16x16x32_bf16 v[88:91], v[218:221], v[194:197], v[88:91]
	v_mfma_f32_16x16x32_bf16 v[80:83], v[210:213], v[202:205], v[80:83]
	v_mfma_f32_16x16x32_bf16 v[72:75], v[218:221], v[202:205], v[72:75]
	s_setprio 0
	s_barrier
	ds_read_b128 v[162:165], v174 offset:16384
	ds_read_b128 v[178:181], v174 offset:17408
	ds_read_b128 v[182:185], v174 offset:18432
	ds_read_b128 v[186:189], v174 offset:19456
	ds_read_b128 v[190:193], v174 offset:20480
	ds_read_b128 v[194:197], v174 offset:21504
	ds_read_b128 v[198:201], v174 offset:22528
	ds_read_b128 v[202:205], v174 offset:23552
	s_add_i32 s64, s52, s22
	v_lshl_add_u64 v[166:167], s[4:5], 0, v[140:141]
	s_mov_b32 m0, s64
	s_nop 0
	global_load_lds_dwordx4 v[166:167], off
	v_lshl_add_u64 v[222:223], s[4:5], 0, v[136:137]
	s_add_i32 m0, s64, 0x2000
	s_nop 0
	global_load_lds_dwordx4 v[222:223], off
	s_mov_b32 m0, s11
	v_lshl_add_u64 v[224:225], s[6:7], 0, v[142:143]
	global_load_lds_dwordx4 v[224:225], off
	v_lshl_add_u64 v[226:227], s[6:7], 0, v[138:139]
	s_mov_b32 m0, s31
	s_nop 0
	global_load_lds_dwordx4 v[226:227], off
	s_add_u32 s64, s4, 0x80000
	s_addc_u32 s65, s5, 0
	s_add_i32 s66, s53, s22
	v_lshl_add_u64 v[228:229], s[64:65], 0, v[140:141]
	s_mov_b32 m0, s66
	s_nop 0
	global_load_lds_dwordx4 v[228:229], off
	v_lshl_add_u64 v[228:229], s[64:65], 0, v[136:137]
	s_add_i32 m0, s66, 0x2000
	s_nop 0
	global_load_lds_dwordx4 v[228:229], off
	s_waitcnt lgkmcnt(0)
	s_waitcnt vmcnt(8)
	s_barrier
; #define PG8_STAGE(bufoff, gbase, voff) do { _Pragma("unroll") for (int _i = 0; _i < 2; ++_i) \
;         __builtin_amdgcn_global_load_lds((const unsigned*)((const char*)(gbase) + (voff)[_i]), (PG8_LAS unsigned*)(lds + (bufoff) + ldsw + _i * 8192), 16, 0, 0); } while (0)
; #define PG8_LDA(dst, b, h) do { _Pragma("unroll") for (int m = 0; m < 4; ++m) _Pragma("unroll") for (int k = 0; k < 2; ++k) dst[m][k] = *(const PG8_LAS bf16x8*)(lds + PG8_SA(b, h) + aoff + m * 2048 + k * 1024); } while (0)
; #define PG8_LDB(dst, b, h) do { _Pragma("unroll") for (int n = 0; n < 2; ++n) _Pragma("unroll") for (int k = 0; k < 2; ++k) dst[n][k] = *(const PG8_LAS bf16x8*)(lds + PG8_SB(b, h) + boff + n * 2048 + k * 1024); } while (0)
; #define PG8_MMA(ai, bj, At, Bt) do { __builtin_amdgcn_s_setprio(1); _Pragma("unroll") for (int m = 0; m < 4; ++m) _Pragma("unroll") for (int n = 0; n < 2; ++n) _Pragma("unroll") for (int k = 0; k < 2; ++k) \
;         acc[ai][bj][m][n] = __builtin_amdgcn_mfma_f32_16x16x32_bf16(Bt[n][k], At[m][k], acc[ai][bj][m][n], 0, 0, 0); __builtin_amdgcn_s_setprio(0); } while (0)
; #define PG8_WAIT_V(n) asm volatile("s_waitcnt vmcnt(" #n ")" ::: "memory")
; #define PG8_WAIT_L(n) asm volatile("s_waitcnt lgkmcnt(" #n ")" ::: "memory")
; #define PG8_BAR __builtin_amdgcn_s_barrier()
; #define PG8_SCHED __builtin_amdgcn_sched_barrier(0)
; template <class Epi>
; __device__ __forceinline__ void gemm_phase(PG8_LAS unsigned char* lds, const Gemm g, const StaticOrder& S, const Epi& E) {
;     ...
;             PG8_BAR; PG8_WAIT_L(0); PG8_MMA(0, 1, At, B1); PG8_BAR;
;             PG8_LDA(At, 0, 1); PG8_STAGE(PG8_SA(0, 0), a2, voffA);
;             PG8_BAR; PG8_WAIT_L(0); PG8_MMA(1, 0, At, B0); PG8_BAR; PG8_SCHED;
;             PG8_STAGE(PG8_SB(0, 1), b2 + hstepB, voffB);
;             PG8_WAIT_V(6); PG8_BAR; PG8_MMA(1, 1, At, B1); PG8_BAR;
;             PG8_LDB(B0, 1, 0); PG8_SCHED; PG8_LDA(At, 1, 0); PG8_STAGE(PG8_SA(0, 1), a2 + hstepA, voffA);
;             PG8_WAIT_L(8); PG8_BAR; PG8_WAIT_L(0); PG8_MMA(0, 0, At, B0); PG8_BAR; PG8_SCHED;
;             PG8_LDB(B1, 1, 1); PG8_STAGE(PG8_SB(1, 0), b3, voffB);
;             PG8_BAR; PG8_WAIT_L(0); PG8_MMA(0, 1, At, B1); PG8_BAR;
	s_setprio 1
	v_mfma_f32_16x16x32_bf16 v[68:71], v[0:3], v[162:165], v[68:71]
	v_mfma_f32_16x16x32_bf16 v[60:63], v[154:157], v[162:165], v[60:63]
	v_mfma_f32_16x16x32_bf16 v[52:55], v[0:3], v[182:185], v[52:55]
	v_mfma_f32_16x16x32_bf16 v[44:47], v[154:157], v[182:185], v[44:47]
	v_mfma_f32_16x16x32_bf16 v[36:39], v[0:3], v[190:193], v[36:39]
	v_mfma_f32_16x16x32_bf16 v[28:31], v[154:157], v[190:193], v[28:31]
	v_mfma_f32_16x16x32_bf16 v[0:3], v[0:3], v[198:201], v[20:23]
	v_mfma_f32_16x16x32_bf16 v[68:71], v[4:7], v[178:181], v[68:71]
	v_mfma_f32_16x16x32_bf16 v[60:63], v[158:161], v[178:181], v[60:63]
	v_mfma_f32_16x16x32_bf16 v[52:55], v[4:7], v[186:189], v[52:55]
	v_mfma_f32_16x16x32_bf16 v[44:47], v[158:161], v[186:189], v[44:47]
	v_mfma_f32_16x16x32_bf16 v[36:39], v[4:7], v[194:197], v[36:39]
	v_mfma_f32_16x16x32_bf16 v[28:31], v[158:161], v[194:197], v[28:31]
	v_mfma_f32_16x16x32_bf16 v[0:3], v[4:7], v[202:205], v[0:3]
	v_mfma_f32_16x16x32_bf16 v[4:7], v[154:157], v[198:201], v[12:15]
	v_mfma_f32_16x16x32_bf16 v[4:7], v[158:161], v[202:205], v[4:7]
	v_mfma_f32_16x16x32_bf16 v[12:15], v[206:209], v[162:165], v[64:67]
	v_mfma_f32_16x16x32_bf16 v[64:67], v[210:213], v[178:181], v[12:15]
	v_mfma_f32_16x16x32_bf16 v[12:15], v[214:217], v[162:165], v[56:59]
	v_mfma_f32_16x16x32_bf16 v[56:59], v[218:221], v[178:181], v[12:15]
	v_mfma_f32_16x16x32_bf16 v[12:15], v[206:209], v[182:185], v[48:51]
	v_mfma_f32_16x16x32_bf16 v[48:51], v[210:213], v[186:189], v[12:15]
	v_mfma_f32_16x16x32_bf16 v[12:15], v[214:217], v[182:185], v[40:43]
	v_mfma_f32_16x16x32_bf16 v[40:43], v[218:221], v[186:189], v[12:15]
	v_mfma_f32_16x16x32_bf16 v[12:15], v[206:209], v[190:193], v[32:35]
	v_mfma_f32_16x16x32_bf16 v[32:35], v[210:213], v[194:197], v[12:15]
	v_mfma_f32_16x16x32_bf16 v[12:15], v[214:217], v[190:193], v[24:27]
	v_mfma_f32_16x16x32_bf16 v[24:27], v[218:221], v[194:197], v[12:15]
	v_mfma_f32_16x16x32_bf16 v[12:15], v[206:209], v[198:201], v[16:19]
	v_mfma_f32_16x16x32_bf16 v[8:11], v[214:217], v[198:201], v[8:11]
	v_mfma_f32_16x16x32_bf16 v[16:19], v[210:213], v[202:205], v[12:15]
	v_mfma_f32_16x16x32_bf16 v[8:11], v[218:221], v[202:205], v[8:11]
	s_setprio 0
	s_add_i32 s64, 0, 0x18000
	v_add_u32_e32 v158, s64, v170
	s_barrier
	s_nop 0
	s_nop 0
	ds_read_b128 v[12:15], v158
	ds_read_b128 v[20:23], v158 offset:1024
	ds_read_b128 v[154:157], v158 offset:2048
	ds_read_b128 v[158:161], v158 offset:3072
	ds_read_b128 v[162:165], v174 offset:32768
	ds_read_b128 v[178:181], v174 offset:33792
	ds_read_b128 v[182:185], v174 offset:34816
	ds_read_b128 v[186:189], v174 offset:35840
	ds_read_b128 v[190:193], v174 offset:36864
	ds_read_b128 v[194:197], v174 offset:37888
	ds_read_b128 v[198:201], v174 offset:38912
	ds_read_b128 v[202:205], v174 offset:39936
	v_add_u32_e32 v177, 0x1c000, v170
	ds_read_b128 v[206:209], v177
	ds_read_b128 v[210:213], v177 offset:1024
	ds_read_b128 v[214:217], v177 offset:2048
	ds_read_b128 v[218:221], v177 offset:3072
	s_add_u32 s6, s6, 0x80000
	s_addc_u32 s7, s7, 0
	s_mov_b32 m0, s34
	v_lshl_add_u64 v[228:229], s[6:7], 0, v[142:143]
	global_load_lds_dwordx4 v[228:229], off
	v_lshl_add_u64 v[228:229], s[6:7], 0, v[138:139]
	s_mov_b32 m0, s35
	s_nop 0
	global_load_lds_dwordx4 v[228:229], off
	s_waitcnt lgkmcnt(0)
	s_waitcnt vmcnt(8)
	s_barrier
	s_setprio 1
	v_mfma_f32_16x16x32_bf16 v[132:135], v[12:15], v[162:165], v[132:135]
	v_mfma_f32_16x16x32_bf16 v[124:127], v[154:157], v[162:165], v[124:127]
	v_mfma_f32_16x16x32_bf16 v[116:119], v[12:15], v[182:185], v[116:119]
	v_mfma_f32_16x16x32_bf16 v[108:111], v[154:157], v[182:185], v[108:111]
	v_mfma_f32_16x16x32_bf16 v[100:103], v[12:15], v[190:193], v[100:103]
	v_mfma_f32_16x16x32_bf16 v[92:95], v[154:157], v[190:193], v[92:95]
	v_mfma_f32_16x16x32_bf16 v[84:87], v[12:15], v[198:201], v[84:87]
	v_mfma_f32_16x16x32_bf16 v[76:79], v[154:157], v[198:201], v[76:79]
	v_mfma_f32_16x16x32_bf16 v[132:135], v[20:23], v[178:181], v[132:135]
	v_mfma_f32_16x16x32_bf16 v[124:127], v[158:161], v[178:181], v[124:127]
	v_mfma_f32_16x16x32_bf16 v[116:119], v[20:23], v[186:189], v[116:119]
	v_mfma_f32_16x16x32_bf16 v[108:111], v[158:161], v[186:189], v[108:111]
	v_mfma_f32_16x16x32_bf16 v[100:103], v[20:23], v[194:197], v[100:103]
	v_mfma_f32_16x16x32_bf16 v[92:95], v[158:161], v[194:197], v[92:95]
	v_mfma_f32_16x16x32_bf16 v[84:87], v[20:23], v[202:205], v[84:87]
	v_mfma_f32_16x16x32_bf16 v[76:79], v[158:161], v[202:205], v[76:79]
	v_mfma_f32_16x16x32_bf16 v[128:131], v[206:209], v[162:165], v[128:131]
	v_mfma_f32_16x16x32_bf16 v[120:123], v[214:217], v[162:165], v[120:123]
	v_mfma_f32_16x16x32_bf16 v[112:115], v[206:209], v[182:185], v[112:115]
	v_mfma_f32_16x16x32_bf16 v[104:107], v[214:217], v[182:185], v[104:107]
	v_mfma_f32_16x16x32_bf16 v[96:99], v[206:209], v[190:193], v[96:99]
	v_mfma_f32_16x16x32_bf16 v[88:91], v[214:217], v[190:193], v[88:91]
	v_mfma_f32_16x16x32_bf16 v[80:83], v[206:209], v[198:201], v[80:83]
	v_mfma_f32_16x16x32_bf16 v[72:75], v[214:217], v[198:201], v[72:75]
	v_mfma_f32_16x16x32_bf16 v[128:131], v[210:213], v[178:181], v[128:131]
	v_mfma_f32_16x16x32_bf16 v[120:123], v[218:221], v[178:181], v[120:123]
	v_mfma_f32_16x16x32_bf16 v[112:115], v[210:213], v[186:189], v[112:115]
	v_mfma_f32_16x16x32_bf16 v[104:107], v[218:221], v[186:189], v[104:107]
	v_mfma_f32_16x16x32_bf16 v[96:99], v[210:213], v[194:197], v[96:99]
	v_mfma_f32_16x16x32_bf16 v[88:91], v[218:221], v[194:197], v[88:91]
	v_mfma_f32_16x16x32_bf16 v[80:83], v[210:213], v[202:205], v[80:83]
	v_mfma_f32_16x16x32_bf16 v[72:75], v[218:221], v[202:205], v[72:75]
	s_setprio 0
	s_barrier
; #define PG8_STAGE(bufoff, gbase, voff) do { _Pragma("unroll") for (int _i = 0; _i < 2; ++_i) \
;         __builtin_amdgcn_global_load_lds((const unsigned*)((const char*)(gbase) + (voff)[_i]), (PG8_LAS unsigned*)(lds + (bufoff) + ldsw + _i * 8192), 16, 0, 0); } while (0)
; #define PG8_LDA(dst, b, h) do { _Pragma("unroll") for (int m = 0; m < 4; ++m) _Pragma("unroll") for (int k = 0; k < 2; ++k) dst[m][k] = *(const PG8_LAS bf16x8*)(lds + PG8_SA(b, h) + aoff + m * 2048 + k * 1024); } while (0)
; #define PG8_LDB(dst, b, h) do { _Pragma("unroll") for (int n = 0; n < 2; ++n) _Pragma("unroll") for (int k = 0; k < 2; ++k) dst[n][k] = *(const PG8_LAS bf16x8*)(lds + PG8_SB(b, h) + boff + n * 2048 + k * 1024); } while (0)
; #define PG8_MMA(ai, bj, At, Bt) do { __builtin_amdgcn_s_setprio(1); _Pragma("unroll") for (int m = 0; m < 4; ++m) _Pragma("unroll") for (int n = 0; n < 2; ++n) _Pragma("unroll") for (int k = 0; k < 2; ++k) \
;         acc[ai][bj][m][n] = __builtin_amdgcn_mfma_f32_16x16x32_bf16(Bt[n][k], At[m][k], acc[ai][bj][m][n], 0, 0, 0); __builtin_amdgcn_s_setprio(0); } while (0)
; #define PG8_WAIT_V(n) asm volatile("s_waitcnt vmcnt(" #n ")" ::: "memory")
; #define PG8_WAIT_L(n) asm volatile("s_waitcnt lgkmcnt(" #n ")" ::: "memory")
; #define PG8_BAR __builtin_amdgcn_s_barrier()
; __device__ __forceinline__ void rstd8(const float* part, int row0, int fq, float (&rs)[8]) {
;     f32x4 v[8][2];
; #pragma unroll
;     for (int k = 0; k < 8; ++k) { const f32x4* p = (const f32x4*)(part + (size_t)(row0 + (k >> 2) * 128 + (k & 3) * 16) * 32 + fq * 8); v[k][0] = p[0]; v[k][1] = p[1]; }
; template <class Epi>
; __device__ __forceinline__ void gemm_phase(PG8_LAS unsigned char* lds, const Gemm g, const StaticOrder& S, const Epi& E) {
;     ...
;             PG8_LDB(B0, 1, 0); PG8_SCHED; PG8_LDA(At, 1, 0); PG8_STAGE(PG8_SA(0, 1), a2 + hstepA, voffA);
;             PG8_WAIT_L(8); PG8_BAR; PG8_WAIT_L(0); PG8_MMA(0, 0, At, B0); PG8_BAR; PG8_SCHED;
;             PG8_LDB(B1, 1, 1); PG8_STAGE(PG8_SB(1, 0), b3, voffB);
;             PG8_BAR; PG8_WAIT_L(0); PG8_MMA(0, 1, At, B1); PG8_BAR;
;             PG8_LDA(At, 1, 1); PG8_STAGE(PG8_SA(1, 0), a3, voffA);
;             PG8_BAR; PG8_WAIT_L(0); PG8_MMA(1, 0, At, B0); PG8_BAR; PG8_SCHED;
;             PG8_STAGE(PG8_SB(1, 1), b3 + hstepB, voffB);
;             PG8_WAIT_V(6); PG8_BAR; PG8_MMA(1, 1, At, B1); PG8_BAR;
	ds_read_b128 v[162:165], v174 offset:49152
	ds_read_b128 v[178:181], v174 offset:50176
	ds_read_b128 v[182:185], v174 offset:51200
	ds_read_b128 v[186:189], v174 offset:52224
	ds_read_b128 v[190:193], v174 offset:53248
	ds_read_b128 v[194:197], v174 offset:54272
	ds_read_b128 v[198:201], v174 offset:55296
	ds_read_b128 v[202:205], v174 offset:56320
	s_add_i32 s6, 0, 0x1c000
	s_add_i32 s7, s64, s22
	v_lshl_add_u64 v[166:167], v[166:167], 0, s[12:13]
	s_mov_b32 m0, s7
	s_nop 0
	global_load_lds_dwordx4 v[166:167], off
	v_lshl_add_u64 v[166:167], v[222:223], 0, s[12:13]
	s_add_i32 m0, s7, 0x2000
	s_nop 0
	global_load_lds_dwordx4 v[166:167], off
	s_mov_b32 m0, s48
	v_lshl_add_u64 v[166:167], v[224:225], 0, s[12:13]
	global_load_lds_dwordx4 v[166:167], off
	v_lshl_add_u64 v[166:167], v[226:227], 0, s[12:13]
	s_mov_b32 m0, s49
	s_nop 0
	global_load_lds_dwordx4 v[166:167], off
	s_add_u32 s4, s4, 0x80080
	s_addc_u32 s5, s5, 0
	s_add_i32 s6, s6, s22
	v_lshl_add_u64 v[228:229], s[4:5], 0, v[140:141]
	s_mov_b32 m0, s6
	s_nop 0
	global_load_lds_dwordx4 v[228:229], off
	v_lshl_add_u64 v[228:229], s[4:5], 0, v[136:137]
	s_add_i32 m0, s6, 0x2000
	s_nop 0
	global_load_lds_dwordx4 v[228:229], off
	s_waitcnt lgkmcnt(0)
	s_waitcnt vmcnt(8)
	s_barrier
	s_setprio 1
	v_mfma_f32_16x16x32_bf16 v[68:71], v[12:15], v[162:165], v[68:71]
	v_mfma_f32_16x16x32_bf16 v[52:55], v[12:15], v[182:185], v[52:55]
	v_mfma_f32_16x16x32_bf16 v[36:39], v[12:15], v[190:193], v[36:39]
	v_mfma_f32_16x16x32_bf16 v[0:3], v[12:15], v[198:201], v[0:3]
	v_mfma_f32_16x16x32_bf16 v[68:71], v[20:23], v[178:181], v[68:71]
	v_mfma_f32_16x16x32_bf16 v[60:63], v[154:157], v[162:165], v[60:63]
	v_mfma_f32_16x16x32_bf16 v[52:55], v[20:23], v[186:189], v[52:55]
	v_mfma_f32_16x16x32_bf16 v[44:47], v[154:157], v[182:185], v[44:47]
	v_mfma_f32_16x16x32_bf16 v[36:39], v[20:23], v[194:197], v[36:39]
	v_mfma_f32_16x16x32_bf16 v[28:31], v[154:157], v[190:193], v[28:31]
	v_mfma_f32_16x16x32_bf16 v[20:23], v[20:23], v[202:205], v[0:3]
	v_mfma_f32_16x16x32_bf16 v[0:3], v[154:157], v[198:201], v[4:7]
	v_mfma_f32_16x16x32_bf16 v[60:63], v[158:161], v[178:181], v[60:63]
	v_mfma_f32_16x16x32_bf16 v[44:47], v[158:161], v[186:189], v[44:47]
	v_mfma_f32_16x16x32_bf16 v[28:31], v[158:161], v[194:197], v[28:31]
	v_mfma_f32_16x16x32_bf16 v[12:15], v[158:161], v[202:205], v[0:3]
	v_mfma_f32_16x16x32_bf16 v[0:3], v[206:209], v[162:165], v[64:67]
	v_mfma_f32_16x16x32_bf16 v[64:67], v[210:213], v[178:181], v[0:3]
	v_mfma_f32_16x16x32_bf16 v[0:3], v[214:217], v[162:165], v[56:59]
	v_mfma_f32_16x16x32_bf16 v[56:59], v[218:221], v[178:181], v[0:3]
	v_mfma_f32_16x16x32_bf16 v[0:3], v[206:209], v[182:185], v[48:51]
	v_mfma_f32_16x16x32_bf16 v[48:51], v[210:213], v[186:189], v[0:3]
	v_mfma_f32_16x16x32_bf16 v[0:3], v[214:217], v[182:185], v[40:43]
	v_mfma_f32_16x16x32_bf16 v[40:43], v[218:221], v[186:189], v[0:3]
	v_mfma_f32_16x16x32_bf16 v[0:3], v[206:209], v[190:193], v[32:35]
	v_mfma_f32_16x16x32_bf16 v[32:35], v[210:213], v[194:197], v[0:3]
	v_mfma_f32_16x16x32_bf16 v[0:3], v[214:217], v[190:193], v[24:27]
	v_mfma_f32_16x16x32_bf16 v[24:27], v[218:221], v[194:197], v[0:3]
	v_mfma_f32_16x16x32_bf16 v[0:3], v[206:209], v[198:201], v[16:19]
	v_mfma_f32_16x16x32_bf16 v[16:19], v[210:213], v[202:205], v[0:3]
	v_mfma_f32_16x16x32_bf16 v[0:3], v[214:217], v[198:201], v[8:11]
	v_mfma_f32_16x16x32_bf16 v[8:11], v[218:221], v[202:205], v[0:3]
	s_setprio 0
	s_add_i32 s63, s63, 2
	s_add_u32 s0, s0, 0x100
	s_addc_u32 s1, s1, 0
	s_add_u32 s61, s61, 0x100
	s_addc_u32 s62, s62, 0
	s_cmp_gt_u32 s63, 29
	s_barrier
	s_cbranch_scc0 .LBB0_1086
	v_lshl_add_u32 v164, s10, 8, v169
	v_or_b32_e32 v160, 16, v164
	v_or_b32_e32 v158, 32, v164
	v_or_b32_e32 v156, 48, v164
	s_mov_b64 s[0:1], -1
	s_cmp_lg_u32 s10, s58
	v_ashrrev_i32_e32 v165, 31, v164
	v_ashrrev_i32_e32 v161, 31, v160
	v_ashrrev_i32_e32 v159, 31, v158
	v_ashrrev_i32_e32 v157, 31, v156
	v_add_u32_e32 v166, 0x80, v164
	s_cbranch_scc0 .LBB0_1089
	v_lshlrev_b64 v[0:1], 7, v[164:165]
	v_lshlrev_b64 v[4:5], 7, v[160:161]
	v_lshl_add_u64 v[162:163], v[144:145], 0, v[0:1]
	v_lshl_add_u64 v[154:155], v[144:145], 0, v[4:5]
	global_load_dwordx4 v[0:3], v[162:163], off
	global_load_dwordx4 v[4:7], v[154:155], off
	global_load_dwordx4 v[178:181], v[162:163], off offset:16
	global_load_dwordx4 v[182:185], v[154:155], off offset:16
	v_lshlrev_b64 v[154:155], 7, v[158:159]
	v_lshlrev_b64 v[186:187], 7, v[156:157]
	v_lshl_add_u64 v[154:155], v[144:145], 0, v[154:155]
	v_lshl_add_u64 v[198:199], v[144:145], 0, v[186:187]
	global_load_dwordx4 v[186:189], v[154:155], off
	global_load_dwordx4 v[190:193], v[198:199], off
	global_load_dwordx4 v[194:197], v[154:155], off offset:16
	s_nop 0
	global_load_dwordx4 v[198:201], v[198:199], off offset:16
	v_add_u32_e32 v154, 0x80, v164
	v_ashrrev_i32_e32 v155, 31, v154
	v_lshlrev_b64 v[202:203], 7, v[154:155]
	v_add_co_u32_e32 v204, vcc, s47, v162
	v_lshl_add_u64 v[210:211], v[144:145], 0, v[202:203]
	s_nop 0
	v_addc_co_u32_e32 v205, vcc, 0, v163, vcc
	global_load_dwordx4 v[202:205], v[204:205], off offset:2048
	s_nop 0
	global_load_dwordx4 v[206:209], v[210:211], off offset:16
	s_nop 0
	global_load_dwordx4 v[210:213], v[210:211], off
	v_and_b32_e32 v177, 64, v176
	v_add_co_u32_e32 v226, vcc, s54, v162
	v_xor_b32_e32 v167, 16, v176
	v_add_u32_e32 v177, 64, v177
	v_addc_co_u32_e32 v227, vcc, 0, v163, vcc
	v_xor_b32_e32 v216, 32, v176
	v_cmp_lt_i32_e32 vcc, v167, v177
	v_lshl_add_u64 v[214:215], v[162:163], 0, s[14:15]
	v_lshl_add_u64 v[222:223], v[162:163], 0, s[16:17]
	v_cndmask_b32_e32 v167, v176, v167, vcc
	v_cmp_lt_i32_e32 vcc, v216, v177
	v_lshl_add_u64 v[162:163], v[162:163], 0, s[18:19]
	v_lshlrev_b32_e32 v167, 2, v167
	v_cndmask_b32_e32 v177, v176, v216, vcc
	global_load_dwordx4 v[214:217], v[214:215], off offset:16
	s_nop 0
	global_load_dwordx4 v[218:221], v[226:227], off
	s_nop 0
	global_load_dwordx4 v[222:225], v[222:223], off offset:16
	s_nop 0
	global_load_dwordx4 v[226:229], v[226:227], off offset:2048
	s_nop 0
	global_load_dwordx4 v[230:233], v[162:163], off offset:16
	v_lshlrev_b32_e32 v177, 2, v177
	v_mov_b64_e32 v[234:235], s[28:29]
	s_waitcnt vmcnt(0)
; __device__ __forceinline__ void rstd8(const float* part, int row0, int fq, float (&rs)[8]) {
;     ...
; #pragma unroll
;     for (int k = 0; k < 8; ++k) { float s = ((v[k][0][0] + v[k][0][1]) + (v[k][0][2] + v[k][0][3])) + ((v[k][1][0] + v[k][1][1]) + (v[k][1][2] + v[k][1][3]));
;         s += __shfl_xor(s, 16); s += __shfl_xor(s, 32); rs[k] = rsqrtf(s * (1.0f / 2048.0f) + EPS); }
;     __device__ __forceinline__ void operator()(const f32x4 (&acc)[2][2][4][2], const pg8::Unit& u, int wr, int wc, int fr, int fq) const {
;     ...
;         if (u.pm != cached_pm) { rstd8(part, row0, fq, rsv);
; #pragma unroll
;             for (int k = 0; k < 8; ++k) mine[k * 64] = rsv[k];
;             cached_pm = u.pm; }
	v_mov_b32_e32 v163, v4
	v_mov_b32_e32 v162, v0
	v_mov_b32_e32 v4, v1
	v_mov_b32_e32 v0, v2
	v_mov_b32_e32 v1, v6
	v_mov_b32_e32 v6, v3
	v_mov_b32_e32 v2, v178
	v_mov_b32_e32 v3, v182
	v_mov_b32_e32 v182, v179
	v_mov_b32_e32 v178, v180
	v_mov_b32_e32 v179, v184
	v_mov_b32_e32 v184, v181
	v_pk_add_f32 v[4:5], v[162:163], v[4:5]
	v_pk_add_f32 v[0:1], v[0:1], v[6:7]
	v_pk_add_f32 v[2:3], v[2:3], v[182:183]
	v_pk_add_f32 v[6:7], v[178:179], v[184:185]
	v_pk_add_f32 v[0:1], v[4:5], v[0:1]
	v_pk_add_f32 v[2:3], v[2:3], v[6:7]
	v_mov_b32_e32 v180, v186
	v_pk_add_f32 v[0:1], v[0:1], v[2:3]
	ds_bpermute_b32 v2, v167, v0
	ds_bpermute_b32 v3, v167, v1
	v_mov_b32_e32 v181, v190
	v_mov_b32_e32 v190, v187
	v_mov_b32_e32 v186, v188
	v_mov_b32_e32 v187, v192
	v_mov_b32_e32 v192, v189
	v_mov_b32_e32 v188, v194
	v_mov_b32_e32 v189, v198
	v_mov_b32_e32 v198, v195
	v_mov_b32_e32 v194, v196
	v_mov_b32_e32 v195, v200
	v_mov_b32_e32 v200, v197
	s_waitcnt lgkmcnt(0)
	v_pk_add_f32 v[0:1], v[0:1], v[2:3]
	v_pk_add_f32 v[162:163], v[180:181], v[190:191]
	v_pk_add_f32 v[4:5], v[186:187], v[192:193]
	v_pk_add_f32 v[6:7], v[188:189], v[198:199]
	v_pk_add_f32 v[178:179], v[194:195], v[200:201]
	ds_bpermute_b32 v2, v177, v0
	ds_bpermute_b32 v3, v177, v1
	v_pk_add_f32 v[4:5], v[162:163], v[4:5]
	v_pk_add_f32 v[6:7], v[6:7], v[178:179]
	v_mov_b32_e32 v162, v212
	v_pk_add_f32 v[4:5], v[4:5], v[6:7]
	ds_bpermute_b32 v6, v167, v4
	ds_bpermute_b32 v7, v167, v5
	s_waitcnt lgkmcnt(2)
	v_pk_add_f32 v[0:1], v[0:1], v[2:3]
	v_mov_b32_e32 v163, v204
	v_pk_fma_f32 v[0:1], v[0:1], s[20:21], v[234:235] op_sel_hi:[1,0,0]
	v_mov_b32_e32 v204, v213
	v_mul_f32_e32 v2, 0x4b800000, v0
	v_mul_f32_e32 v3, 0x4b800000, v1
	v_cmp_gt_f32_e32 vcc, s55, v0
	v_cmp_gt_f32_e64 s[0:1], s55, v1
	v_pk_add_f32 v[162:163], v[162:163], v[204:205]
	v_cndmask_b32_e32 v0, v0, v2, vcc
	v_cndmask_b32_e64 v1, v1, v3, s[0:1]
	s_waitcnt lgkmcnt(0)
	v_pk_add_f32 v[2:3], v[4:5], v[6:7]
	ds_bpermute_b32 v4, v177, v2
	ds_bpermute_b32 v5, v177, v3
	v_rsq_f32_e32 v0, v0
	v_rsq_f32_e32 v1, v1
	v_mov_b32_e32 v178, v208
	v_mov_b32_e32 v179, v216
	s_waitcnt lgkmcnt(0)
	v_pk_add_f32 v[2:3], v[2:3], v[4:5]
	v_pk_mul_f32 v[6:7], v[0:1], s[30:31] op_sel_hi:[1,0]
	v_pk_fma_f32 v[2:3], v[2:3], s[20:21], v[234:235] op_sel_hi:[1,0,0]
	v_cndmask_b32_e64 v1, v1, v7, s[0:1]
	v_mul_f32_e32 v4, 0x4b800000, v2
	v_cmp_gt_f32_e64 s[0:1], s55, v2
	v_mov_b32_e32 v5, v202
	v_mov_b32_e32 v202, v211
	v_cndmask_b32_e64 v2, v2, v4, s[0:1]
	v_mov_b32_e32 v4, v210
	v_pk_add_f32 v[4:5], v[4:5], v[202:203]
	v_mov_b32_e32 v216, v209
	v_pk_add_f32 v[4:5], v[4:5], v[162:163]
	v_mov_b32_e32 v162, v206
	v_mov_b32_e32 v163, v214
	v_mov_b32_e32 v214, v207
	v_pk_add_f32 v[162:163], v[162:163], v[214:215]
	v_pk_add_f32 v[178:179], v[178:179], v[216:217]
	v_mul_f32_e32 v7, 0x4b800000, v3
	v_pk_add_f32 v[162:163], v[162:163], v[178:179]
	v_cmp_gt_f32_e64 s[4:5], s55, v3
	v_pk_add_f32 v[4:5], v[4:5], v[162:163]
	ds_bpermute_b32 v162, v167, v4
	ds_bpermute_b32 v163, v167, v5
	v_cndmask_b32_e64 v3, v3, v7, s[4:5]
	v_rsq_f32_e32 v2, v2
	v_rsq_f32_e32 v3, v3
	v_cndmask_b32_e32 v0, v0, v6, vcc
	s_waitcnt lgkmcnt(0)
	v_pk_add_f32 v[4:5], v[4:5], v[162:163]
	ds_bpermute_b32 v162, v177, v4
	ds_bpermute_b32 v163, v177, v5
	v_pk_mul_f32 v[6:7], v[2:3], s[30:31] op_sel_hi:[1,0]
	v_mov_b32_e32 v178, v226
	v_cndmask_b32_e64 v3, v3, v7, s[4:5]
	v_cndmask_b32_e64 v2, v2, v6, s[0:1]
	s_waitcnt lgkmcnt(0)
	v_pk_add_f32 v[4:5], v[4:5], v[162:163]
	v_mov_b32_e32 v6, v219
	v_mov_b32_e32 v7, v220
	v_mov_b32_e32 v219, v221
	v_mov_b32_e32 v162, v223
	v_mov_b32_e32 v163, v224
	v_mov_b32_e32 v223, v225
	v_mov_b32_e32 v179, v230
	v_mov_b32_e32 v230, v227
	v_mov_b32_e32 v180, v228
	v_mov_b32_e32 v181, v232
	v_mov_b32_e32 v232, v229
	v_pk_add_f32 v[6:7], v[6:7], v[218:219]
	v_pk_add_f32 v[162:163], v[162:163], v[222:223]
	v_pk_add_f32 v[178:179], v[178:179], v[230:231]
	v_pk_add_f32 v[180:181], v[180:181], v[232:233]
	v_pk_add_f32 v[6:7], v[6:7], v[6:7] op_sel:[0,1] op_sel_hi:[1,0]
	v_pk_add_f32 v[162:163], v[162:163], v[162:163] op_sel:[0,1] op_sel_hi:[1,0]
	v_pk_add_f32 v[178:179], v[178:179], v[180:181]
	v_pk_fma_f32 v[4:5], v[4:5], s[20:21], v[234:235] op_sel_hi:[1,0,0]
	v_mov_b32_e32 v7, v178
	v_mov_b32_e32 v163, v179
	v_pk_add_f32 v[6:7], v[6:7], v[162:163]
	ds_bpermute_b32 v162, v167, v6
	ds_bpermute_b32 v163, v167, v7
	v_mul_f32_e32 v167, 0x4b800000, v4
	v_cmp_gt_f32_e32 vcc, s55, v4
	v_cmp_gt_f32_e64 s[0:1], s55, v5
	s_waitcnt lgkmcnt(0)
	v_pk_add_f32 v[6:7], v[6:7], v[162:163]
	ds_bpermute_b32 v162, v177, v6
	ds_bpermute_b32 v163, v177, v7
	v_cndmask_b32_e32 v4, v4, v167, vcc
	v_mul_f32_e32 v167, 0x4b800000, v5
	v_cndmask_b32_e64 v5, v5, v167, s[0:1]
	v_rsq_f32_e32 v4, v4
	s_waitcnt lgkmcnt(0)
	v_pk_add_f32 v[6:7], v[6:7], v[162:163]
	v_rsq_f32_e32 v5, v5
	v_pk_fma_f32 v[6:7], v[6:7], s[20:21], v[234:235] op_sel_hi:[1,0,0]
	s_nop 0
	v_mul_f32_e32 v162, 0x4b800000, v6
	v_cmp_gt_f32_e64 s[4:5], s55, v6
	v_cmp_gt_f32_e64 s[6:7], s55, v7
	s_nop 0
	v_cndmask_b32_e64 v6, v6, v162, s[4:5]
	v_mul_f32_e32 v162, 0x4b800000, v7
	v_cndmask_b32_e64 v7, v7, v162, s[6:7]
	v_rsq_f32_e32 v6, v6
	v_rsq_f32_e32 v7, v7
	v_pk_mul_f32 v[162:163], v[4:5], s[30:31] op_sel_hi:[1,0]
	s_nop 0
	v_cndmask_b32_e64 v5, v5, v163, s[0:1]
	v_cndmask_b32_e32 v4, v4, v162, vcc
	v_pk_mul_f32 v[162:163], v[6:7], s[30:31] op_sel_hi:[1,0]
	s_mov_b64 s[0:1], 0
	v_cndmask_b32_e64 v7, v7, v163, s[6:7]
	v_cndmask_b32_e64 v6, v6, v162, s[4:5]
	ds_write2st64_b32 v171, v0, v1 offset1:1
	ds_write2st64_b32 v171, v2, v3 offset0:2 offset1:3
	ds_write2st64_b32 v171, v4, v5 offset0:4 offset1:5
	ds_write2st64_b32 v171, v6, v7 offset0:6 offset1:7
	v_mov_b64_e32 v[162:163], v[154:155]

; #define PG8_STAGE(bufoff, gbase, voff) do { _Pragma("unroll") for (int _i = 0; _i < 2; ++_i) \
;         __builtin_amdgcn_global_load_lds((const unsigned*)((const char*)(gbase) + (voff)[_i]), (PG8_LAS unsigned*)(lds + (bufoff) + ldsw + _i * 8192), 16, 0, 0); } while (0)
; #define PG8_LDA(dst, b, h) do { _Pragma("unroll") for (int m = 0; m < 4; ++m) _Pragma("unroll") for (int k = 0; k < 2; ++k) dst[m][k] = *(const PG8_LAS bf16x8*)(lds + PG8_SA(b, h) + aoff + m * 2048 + k * 1024); } while (0)
; #define PG8_LDB(dst, b, h) do { _Pragma("unroll") for (int n = 0; n < 2; ++n) _Pragma("unroll") for (int k = 0; k < 2; ++k) dst[n][k] = *(const PG8_LAS bf16x8*)(lds + PG8_SB(b, h) + boff + n * 2048 + k * 1024); } while (0)
; #define PG8_MMA(ai, bj, At, Bt) do { __builtin_amdgcn_s_setprio(1); _Pragma("unroll") for (int m = 0; m < 4; ++m) _Pragma("unroll") for (int n = 0; n < 2; ++n) _Pragma("unroll") for (int k = 0; k < 2; ++k) \
;         acc[ai][bj][m][n] = __builtin_amdgcn_mfma_f32_16x16x32_bf16(Bt[n][k], At[m][k], acc[ai][bj][m][n], 0, 0, 0); __builtin_amdgcn_s_setprio(0); } while (0)
; #define PG8_WAIT_V(n) asm volatile("s_waitcnt vmcnt(" #n ")" ::: "memory")
; #define PG8_WAIT_L(n) asm volatile("s_waitcnt lgkmcnt(" #n ")" ::: "memory")
; template <class Epi>
; __device__ __forceinline__ void gemm_phase(PG8_LAS unsigned char* lds, const Gemm g, const StaticOrder& S, const Epi& E) {
;     ...
;         for (int t = 0; t < nt; t += 2) {
;             const bool last = (t == nt - 2);
;             const char* a1 = cA + (size_t)(t + 1) * kstep;
;             const char* a2 = last ? nA : cA + (size_t)(t + 2) * kstep; const char* b2 = last ? nB : cB + (size_t)(t + 2) * kstep;
;             const char* a3 = a2 + kstep; const char* b3 = b2 + kstep;
;             PG8_LDB(B0, 0, 0); PG8_SCHED; PG8_LDA(At, 0, 0); PG8_STAGE(PG8_SA(1, 1), a1 + hstepA, voffA);
;             PG8_WAIT_L(8); PG8_BAR; PG8_WAIT_L(0); PG8_MMA(0, 0, At, B0); PG8_BAR; PG8_SCHED;
;             PG8_LDB(B1, 0, 1); PG8_STAGE(PG8_SB(0, 0), b2, voffB);
;             PG8_BAR; PG8_WAIT_L(0); PG8_MMA(0, 1, At, B1); PG8_BAR;
;             PG8_LDA(At, 0, 1); PG8_STAGE(PG8_SA(0, 0), a2, voffA);
;             PG8_BAR; PG8_WAIT_L(0); PG8_MMA(1, 0, At, B0); PG8_BAR; PG8_SCHED;
;             PG8_STAGE(PG8_SB(0, 1), b2 + hstepB, voffB);
;             PG8_WAIT_V(6); PG8_BAR; PG8_MMA(1, 1, At, B1); PG8_BAR;
.LBB0_1170:
	ds_read_b128 v[144:147], v155
	ds_read_b128 v[148:151], v155 offset:1024
	ds_read_b128 v[158:161], v155 offset:2048
	ds_read_b128 v[162:165], v155 offset:3072
	ds_read_b128 v[166:169], v156
	ds_read_b128 v[170:173], v156 offset:1024
	ds_read_b128 v[174:177], v156 offset:2048
	ds_read_b128 v[178:181], v156 offset:3072
	ds_read_b128 v[182:185], v156 offset:4096
	ds_read_b128 v[186:189], v156 offset:5120
	ds_read_b128 v[190:193], v156 offset:6144
	ds_read_b128 v[194:197], v156 offset:7168
	ds_read_b128 v[198:201], v157
	ds_read_b128 v[202:205], v157 offset:1024
	ds_read_b128 v[206:209], v157 offset:2048
	ds_read_b128 v[210:213], v157 offset:3072
	s_add_u32 s12, s10, 0xffea0080
	s_addc_u32 s13, s11, -1
	s_cmpk_eq_i32 s38, 0x54
	s_cselect_b32 s15, s3, s13
	s_cselect_b32 s14, s2, s12
	s_cselect_b32 s13, s5, s37
	s_cselect_b32 s12, s4, s36
	v_lshl_add_u64 v[222:223], s[10:11], 0, v[136:137]
	s_add_i32 m0, s19, 0xc000
	s_nop 0
	global_load_lds_dwordx4 v[222:223], off
	v_lshl_add_u64 v[222:223], s[10:11], 0, v[138:139]
	s_add_i32 m0, s19, 0xe000
	s_nop 0
	global_load_lds_dwordx4 v[222:223], off
	s_waitcnt lgkmcnt(0)
	s_waitcnt vmcnt(8)
	s_barrier
	s_setprio 1
	v_mfma_f32_16x16x32_bf16 v[124:127], v[144:147], v[166:169], v[124:127]
	v_mfma_f32_16x16x32_bf16 v[120:123], v[158:161], v[166:169], v[120:123]
	v_mfma_f32_16x16x32_bf16 v[108:111], v[144:147], v[174:177], v[108:111]
	v_mfma_f32_16x16x32_bf16 v[104:107], v[158:161], v[174:177], v[104:107]
	v_mfma_f32_16x16x32_bf16 v[88:91], v[144:147], v[182:185], v[88:91]
	v_mfma_f32_16x16x32_bf16 v[92:95], v[158:161], v[182:185], v[92:95]
	v_mfma_f32_16x16x32_bf16 v[72:75], v[144:147], v[190:193], v[72:75]
	v_mfma_f32_16x16x32_bf16 v[76:79], v[158:161], v[190:193], v[76:79]
	v_mfma_f32_16x16x32_bf16 v[124:127], v[148:151], v[170:173], v[124:127]
	v_mfma_f32_16x16x32_bf16 v[120:123], v[162:165], v[170:173], v[120:123]
	v_mfma_f32_16x16x32_bf16 v[108:111], v[148:151], v[178:181], v[108:111]
	v_mfma_f32_16x16x32_bf16 v[104:107], v[162:165], v[178:181], v[104:107]
	v_mfma_f32_16x16x32_bf16 v[88:91], v[148:151], v[186:189], v[88:91]
	v_mfma_f32_16x16x32_bf16 v[92:95], v[162:165], v[186:189], v[92:95]
	v_mfma_f32_16x16x32_bf16 v[72:75], v[148:151], v[194:197], v[72:75]
	v_mfma_f32_16x16x32_bf16 v[76:79], v[162:165], v[194:197], v[76:79]
	v_mfma_f32_16x16x32_bf16 v[116:119], v[198:201], v[166:169], v[116:119]
	v_mfma_f32_16x16x32_bf16 v[112:115], v[206:209], v[166:169], v[112:115]
	v_mfma_f32_16x16x32_bf16 v[100:103], v[198:201], v[174:177], v[100:103]
	v_mfma_f32_16x16x32_bf16 v[96:99], v[206:209], v[174:177], v[96:99]
	v_mfma_f32_16x16x32_bf16 v[80:83], v[198:201], v[182:185], v[80:83]
	v_mfma_f32_16x16x32_bf16 v[84:87], v[206:209], v[182:185], v[84:87]
	v_mfma_f32_16x16x32_bf16 v[64:67], v[198:201], v[190:193], v[64:67]
	v_mfma_f32_16x16x32_bf16 v[68:71], v[206:209], v[190:193], v[68:71]
	v_mfma_f32_16x16x32_bf16 v[116:119], v[202:205], v[170:173], v[116:119]
	v_mfma_f32_16x16x32_bf16 v[112:115], v[210:213], v[170:173], v[112:115]
	v_mfma_f32_16x16x32_bf16 v[100:103], v[202:205], v[178:181], v[100:103]
	v_mfma_f32_16x16x32_bf16 v[96:99], v[210:213], v[178:181], v[96:99]
	v_mfma_f32_16x16x32_bf16 v[80:83], v[202:205], v[186:189], v[80:83]
	v_mfma_f32_16x16x32_bf16 v[84:87], v[210:213], v[186:189], v[84:87]
	v_mfma_f32_16x16x32_bf16 v[64:67], v[202:205], v[194:197], v[64:67]
	v_mfma_f32_16x16x32_bf16 v[68:71], v[210:213], v[194:197], v[68:71]
	s_setprio 0
	s_barrier
	ds_read_b128 v[166:169], v156 offset:16384
	ds_read_b128 v[170:173], v156 offset:17408
	ds_read_b128 v[174:177], v156 offset:18432
	ds_read_b128 v[178:181], v156 offset:19456
	ds_read_b128 v[182:185], v156 offset:20480
	ds_read_b128 v[186:189], v156 offset:21504
	ds_read_b128 v[190:193], v156 offset:22528
	ds_read_b128 v[194:197], v156 offset:23552
	s_add_i32 s39, s29, s18
	v_lshl_add_u64 v[214:215], s[12:13], 0, v[130:131]
	s_mov_b32 m0, s39
	s_nop 0
	global_load_lds_dwordx4 v[214:215], off
	v_lshl_add_u64 v[216:217], s[12:13], 0, v[134:135]
	s_add_i32 m0, s39, 0x2000
	s_nop 0
	global_load_lds_dwordx4 v[216:217], off
	s_mov_b32 m0, s19
	v_lshl_add_u64 v[218:219], s[14:15], 0, v[128:129]
	global_load_lds_dwordx4 v[218:219], off
	v_lshl_add_u64 v[220:221], s[14:15], 0, v[132:133]
	s_mov_b32 m0, s20
	s_nop 0
	global_load_lds_dwordx4 v[220:221], off
	s_add_u32 s40, s12, 0x160000
	s_addc_u32 s41, s13, 0
	s_add_i32 s39, s30, s18
	v_lshl_add_u64 v[222:223], s[40:41], 0, v[130:131]
	s_mov_b32 m0, s39
	s_nop 0
	global_load_lds_dwordx4 v[222:223], off
	v_lshl_add_u64 v[222:223], s[40:41], 0, v[134:135]
	s_add_i32 m0, s39, 0x2000
	s_nop 0
	global_load_lds_dwordx4 v[222:223], off
	s_waitcnt lgkmcnt(0)
	s_waitcnt vmcnt(8)
	s_barrier
; #define PG8_STAGE(bufoff, gbase, voff) do { _Pragma("unroll") for (int _i = 0; _i < 2; ++_i) \
;         __builtin_amdgcn_global_load_lds((const unsigned*)((const char*)(gbase) + (voff)[_i]), (PG8_LAS unsigned*)(lds + (bufoff) + ldsw + _i * 8192), 16, 0, 0); } while (0)
; #define PG8_LDA(dst, b, h) do { _Pragma("unroll") for (int m = 0; m < 4; ++m) _Pragma("unroll") for (int k = 0; k < 2; ++k) dst[m][k] = *(const PG8_LAS bf16x8*)(lds + PG8_SA(b, h) + aoff + m * 2048 + k * 1024); } while (0)
; #define PG8_LDB(dst, b, h) do { _Pragma("unroll") for (int n = 0; n < 2; ++n) _Pragma("unroll") for (int k = 0; k < 2; ++k) dst[n][k] = *(const PG8_LAS bf16x8*)(lds + PG8_SB(b, h) + boff + n * 2048 + k * 1024); } while (0)
; #define PG8_MMA(ai, bj, At, Bt) do { __builtin_amdgcn_s_setprio(1); _Pragma("unroll") for (int m = 0; m < 4; ++m) _Pragma("unroll") for (int n = 0; n < 2; ++n) _Pragma("unroll") for (int k = 0; k < 2; ++k) \
;         acc[ai][bj][m][n] = __builtin_amdgcn_mfma_f32_16x16x32_bf16(Bt[n][k], At[m][k], acc[ai][bj][m][n], 0, 0, 0); __builtin_amdgcn_s_setprio(0); } while (0)
; #define PG8_WAIT_V(n) asm volatile("s_waitcnt vmcnt(" #n ")" ::: "memory")
; #define PG8_WAIT_L(n) asm volatile("s_waitcnt lgkmcnt(" #n ")" ::: "memory")
; #define PG8_BAR __builtin_amdgcn_s_barrier()
; #define PG8_SCHED __builtin_amdgcn_sched_barrier(0)
; template <class Epi>
; __device__ __forceinline__ void gemm_phase(PG8_LAS unsigned char* lds, const Gemm g, const StaticOrder& S, const Epi& E) {
;     ...
;             PG8_BAR; PG8_WAIT_L(0); PG8_MMA(0, 1, At, B1); PG8_BAR;
;             PG8_LDA(At, 0, 1); PG8_STAGE(PG8_SA(0, 0), a2, voffA);
;             PG8_BAR; PG8_WAIT_L(0); PG8_MMA(1, 0, At, B0); PG8_BAR; PG8_SCHED;
;             PG8_STAGE(PG8_SB(0, 1), b2 + hstepB, voffB);
;             PG8_WAIT_V(6); PG8_BAR; PG8_MMA(1, 1, At, B1); PG8_BAR;
;             PG8_LDB(B0, 1, 0); PG8_SCHED; PG8_LDA(At, 1, 0); PG8_STAGE(PG8_SA(0, 1), a2 + hstepA, voffA);
;             PG8_WAIT_L(8); PG8_BAR; PG8_WAIT_L(0); PG8_MMA(0, 0, At, B0); PG8_BAR; PG8_SCHED;
;             PG8_LDB(B1, 1, 1); PG8_STAGE(PG8_SB(1, 0), b3, voffB);
;             PG8_BAR; PG8_WAIT_L(0); PG8_MMA(0, 1, At, B1); PG8_BAR;
	s_setprio 1
	v_mfma_f32_16x16x32_bf16 v[56:59], v[144:147], v[166:169], v[56:59]
	v_mfma_f32_16x16x32_bf16 v[60:63], v[158:161], v[166:169], v[60:63]
	v_mfma_f32_16x16x32_bf16 v[40:43], v[144:147], v[174:177], v[40:43]
	v_mfma_f32_16x16x32_bf16 v[44:47], v[158:161], v[174:177], v[44:47]
	v_mfma_f32_16x16x32_bf16 v[24:27], v[144:147], v[182:185], v[24:27]
	v_mfma_f32_16x16x32_bf16 v[28:31], v[158:161], v[182:185], v[28:31]
	v_mfma_f32_16x16x32_bf16 v[8:11], v[144:147], v[190:193], v[8:11]
	v_mfma_f32_16x16x32_bf16 v[12:15], v[158:161], v[190:193], v[12:15]
	v_mfma_f32_16x16x32_bf16 v[56:59], v[148:151], v[170:173], v[56:59]
	v_mfma_f32_16x16x32_bf16 v[60:63], v[162:165], v[170:173], v[60:63]
	v_mfma_f32_16x16x32_bf16 v[40:43], v[148:151], v[178:181], v[40:43]
	v_mfma_f32_16x16x32_bf16 v[44:47], v[162:165], v[178:181], v[44:47]
	v_mfma_f32_16x16x32_bf16 v[24:27], v[148:151], v[186:189], v[24:27]
	v_mfma_f32_16x16x32_bf16 v[28:31], v[162:165], v[186:189], v[28:31]
	v_mfma_f32_16x16x32_bf16 v[8:11], v[148:151], v[194:197], v[8:11]
	v_mfma_f32_16x16x32_bf16 v[12:15], v[162:165], v[194:197], v[12:15]
	v_mfma_f32_16x16x32_bf16 v[48:51], v[198:201], v[166:169], v[48:51]
	v_mfma_f32_16x16x32_bf16 v[52:55], v[206:209], v[166:169], v[52:55]
	v_mfma_f32_16x16x32_bf16 v[32:35], v[198:201], v[174:177], v[32:35]
	v_mfma_f32_16x16x32_bf16 v[36:39], v[206:209], v[174:177], v[36:39]
	v_mfma_f32_16x16x32_bf16 v[16:19], v[198:201], v[182:185], v[16:19]
	v_mfma_f32_16x16x32_bf16 v[20:23], v[206:209], v[182:185], v[20:23]
	v_mfma_f32_16x16x32_bf16 v[0:3], v[198:201], v[190:193], v[0:3]
	v_mfma_f32_16x16x32_bf16 v[4:7], v[206:209], v[190:193], v[4:7]
	v_mfma_f32_16x16x32_bf16 v[48:51], v[202:205], v[170:173], v[48:51]
	v_mfma_f32_16x16x32_bf16 v[52:55], v[210:213], v[170:173], v[52:55]
	v_mfma_f32_16x16x32_bf16 v[32:35], v[202:205], v[178:181], v[32:35]
	v_mfma_f32_16x16x32_bf16 v[36:39], v[210:213], v[178:181], v[36:39]
	v_mfma_f32_16x16x32_bf16 v[16:19], v[202:205], v[186:189], v[16:19]
	v_mfma_f32_16x16x32_bf16 v[20:23], v[210:213], v[186:189], v[20:23]
	v_mfma_f32_16x16x32_bf16 v[0:3], v[202:205], v[194:197], v[0:3]
	v_mfma_f32_16x16x32_bf16 v[4:7], v[210:213], v[194:197], v[4:7]
	s_setprio 0
	s_add_i32 s39, 0, 0x18000
	v_add_u32_e32 v162, s39, v153
	s_barrier
	ds_read_b128 v[144:147], v162
	ds_read_b128 v[148:151], v162 offset:1024
	ds_read_b128 v[158:161], v162 offset:2048
	ds_read_b128 v[162:165], v162 offset:3072
	ds_read_b128 v[166:169], v156 offset:32768
	ds_read_b128 v[170:173], v156 offset:33792
	ds_read_b128 v[174:177], v156 offset:34816
	ds_read_b128 v[178:181], v156 offset:35840
	ds_read_b128 v[182:185], v156 offset:36864
	ds_read_b128 v[186:189], v156 offset:37888
	ds_read_b128 v[190:193], v156 offset:38912
	ds_read_b128 v[194:197], v156 offset:39936
	v_add_u32_e32 v210, 0x1c000, v153
	ds_read_b128 v[198:201], v210
	ds_read_b128 v[202:205], v210 offset:1024
	ds_read_b128 v[206:209], v210 offset:2048
	ds_read_b128 v[210:213], v210 offset:3072
	s_add_u32 s14, s14, 0x160000
	s_addc_u32 s15, s15, 0
	s_mov_b32 m0, s21
	v_lshl_add_u64 v[222:223], s[14:15], 0, v[128:129]
	global_load_lds_dwordx4 v[222:223], off
	v_lshl_add_u64 v[222:223], s[14:15], 0, v[132:133]
	s_mov_b32 m0, s22
	s_nop 0
	global_load_lds_dwordx4 v[222:223], off
	s_waitcnt lgkmcnt(0)
	s_waitcnt vmcnt(8)
	s_barrier
	s_setprio 1
	v_mfma_f32_16x16x32_bf16 v[124:127], v[144:147], v[166:169], v[124:127]
	v_mfma_f32_16x16x32_bf16 v[120:123], v[158:161], v[166:169], v[120:123]
	v_mfma_f32_16x16x32_bf16 v[108:111], v[144:147], v[174:177], v[108:111]
	v_mfma_f32_16x16x32_bf16 v[104:107], v[158:161], v[174:177], v[104:107]
	v_mfma_f32_16x16x32_bf16 v[88:91], v[144:147], v[182:185], v[88:91]
	v_mfma_f32_16x16x32_bf16 v[92:95], v[158:161], v[182:185], v[92:95]
	v_mfma_f32_16x16x32_bf16 v[72:75], v[144:147], v[190:193], v[72:75]
	v_mfma_f32_16x16x32_bf16 v[76:79], v[158:161], v[190:193], v[76:79]
	v_mfma_f32_16x16x32_bf16 v[124:127], v[148:151], v[170:173], v[124:127]
	v_mfma_f32_16x16x32_bf16 v[120:123], v[162:165], v[170:173], v[120:123]
	v_mfma_f32_16x16x32_bf16 v[108:111], v[148:151], v[178:181], v[108:111]
	v_mfma_f32_16x16x32_bf16 v[104:107], v[162:165], v[178:181], v[104:107]
	v_mfma_f32_16x16x32_bf16 v[88:91], v[148:151], v[186:189], v[88:91]
	v_mfma_f32_16x16x32_bf16 v[92:95], v[162:165], v[186:189], v[92:95]
	v_mfma_f32_16x16x32_bf16 v[72:75], v[148:151], v[194:197], v[72:75]
	v_mfma_f32_16x16x32_bf16 v[76:79], v[162:165], v[194:197], v[76:79]
	v_mfma_f32_16x16x32_bf16 v[116:119], v[198:201], v[166:169], v[116:119]
	v_mfma_f32_16x16x32_bf16 v[112:115], v[206:209], v[166:169], v[112:115]
	v_mfma_f32_16x16x32_bf16 v[100:103], v[198:201], v[174:177], v[100:103]
	v_mfma_f32_16x16x32_bf16 v[96:99], v[206:209], v[174:177], v[96:99]
	v_mfma_f32_16x16x32_bf16 v[80:83], v[198:201], v[182:185], v[80:83]
	v_mfma_f32_16x16x32_bf16 v[84:87], v[206:209], v[182:185], v[84:87]
	v_mfma_f32_16x16x32_bf16 v[64:67], v[198:201], v[190:193], v[64:67]
	v_mfma_f32_16x16x32_bf16 v[68:71], v[206:209], v[190:193], v[68:71]
	v_mfma_f32_16x16x32_bf16 v[116:119], v[202:205], v[170:173], v[116:119]
	v_mfma_f32_16x16x32_bf16 v[112:115], v[210:213], v[170:173], v[112:115]
	v_mfma_f32_16x16x32_bf16 v[100:103], v[202:205], v[178:181], v[100:103]
	v_mfma_f32_16x16x32_bf16 v[96:99], v[210:213], v[178:181], v[96:99]
	v_mfma_f32_16x16x32_bf16 v[80:83], v[202:205], v[186:189], v[80:83]
	v_mfma_f32_16x16x32_bf16 v[84:87], v[210:213], v[186:189], v[84:87]
	v_mfma_f32_16x16x32_bf16 v[64:67], v[202:205], v[194:197], v[64:67]
	v_mfma_f32_16x16x32_bf16 v[68:71], v[210:213], v[194:197], v[68:71]
	s_setprio 0
	s_barrier
; #define PG8_STAGE(bufoff, gbase, voff) do { _Pragma("unroll") for (int _i = 0; _i < 2; ++_i) \
;         __builtin_amdgcn_global_load_lds((const unsigned*)((const char*)(gbase) + (voff)[_i]), (PG8_LAS unsigned*)(lds + (bufoff) + ldsw + _i * 8192), 16, 0, 0); } while (0)
; #define PG8_LDA(dst, b, h) do { _Pragma("unroll") for (int m = 0; m < 4; ++m) _Pragma("unroll") for (int k = 0; k < 2; ++k) dst[m][k] = *(const PG8_LAS bf16x8*)(lds + PG8_SA(b, h) + aoff + m * 2048 + k * 1024); } while (0)
; #define PG8_LDB(dst, b, h) do { _Pragma("unroll") for (int n = 0; n < 2; ++n) _Pragma("unroll") for (int k = 0; k < 2; ++k) dst[n][k] = *(const PG8_LAS bf16x8*)(lds + PG8_SB(b, h) + boff + n * 2048 + k * 1024); } while (0)
; #define PG8_MMA(ai, bj, At, Bt) do { __builtin_amdgcn_s_setprio(1); _Pragma("unroll") for (int m = 0; m < 4; ++m) _Pragma("unroll") for (int n = 0; n < 2; ++n) _Pragma("unroll") for (int k = 0; k < 2; ++k) \
;         acc[ai][bj][m][n] = __builtin_amdgcn_mfma_f32_16x16x32_bf16(Bt[n][k], At[m][k], acc[ai][bj][m][n], 0, 0, 0); __builtin_amdgcn_s_setprio(0); } while (0)
; #define PG8_WAIT_V(n) asm volatile("s_waitcnt vmcnt(" #n ")" ::: "memory")
; #define PG8_WAIT_L(n) asm volatile("s_waitcnt lgkmcnt(" #n ")" ::: "memory")
; template <class Epi>
; __device__ __forceinline__ void gemm_phase(PG8_LAS unsigned char* lds, const Gemm g, const StaticOrder& S, const Epi& E) {
;     ...
;             PG8_LDB(B1, 1, 1); PG8_STAGE(PG8_SB(1, 0), b3, voffB);
;             PG8_BAR; PG8_WAIT_L(0); PG8_MMA(0, 1, At, B1); PG8_BAR;
;             PG8_LDA(At, 1, 1); PG8_STAGE(PG8_SA(1, 0), a3, voffA);
;             PG8_BAR; PG8_WAIT_L(0); PG8_MMA(1, 0, At, B0); PG8_BAR; PG8_SCHED;
;             PG8_STAGE(PG8_SB(1, 1), b3 + hstepB, voffB);
;             PG8_WAIT_V(6); PG8_BAR; PG8_MMA(1, 1, At, B1); PG8_BAR;
;     __device__ __forceinline__ void operator()(const f32x4 (&acc)[2][2][4][2], const pg8::Unit& u, int wr, int wc, int fr, int fq) const {
;         const int row0 = u.pm * 256 + wr * 64 + fr, col0 = u.pn * 256 + wc * 32 + 8 * fq;
; #pragma unroll
;         for (int ai = 0; ai < 2; ++ai) {
;             u32x4 rb[4][2];
; #pragma unroll
;             for (int m = 0; m < 4; ++m)
; #pragma unroll
;                 for (int bj = 0; bj < 2; ++bj) rb[m][bj] = *(const u32x4*)(resb + (size_t)(row0 + ai * 128 + m * 16) * DM + col0 + bj * 128);
	ds_read_b128 v[166:169], v156 offset:49152
	ds_read_b128 v[170:173], v156 offset:50176
	ds_read_b128 v[174:177], v156 offset:51200
	ds_read_b128 v[178:181], v156 offset:52224
	ds_read_b128 v[182:185], v156 offset:53248
	ds_read_b128 v[186:189], v156 offset:54272
	ds_read_b128 v[190:193], v156 offset:55296
	ds_read_b128 v[194:197], v156 offset:56320
	s_add_i32 s14, 0, 0x1c000
	s_add_i32 s15, s39, s18
	v_lshl_add_u64 v[214:215], v[214:215], 0, s[6:7]
	s_mov_b32 m0, s15
	s_nop 0
	global_load_lds_dwordx4 v[214:215], off
	v_lshl_add_u64 v[214:215], v[216:217], 0, s[6:7]
	s_add_i32 m0, s15, 0x2000
	s_nop 0
	global_load_lds_dwordx4 v[214:215], off
	s_mov_b32 m0, s25
	v_lshl_add_u64 v[214:215], v[218:219], 0, s[6:7]
	global_load_lds_dwordx4 v[214:215], off
	v_lshl_add_u64 v[214:215], v[220:221], 0, s[6:7]
	s_mov_b32 m0, s27
	s_nop 0
	global_load_lds_dwordx4 v[214:215], off
	s_add_u32 s12, s12, 0x160080
	s_addc_u32 s13, s13, 0
	s_add_i32 s14, s14, s18
	v_lshl_add_u64 v[222:223], s[12:13], 0, v[130:131]
	s_mov_b32 m0, s14
	s_nop 0
	global_load_lds_dwordx4 v[222:223], off
	v_lshl_add_u64 v[222:223], s[12:13], 0, v[134:135]
	s_add_i32 m0, s14, 0x2000
	s_nop 0
	global_load_lds_dwordx4 v[222:223], off
	s_waitcnt lgkmcnt(0)
	s_waitcnt vmcnt(8)
	s_barrier
	s_setprio 1
	v_mfma_f32_16x16x32_bf16 v[56:59], v[144:147], v[166:169], v[56:59]
	v_mfma_f32_16x16x32_bf16 v[60:63], v[158:161], v[166:169], v[60:63]
	v_mfma_f32_16x16x32_bf16 v[40:43], v[144:147], v[174:177], v[40:43]
	v_mfma_f32_16x16x32_bf16 v[44:47], v[158:161], v[174:177], v[44:47]
	v_mfma_f32_16x16x32_bf16 v[24:27], v[144:147], v[182:185], v[24:27]
	v_mfma_f32_16x16x32_bf16 v[28:31], v[158:161], v[182:185], v[28:31]
	v_mfma_f32_16x16x32_bf16 v[8:11], v[144:147], v[190:193], v[8:11]
	v_mfma_f32_16x16x32_bf16 v[12:15], v[158:161], v[190:193], v[12:15]
	v_mfma_f32_16x16x32_bf16 v[56:59], v[148:151], v[170:173], v[56:59]
	v_mfma_f32_16x16x32_bf16 v[60:63], v[162:165], v[170:173], v[60:63]
	v_mfma_f32_16x16x32_bf16 v[40:43], v[148:151], v[178:181], v[40:43]
	v_mfma_f32_16x16x32_bf16 v[44:47], v[162:165], v[178:181], v[44:47]
	v_mfma_f32_16x16x32_bf16 v[24:27], v[148:151], v[186:189], v[24:27]
	v_mfma_f32_16x16x32_bf16 v[28:31], v[162:165], v[186:189], v[28:31]
	v_mfma_f32_16x16x32_bf16 v[8:11], v[148:151], v[194:197], v[8:11]
	v_mfma_f32_16x16x32_bf16 v[12:15], v[162:165], v[194:197], v[12:15]
	v_mfma_f32_16x16x32_bf16 v[48:51], v[198:201], v[166:169], v[48:51]
	v_mfma_f32_16x16x32_bf16 v[52:55], v[206:209], v[166:169], v[52:55]
	v_mfma_f32_16x16x32_bf16 v[32:35], v[198:201], v[174:177], v[32:35]
	v_mfma_f32_16x16x32_bf16 v[36:39], v[206:209], v[174:177], v[36:39]
	v_mfma_f32_16x16x32_bf16 v[16:19], v[198:201], v[182:185], v[16:19]
	v_mfma_f32_16x16x32_bf16 v[20:23], v[206:209], v[182:185], v[20:23]
	v_mfma_f32_16x16x32_bf16 v[0:3], v[198:201], v[190:193], v[0:3]
	v_mfma_f32_16x16x32_bf16 v[4:7], v[206:209], v[190:193], v[4:7]
	v_mfma_f32_16x16x32_bf16 v[48:51], v[202:205], v[170:173], v[48:51]
	v_mfma_f32_16x16x32_bf16 v[52:55], v[210:213], v[170:173], v[52:55]
	v_mfma_f32_16x16x32_bf16 v[32:35], v[202:205], v[178:181], v[32:35]
	v_mfma_f32_16x16x32_bf16 v[36:39], v[210:213], v[178:181], v[36:39]
	v_mfma_f32_16x16x32_bf16 v[16:19], v[202:205], v[186:189], v[16:19]
	v_mfma_f32_16x16x32_bf16 v[20:23], v[210:213], v[186:189], v[20:23]
	v_mfma_f32_16x16x32_bf16 v[0:3], v[202:205], v[194:197], v[0:3]
	v_mfma_f32_16x16x32_bf16 v[4:7], v[210:213], v[194:197], v[4:7]
	s_setprio 0
	s_add_i32 s38, s38, 2
	s_add_u32 s10, s10, 0x100
	s_addc_u32 s11, s11, 0
	s_add_u32 s36, s36, 0x100
	s_addc_u32 s37, s37, 0
	s_cmpk_gt_u32 s38, 0x55
	s_barrier
	s_cbranch_scc0 .LBB0_1170
	s_andn2_b64 vcc, exec, s[8:9]
	s_cbranch_vccnz .LBB0_1158
	v_lshl_or_b32 v144, s35, 8, v154
	v_lshl_add_u32 v148, s34, 8, v152
	v_ashrrev_i32_e32 v145, 31, v144
	v_ashrrev_i32_e32 v149, 31, v148
	v_lshl_add_u64 v[146:147], v[144:145], 1, s[76:77]
	v_lshlrev_b64 v[150:151], 12, v[148:149]
	v_or_b32_e32 v182, 16, v148
	v_lshl_add_u64 v[150:151], v[146:147], 0, v[150:151]
	v_ashrrev_i32_e32 v183, 31, v182
	global_load_dwordx4 v[158:161], v[150:151], off
	global_load_dwordx4 v[162:165], v[150:151], off offset:256
	v_lshlrev_b64 v[150:151], 12, v[182:183]
	v_lshl_add_u64 v[150:151], v[146:147], 0, v[150:151]
	v_or_b32_e32 v190, 32, v148
	global_load_dwordx4 v[166:169], v[150:151], off
	global_load_dwordx4 v[170:173], v[150:151], off offset:256
	v_ashrrev_i32_e32 v191, 31, v190
	v_lshlrev_b64 v[150:151], 12, v[190:191]
	v_lshl_add_u64 v[150:151], v[146:147], 0, v[150:151]
	global_load_dwordx4 v[174:177], v[150:151], off
	global_load_dwordx4 v[178:181], v[150:151], off offset:256
	v_or_b32_e32 v150, 48, v148
	v_ashrrev_i32_e32 v151, 31, v150
	v_lshlrev_b64 v[184:185], 13, v[148:149]
	v_lshlrev_b64 v[186:187], 12, v[150:151]
	v_lshlrev_b64 v[144:145], 2, v[144:145]
	v_lshl_add_u64 v[184:185], s[42:43], 0, v[184:185]
	v_lshlrev_b64 v[182:183], 13, v[182:183]
	v_lshl_add_u64 v[186:187], v[146:147], 0, v[186:187]
	v_lshl_add_u64 v[192:193], v[184:185], 0, v[144:145]
	v_lshl_add_u64 v[194:195], s[42:43], 0, v[182:183]
	global_load_dwordx4 v[182:185], v[186:187], off offset:256
	s_nop 0
	global_load_dwordx4 v[186:189], v[186:187], off
	v_lshl_add_u64 v[194:195], v[194:195], 0, v[144:145]
	s_waitcnt vmcnt(0)
;     __device__ __forceinline__ void operator()(const f32x4 (&acc)[2][2][4][2], const pg8::Unit& u, int wr, int wc, int fr, int fq) const {
;     ...
;                 for (int bj = 0; bj < 2; ++bj) rb[m][bj] = *(const u32x4*)(resb + (size_t)(row0 + ai * 128 + m * 16) * DM + col0 + bj * 128);
; #pragma unroll
;             for (int m = 0; m < 4; ++m) {
;                 const int r = row0 + ai * 128 + m * 16; float ss = 0.f;
; #pragma unroll
;                 for (int bj = 0; bj < 2; ++bj) {
;                     const size_t off = (size_t)r * DM + col0 + bj * 128;
;                     float rv[8], o[8]; unpack8(rb[m][bj], rv);
; #pragma unroll
;                     for (int n = 0; n < 2; ++n)
; #pragma unroll
;                         for (int i = 0; i < 4; ++i) o[n * 4 + i] = rv[n * 4 + i] + coef * acc[ai][bj][m][n][i];
;                     if (outf) { *(f32x4*)(outf + off) = (f32x4){o[0], o[1], o[2], o[3]}; *(f32x4*)(outf + off + 4) = (f32x4){o[4], o[5], o[6], o[7]}; }
	v_lshlrev_b32_e32 v196, 16, v160
	v_and_b32_e32 v197, 0xffff0000, v160
	v_lshlrev_b32_e32 v160, 16, v161
	v_and_b32_e32 v161, 0xffff0000, v161
	v_lshlrev_b32_e32 v198, 16, v158
	v_and_b32_e32 v199, 0xffff0000, v158
	v_lshlrev_b32_e32 v158, 16, v159
	v_and_b32_e32 v159, 0xffff0000, v159
	v_lshlrev_b32_e32 v200, 16, v164
	v_and_b32_e32 v201, 0xffff0000, v164
	v_lshlrev_b32_e32 v164, 16, v165
	v_and_b32_e32 v165, 0xffff0000, v165
	v_lshlrev_b32_e32 v202, 16, v162
	v_and_b32_e32 v203, 0xffff0000, v162
	v_lshlrev_b32_e32 v162, 16, v163
	v_and_b32_e32 v163, 0xffff0000, v163
	v_pk_fma_f32 v[122:123], v[122:123], 0.5, v[160:161] op_sel_hi:[1,0,1]
	v_pk_fma_f32 v[126:127], v[126:127], 0.5, v[158:159] op_sel_hi:[1,0,1]
	v_pk_fma_f32 v[114:115], v[114:115], 0.5, v[164:165] op_sel_hi:[1,0,1]
	v_pk_fma_f32 v[118:119], v[118:119], 0.5, v[162:163] op_sel_hi:[1,0,1]
	v_lshlrev_b32_e32 v158, 16, v168
	v_and_b32_e32 v159, 0xffff0000, v168
	v_lshlrev_b32_e32 v160, 16, v169
	v_and_b32_e32 v161, 0xffff0000, v169
	v_lshlrev_b32_e32 v162, 16, v166
	v_and_b32_e32 v163, 0xffff0000, v166
	v_lshlrev_b32_e32 v164, 16, v167
	v_and_b32_e32 v165, 0xffff0000, v167
	v_lshlrev_b32_e32 v168, 16, v173
	v_and_b32_e32 v169, 0xffff0000, v173
	v_pk_fma_f32 v[124:125], v[124:125], 0.5, v[198:199] op_sel_hi:[1,0,1]
	v_lshlrev_b32_e32 v166, 16, v172
	v_and_b32_e32 v167, 0xffff0000, v172
	v_lshlrev_b32_e32 v172, 16, v170
	v_and_b32_e32 v173, 0xffff0000, v170
	v_lshlrev_b32_e32 v170, 16, v171
	v_and_b32_e32 v171, 0xffff0000, v171
	v_pk_fma_f32 v[108:109], v[108:109], 0.5, v[162:163] op_sel_hi:[1,0,1]
	v_pk_fma_f32 v[110:111], v[110:111], 0.5, v[164:165] op_sel_hi:[1,0,1]
	v_pk_fma_f32 v[98:99], v[98:99], 0.5, v[168:169] op_sel_hi:[1,0,1]
	v_pk_fma_f32 v[120:121], v[120:121], 0.5, v[196:197] op_sel_hi:[1,0,1]
	v_pk_fma_f32 v[112:113], v[112:113], 0.5, v[200:201] op_sel_hi:[1,0,1]
	v_pk_fma_f32 v[116:117], v[116:117], 0.5, v[202:203] op_sel_hi:[1,0,1]
	global_store_dwordx4 v[192:193], v[124:127], off
	global_store_dwordx4 v[192:193], v[120:123], off offset:16
	global_store_dwordx4 v[192:193], v[116:119], off offset:512
	global_store_dwordx4 v[192:193], v[112:115], off offset:528
	v_pk_fma_f32 v[104:105], v[104:105], 0.5, v[158:159] op_sel_hi:[1,0,1]
	v_pk_fma_f32 v[106:107], v[106:107], 0.5, v[160:161] op_sel_hi:[1,0,1]
	v_pk_fma_f32 v[96:97], v[96:97], 0.5, v[166:167] op_sel_hi:[1,0,1]
	v_pk_fma_f32 v[100:101], v[100:101], 0.5, v[172:173] op_sel_hi:[1,0,1]
	v_pk_fma_f32 v[102:103], v[102:103], 0.5, v[170:171] op_sel_hi:[1,0,1]
	global_store_dwordx4 v[194:195], v[108:111], off
	global_store_dwordx4 v[194:195], v[104:107], off offset:16
	global_store_dwordx4 v[194:195], v[100:103], off offset:512
	global_store_dwordx4 v[194:195], v[96:99], off offset:528
	s_nop 0
	v_add_u32_e32 v100, 0xa0, v148
	v_lshlrev_b32_e32 v98, 16, v176
	v_and_b32_e32 v99, 0xffff0000, v176
	v_pk_fma_f32 v[92:93], v[92:93], 0.5, v[98:99] op_sel_hi:[1,0,1]
	v_lshlrev_b32_e32 v98, 16, v177
	v_and_b32_e32 v99, 0xffff0000, v177
	v_lshlrev_b64 v[96:97], 13, v[190:191]
	v_pk_fma_f32 v[94:95], v[94:95], 0.5, v[98:99] op_sel_hi:[1,0,1]
	v_lshlrev_b32_e32 v98, 16, v174
	v_and_b32_e32 v99, 0xffff0000, v174
	v_lshl_add_u64 v[96:97], s[42:43], 0, v[96:97]
	v_pk_fma_f32 v[88:89], v[88:89], 0.5, v[98:99] op_sel_hi:[1,0,1]
	v_lshlrev_b32_e32 v98, 16, v175
	v_and_b32_e32 v99, 0xffff0000, v175
	v_lshl_add_u64 v[96:97], v[96:97], 0, v[144:145]
	v_pk_fma_f32 v[90:91], v[90:91], 0.5, v[98:99] op_sel_hi:[1,0,1]
	global_store_dwordx4 v[96:97], v[88:91], off
	global_store_dwordx4 v[96:97], v[92:95], off offset:16
	v_add_u32_e32 v98, 0x90, v148
	v_lshlrev_b32_e32 v88, 16, v180
	v_and_b32_e32 v89, 0xffff0000, v180
	v_pk_fma_f32 v[84:85], v[84:85], 0.5, v[88:89] op_sel_hi:[1,0,1]
	v_lshlrev_b32_e32 v88, 16, v181
	v_and_b32_e32 v89, 0xffff0000, v181
	v_pk_fma_f32 v[86:87], v[86:87], 0.5, v[88:89] op_sel_hi:[1,0,1]
	v_lshlrev_b32_e32 v88, 16, v178
	v_and_b32_e32 v89, 0xffff0000, v178
	v_pk_fma_f32 v[80:81], v[80:81], 0.5, v[88:89] op_sel_hi:[1,0,1]
	v_lshlrev_b32_e32 v88, 16, v179
	v_and_b32_e32 v89, 0xffff0000, v179
	v_pk_fma_f32 v[82:83], v[82:83], 0.5, v[88:89] op_sel_hi:[1,0,1]
	global_store_dwordx4 v[96:97], v[80:83], off offset:512
	global_store_dwordx4 v[96:97], v[84:87], off offset:528
	v_add_u32_e32 v96, 0x80, v148
	v_lshlrev_b32_e32 v82, 16, v188
	v_and_b32_e32 v83, 0xffff0000, v188
	v_pk_fma_f32 v[76:77], v[76:77], 0.5, v[82:83] op_sel_hi:[1,0,1]
	v_lshlrev_b32_e32 v82, 16, v189
	v_and_b32_e32 v83, 0xffff0000, v189
	v_lshlrev_b64 v[80:81], 13, v[150:151]
	v_pk_fma_f32 v[78:79], v[78:79], 0.5, v[82:83] op_sel_hi:[1,0,1]
	v_lshlrev_b32_e32 v82, 16, v186
	v_and_b32_e32 v83, 0xffff0000, v186
	v_lshl_add_u64 v[80:81], s[42:43], 0, v[80:81]
	v_pk_fma_f32 v[72:73], v[72:73], 0.5, v[82:83] op_sel_hi:[1,0,1]
	v_lshlrev_b32_e32 v82, 16, v187
	v_and_b32_e32 v83, 0xffff0000, v187
	v_lshl_add_u64 v[80:81], v[80:81], 0, v[144:145]
	v_pk_fma_f32 v[74:75], v[74:75], 0.5, v[82:83] op_sel_hi:[1,0,1]
	global_store_dwordx4 v[80:81], v[72:75], off
	global_store_dwordx4 v[80:81], v[76:79], off offset:16
	v_ashrrev_i32_e32 v97, 31, v96
	v_lshlrev_b32_e32 v72, 16, v184
	v_and_b32_e32 v73, 0xffff0000, v184
	v_pk_fma_f32 v[68:69], v[68:69], 0.5, v[72:73] op_sel_hi:[1,0,1]
	v_lshlrev_b32_e32 v72, 16, v185
	v_and_b32_e32 v73, 0xffff0000, v185
	v_pk_fma_f32 v[70:71], v[70:71], 0.5, v[72:73] op_sel_hi:[1,0,1]
	v_lshlrev_b32_e32 v72, 16, v182
	v_and_b32_e32 v73, 0xffff0000, v182
	v_pk_fma_f32 v[64:65], v[64:65], 0.5, v[72:73] op_sel_hi:[1,0,1]
	v_lshlrev_b32_e32 v72, 16, v183
	v_and_b32_e32 v73, 0xffff0000, v183
	v_pk_fma_f32 v[66:67], v[66:67], 0.5, v[72:73] op_sel_hi:[1,0,1]
	global_store_dwordx4 v[80:81], v[64:67], off offset:512
	global_store_dwordx4 v[80:81], v[68:71], off offset:528
	v_ashrrev_i32_e32 v99, 31, v98
	v_lshlrev_b64 v[64:65], 12, v[96:97]
	v_lshl_add_u64 v[64:65], v[146:147], 0, v[64:65]
	global_load_dwordx4 v[68:71], v[64:65], off
	global_load_dwordx4 v[72:75], v[64:65], off offset:256
	v_lshlrev_b64 v[64:65], 12, v[98:99]
	v_lshl_add_u64 v[64:65], v[146:147], 0, v[64:65]
	global_load_dwordx4 v[76:79], v[64:65], off
	global_load_dwordx4 v[80:83], v[64:65], off offset:256
	v_ashrrev_i32_e32 v101, 31, v100
	v_lshlrev_b64 v[64:65], 12, v[100:101]
	v_lshl_add_u64 v[64:65], v[146:147], 0, v[64:65]
	global_load_dwordx4 v[84:87], v[64:65], off
	global_load_dwordx4 v[88:91], v[64:65], off offset:256
	v_add_u32_e32 v102, 0xb0, v148
	v_ashrrev_i32_e32 v103, 31, v102
	v_lshlrev_b64 v[64:65], 12, v[102:103]
	v_lshl_add_u64 v[92:93], v[146:147], 0, v[64:65]
	global_load_dwordx4 v[64:67], v[92:93], off offset:256
	s_nop 0
	global_load_dwordx4 v[92:95], v[92:93], off
	v_lshlrev_b64 v[96:97], 13, v[96:97]
	v_lshl_add_u64 v[96:97], s[42:43], 0, v[96:97]
	v_lshl_add_u64 v[96:97], v[96:97], 0, v[144:145]
	s_waitcnt vmcnt(0)
;     __device__ __forceinline__ void operator()(const f32x4 (&acc)[2][2][4][2], const pg8::Unit& u, int wr, int wc, int fr, int fq) const {
;     ...
;             for (int m = 0; m < 4; ++m) {
;                 const int r = row0 + ai * 128 + m * 16; float ss = 0.f;
; #pragma unroll
;                 for (int bj = 0; bj < 2; ++bj) {
;                     const size_t off = (size_t)r * DM + col0 + bj * 128;
;                     float rv[8], o[8]; unpack8(rb[m][bj], rv);
; #pragma unroll
;                     for (int n = 0; n < 2; ++n)
; #pragma unroll
;                         for (int i = 0; i < 4; ++i) o[n * 4 + i] = rv[n * 4 + i] + coef * acc[ai][bj][m][n][i];
;                     if (outf) { *(f32x4*)(outf + off) = (f32x4){o[0], o[1], o[2], o[3]}; *(f32x4*)(outf + off + 4) = (f32x4){o[4], o[5], o[6], o[7]}; }
	v_lshlrev_b32_e32 v104, 16, v70
	v_and_b32_e32 v105, 0xffff0000, v70
	v_lshlrev_b32_e32 v70, 16, v71
	v_and_b32_e32 v71, 0xffff0000, v71
	v_pk_fma_f32 v[62:63], v[62:63], 0.5, v[70:71] op_sel_hi:[1,0,1]
	v_lshlrev_b32_e32 v70, 16, v68
	v_and_b32_e32 v71, 0xffff0000, v68
	v_lshlrev_b32_e32 v68, 16, v69
	v_and_b32_e32 v69, 0xffff0000, v69
	v_pk_fma_f32 v[56:57], v[56:57], 0.5, v[70:71] op_sel_hi:[1,0,1]
	v_pk_fma_f32 v[58:59], v[58:59], 0.5, v[68:69] op_sel_hi:[1,0,1]
	v_pk_fma_f32 v[60:61], v[60:61], 0.5, v[104:105] op_sel_hi:[1,0,1]
	global_store_dwordx4 v[96:97], v[56:59], off
	global_store_dwordx4 v[96:97], v[60:63], off offset:16
	s_nop 0
	v_lshlrev_b32_e32 v56, 16, v74
	v_and_b32_e32 v57, 0xffff0000, v74
	v_pk_fma_f32 v[52:53], v[52:53], 0.5, v[56:57] op_sel_hi:[1,0,1]
	v_lshlrev_b32_e32 v56, 16, v75
	v_and_b32_e32 v57, 0xffff0000, v75
	v_pk_fma_f32 v[54:55], v[54:55], 0.5, v[56:57] op_sel_hi:[1,0,1]
	v_lshlrev_b32_e32 v56, 16, v72
	v_and_b32_e32 v57, 0xffff0000, v72
	v_pk_fma_f32 v[48:49], v[48:49], 0.5, v[56:57] op_sel_hi:[1,0,1]
	v_lshlrev_b32_e32 v56, 16, v73
	v_and_b32_e32 v57, 0xffff0000, v73
	v_pk_fma_f32 v[50:51], v[50:51], 0.5, v[56:57] op_sel_hi:[1,0,1]
	global_store_dwordx4 v[96:97], v[48:51], off offset:512
	global_store_dwordx4 v[96:97], v[52:55], off offset:528
	s_nop 0
	v_lshlrev_b32_e32 v50, 16, v78
	v_and_b32_e32 v51, 0xffff0000, v78
	v_pk_fma_f32 v[44:45], v[44:45], 0.5, v[50:51] op_sel_hi:[1,0,1]
	v_lshlrev_b32_e32 v50, 16, v79
	v_and_b32_e32 v51, 0xffff0000, v79
	v_lshlrev_b64 v[48:49], 13, v[98:99]
	v_pk_fma_f32 v[46:47], v[46:47], 0.5, v[50:51] op_sel_hi:[1,0,1]
	v_lshlrev_b32_e32 v50, 16, v76
	v_and_b32_e32 v51, 0xffff0000, v76
	v_lshl_add_u64 v[48:49], s[42:43], 0, v[48:49]
	v_pk_fma_f32 v[40:41], v[40:41], 0.5, v[50:51] op_sel_hi:[1,0,1]
	v_lshlrev_b32_e32 v50, 16, v77
	v_and_b32_e32 v51, 0xffff0000, v77
	v_lshl_add_u64 v[48:49], v[48:49], 0, v[144:145]
	v_pk_fma_f32 v[42:43], v[42:43], 0.5, v[50:51] op_sel_hi:[1,0,1]
	global_store_dwordx4 v[48:49], v[40:43], off
	global_store_dwordx4 v[48:49], v[44:47], off offset:16
	s_nop 0
	v_lshlrev_b32_e32 v40, 16, v82
	v_and_b32_e32 v41, 0xffff0000, v82
	v_pk_fma_f32 v[36:37], v[36:37], 0.5, v[40:41] op_sel_hi:[1,0,1]
	v_lshlrev_b32_e32 v40, 16, v83
	v_and_b32_e32 v41, 0xffff0000, v83
	v_pk_fma_f32 v[38:39], v[38:39], 0.5, v[40:41] op_sel_hi:[1,0,1]
	v_lshlrev_b32_e32 v40, 16, v80
	v_and_b32_e32 v41, 0xffff0000, v80
	v_pk_fma_f32 v[32:33], v[32:33], 0.5, v[40:41] op_sel_hi:[1,0,1]
	v_lshlrev_b32_e32 v40, 16, v81
	v_and_b32_e32 v41, 0xffff0000, v81
	v_pk_fma_f32 v[34:35], v[34:35], 0.5, v[40:41] op_sel_hi:[1,0,1]
	global_store_dwordx4 v[48:49], v[32:35], off offset:512
	global_store_dwordx4 v[48:49], v[36:39], off offset:528
	s_nop 0
	v_lshlrev_b32_e32 v34, 16, v86
	v_and_b32_e32 v35, 0xffff0000, v86
	v_pk_fma_f32 v[28:29], v[28:29], 0.5, v[34:35] op_sel_hi:[1,0,1]
	v_lshlrev_b32_e32 v34, 16, v87
	v_and_b32_e32 v35, 0xffff0000, v87
	v_lshlrev_b64 v[32:33], 13, v[100:101]
	v_pk_fma_f32 v[30:31], v[30:31], 0.5, v[34:35] op_sel_hi:[1,0,1]
	v_lshlrev_b32_e32 v34, 16, v84
	v_and_b32_e32 v35, 0xffff0000, v84
	v_lshl_add_u64 v[32:33], s[42:43], 0, v[32:33]
	v_pk_fma_f32 v[24:25], v[24:25], 0.5, v[34:35] op_sel_hi:[1,0,1]
	v_lshlrev_b32_e32 v34, 16, v85
	v_and_b32_e32 v35, 0xffff0000, v85
	v_lshl_add_u64 v[32:33], v[32:33], 0, v[144:145]
	v_pk_fma_f32 v[26:27], v[26:27], 0.5, v[34:35] op_sel_hi:[1,0,1]
	global_store_dwordx4 v[32:33], v[24:27], off
	global_store_dwordx4 v[32:33], v[28:31], off offset:16
	s_nop 0
	v_lshlrev_b32_e32 v24, 16, v90
	v_and_b32_e32 v25, 0xffff0000, v90
	v_pk_fma_f32 v[20:21], v[20:21], 0.5, v[24:25] op_sel_hi:[1,0,1]
	v_lshlrev_b32_e32 v24, 16, v91
	v_and_b32_e32 v25, 0xffff0000, v91
	v_pk_fma_f32 v[22:23], v[22:23], 0.5, v[24:25] op_sel_hi:[1,0,1]
	v_lshlrev_b32_e32 v24, 16, v88
	v_and_b32_e32 v25, 0xffff0000, v88
	v_pk_fma_f32 v[16:17], v[16:17], 0.5, v[24:25] op_sel_hi:[1,0,1]
	v_lshlrev_b32_e32 v24, 16, v89
	v_and_b32_e32 v25, 0xffff0000, v89
	v_pk_fma_f32 v[18:19], v[18:19], 0.5, v[24:25] op_sel_hi:[1,0,1]
	global_store_dwordx4 v[32:33], v[16:19], off offset:512
	global_store_dwordx4 v[32:33], v[20:23], off offset:528
	s_nop 0
	v_lshlrev_b32_e32 v18, 16, v94
	v_and_b32_e32 v19, 0xffff0000, v94
	v_pk_fma_f32 v[12:13], v[12:13], 0.5, v[18:19] op_sel_hi:[1,0,1]
	v_lshlrev_b32_e32 v18, 16, v95
	v_and_b32_e32 v19, 0xffff0000, v95
	v_lshlrev_b64 v[16:17], 13, v[102:103]
	v_pk_fma_f32 v[14:15], v[14:15], 0.5, v[18:19] op_sel_hi:[1,0,1]
	v_lshlrev_b32_e32 v18, 16, v92
	v_and_b32_e32 v19, 0xffff0000, v92
	v_lshl_add_u64 v[16:17], s[42:43], 0, v[16:17]
	v_pk_fma_f32 v[8:9], v[8:9], 0.5, v[18:19] op_sel_hi:[1,0,1]
	v_lshlrev_b32_e32 v18, 16, v93
	v_and_b32_e32 v19, 0xffff0000, v93
	v_lshl_add_u64 v[16:17], v[16:17], 0, v[144:145]
	v_pk_fma_f32 v[10:11], v[10:11], 0.5, v[18:19] op_sel_hi:[1,0,1]
	global_store_dwordx4 v[16:17], v[8:11], off
	global_store_dwordx4 v[16:17], v[12:15], off offset:16
	s_nop 0
	v_lshlrev_b32_e32 v8, 16, v66
	v_and_b32_e32 v9, 0xffff0000, v66
	v_pk_fma_f32 v[4:5], v[4:5], 0.5, v[8:9] op_sel_hi:[1,0,1]
	v_lshlrev_b32_e32 v8, 16, v67
	v_and_b32_e32 v9, 0xffff0000, v67
	v_pk_fma_f32 v[6:7], v[6:7], 0.5, v[8:9] op_sel_hi:[1,0,1]
	v_lshlrev_b32_e32 v8, 16, v64
	v_and_b32_e32 v9, 0xffff0000, v64
	v_pk_fma_f32 v[0:1], v[0:1], 0.5, v[8:9] op_sel_hi:[1,0,1]
	v_lshlrev_b32_e32 v8, 16, v65
	v_and_b32_e32 v9, 0xffff0000, v65
	v_pk_fma_f32 v[2:3], v[2:3], 0.5, v[8:9] op_sel_hi:[1,0,1]
	global_store_dwordx4 v[16:17], v[0:3], off offset:512
	global_store_dwordx4 v[16:17], v[4:7], off offset:528
	s_branch .LBB0_1158
